# plus: lean cached-scale epilogue for MLP-up L1 (byte-quant, conservative event pre-check) + hand-written pipelined pool phase
# speedup vs baseline: 1.0125x; 1.0031x over previous
.LBB0_345:
	s_mov_b64 s[0:1], s[78:79]
	s_load_dword s0, s[0:1], 0xa8
	v_writelane_b32 v255, s78, 0
	s_waitcnt lgkmcnt(0)
	s_cmp_gt_i32 s0, 2
	v_writelane_b32 v255, s79, 1
	v_writelane_b32 v255, s81, 2
	s_cbranch_scc1 .LBB0_373
	s_mov_b64 s[0:1], s[78:79]
	s_load_dword s0, s[0:1], 0xac
	s_waitcnt lgkmcnt(0)
	s_cmp_lt_i32 s0, 3
	s_cbranch_scc1 .LBB0_373
	s_mov_b64 s[0:1], s[78:79]
	s_load_dwordx2 s[0:1], s[0:1], 0xa0
	s_lshl_b32 s3, s80, 3
	s_add_i32 s7, s3, s81
	s_mov_b32 s6, -1
	s_mov_b32 s2, -1
	s_cmpk_gt_i32 s7, 0x5ff
	s_cbranch_scc1 .LBB0_369
	s_waitcnt lgkmcnt(0)
	s_add_u32 s8, s0, 0x46a00000
	s_addc_u32 s9, s1, 0
	s_add_u32 s12, s0, 0x54a00000
	s_addc_u32 s13, s1, 0
	s_lshl_b32 s10, s77, 3
	v_mbcnt_lo_u32_b32 v0, -1, 0
	v_mbcnt_hi_u32_b32 v0, -1, v0
	v_mov_b32_e32 v45, 0
	v_mov_b32_e32 v47, 0
.Lpool_item:
	s_mul_hi_u32 s14, s7, 0xaaaaaaab
	s_lshr_b32 s14, s14, 2
	s_mul_i32 s15, s14, 6
	s_sub_u32 s15, s7, s15
	s_and_b32 s16, s14, 31
	s_lshr_b32 s17, s14, 5
	s_lshl_b32 s18, s15, 10
	v_lshl_add_u32 v1, v0, 4, s18
	v_lshrrev_b32_e32 v51, 1, v1
	v_mov_b32_e32 v2, 2
	v_cmp_le_u32_e32 vcc, 0x300, v51
	s_nop 1
	v_cndmask_b32_e64 v2, v2, 4, vcc
	v_cmp_le_u32_e32 vcc, 0x600, v51
	s_nop 1
	v_cndmask_b32_e64 v2, v2, 8, vcc
	v_cmp_le_u32_e32 vcc, 0x900, v51
	s_nop 1
	v_cndmask_b32_e64 v2, v2, 16, vcc
	v_ffbh_u32_e32 v53, v2
	v_add_u32_e32 v53, 0xffffffe1, v53
	v_ldexp_f32 v3, 1.0, v53
	v_sub_u32_e32 v49, 16, v2
	v_lshl_add_u32 v49, v49, 13, v1
	v_add_u32_e32 v50, 0x20000, v1
	s_lshl_b32 s19, s16, 6
	s_cmp_eq_u32 s16, 0
	s_cselect_b32 s26, 0, 16
	s_sub_u32 s27, s19, s26
	s_lshl_b32 s28, s17, 24
	s_lshr_b32 s29, s17, 8
	s_lshl_b32 s30, s27, 13
	s_add_u32 s20, s8, s28
	s_addc_u32 s21, s9, s29
	s_add_u32 s20, s20, s30
	s_addc_u32 s21, s21, 0
	s_sub_u32 s22, s20, 0x20000
	s_subb_u32 s23, s21, 0
	s_lshl_b32 s30, s19, 13
	s_add_u32 s24, s12, s28
	s_addc_u32 s25, s13, s29
	s_add_u32 s24, s24, s30
	s_addc_u32 s25, s25, 0
	v_mov_b32_e32 v4, 0
	v_mov_b32_e32 v5, 0
	v_mov_b32_e32 v6, 0
	v_mov_b32_e32 v7, 0
	v_mov_b32_e32 v8, 0
	v_mov_b32_e32 v9, 0
	v_mov_b32_e32 v10, 0
	v_mov_b32_e32 v11, 0
	s_cmp_eq_u32 s16, 0
	s_cbranch_scc1 .Lpool_tc0
.Lpool_tcn:
	global_load_dwordx4 v[64:67], v1, s[20:21]
	global_load_dwordx4 v[96:99], v50, s[22:23]
	s_add_u32 s20, s20, 0x2000
	s_addc_u32 s21, s21, 0
	s_add_u32 s22, s22, 0x2000
	s_addc_u32 s23, s23, 0
	global_load_dwordx4 v[68:71], v1, s[20:21]
	global_load_dwordx4 v[100:103], v50, s[22:23]
	s_add_u32 s20, s20, 0x2000
	s_addc_u32 s21, s21, 0
	s_add_u32 s22, s22, 0x2000
	s_addc_u32 s23, s23, 0
	global_load_dwordx4 v[72:75], v1, s[20:21]
	v_cmp_ge_u32_e32 vcc, 2, v2
	s_nop 1
	v_cndmask_b32_e32 v55, v50, v49, vcc
	global_load_dwordx4 v[104:107], v55, s[22:23]
	s_add_u32 s20, s20, 0x2000
	s_addc_u32 s21, s21, 0
	s_add_u32 s22, s22, 0x2000
	s_addc_u32 s23, s23, 0
	global_load_dwordx4 v[76:79], v1, s[20:21]
	v_cmp_ge_u32_e32 vcc, 3, v2
	s_nop 1
	v_cndmask_b32_e32 v55, v50, v49, vcc
	global_load_dwordx4 v[108:111], v55, s[22:23]
	s_add_u32 s20, s20, 0x2000
	s_addc_u32 s21, s21, 0
	s_add_u32 s22, s22, 0x2000
	s_addc_u32 s23, s23, 0
	global_load_dwordx4 v[80:83], v1, s[20:21]
	v_cmp_ge_u32_e32 vcc, 4, v2
	s_nop 1
	v_cndmask_b32_e32 v55, v50, v49, vcc
	global_load_dwordx4 v[112:115], v55, s[22:23]
	s_add_u32 s20, s20, 0x2000
	s_addc_u32 s21, s21, 0
	s_add_u32 s22, s22, 0x2000
	s_addc_u32 s23, s23, 0
	global_load_dwordx4 v[84:87], v1, s[20:21]
	v_cmp_ge_u32_e32 vcc, 5, v2
	s_nop 1
	v_cndmask_b32_e32 v55, v50, v49, vcc
	global_load_dwordx4 v[116:119], v55, s[22:23]
	s_add_u32 s20, s20, 0x2000
	s_addc_u32 s21, s21, 0
	s_add_u32 s22, s22, 0x2000
	s_addc_u32 s23, s23, 0
	global_load_dwordx4 v[88:91], v1, s[20:21]
	v_cmp_ge_u32_e32 vcc, 6, v2
	s_nop 1
	v_cndmask_b32_e32 v55, v50, v49, vcc
	global_load_dwordx4 v[120:123], v55, s[22:23]
	s_add_u32 s20, s20, 0x2000
	s_addc_u32 s21, s21, 0
	s_add_u32 s22, s22, 0x2000
	s_addc_u32 s23, s23, 0
	global_load_dwordx4 v[92:95], v1, s[20:21]
	v_cmp_ge_u32_e32 vcc, 7, v2
	s_nop 1
	v_cndmask_b32_e32 v55, v50, v49, vcc
	global_load_dwordx4 v[124:127], v55, s[22:23]
	s_add_u32 s20, s20, 0x2000
	s_addc_u32 s21, s21, 0
	s_add_u32 s22, s22, 0x2000
	s_addc_u32 s23, s23, 0
	global_load_dwordx4 v[128:131], v1, s[20:21]
	v_cmp_ge_u32_e32 vcc, 8, v2
	s_nop 1
	v_cndmask_b32_e32 v55, v50, v49, vcc
	global_load_dwordx4 v[160:163], v55, s[22:23]
	s_add_u32 s20, s20, 0x2000
	s_addc_u32 s21, s21, 0
	s_add_u32 s22, s22, 0x2000
	s_addc_u32 s23, s23, 0
	global_load_dwordx4 v[132:135], v1, s[20:21]
	v_cmp_ge_u32_e32 vcc, 9, v2
	s_nop 1
	v_cndmask_b32_e32 v55, v50, v49, vcc
	global_load_dwordx4 v[164:167], v55, s[22:23]
	s_add_u32 s20, s20, 0x2000
	s_addc_u32 s21, s21, 0
	s_add_u32 s22, s22, 0x2000
	s_addc_u32 s23, s23, 0
	global_load_dwordx4 v[136:139], v1, s[20:21]
	v_cmp_ge_u32_e32 vcc, 10, v2
	s_nop 1
	v_cndmask_b32_e32 v55, v50, v49, vcc
	global_load_dwordx4 v[168:171], v55, s[22:23]
	s_add_u32 s20, s20, 0x2000
	s_addc_u32 s21, s21, 0
	s_add_u32 s22, s22, 0x2000
	s_addc_u32 s23, s23, 0
	global_load_dwordx4 v[140:143], v1, s[20:21]
	v_cmp_ge_u32_e32 vcc, 11, v2
	s_nop 1
	v_cndmask_b32_e32 v55, v50, v49, vcc
	global_load_dwordx4 v[172:175], v55, s[22:23]
	s_add_u32 s20, s20, 0x2000
	s_addc_u32 s21, s21, 0
	s_add_u32 s22, s22, 0x2000
	s_addc_u32 s23, s23, 0
	global_load_dwordx4 v[144:147], v1, s[20:21]
	v_cmp_ge_u32_e32 vcc, 12, v2
	s_nop 1
	v_cndmask_b32_e32 v55, v50, v49, vcc
	global_load_dwordx4 v[176:179], v55, s[22:23]
	s_add_u32 s20, s20, 0x2000
	s_addc_u32 s21, s21, 0
	s_add_u32 s22, s22, 0x2000
	s_addc_u32 s23, s23, 0
	global_load_dwordx4 v[148:151], v1, s[20:21]
	v_cmp_ge_u32_e32 vcc, 13, v2
	s_nop 1
	v_cndmask_b32_e32 v55, v50, v49, vcc
	global_load_dwordx4 v[180:183], v55, s[22:23]
	s_add_u32 s20, s20, 0x2000
	s_addc_u32 s21, s21, 0
	s_add_u32 s22, s22, 0x2000
	s_addc_u32 s23, s23, 0
	global_load_dwordx4 v[152:155], v1, s[20:21]
	v_cmp_ge_u32_e32 vcc, 14, v2
	s_nop 1
	v_cndmask_b32_e32 v55, v50, v49, vcc
	global_load_dwordx4 v[184:187], v55, s[22:23]
	s_add_u32 s20, s20, 0x2000
	s_addc_u32 s21, s21, 0
	s_add_u32 s22, s22, 0x2000
	s_addc_u32 s23, s23, 0
	global_load_dwordx4 v[156:159], v1, s[20:21]
	v_cmp_ge_u32_e32 vcc, 15, v2
	s_nop 1
	v_cndmask_b32_e32 v55, v50, v49, vcc
	global_load_dwordx4 v[188:191], v55, s[22:23]
	s_add_u32 s20, s20, 0x2000
	s_addc_u32 s21, s21, 0
	s_add_u32 s22, s22, 0x2000
	s_addc_u32 s23, s23, 0
	s_waitcnt vmcnt(16)
	v_lshlrev_b32_e32 v12, 16, v64
	v_and_b32_e32 v13, 0xffff0000, v64
	v_lshlrev_b32_e32 v20, 16, v96
	v_and_b32_e32 v21, 0xffff0000, v96
	v_lshlrev_b32_e32 v14, 16, v65
	v_and_b32_e32 v15, 0xffff0000, v65
	v_lshlrev_b32_e32 v22, 16, v97
	v_and_b32_e32 v23, 0xffff0000, v97
	v_lshlrev_b32_e32 v16, 16, v66
	v_and_b32_e32 v17, 0xffff0000, v66
	v_lshlrev_b32_e32 v24, 16, v98
	v_and_b32_e32 v25, 0xffff0000, v98
	v_lshlrev_b32_e32 v18, 16, v67
	v_and_b32_e32 v19, 0xffff0000, v67
	v_lshlrev_b32_e32 v26, 16, v99
	v_and_b32_e32 v27, 0xffff0000, v99
	v_mov_b32_e32 v44, 0
	v_pk_fma_f32 v[20:21], v[44:45], v[20:21], v[12:13] op_sel_hi:[0,1,1] neg_lo:[1,0,0] neg_hi:[1,0,0]
	v_pk_fma_f32 v[22:23], v[44:45], v[22:23], v[14:15] op_sel_hi:[0,1,1] neg_lo:[1,0,0] neg_hi:[1,0,0]
	v_pk_fma_f32 v[24:25], v[44:45], v[24:25], v[16:17] op_sel_hi:[0,1,1] neg_lo:[1,0,0] neg_hi:[1,0,0]
	v_pk_fma_f32 v[26:27], v[44:45], v[26:27], v[18:19] op_sel_hi:[0,1,1] neg_lo:[1,0,0] neg_hi:[1,0,0]
	v_pk_add_f32 v[4:5], v[4:5], v[20:21]
	v_pk_add_f32 v[6:7], v[6:7], v[22:23]
	v_pk_add_f32 v[8:9], v[8:9], v[24:25]
	v_pk_add_f32 v[10:11], v[10:11], v[26:27]
	v_lshlrev_b32_e32 v12, 16, v68
	v_and_b32_e32 v13, 0xffff0000, v68
	v_lshlrev_b32_e32 v20, 16, v100
	v_and_b32_e32 v21, 0xffff0000, v100
	v_lshlrev_b32_e32 v14, 16, v69
	v_and_b32_e32 v15, 0xffff0000, v69
	v_lshlrev_b32_e32 v22, 16, v101
	v_and_b32_e32 v23, 0xffff0000, v101
	v_lshlrev_b32_e32 v16, 16, v70
	v_and_b32_e32 v17, 0xffff0000, v70
	v_lshlrev_b32_e32 v24, 16, v102
	v_and_b32_e32 v25, 0xffff0000, v102
	v_lshlrev_b32_e32 v18, 16, v71
	v_and_b32_e32 v19, 0xffff0000, v71
	v_lshlrev_b32_e32 v26, 16, v103
	v_and_b32_e32 v27, 0xffff0000, v103
	v_mov_b32_e32 v44, 0
	v_pk_fma_f32 v[20:21], v[44:45], v[20:21], v[12:13] op_sel_hi:[0,1,1] neg_lo:[1,0,0] neg_hi:[1,0,0]
	v_pk_fma_f32 v[22:23], v[44:45], v[22:23], v[14:15] op_sel_hi:[0,1,1] neg_lo:[1,0,0] neg_hi:[1,0,0]
	v_pk_fma_f32 v[24:25], v[44:45], v[24:25], v[16:17] op_sel_hi:[0,1,1] neg_lo:[1,0,0] neg_hi:[1,0,0]
	v_pk_fma_f32 v[26:27], v[44:45], v[26:27], v[18:19] op_sel_hi:[0,1,1] neg_lo:[1,0,0] neg_hi:[1,0,0]
	v_pk_add_f32 v[4:5], v[4:5], v[20:21]
	v_pk_add_f32 v[6:7], v[6:7], v[22:23]
	v_pk_add_f32 v[8:9], v[8:9], v[24:25]
	v_pk_add_f32 v[10:11], v[10:11], v[26:27]
	v_lshlrev_b32_e32 v12, 16, v72
	v_and_b32_e32 v13, 0xffff0000, v72
	v_lshlrev_b32_e32 v20, 16, v104
	v_and_b32_e32 v21, 0xffff0000, v104
	v_lshlrev_b32_e32 v14, 16, v73
	v_and_b32_e32 v15, 0xffff0000, v73
	v_lshlrev_b32_e32 v22, 16, v105
	v_and_b32_e32 v23, 0xffff0000, v105
	v_lshlrev_b32_e32 v16, 16, v74
	v_and_b32_e32 v17, 0xffff0000, v74
	v_lshlrev_b32_e32 v24, 16, v106
	v_and_b32_e32 v25, 0xffff0000, v106
	v_lshlrev_b32_e32 v18, 16, v75
	v_and_b32_e32 v19, 0xffff0000, v75
	v_lshlrev_b32_e32 v26, 16, v107
	v_and_b32_e32 v27, 0xffff0000, v107
	v_cmp_ge_u32_e32 vcc, 2, v2
	s_nop 1
	v_cndmask_b32_e64 v44, 0, 1.0, vcc
	v_pk_fma_f32 v[20:21], v[44:45], v[20:21], v[12:13] op_sel_hi:[0,1,1] neg_lo:[1,0,0] neg_hi:[1,0,0]
	v_pk_fma_f32 v[22:23], v[44:45], v[22:23], v[14:15] op_sel_hi:[0,1,1] neg_lo:[1,0,0] neg_hi:[1,0,0]
	v_pk_fma_f32 v[24:25], v[44:45], v[24:25], v[16:17] op_sel_hi:[0,1,1] neg_lo:[1,0,0] neg_hi:[1,0,0]
	v_pk_fma_f32 v[26:27], v[44:45], v[26:27], v[18:19] op_sel_hi:[0,1,1] neg_lo:[1,0,0] neg_hi:[1,0,0]
	v_pk_add_f32 v[4:5], v[4:5], v[20:21]
	v_pk_add_f32 v[6:7], v[6:7], v[22:23]
	v_pk_add_f32 v[8:9], v[8:9], v[24:25]
	v_pk_add_f32 v[10:11], v[10:11], v[26:27]
	v_lshlrev_b32_e32 v12, 16, v76
	v_and_b32_e32 v13, 0xffff0000, v76
	v_lshlrev_b32_e32 v20, 16, v108
	v_and_b32_e32 v21, 0xffff0000, v108
	v_lshlrev_b32_e32 v14, 16, v77
	v_and_b32_e32 v15, 0xffff0000, v77
	v_lshlrev_b32_e32 v22, 16, v109
	v_and_b32_e32 v23, 0xffff0000, v109
	v_lshlrev_b32_e32 v16, 16, v78
	v_and_b32_e32 v17, 0xffff0000, v78
	v_lshlrev_b32_e32 v24, 16, v110
	v_and_b32_e32 v25, 0xffff0000, v110
	v_lshlrev_b32_e32 v18, 16, v79
	v_and_b32_e32 v19, 0xffff0000, v79
	v_lshlrev_b32_e32 v26, 16, v111
	v_and_b32_e32 v27, 0xffff0000, v111
	v_cmp_ge_u32_e32 vcc, 3, v2
	s_nop 1
	v_cndmask_b32_e64 v44, 0, 1.0, vcc
	v_pk_fma_f32 v[20:21], v[44:45], v[20:21], v[12:13] op_sel_hi:[0,1,1] neg_lo:[1,0,0] neg_hi:[1,0,0]
	v_pk_fma_f32 v[22:23], v[44:45], v[22:23], v[14:15] op_sel_hi:[0,1,1] neg_lo:[1,0,0] neg_hi:[1,0,0]
	v_pk_fma_f32 v[24:25], v[44:45], v[24:25], v[16:17] op_sel_hi:[0,1,1] neg_lo:[1,0,0] neg_hi:[1,0,0]
	v_pk_fma_f32 v[26:27], v[44:45], v[26:27], v[18:19] op_sel_hi:[0,1,1] neg_lo:[1,0,0] neg_hi:[1,0,0]
	v_pk_add_f32 v[4:5], v[4:5], v[20:21]
	v_pk_add_f32 v[6:7], v[6:7], v[22:23]
	v_pk_add_f32 v[8:9], v[8:9], v[24:25]
	v_pk_add_f32 v[10:11], v[10:11], v[26:27]
	v_lshlrev_b32_e32 v12, 16, v80
	v_and_b32_e32 v13, 0xffff0000, v80
	v_lshlrev_b32_e32 v20, 16, v112
	v_and_b32_e32 v21, 0xffff0000, v112
	v_lshlrev_b32_e32 v14, 16, v81
	v_and_b32_e32 v15, 0xffff0000, v81
	v_lshlrev_b32_e32 v22, 16, v113
	v_and_b32_e32 v23, 0xffff0000, v113
	v_lshlrev_b32_e32 v16, 16, v82
	v_and_b32_e32 v17, 0xffff0000, v82
	v_lshlrev_b32_e32 v24, 16, v114
	v_and_b32_e32 v25, 0xffff0000, v114
	v_lshlrev_b32_e32 v18, 16, v83
	v_and_b32_e32 v19, 0xffff0000, v83
	v_lshlrev_b32_e32 v26, 16, v115
	v_and_b32_e32 v27, 0xffff0000, v115
	v_cmp_ge_u32_e32 vcc, 4, v2
	s_nop 1
	v_cndmask_b32_e64 v44, 0, 1.0, vcc
	v_pk_fma_f32 v[20:21], v[44:45], v[20:21], v[12:13] op_sel_hi:[0,1,1] neg_lo:[1,0,0] neg_hi:[1,0,0]
	v_pk_fma_f32 v[22:23], v[44:45], v[22:23], v[14:15] op_sel_hi:[0,1,1] neg_lo:[1,0,0] neg_hi:[1,0,0]
	v_pk_fma_f32 v[24:25], v[44:45], v[24:25], v[16:17] op_sel_hi:[0,1,1] neg_lo:[1,0,0] neg_hi:[1,0,0]
	v_pk_fma_f32 v[26:27], v[44:45], v[26:27], v[18:19] op_sel_hi:[0,1,1] neg_lo:[1,0,0] neg_hi:[1,0,0]
	v_pk_add_f32 v[4:5], v[4:5], v[20:21]
	v_pk_add_f32 v[6:7], v[6:7], v[22:23]
	v_pk_add_f32 v[8:9], v[8:9], v[24:25]
	v_pk_add_f32 v[10:11], v[10:11], v[26:27]
	v_lshlrev_b32_e32 v12, 16, v84
	v_and_b32_e32 v13, 0xffff0000, v84
	v_lshlrev_b32_e32 v20, 16, v116
	v_and_b32_e32 v21, 0xffff0000, v116
	v_lshlrev_b32_e32 v14, 16, v85
	v_and_b32_e32 v15, 0xffff0000, v85
	v_lshlrev_b32_e32 v22, 16, v117
	v_and_b32_e32 v23, 0xffff0000, v117
	v_lshlrev_b32_e32 v16, 16, v86
	v_and_b32_e32 v17, 0xffff0000, v86
	v_lshlrev_b32_e32 v24, 16, v118
	v_and_b32_e32 v25, 0xffff0000, v118
	v_lshlrev_b32_e32 v18, 16, v87
	v_and_b32_e32 v19, 0xffff0000, v87
	v_lshlrev_b32_e32 v26, 16, v119
	v_and_b32_e32 v27, 0xffff0000, v119
	v_cmp_ge_u32_e32 vcc, 5, v2
	s_nop 1
	v_cndmask_b32_e64 v44, 0, 1.0, vcc
	v_pk_fma_f32 v[20:21], v[44:45], v[20:21], v[12:13] op_sel_hi:[0,1,1] neg_lo:[1,0,0] neg_hi:[1,0,0]
	v_pk_fma_f32 v[22:23], v[44:45], v[22:23], v[14:15] op_sel_hi:[0,1,1] neg_lo:[1,0,0] neg_hi:[1,0,0]
	v_pk_fma_f32 v[24:25], v[44:45], v[24:25], v[16:17] op_sel_hi:[0,1,1] neg_lo:[1,0,0] neg_hi:[1,0,0]
	v_pk_fma_f32 v[26:27], v[44:45], v[26:27], v[18:19] op_sel_hi:[0,1,1] neg_lo:[1,0,0] neg_hi:[1,0,0]
	v_pk_add_f32 v[4:5], v[4:5], v[20:21]
	v_pk_add_f32 v[6:7], v[6:7], v[22:23]
	v_pk_add_f32 v[8:9], v[8:9], v[24:25]
	v_pk_add_f32 v[10:11], v[10:11], v[26:27]
	v_lshlrev_b32_e32 v12, 16, v88
	v_and_b32_e32 v13, 0xffff0000, v88
	v_lshlrev_b32_e32 v20, 16, v120
	v_and_b32_e32 v21, 0xffff0000, v120
	v_lshlrev_b32_e32 v14, 16, v89
	v_and_b32_e32 v15, 0xffff0000, v89
	v_lshlrev_b32_e32 v22, 16, v121
	v_and_b32_e32 v23, 0xffff0000, v121
	v_lshlrev_b32_e32 v16, 16, v90
	v_and_b32_e32 v17, 0xffff0000, v90
	v_lshlrev_b32_e32 v24, 16, v122
	v_and_b32_e32 v25, 0xffff0000, v122
	v_lshlrev_b32_e32 v18, 16, v91
	v_and_b32_e32 v19, 0xffff0000, v91
	v_lshlrev_b32_e32 v26, 16, v123
	v_and_b32_e32 v27, 0xffff0000, v123
	v_cmp_ge_u32_e32 vcc, 6, v2
	s_nop 1
	v_cndmask_b32_e64 v44, 0, 1.0, vcc
	v_pk_fma_f32 v[20:21], v[44:45], v[20:21], v[12:13] op_sel_hi:[0,1,1] neg_lo:[1,0,0] neg_hi:[1,0,0]
	v_pk_fma_f32 v[22:23], v[44:45], v[22:23], v[14:15] op_sel_hi:[0,1,1] neg_lo:[1,0,0] neg_hi:[1,0,0]
	v_pk_fma_f32 v[24:25], v[44:45], v[24:25], v[16:17] op_sel_hi:[0,1,1] neg_lo:[1,0,0] neg_hi:[1,0,0]
	v_pk_fma_f32 v[26:27], v[44:45], v[26:27], v[18:19] op_sel_hi:[0,1,1] neg_lo:[1,0,0] neg_hi:[1,0,0]
	v_pk_add_f32 v[4:5], v[4:5], v[20:21]
	v_pk_add_f32 v[6:7], v[6:7], v[22:23]
	v_pk_add_f32 v[8:9], v[8:9], v[24:25]
	v_pk_add_f32 v[10:11], v[10:11], v[26:27]
	v_lshlrev_b32_e32 v12, 16, v92
	v_and_b32_e32 v13, 0xffff0000, v92
	v_lshlrev_b32_e32 v20, 16, v124
	v_and_b32_e32 v21, 0xffff0000, v124
	v_lshlrev_b32_e32 v14, 16, v93
	v_and_b32_e32 v15, 0xffff0000, v93
	v_lshlrev_b32_e32 v22, 16, v125
	v_and_b32_e32 v23, 0xffff0000, v125
	v_lshlrev_b32_e32 v16, 16, v94
	v_and_b32_e32 v17, 0xffff0000, v94
	v_lshlrev_b32_e32 v24, 16, v126
	v_and_b32_e32 v25, 0xffff0000, v126
	v_lshlrev_b32_e32 v18, 16, v95
	v_and_b32_e32 v19, 0xffff0000, v95
	v_lshlrev_b32_e32 v26, 16, v127
	v_and_b32_e32 v27, 0xffff0000, v127
	v_cmp_ge_u32_e32 vcc, 7, v2
	s_nop 1
	v_cndmask_b32_e64 v44, 0, 1.0, vcc
	v_pk_fma_f32 v[20:21], v[44:45], v[20:21], v[12:13] op_sel_hi:[0,1,1] neg_lo:[1,0,0] neg_hi:[1,0,0]
	v_pk_fma_f32 v[22:23], v[44:45], v[22:23], v[14:15] op_sel_hi:[0,1,1] neg_lo:[1,0,0] neg_hi:[1,0,0]
	v_pk_fma_f32 v[24:25], v[44:45], v[24:25], v[16:17] op_sel_hi:[0,1,1] neg_lo:[1,0,0] neg_hi:[1,0,0]
	v_pk_fma_f32 v[26:27], v[44:45], v[26:27], v[18:19] op_sel_hi:[0,1,1] neg_lo:[1,0,0] neg_hi:[1,0,0]
	v_pk_add_f32 v[4:5], v[4:5], v[20:21]
	v_pk_add_f32 v[6:7], v[6:7], v[22:23]
	v_pk_add_f32 v[8:9], v[8:9], v[24:25]
	v_pk_add_f32 v[10:11], v[10:11], v[26:27]
	global_load_dwordx4 v[64:67], v1, s[20:21]
	global_load_dwordx4 v[96:99], v49, s[22:23]
	s_add_u32 s20, s20, 0x2000
	s_addc_u32 s21, s21, 0
	s_add_u32 s22, s22, 0x2000
	s_addc_u32 s23, s23, 0
	global_load_dwordx4 v[68:71], v1, s[20:21]
	global_load_dwordx4 v[100:103], v49, s[22:23]
	s_add_u32 s20, s20, 0x2000
	s_addc_u32 s21, s21, 0
	s_add_u32 s22, s22, 0x2000
	s_addc_u32 s23, s23, 0
	global_load_dwordx4 v[72:75], v1, s[20:21]
	global_load_dwordx4 v[104:107], v49, s[22:23]
	s_add_u32 s20, s20, 0x2000
	s_addc_u32 s21, s21, 0
	s_add_u32 s22, s22, 0x2000
	s_addc_u32 s23, s23, 0
	global_load_dwordx4 v[76:79], v1, s[20:21]
	global_load_dwordx4 v[108:111], v49, s[22:23]
	s_add_u32 s20, s20, 0x2000
	s_addc_u32 s21, s21, 0
	s_add_u32 s22, s22, 0x2000
	s_addc_u32 s23, s23, 0
	global_load_dwordx4 v[80:83], v1, s[20:21]
	global_load_dwordx4 v[112:115], v49, s[22:23]
	s_add_u32 s20, s20, 0x2000
	s_addc_u32 s21, s21, 0
	s_add_u32 s22, s22, 0x2000
	s_addc_u32 s23, s23, 0
	global_load_dwordx4 v[84:87], v1, s[20:21]
	global_load_dwordx4 v[116:119], v49, s[22:23]
	s_add_u32 s20, s20, 0x2000
	s_addc_u32 s21, s21, 0
	s_add_u32 s22, s22, 0x2000
	s_addc_u32 s23, s23, 0
	global_load_dwordx4 v[88:91], v1, s[20:21]
	global_load_dwordx4 v[120:123], v49, s[22:23]
	s_add_u32 s20, s20, 0x2000
	s_addc_u32 s21, s21, 0
	s_add_u32 s22, s22, 0x2000
	s_addc_u32 s23, s23, 0
	global_load_dwordx4 v[92:95], v1, s[20:21]
	global_load_dwordx4 v[124:127], v49, s[22:23]
	s_add_u32 s20, s20, 0x2000
	s_addc_u32 s21, s21, 0
	s_add_u32 s22, s22, 0x2000
	s_addc_u32 s23, s23, 0
	s_waitcnt vmcnt(16)
	v_lshlrev_b32_e32 v12, 16, v128
	v_and_b32_e32 v13, 0xffff0000, v128
	v_lshlrev_b32_e32 v20, 16, v160
	v_and_b32_e32 v21, 0xffff0000, v160
	v_lshlrev_b32_e32 v14, 16, v129
	v_and_b32_e32 v15, 0xffff0000, v129
	v_lshlrev_b32_e32 v22, 16, v161
	v_and_b32_e32 v23, 0xffff0000, v161
	v_lshlrev_b32_e32 v16, 16, v130
	v_and_b32_e32 v17, 0xffff0000, v130
	v_lshlrev_b32_e32 v24, 16, v162
	v_and_b32_e32 v25, 0xffff0000, v162
	v_lshlrev_b32_e32 v18, 16, v131
	v_and_b32_e32 v19, 0xffff0000, v131
	v_lshlrev_b32_e32 v26, 16, v163
	v_and_b32_e32 v27, 0xffff0000, v163
	v_cmp_ge_u32_e32 vcc, 8, v2
	s_nop 1
	v_cndmask_b32_e64 v44, 0, 1.0, vcc
	v_pk_fma_f32 v[20:21], v[44:45], v[20:21], v[12:13] op_sel_hi:[0,1,1] neg_lo:[1,0,0] neg_hi:[1,0,0]
	v_pk_fma_f32 v[22:23], v[44:45], v[22:23], v[14:15] op_sel_hi:[0,1,1] neg_lo:[1,0,0] neg_hi:[1,0,0]
	v_pk_fma_f32 v[24:25], v[44:45], v[24:25], v[16:17] op_sel_hi:[0,1,1] neg_lo:[1,0,0] neg_hi:[1,0,0]
	v_pk_fma_f32 v[26:27], v[44:45], v[26:27], v[18:19] op_sel_hi:[0,1,1] neg_lo:[1,0,0] neg_hi:[1,0,0]
	v_pk_add_f32 v[4:5], v[4:5], v[20:21]
	v_pk_add_f32 v[6:7], v[6:7], v[22:23]
	v_pk_add_f32 v[8:9], v[8:9], v[24:25]
	v_pk_add_f32 v[10:11], v[10:11], v[26:27]
	v_lshlrev_b32_e32 v12, 16, v132
	v_and_b32_e32 v13, 0xffff0000, v132
	v_lshlrev_b32_e32 v20, 16, v164
	v_and_b32_e32 v21, 0xffff0000, v164
	v_lshlrev_b32_e32 v14, 16, v133
	v_and_b32_e32 v15, 0xffff0000, v133
	v_lshlrev_b32_e32 v22, 16, v165
	v_and_b32_e32 v23, 0xffff0000, v165
	v_lshlrev_b32_e32 v16, 16, v134
	v_and_b32_e32 v17, 0xffff0000, v134
	v_lshlrev_b32_e32 v24, 16, v166
	v_and_b32_e32 v25, 0xffff0000, v166
	v_lshlrev_b32_e32 v18, 16, v135
	v_and_b32_e32 v19, 0xffff0000, v135
	v_lshlrev_b32_e32 v26, 16, v167
	v_and_b32_e32 v27, 0xffff0000, v167
	v_cmp_ge_u32_e32 vcc, 9, v2
	s_nop 1
	v_cndmask_b32_e64 v44, 0, 1.0, vcc
	v_pk_fma_f32 v[20:21], v[44:45], v[20:21], v[12:13] op_sel_hi:[0,1,1] neg_lo:[1,0,0] neg_hi:[1,0,0]
	v_pk_fma_f32 v[22:23], v[44:45], v[22:23], v[14:15] op_sel_hi:[0,1,1] neg_lo:[1,0,0] neg_hi:[1,0,0]
	v_pk_fma_f32 v[24:25], v[44:45], v[24:25], v[16:17] op_sel_hi:[0,1,1] neg_lo:[1,0,0] neg_hi:[1,0,0]
	v_pk_fma_f32 v[26:27], v[44:45], v[26:27], v[18:19] op_sel_hi:[0,1,1] neg_lo:[1,0,0] neg_hi:[1,0,0]
	v_pk_add_f32 v[4:5], v[4:5], v[20:21]
	v_pk_add_f32 v[6:7], v[6:7], v[22:23]
	v_pk_add_f32 v[8:9], v[8:9], v[24:25]
	v_pk_add_f32 v[10:11], v[10:11], v[26:27]
	v_lshlrev_b32_e32 v12, 16, v136
	v_and_b32_e32 v13, 0xffff0000, v136
	v_lshlrev_b32_e32 v20, 16, v168
	v_and_b32_e32 v21, 0xffff0000, v168
	v_lshlrev_b32_e32 v14, 16, v137
	v_and_b32_e32 v15, 0xffff0000, v137
	v_lshlrev_b32_e32 v22, 16, v169
	v_and_b32_e32 v23, 0xffff0000, v169
	v_lshlrev_b32_e32 v16, 16, v138
	v_and_b32_e32 v17, 0xffff0000, v138
	v_lshlrev_b32_e32 v24, 16, v170
	v_and_b32_e32 v25, 0xffff0000, v170
	v_lshlrev_b32_e32 v18, 16, v139
	v_and_b32_e32 v19, 0xffff0000, v139
	v_lshlrev_b32_e32 v26, 16, v171
	v_and_b32_e32 v27, 0xffff0000, v171
	v_cmp_ge_u32_e32 vcc, 10, v2
	s_nop 1
	v_cndmask_b32_e64 v44, 0, 1.0, vcc
	v_pk_fma_f32 v[20:21], v[44:45], v[20:21], v[12:13] op_sel_hi:[0,1,1] neg_lo:[1,0,0] neg_hi:[1,0,0]
	v_pk_fma_f32 v[22:23], v[44:45], v[22:23], v[14:15] op_sel_hi:[0,1,1] neg_lo:[1,0,0] neg_hi:[1,0,0]
	v_pk_fma_f32 v[24:25], v[44:45], v[24:25], v[16:17] op_sel_hi:[0,1,1] neg_lo:[1,0,0] neg_hi:[1,0,0]
	v_pk_fma_f32 v[26:27], v[44:45], v[26:27], v[18:19] op_sel_hi:[0,1,1] neg_lo:[1,0,0] neg_hi:[1,0,0]
	v_pk_add_f32 v[4:5], v[4:5], v[20:21]
	v_pk_add_f32 v[6:7], v[6:7], v[22:23]
	v_pk_add_f32 v[8:9], v[8:9], v[24:25]
	v_pk_add_f32 v[10:11], v[10:11], v[26:27]
	v_lshlrev_b32_e32 v12, 16, v140
	v_and_b32_e32 v13, 0xffff0000, v140
	v_lshlrev_b32_e32 v20, 16, v172
	v_and_b32_e32 v21, 0xffff0000, v172
	v_lshlrev_b32_e32 v14, 16, v141
	v_and_b32_e32 v15, 0xffff0000, v141
	v_lshlrev_b32_e32 v22, 16, v173
	v_and_b32_e32 v23, 0xffff0000, v173
	v_lshlrev_b32_e32 v16, 16, v142
	v_and_b32_e32 v17, 0xffff0000, v142
	v_lshlrev_b32_e32 v24, 16, v174
	v_and_b32_e32 v25, 0xffff0000, v174
	v_lshlrev_b32_e32 v18, 16, v143
	v_and_b32_e32 v19, 0xffff0000, v143
	v_lshlrev_b32_e32 v26, 16, v175
	v_and_b32_e32 v27, 0xffff0000, v175
	v_cmp_ge_u32_e32 vcc, 11, v2
	s_nop 1
	v_cndmask_b32_e64 v44, 0, 1.0, vcc
	v_pk_fma_f32 v[20:21], v[44:45], v[20:21], v[12:13] op_sel_hi:[0,1,1] neg_lo:[1,0,0] neg_hi:[1,0,0]
	v_pk_fma_f32 v[22:23], v[44:45], v[22:23], v[14:15] op_sel_hi:[0,1,1] neg_lo:[1,0,0] neg_hi:[1,0,0]
	v_pk_fma_f32 v[24:25], v[44:45], v[24:25], v[16:17] op_sel_hi:[0,1,1] neg_lo:[1,0,0] neg_hi:[1,0,0]
	v_pk_fma_f32 v[26:27], v[44:45], v[26:27], v[18:19] op_sel_hi:[0,1,1] neg_lo:[1,0,0] neg_hi:[1,0,0]
	v_pk_add_f32 v[4:5], v[4:5], v[20:21]
	v_pk_add_f32 v[6:7], v[6:7], v[22:23]
	v_pk_add_f32 v[8:9], v[8:9], v[24:25]
	v_pk_add_f32 v[10:11], v[10:11], v[26:27]
	v_lshlrev_b32_e32 v12, 16, v144
	v_and_b32_e32 v13, 0xffff0000, v144
	v_lshlrev_b32_e32 v20, 16, v176
	v_and_b32_e32 v21, 0xffff0000, v176
	v_lshlrev_b32_e32 v14, 16, v145
	v_and_b32_e32 v15, 0xffff0000, v145
	v_lshlrev_b32_e32 v22, 16, v177
	v_and_b32_e32 v23, 0xffff0000, v177
	v_lshlrev_b32_e32 v16, 16, v146
	v_and_b32_e32 v17, 0xffff0000, v146
	v_lshlrev_b32_e32 v24, 16, v178
	v_and_b32_e32 v25, 0xffff0000, v178
	v_lshlrev_b32_e32 v18, 16, v147
	v_and_b32_e32 v19, 0xffff0000, v147
	v_lshlrev_b32_e32 v26, 16, v179
	v_and_b32_e32 v27, 0xffff0000, v179
	v_cmp_ge_u32_e32 vcc, 12, v2
	s_nop 1
	v_cndmask_b32_e64 v44, 0, 1.0, vcc
	v_pk_fma_f32 v[20:21], v[44:45], v[20:21], v[12:13] op_sel_hi:[0,1,1] neg_lo:[1,0,0] neg_hi:[1,0,0]
	v_pk_fma_f32 v[22:23], v[44:45], v[22:23], v[14:15] op_sel_hi:[0,1,1] neg_lo:[1,0,0] neg_hi:[1,0,0]
	v_pk_fma_f32 v[24:25], v[44:45], v[24:25], v[16:17] op_sel_hi:[0,1,1] neg_lo:[1,0,0] neg_hi:[1,0,0]
	v_pk_fma_f32 v[26:27], v[44:45], v[26:27], v[18:19] op_sel_hi:[0,1,1] neg_lo:[1,0,0] neg_hi:[1,0,0]
	v_pk_add_f32 v[4:5], v[4:5], v[20:21]
	v_pk_add_f32 v[6:7], v[6:7], v[22:23]
	v_pk_add_f32 v[8:9], v[8:9], v[24:25]
	v_pk_add_f32 v[10:11], v[10:11], v[26:27]
	v_lshlrev_b32_e32 v12, 16, v148
	v_and_b32_e32 v13, 0xffff0000, v148
	v_lshlrev_b32_e32 v20, 16, v180
	v_and_b32_e32 v21, 0xffff0000, v180
	v_lshlrev_b32_e32 v14, 16, v149
	v_and_b32_e32 v15, 0xffff0000, v149
	v_lshlrev_b32_e32 v22, 16, v181
	v_and_b32_e32 v23, 0xffff0000, v181
	v_lshlrev_b32_e32 v16, 16, v150
	v_and_b32_e32 v17, 0xffff0000, v150
	v_lshlrev_b32_e32 v24, 16, v182
	v_and_b32_e32 v25, 0xffff0000, v182
	v_lshlrev_b32_e32 v18, 16, v151
	v_and_b32_e32 v19, 0xffff0000, v151
	v_lshlrev_b32_e32 v26, 16, v183
	v_and_b32_e32 v27, 0xffff0000, v183
	v_cmp_ge_u32_e32 vcc, 13, v2
	s_nop 1
	v_cndmask_b32_e64 v44, 0, 1.0, vcc
	v_pk_fma_f32 v[20:21], v[44:45], v[20:21], v[12:13] op_sel_hi:[0,1,1] neg_lo:[1,0,0] neg_hi:[1,0,0]
	v_pk_fma_f32 v[22:23], v[44:45], v[22:23], v[14:15] op_sel_hi:[0,1,1] neg_lo:[1,0,0] neg_hi:[1,0,0]
	v_pk_fma_f32 v[24:25], v[44:45], v[24:25], v[16:17] op_sel_hi:[0,1,1] neg_lo:[1,0,0] neg_hi:[1,0,0]
	v_pk_fma_f32 v[26:27], v[44:45], v[26:27], v[18:19] op_sel_hi:[0,1,1] neg_lo:[1,0,0] neg_hi:[1,0,0]
	v_pk_add_f32 v[4:5], v[4:5], v[20:21]
	v_pk_add_f32 v[6:7], v[6:7], v[22:23]
	v_pk_add_f32 v[8:9], v[8:9], v[24:25]
	v_pk_add_f32 v[10:11], v[10:11], v[26:27]
	v_lshlrev_b32_e32 v12, 16, v152
	v_and_b32_e32 v13, 0xffff0000, v152
	v_lshlrev_b32_e32 v20, 16, v184
	v_and_b32_e32 v21, 0xffff0000, v184
	v_lshlrev_b32_e32 v14, 16, v153
	v_and_b32_e32 v15, 0xffff0000, v153
	v_lshlrev_b32_e32 v22, 16, v185
	v_and_b32_e32 v23, 0xffff0000, v185
	v_lshlrev_b32_e32 v16, 16, v154
	v_and_b32_e32 v17, 0xffff0000, v154
	v_lshlrev_b32_e32 v24, 16, v186
	v_and_b32_e32 v25, 0xffff0000, v186
	v_lshlrev_b32_e32 v18, 16, v155
	v_and_b32_e32 v19, 0xffff0000, v155
	v_lshlrev_b32_e32 v26, 16, v187
	v_and_b32_e32 v27, 0xffff0000, v187
	v_cmp_ge_u32_e32 vcc, 14, v2
	s_nop 1
	v_cndmask_b32_e64 v44, 0, 1.0, vcc
	v_pk_fma_f32 v[20:21], v[44:45], v[20:21], v[12:13] op_sel_hi:[0,1,1] neg_lo:[1,0,0] neg_hi:[1,0,0]
	v_pk_fma_f32 v[22:23], v[44:45], v[22:23], v[14:15] op_sel_hi:[0,1,1] neg_lo:[1,0,0] neg_hi:[1,0,0]
	v_pk_fma_f32 v[24:25], v[44:45], v[24:25], v[16:17] op_sel_hi:[0,1,1] neg_lo:[1,0,0] neg_hi:[1,0,0]
	v_pk_fma_f32 v[26:27], v[44:45], v[26:27], v[18:19] op_sel_hi:[0,1,1] neg_lo:[1,0,0] neg_hi:[1,0,0]
	v_pk_add_f32 v[4:5], v[4:5], v[20:21]
	v_pk_add_f32 v[6:7], v[6:7], v[22:23]
	v_pk_add_f32 v[8:9], v[8:9], v[24:25]
	v_pk_add_f32 v[10:11], v[10:11], v[26:27]
	v_lshlrev_b32_e32 v12, 16, v156
	v_and_b32_e32 v13, 0xffff0000, v156
	v_lshlrev_b32_e32 v20, 16, v188
	v_and_b32_e32 v21, 0xffff0000, v188
	v_lshlrev_b32_e32 v14, 16, v157
	v_and_b32_e32 v15, 0xffff0000, v157
	v_lshlrev_b32_e32 v22, 16, v189
	v_and_b32_e32 v23, 0xffff0000, v189
	v_lshlrev_b32_e32 v16, 16, v158
	v_and_b32_e32 v17, 0xffff0000, v158
	v_lshlrev_b32_e32 v24, 16, v190
	v_and_b32_e32 v25, 0xffff0000, v190
	v_lshlrev_b32_e32 v18, 16, v159
	v_and_b32_e32 v19, 0xffff0000, v159
	v_lshlrev_b32_e32 v26, 16, v191
	v_and_b32_e32 v27, 0xffff0000, v191
	v_cmp_ge_u32_e32 vcc, 15, v2
	s_nop 1
	v_cndmask_b32_e64 v44, 0, 1.0, vcc
	v_pk_fma_f32 v[20:21], v[44:45], v[20:21], v[12:13] op_sel_hi:[0,1,1] neg_lo:[1,0,0] neg_hi:[1,0,0]
	v_pk_fma_f32 v[22:23], v[44:45], v[22:23], v[14:15] op_sel_hi:[0,1,1] neg_lo:[1,0,0] neg_hi:[1,0,0]
	v_pk_fma_f32 v[24:25], v[44:45], v[24:25], v[16:17] op_sel_hi:[0,1,1] neg_lo:[1,0,0] neg_hi:[1,0,0]
	v_pk_fma_f32 v[26:27], v[44:45], v[26:27], v[18:19] op_sel_hi:[0,1,1] neg_lo:[1,0,0] neg_hi:[1,0,0]
	v_pk_add_f32 v[4:5], v[4:5], v[20:21]
	v_pk_add_f32 v[6:7], v[6:7], v[22:23]
	v_pk_add_f32 v[8:9], v[8:9], v[24:25]
	v_pk_add_f32 v[10:11], v[10:11], v[26:27]
	global_load_dwordx4 v[128:131], v1, s[20:21]
	global_load_dwordx4 v[160:163], v49, s[22:23]
	s_add_u32 s20, s20, 0x2000
	s_addc_u32 s21, s21, 0
	s_add_u32 s22, s22, 0x2000
	s_addc_u32 s23, s23, 0
	global_load_dwordx4 v[132:135], v1, s[20:21]
	global_load_dwordx4 v[164:167], v49, s[22:23]
	s_add_u32 s20, s20, 0x2000
	s_addc_u32 s21, s21, 0
	s_add_u32 s22, s22, 0x2000
	s_addc_u32 s23, s23, 0
	global_load_dwordx4 v[136:139], v1, s[20:21]
	global_load_dwordx4 v[168:171], v49, s[22:23]
	s_add_u32 s20, s20, 0x2000
	s_addc_u32 s21, s21, 0
	s_add_u32 s22, s22, 0x2000
	s_addc_u32 s23, s23, 0
	global_load_dwordx4 v[140:143], v1, s[20:21]
	global_load_dwordx4 v[172:175], v49, s[22:23]
	s_add_u32 s20, s20, 0x2000
	s_addc_u32 s21, s21, 0
	s_add_u32 s22, s22, 0x2000
	s_addc_u32 s23, s23, 0
	global_load_dwordx4 v[144:147], v1, s[20:21]
	global_load_dwordx4 v[176:179], v49, s[22:23]
	s_add_u32 s20, s20, 0x2000
	s_addc_u32 s21, s21, 0
	s_add_u32 s22, s22, 0x2000
	s_addc_u32 s23, s23, 0
	global_load_dwordx4 v[148:151], v1, s[20:21]
	global_load_dwordx4 v[180:183], v49, s[22:23]
	s_add_u32 s20, s20, 0x2000
	s_addc_u32 s21, s21, 0
	s_add_u32 s22, s22, 0x2000
	s_addc_u32 s23, s23, 0
	global_load_dwordx4 v[152:155], v1, s[20:21]
	global_load_dwordx4 v[184:187], v49, s[22:23]
	s_add_u32 s20, s20, 0x2000
	s_addc_u32 s21, s21, 0
	s_add_u32 s22, s22, 0x2000
	s_addc_u32 s23, s23, 0
	global_load_dwordx4 v[156:159], v1, s[20:21]
	global_load_dwordx4 v[188:191], v49, s[22:23]
	s_add_u32 s20, s20, 0x2000
	s_addc_u32 s21, s21, 0
	s_add_u32 s22, s22, 0x2000
	s_addc_u32 s23, s23, 0
	s_waitcnt vmcnt(16)
	v_mov_b32_e32 v44, 1.0
	v_lshlrev_b32_e32 v12, 16, v64
	v_and_b32_e32 v13, 0xffff0000, v64
	v_lshlrev_b32_e32 v20, 16, v96
	v_and_b32_e32 v21, 0xffff0000, v96
	v_lshlrev_b32_e32 v14, 16, v65
	v_and_b32_e32 v15, 0xffff0000, v65
	v_lshlrev_b32_e32 v22, 16, v97
	v_and_b32_e32 v23, 0xffff0000, v97
	v_lshlrev_b32_e32 v16, 16, v66
	v_and_b32_e32 v17, 0xffff0000, v66
	v_lshlrev_b32_e32 v24, 16, v98
	v_and_b32_e32 v25, 0xffff0000, v98
	v_lshlrev_b32_e32 v18, 16, v67
	v_and_b32_e32 v19, 0xffff0000, v67
	v_lshlrev_b32_e32 v26, 16, v99
	v_and_b32_e32 v27, 0xffff0000, v99
	v_pk_fma_f32 v[20:21], v[44:45], v[20:21], v[12:13] op_sel_hi:[0,1,1] neg_lo:[1,0,0] neg_hi:[1,0,0]
	v_pk_fma_f32 v[22:23], v[44:45], v[22:23], v[14:15] op_sel_hi:[0,1,1] neg_lo:[1,0,0] neg_hi:[1,0,0]
	v_pk_fma_f32 v[24:25], v[44:45], v[24:25], v[16:17] op_sel_hi:[0,1,1] neg_lo:[1,0,0] neg_hi:[1,0,0]
	v_pk_fma_f32 v[26:27], v[44:45], v[26:27], v[18:19] op_sel_hi:[0,1,1] neg_lo:[1,0,0] neg_hi:[1,0,0]
	v_pk_add_f32 v[4:5], v[4:5], v[20:21]
	v_pk_add_f32 v[6:7], v[6:7], v[22:23]
	v_pk_add_f32 v[8:9], v[8:9], v[24:25]
	v_pk_add_f32 v[10:11], v[10:11], v[26:27]
	v_mov_b32_e32 v46, v3
	v_pk_fma_f32 v[28:29], v[46:47], v[4:5], v[12:13] op_sel_hi:[0,1,1] neg_lo:[0,0,1] neg_hi:[0,0,1]
	v_pk_fma_f32 v[30:31], v[46:47], v[6:7], v[14:15] op_sel_hi:[0,1,1] neg_lo:[0,0,1] neg_hi:[0,0,1]
	v_pk_fma_f32 v[32:33], v[46:47], v[8:9], v[16:17] op_sel_hi:[0,1,1] neg_lo:[0,0,1] neg_hi:[0,0,1]
	v_pk_fma_f32 v[34:35], v[46:47], v[10:11], v[18:19] op_sel_hi:[0,1,1] neg_lo:[0,0,1] neg_hi:[0,0,1]
	v_cvt_pk_bf16_f32 v36, v28, v29
	v_cvt_pk_bf16_f32 v37, v30, v31
	v_cvt_pk_bf16_f32 v38, v32, v33
	v_cvt_pk_bf16_f32 v39, v34, v35
	global_store_dwordx4 v1, v[36:39], s[24:25]
	s_add_u32 s24, s24, 0x2000
	s_addc_u32 s25, s25, 0
	v_lshlrev_b32_e32 v12, 16, v68
	v_and_b32_e32 v13, 0xffff0000, v68
	v_lshlrev_b32_e32 v20, 16, v100
	v_and_b32_e32 v21, 0xffff0000, v100
	v_lshlrev_b32_e32 v14, 16, v69
	v_and_b32_e32 v15, 0xffff0000, v69
	v_lshlrev_b32_e32 v22, 16, v101
	v_and_b32_e32 v23, 0xffff0000, v101
	v_lshlrev_b32_e32 v16, 16, v70
	v_and_b32_e32 v17, 0xffff0000, v70
	v_lshlrev_b32_e32 v24, 16, v102
	v_and_b32_e32 v25, 0xffff0000, v102
	v_lshlrev_b32_e32 v18, 16, v71
	v_and_b32_e32 v19, 0xffff0000, v71
	v_lshlrev_b32_e32 v26, 16, v103
	v_and_b32_e32 v27, 0xffff0000, v103
	v_pk_fma_f32 v[20:21], v[44:45], v[20:21], v[12:13] op_sel_hi:[0,1,1] neg_lo:[1,0,0] neg_hi:[1,0,0]
	v_pk_fma_f32 v[22:23], v[44:45], v[22:23], v[14:15] op_sel_hi:[0,1,1] neg_lo:[1,0,0] neg_hi:[1,0,0]
	v_pk_fma_f32 v[24:25], v[44:45], v[24:25], v[16:17] op_sel_hi:[0,1,1] neg_lo:[1,0,0] neg_hi:[1,0,0]
	v_pk_fma_f32 v[26:27], v[44:45], v[26:27], v[18:19] op_sel_hi:[0,1,1] neg_lo:[1,0,0] neg_hi:[1,0,0]
	v_pk_add_f32 v[4:5], v[4:5], v[20:21]
	v_pk_add_f32 v[6:7], v[6:7], v[22:23]
	v_pk_add_f32 v[8:9], v[8:9], v[24:25]
	v_pk_add_f32 v[10:11], v[10:11], v[26:27]
	v_mov_b32_e32 v46, v3
	v_pk_fma_f32 v[28:29], v[46:47], v[4:5], v[12:13] op_sel_hi:[0,1,1] neg_lo:[0,0,1] neg_hi:[0,0,1]
	v_pk_fma_f32 v[30:31], v[46:47], v[6:7], v[14:15] op_sel_hi:[0,1,1] neg_lo:[0,0,1] neg_hi:[0,0,1]
	v_pk_fma_f32 v[32:33], v[46:47], v[8:9], v[16:17] op_sel_hi:[0,1,1] neg_lo:[0,0,1] neg_hi:[0,0,1]
	v_pk_fma_f32 v[34:35], v[46:47], v[10:11], v[18:19] op_sel_hi:[0,1,1] neg_lo:[0,0,1] neg_hi:[0,0,1]
	v_cvt_pk_bf16_f32 v40, v28, v29
	v_cvt_pk_bf16_f32 v41, v30, v31
	v_cvt_pk_bf16_f32 v42, v32, v33
	v_cvt_pk_bf16_f32 v43, v34, v35
	global_store_dwordx4 v1, v[40:43], s[24:25]
	s_add_u32 s24, s24, 0x2000
	s_addc_u32 s25, s25, 0
	v_lshlrev_b32_e32 v12, 16, v72
	v_and_b32_e32 v13, 0xffff0000, v72
	v_lshlrev_b32_e32 v20, 16, v104
	v_and_b32_e32 v21, 0xffff0000, v104
	v_lshlrev_b32_e32 v14, 16, v73
	v_and_b32_e32 v15, 0xffff0000, v73
	v_lshlrev_b32_e32 v22, 16, v105
	v_and_b32_e32 v23, 0xffff0000, v105
	v_lshlrev_b32_e32 v16, 16, v74
	v_and_b32_e32 v17, 0xffff0000, v74
	v_lshlrev_b32_e32 v24, 16, v106
	v_and_b32_e32 v25, 0xffff0000, v106
	v_lshlrev_b32_e32 v18, 16, v75
	v_and_b32_e32 v19, 0xffff0000, v75
	v_lshlrev_b32_e32 v26, 16, v107
	v_and_b32_e32 v27, 0xffff0000, v107
	v_pk_fma_f32 v[20:21], v[44:45], v[20:21], v[12:13] op_sel_hi:[0,1,1] neg_lo:[1,0,0] neg_hi:[1,0,0]
	v_pk_fma_f32 v[22:23], v[44:45], v[22:23], v[14:15] op_sel_hi:[0,1,1] neg_lo:[1,0,0] neg_hi:[1,0,0]
	v_pk_fma_f32 v[24:25], v[44:45], v[24:25], v[16:17] op_sel_hi:[0,1,1] neg_lo:[1,0,0] neg_hi:[1,0,0]
	v_pk_fma_f32 v[26:27], v[44:45], v[26:27], v[18:19] op_sel_hi:[0,1,1] neg_lo:[1,0,0] neg_hi:[1,0,0]
	v_pk_add_f32 v[4:5], v[4:5], v[20:21]
	v_pk_add_f32 v[6:7], v[6:7], v[22:23]
	v_pk_add_f32 v[8:9], v[8:9], v[24:25]
	v_pk_add_f32 v[10:11], v[10:11], v[26:27]
	v_mov_b32_e32 v46, v3
	v_pk_fma_f32 v[28:29], v[46:47], v[4:5], v[12:13] op_sel_hi:[0,1,1] neg_lo:[0,0,1] neg_hi:[0,0,1]
	v_pk_fma_f32 v[30:31], v[46:47], v[6:7], v[14:15] op_sel_hi:[0,1,1] neg_lo:[0,0,1] neg_hi:[0,0,1]
	v_pk_fma_f32 v[32:33], v[46:47], v[8:9], v[16:17] op_sel_hi:[0,1,1] neg_lo:[0,0,1] neg_hi:[0,0,1]
	v_pk_fma_f32 v[34:35], v[46:47], v[10:11], v[18:19] op_sel_hi:[0,1,1] neg_lo:[0,0,1] neg_hi:[0,0,1]
	v_cvt_pk_bf16_f32 v36, v28, v29
	v_cvt_pk_bf16_f32 v37, v30, v31
	v_cvt_pk_bf16_f32 v38, v32, v33
	v_cvt_pk_bf16_f32 v39, v34, v35
	global_store_dwordx4 v1, v[36:39], s[24:25]
	s_add_u32 s24, s24, 0x2000
	s_addc_u32 s25, s25, 0
	v_lshlrev_b32_e32 v12, 16, v76
	v_and_b32_e32 v13, 0xffff0000, v76
	v_lshlrev_b32_e32 v20, 16, v108
	v_and_b32_e32 v21, 0xffff0000, v108
	v_lshlrev_b32_e32 v14, 16, v77
	v_and_b32_e32 v15, 0xffff0000, v77
	v_lshlrev_b32_e32 v22, 16, v109
	v_and_b32_e32 v23, 0xffff0000, v109
	v_lshlrev_b32_e32 v16, 16, v78
	v_and_b32_e32 v17, 0xffff0000, v78
	v_lshlrev_b32_e32 v24, 16, v110
	v_and_b32_e32 v25, 0xffff0000, v110
	v_lshlrev_b32_e32 v18, 16, v79
	v_and_b32_e32 v19, 0xffff0000, v79
	v_lshlrev_b32_e32 v26, 16, v111
	v_and_b32_e32 v27, 0xffff0000, v111
	v_pk_fma_f32 v[20:21], v[44:45], v[20:21], v[12:13] op_sel_hi:[0,1,1] neg_lo:[1,0,0] neg_hi:[1,0,0]
	v_pk_fma_f32 v[22:23], v[44:45], v[22:23], v[14:15] op_sel_hi:[0,1,1] neg_lo:[1,0,0] neg_hi:[1,0,0]
	v_pk_fma_f32 v[24:25], v[44:45], v[24:25], v[16:17] op_sel_hi:[0,1,1] neg_lo:[1,0,0] neg_hi:[1,0,0]
	v_pk_fma_f32 v[26:27], v[44:45], v[26:27], v[18:19] op_sel_hi:[0,1,1] neg_lo:[1,0,0] neg_hi:[1,0,0]
	v_pk_add_f32 v[4:5], v[4:5], v[20:21]
	v_pk_add_f32 v[6:7], v[6:7], v[22:23]
	v_pk_add_f32 v[8:9], v[8:9], v[24:25]
	v_pk_add_f32 v[10:11], v[10:11], v[26:27]
	v_mov_b32_e32 v46, v3
	v_pk_fma_f32 v[28:29], v[46:47], v[4:5], v[12:13] op_sel_hi:[0,1,1] neg_lo:[0,0,1] neg_hi:[0,0,1]
	v_pk_fma_f32 v[30:31], v[46:47], v[6:7], v[14:15] op_sel_hi:[0,1,1] neg_lo:[0,0,1] neg_hi:[0,0,1]
	v_pk_fma_f32 v[32:33], v[46:47], v[8:9], v[16:17] op_sel_hi:[0,1,1] neg_lo:[0,0,1] neg_hi:[0,0,1]
	v_pk_fma_f32 v[34:35], v[46:47], v[10:11], v[18:19] op_sel_hi:[0,1,1] neg_lo:[0,0,1] neg_hi:[0,0,1]
	v_cvt_pk_bf16_f32 v40, v28, v29
	v_cvt_pk_bf16_f32 v41, v30, v31
	v_cvt_pk_bf16_f32 v42, v32, v33
	v_cvt_pk_bf16_f32 v43, v34, v35
	global_store_dwordx4 v1, v[40:43], s[24:25]
	s_add_u32 s24, s24, 0x2000
	s_addc_u32 s25, s25, 0
	v_lshlrev_b32_e32 v12, 16, v80
	v_and_b32_e32 v13, 0xffff0000, v80
	v_lshlrev_b32_e32 v20, 16, v112
	v_and_b32_e32 v21, 0xffff0000, v112
	v_lshlrev_b32_e32 v14, 16, v81
	v_and_b32_e32 v15, 0xffff0000, v81
	v_lshlrev_b32_e32 v22, 16, v113
	v_and_b32_e32 v23, 0xffff0000, v113
	v_lshlrev_b32_e32 v16, 16, v82
	v_and_b32_e32 v17, 0xffff0000, v82
	v_lshlrev_b32_e32 v24, 16, v114
	v_and_b32_e32 v25, 0xffff0000, v114
	v_lshlrev_b32_e32 v18, 16, v83
	v_and_b32_e32 v19, 0xffff0000, v83
	v_lshlrev_b32_e32 v26, 16, v115
	v_and_b32_e32 v27, 0xffff0000, v115
	v_pk_fma_f32 v[20:21], v[44:45], v[20:21], v[12:13] op_sel_hi:[0,1,1] neg_lo:[1,0,0] neg_hi:[1,0,0]
	v_pk_fma_f32 v[22:23], v[44:45], v[22:23], v[14:15] op_sel_hi:[0,1,1] neg_lo:[1,0,0] neg_hi:[1,0,0]
	v_pk_fma_f32 v[24:25], v[44:45], v[24:25], v[16:17] op_sel_hi:[0,1,1] neg_lo:[1,0,0] neg_hi:[1,0,0]
	v_pk_fma_f32 v[26:27], v[44:45], v[26:27], v[18:19] op_sel_hi:[0,1,1] neg_lo:[1,0,0] neg_hi:[1,0,0]
	v_pk_add_f32 v[4:5], v[4:5], v[20:21]
	v_pk_add_f32 v[6:7], v[6:7], v[22:23]
	v_pk_add_f32 v[8:9], v[8:9], v[24:25]
	v_pk_add_f32 v[10:11], v[10:11], v[26:27]
	v_mov_b32_e32 v46, v3
	v_pk_fma_f32 v[28:29], v[46:47], v[4:5], v[12:13] op_sel_hi:[0,1,1] neg_lo:[0,0,1] neg_hi:[0,0,1]
	v_pk_fma_f32 v[30:31], v[46:47], v[6:7], v[14:15] op_sel_hi:[0,1,1] neg_lo:[0,0,1] neg_hi:[0,0,1]
	v_pk_fma_f32 v[32:33], v[46:47], v[8:9], v[16:17] op_sel_hi:[0,1,1] neg_lo:[0,0,1] neg_hi:[0,0,1]
	v_pk_fma_f32 v[34:35], v[46:47], v[10:11], v[18:19] op_sel_hi:[0,1,1] neg_lo:[0,0,1] neg_hi:[0,0,1]
	v_cvt_pk_bf16_f32 v36, v28, v29
	v_cvt_pk_bf16_f32 v37, v30, v31
	v_cvt_pk_bf16_f32 v38, v32, v33
	v_cvt_pk_bf16_f32 v39, v34, v35
	global_store_dwordx4 v1, v[36:39], s[24:25]
	s_add_u32 s24, s24, 0x2000
	s_addc_u32 s25, s25, 0
	v_lshlrev_b32_e32 v12, 16, v84
	v_and_b32_e32 v13, 0xffff0000, v84
	v_lshlrev_b32_e32 v20, 16, v116
	v_and_b32_e32 v21, 0xffff0000, v116
	v_lshlrev_b32_e32 v14, 16, v85
	v_and_b32_e32 v15, 0xffff0000, v85
	v_lshlrev_b32_e32 v22, 16, v117
	v_and_b32_e32 v23, 0xffff0000, v117
	v_lshlrev_b32_e32 v16, 16, v86
	v_and_b32_e32 v17, 0xffff0000, v86
	v_lshlrev_b32_e32 v24, 16, v118
	v_and_b32_e32 v25, 0xffff0000, v118
	v_lshlrev_b32_e32 v18, 16, v87
	v_and_b32_e32 v19, 0xffff0000, v87
	v_lshlrev_b32_e32 v26, 16, v119
	v_and_b32_e32 v27, 0xffff0000, v119
	v_pk_fma_f32 v[20:21], v[44:45], v[20:21], v[12:13] op_sel_hi:[0,1,1] neg_lo:[1,0,0] neg_hi:[1,0,0]
	v_pk_fma_f32 v[22:23], v[44:45], v[22:23], v[14:15] op_sel_hi:[0,1,1] neg_lo:[1,0,0] neg_hi:[1,0,0]
	v_pk_fma_f32 v[24:25], v[44:45], v[24:25], v[16:17] op_sel_hi:[0,1,1] neg_lo:[1,0,0] neg_hi:[1,0,0]
	v_pk_fma_f32 v[26:27], v[44:45], v[26:27], v[18:19] op_sel_hi:[0,1,1] neg_lo:[1,0,0] neg_hi:[1,0,0]
	v_pk_add_f32 v[4:5], v[4:5], v[20:21]
	v_pk_add_f32 v[6:7], v[6:7], v[22:23]
	v_pk_add_f32 v[8:9], v[8:9], v[24:25]
	v_pk_add_f32 v[10:11], v[10:11], v[26:27]
	v_mov_b32_e32 v46, v3
	v_pk_fma_f32 v[28:29], v[46:47], v[4:5], v[12:13] op_sel_hi:[0,1,1] neg_lo:[0,0,1] neg_hi:[0,0,1]
	v_pk_fma_f32 v[30:31], v[46:47], v[6:7], v[14:15] op_sel_hi:[0,1,1] neg_lo:[0,0,1] neg_hi:[0,0,1]
	v_pk_fma_f32 v[32:33], v[46:47], v[8:9], v[16:17] op_sel_hi:[0,1,1] neg_lo:[0,0,1] neg_hi:[0,0,1]
	v_pk_fma_f32 v[34:35], v[46:47], v[10:11], v[18:19] op_sel_hi:[0,1,1] neg_lo:[0,0,1] neg_hi:[0,0,1]
	v_cvt_pk_bf16_f32 v40, v28, v29
	v_cvt_pk_bf16_f32 v41, v30, v31
	v_cvt_pk_bf16_f32 v42, v32, v33
	v_cvt_pk_bf16_f32 v43, v34, v35
	global_store_dwordx4 v1, v[40:43], s[24:25]
	s_add_u32 s24, s24, 0x2000
	s_addc_u32 s25, s25, 0
	v_lshlrev_b32_e32 v12, 16, v88
	v_and_b32_e32 v13, 0xffff0000, v88
	v_lshlrev_b32_e32 v20, 16, v120
	v_and_b32_e32 v21, 0xffff0000, v120
	v_lshlrev_b32_e32 v14, 16, v89
	v_and_b32_e32 v15, 0xffff0000, v89
	v_lshlrev_b32_e32 v22, 16, v121
	v_and_b32_e32 v23, 0xffff0000, v121
	v_lshlrev_b32_e32 v16, 16, v90
	v_and_b32_e32 v17, 0xffff0000, v90
	v_lshlrev_b32_e32 v24, 16, v122
	v_and_b32_e32 v25, 0xffff0000, v122
	v_lshlrev_b32_e32 v18, 16, v91
	v_and_b32_e32 v19, 0xffff0000, v91
	v_lshlrev_b32_e32 v26, 16, v123
	v_and_b32_e32 v27, 0xffff0000, v123
	v_pk_fma_f32 v[20:21], v[44:45], v[20:21], v[12:13] op_sel_hi:[0,1,1] neg_lo:[1,0,0] neg_hi:[1,0,0]
	v_pk_fma_f32 v[22:23], v[44:45], v[22:23], v[14:15] op_sel_hi:[0,1,1] neg_lo:[1,0,0] neg_hi:[1,0,0]
	v_pk_fma_f32 v[24:25], v[44:45], v[24:25], v[16:17] op_sel_hi:[0,1,1] neg_lo:[1,0,0] neg_hi:[1,0,0]
	v_pk_fma_f32 v[26:27], v[44:45], v[26:27], v[18:19] op_sel_hi:[0,1,1] neg_lo:[1,0,0] neg_hi:[1,0,0]
	v_pk_add_f32 v[4:5], v[4:5], v[20:21]
	v_pk_add_f32 v[6:7], v[6:7], v[22:23]
	v_pk_add_f32 v[8:9], v[8:9], v[24:25]
	v_pk_add_f32 v[10:11], v[10:11], v[26:27]
	v_mov_b32_e32 v46, v3
	v_pk_fma_f32 v[28:29], v[46:47], v[4:5], v[12:13] op_sel_hi:[0,1,1] neg_lo:[0,0,1] neg_hi:[0,0,1]
	v_pk_fma_f32 v[30:31], v[46:47], v[6:7], v[14:15] op_sel_hi:[0,1,1] neg_lo:[0,0,1] neg_hi:[0,0,1]
	v_pk_fma_f32 v[32:33], v[46:47], v[8:9], v[16:17] op_sel_hi:[0,1,1] neg_lo:[0,0,1] neg_hi:[0,0,1]
	v_pk_fma_f32 v[34:35], v[46:47], v[10:11], v[18:19] op_sel_hi:[0,1,1] neg_lo:[0,0,1] neg_hi:[0,0,1]
	v_cvt_pk_bf16_f32 v36, v28, v29
	v_cvt_pk_bf16_f32 v37, v30, v31
	v_cvt_pk_bf16_f32 v38, v32, v33
	v_cvt_pk_bf16_f32 v39, v34, v35
	global_store_dwordx4 v1, v[36:39], s[24:25]
	s_add_u32 s24, s24, 0x2000
	s_addc_u32 s25, s25, 0
	v_lshlrev_b32_e32 v12, 16, v92
	v_and_b32_e32 v13, 0xffff0000, v92
	v_lshlrev_b32_e32 v20, 16, v124
	v_and_b32_e32 v21, 0xffff0000, v124
	v_lshlrev_b32_e32 v14, 16, v93
	v_and_b32_e32 v15, 0xffff0000, v93
	v_lshlrev_b32_e32 v22, 16, v125
	v_and_b32_e32 v23, 0xffff0000, v125
	v_lshlrev_b32_e32 v16, 16, v94
	v_and_b32_e32 v17, 0xffff0000, v94
	v_lshlrev_b32_e32 v24, 16, v126
	v_and_b32_e32 v25, 0xffff0000, v126
	v_lshlrev_b32_e32 v18, 16, v95
	v_and_b32_e32 v19, 0xffff0000, v95
	v_lshlrev_b32_e32 v26, 16, v127
	v_and_b32_e32 v27, 0xffff0000, v127
	v_pk_fma_f32 v[20:21], v[44:45], v[20:21], v[12:13] op_sel_hi:[0,1,1] neg_lo:[1,0,0] neg_hi:[1,0,0]
	v_pk_fma_f32 v[22:23], v[44:45], v[22:23], v[14:15] op_sel_hi:[0,1,1] neg_lo:[1,0,0] neg_hi:[1,0,0]
	v_pk_fma_f32 v[24:25], v[44:45], v[24:25], v[16:17] op_sel_hi:[0,1,1] neg_lo:[1,0,0] neg_hi:[1,0,0]
	v_pk_fma_f32 v[26:27], v[44:45], v[26:27], v[18:19] op_sel_hi:[0,1,1] neg_lo:[1,0,0] neg_hi:[1,0,0]
	v_pk_add_f32 v[4:5], v[4:5], v[20:21]
	v_pk_add_f32 v[6:7], v[6:7], v[22:23]
	v_pk_add_f32 v[8:9], v[8:9], v[24:25]
	v_pk_add_f32 v[10:11], v[10:11], v[26:27]
	v_mov_b32_e32 v46, v3
	v_pk_fma_f32 v[28:29], v[46:47], v[4:5], v[12:13] op_sel_hi:[0,1,1] neg_lo:[0,0,1] neg_hi:[0,0,1]
	v_pk_fma_f32 v[30:31], v[46:47], v[6:7], v[14:15] op_sel_hi:[0,1,1] neg_lo:[0,0,1] neg_hi:[0,0,1]
	v_pk_fma_f32 v[32:33], v[46:47], v[8:9], v[16:17] op_sel_hi:[0,1,1] neg_lo:[0,0,1] neg_hi:[0,0,1]
	v_pk_fma_f32 v[34:35], v[46:47], v[10:11], v[18:19] op_sel_hi:[0,1,1] neg_lo:[0,0,1] neg_hi:[0,0,1]
	v_cvt_pk_bf16_f32 v40, v28, v29
	v_cvt_pk_bf16_f32 v41, v30, v31
	v_cvt_pk_bf16_f32 v42, v32, v33
	v_cvt_pk_bf16_f32 v43, v34, v35
	global_store_dwordx4 v1, v[40:43], s[24:25]
	s_add_u32 s24, s24, 0x2000
	s_addc_u32 s25, s25, 0
	global_load_dwordx4 v[64:67], v1, s[20:21]
	global_load_dwordx4 v[96:99], v49, s[22:23]
	s_add_u32 s20, s20, 0x2000
	s_addc_u32 s21, s21, 0
	s_add_u32 s22, s22, 0x2000
	s_addc_u32 s23, s23, 0
	global_load_dwordx4 v[68:71], v1, s[20:21]
	global_load_dwordx4 v[100:103], v49, s[22:23]
	s_add_u32 s20, s20, 0x2000
	s_addc_u32 s21, s21, 0
	s_add_u32 s22, s22, 0x2000
	s_addc_u32 s23, s23, 0
	global_load_dwordx4 v[72:75], v1, s[20:21]
	global_load_dwordx4 v[104:107], v49, s[22:23]
	s_add_u32 s20, s20, 0x2000
	s_addc_u32 s21, s21, 0
	s_add_u32 s22, s22, 0x2000
	s_addc_u32 s23, s23, 0
	global_load_dwordx4 v[76:79], v1, s[20:21]
	global_load_dwordx4 v[108:111], v49, s[22:23]
	s_add_u32 s20, s20, 0x2000
	s_addc_u32 s21, s21, 0
	s_add_u32 s22, s22, 0x2000
	s_addc_u32 s23, s23, 0
	global_load_dwordx4 v[80:83], v1, s[20:21]
	global_load_dwordx4 v[112:115], v49, s[22:23]
	s_add_u32 s20, s20, 0x2000
	s_addc_u32 s21, s21, 0
	s_add_u32 s22, s22, 0x2000
	s_addc_u32 s23, s23, 0
	global_load_dwordx4 v[84:87], v1, s[20:21]
	global_load_dwordx4 v[116:119], v49, s[22:23]
	s_add_u32 s20, s20, 0x2000
	s_addc_u32 s21, s21, 0
	s_add_u32 s22, s22, 0x2000
	s_addc_u32 s23, s23, 0
	global_load_dwordx4 v[88:91], v1, s[20:21]
	global_load_dwordx4 v[120:123], v49, s[22:23]
	s_add_u32 s20, s20, 0x2000
	s_addc_u32 s21, s21, 0
	s_add_u32 s22, s22, 0x2000
	s_addc_u32 s23, s23, 0
	global_load_dwordx4 v[92:95], v1, s[20:21]
	global_load_dwordx4 v[124:127], v49, s[22:23]
	s_add_u32 s20, s20, 0x2000
	s_addc_u32 s21, s21, 0
	s_add_u32 s22, s22, 0x2000
	s_addc_u32 s23, s23, 0
	s_waitcnt vmcnt(24)
	v_mov_b32_e32 v44, 1.0
	v_lshlrev_b32_e32 v12, 16, v128
	v_and_b32_e32 v13, 0xffff0000, v128
	v_lshlrev_b32_e32 v20, 16, v160
	v_and_b32_e32 v21, 0xffff0000, v160
	v_lshlrev_b32_e32 v14, 16, v129
	v_and_b32_e32 v15, 0xffff0000, v129
	v_lshlrev_b32_e32 v22, 16, v161
	v_and_b32_e32 v23, 0xffff0000, v161
	v_lshlrev_b32_e32 v16, 16, v130
	v_and_b32_e32 v17, 0xffff0000, v130
	v_lshlrev_b32_e32 v24, 16, v162
	v_and_b32_e32 v25, 0xffff0000, v162
	v_lshlrev_b32_e32 v18, 16, v131
	v_and_b32_e32 v19, 0xffff0000, v131
	v_lshlrev_b32_e32 v26, 16, v163
	v_and_b32_e32 v27, 0xffff0000, v163
	v_pk_fma_f32 v[20:21], v[44:45], v[20:21], v[12:13] op_sel_hi:[0,1,1] neg_lo:[1,0,0] neg_hi:[1,0,0]
	v_pk_fma_f32 v[22:23], v[44:45], v[22:23], v[14:15] op_sel_hi:[0,1,1] neg_lo:[1,0,0] neg_hi:[1,0,0]
	v_pk_fma_f32 v[24:25], v[44:45], v[24:25], v[16:17] op_sel_hi:[0,1,1] neg_lo:[1,0,0] neg_hi:[1,0,0]
	v_pk_fma_f32 v[26:27], v[44:45], v[26:27], v[18:19] op_sel_hi:[0,1,1] neg_lo:[1,0,0] neg_hi:[1,0,0]
	v_pk_add_f32 v[4:5], v[4:5], v[20:21]
	v_pk_add_f32 v[6:7], v[6:7], v[22:23]
	v_pk_add_f32 v[8:9], v[8:9], v[24:25]
	v_pk_add_f32 v[10:11], v[10:11], v[26:27]
	v_mov_b32_e32 v46, v3
	v_pk_fma_f32 v[28:29], v[46:47], v[4:5], v[12:13] op_sel_hi:[0,1,1] neg_lo:[0,0,1] neg_hi:[0,0,1]
	v_pk_fma_f32 v[30:31], v[46:47], v[6:7], v[14:15] op_sel_hi:[0,1,1] neg_lo:[0,0,1] neg_hi:[0,0,1]
	v_pk_fma_f32 v[32:33], v[46:47], v[8:9], v[16:17] op_sel_hi:[0,1,1] neg_lo:[0,0,1] neg_hi:[0,0,1]
	v_pk_fma_f32 v[34:35], v[46:47], v[10:11], v[18:19] op_sel_hi:[0,1,1] neg_lo:[0,0,1] neg_hi:[0,0,1]
	v_cvt_pk_bf16_f32 v36, v28, v29
	v_cvt_pk_bf16_f32 v37, v30, v31
	v_cvt_pk_bf16_f32 v38, v32, v33
	v_cvt_pk_bf16_f32 v39, v34, v35
	global_store_dwordx4 v1, v[36:39], s[24:25]
	s_add_u32 s24, s24, 0x2000
	s_addc_u32 s25, s25, 0
	v_lshlrev_b32_e32 v12, 16, v132
	v_and_b32_e32 v13, 0xffff0000, v132
	v_lshlrev_b32_e32 v20, 16, v164
	v_and_b32_e32 v21, 0xffff0000, v164
	v_lshlrev_b32_e32 v14, 16, v133
	v_and_b32_e32 v15, 0xffff0000, v133
	v_lshlrev_b32_e32 v22, 16, v165
	v_and_b32_e32 v23, 0xffff0000, v165
	v_lshlrev_b32_e32 v16, 16, v134
	v_and_b32_e32 v17, 0xffff0000, v134
	v_lshlrev_b32_e32 v24, 16, v166
	v_and_b32_e32 v25, 0xffff0000, v166
	v_lshlrev_b32_e32 v18, 16, v135
	v_and_b32_e32 v19, 0xffff0000, v135
	v_lshlrev_b32_e32 v26, 16, v167
	v_and_b32_e32 v27, 0xffff0000, v167
	v_pk_fma_f32 v[20:21], v[44:45], v[20:21], v[12:13] op_sel_hi:[0,1,1] neg_lo:[1,0,0] neg_hi:[1,0,0]
	v_pk_fma_f32 v[22:23], v[44:45], v[22:23], v[14:15] op_sel_hi:[0,1,1] neg_lo:[1,0,0] neg_hi:[1,0,0]
	v_pk_fma_f32 v[24:25], v[44:45], v[24:25], v[16:17] op_sel_hi:[0,1,1] neg_lo:[1,0,0] neg_hi:[1,0,0]
	v_pk_fma_f32 v[26:27], v[44:45], v[26:27], v[18:19] op_sel_hi:[0,1,1] neg_lo:[1,0,0] neg_hi:[1,0,0]
	v_pk_add_f32 v[4:5], v[4:5], v[20:21]
	v_pk_add_f32 v[6:7], v[6:7], v[22:23]
	v_pk_add_f32 v[8:9], v[8:9], v[24:25]
	v_pk_add_f32 v[10:11], v[10:11], v[26:27]
	v_mov_b32_e32 v46, v3
	v_pk_fma_f32 v[28:29], v[46:47], v[4:5], v[12:13] op_sel_hi:[0,1,1] neg_lo:[0,0,1] neg_hi:[0,0,1]
	v_pk_fma_f32 v[30:31], v[46:47], v[6:7], v[14:15] op_sel_hi:[0,1,1] neg_lo:[0,0,1] neg_hi:[0,0,1]
	v_pk_fma_f32 v[32:33], v[46:47], v[8:9], v[16:17] op_sel_hi:[0,1,1] neg_lo:[0,0,1] neg_hi:[0,0,1]
	v_pk_fma_f32 v[34:35], v[46:47], v[10:11], v[18:19] op_sel_hi:[0,1,1] neg_lo:[0,0,1] neg_hi:[0,0,1]
	v_cvt_pk_bf16_f32 v40, v28, v29
	v_cvt_pk_bf16_f32 v41, v30, v31
	v_cvt_pk_bf16_f32 v42, v32, v33
	v_cvt_pk_bf16_f32 v43, v34, v35
	global_store_dwordx4 v1, v[40:43], s[24:25]
	s_add_u32 s24, s24, 0x2000
	s_addc_u32 s25, s25, 0
	v_lshlrev_b32_e32 v12, 16, v136
	v_and_b32_e32 v13, 0xffff0000, v136
	v_lshlrev_b32_e32 v20, 16, v168
	v_and_b32_e32 v21, 0xffff0000, v168
	v_lshlrev_b32_e32 v14, 16, v137
	v_and_b32_e32 v15, 0xffff0000, v137
	v_lshlrev_b32_e32 v22, 16, v169
	v_and_b32_e32 v23, 0xffff0000, v169
	v_lshlrev_b32_e32 v16, 16, v138
	v_and_b32_e32 v17, 0xffff0000, v138
	v_lshlrev_b32_e32 v24, 16, v170
	v_and_b32_e32 v25, 0xffff0000, v170
	v_lshlrev_b32_e32 v18, 16, v139
	v_and_b32_e32 v19, 0xffff0000, v139
	v_lshlrev_b32_e32 v26, 16, v171
	v_and_b32_e32 v27, 0xffff0000, v171
	v_pk_fma_f32 v[20:21], v[44:45], v[20:21], v[12:13] op_sel_hi:[0,1,1] neg_lo:[1,0,0] neg_hi:[1,0,0]
	v_pk_fma_f32 v[22:23], v[44:45], v[22:23], v[14:15] op_sel_hi:[0,1,1] neg_lo:[1,0,0] neg_hi:[1,0,0]
	v_pk_fma_f32 v[24:25], v[44:45], v[24:25], v[16:17] op_sel_hi:[0,1,1] neg_lo:[1,0,0] neg_hi:[1,0,0]
	v_pk_fma_f32 v[26:27], v[44:45], v[26:27], v[18:19] op_sel_hi:[0,1,1] neg_lo:[1,0,0] neg_hi:[1,0,0]
	v_pk_add_f32 v[4:5], v[4:5], v[20:21]
	v_pk_add_f32 v[6:7], v[6:7], v[22:23]
	v_pk_add_f32 v[8:9], v[8:9], v[24:25]
	v_pk_add_f32 v[10:11], v[10:11], v[26:27]
	v_mov_b32_e32 v46, v3
	v_pk_fma_f32 v[28:29], v[46:47], v[4:5], v[12:13] op_sel_hi:[0,1,1] neg_lo:[0,0,1] neg_hi:[0,0,1]
	v_pk_fma_f32 v[30:31], v[46:47], v[6:7], v[14:15] op_sel_hi:[0,1,1] neg_lo:[0,0,1] neg_hi:[0,0,1]
	v_pk_fma_f32 v[32:33], v[46:47], v[8:9], v[16:17] op_sel_hi:[0,1,1] neg_lo:[0,0,1] neg_hi:[0,0,1]
	v_pk_fma_f32 v[34:35], v[46:47], v[10:11], v[18:19] op_sel_hi:[0,1,1] neg_lo:[0,0,1] neg_hi:[0,0,1]
	v_cvt_pk_bf16_f32 v36, v28, v29
	v_cvt_pk_bf16_f32 v37, v30, v31
	v_cvt_pk_bf16_f32 v38, v32, v33
	v_cvt_pk_bf16_f32 v39, v34, v35
	global_store_dwordx4 v1, v[36:39], s[24:25]
	s_add_u32 s24, s24, 0x2000
	s_addc_u32 s25, s25, 0
	v_lshlrev_b32_e32 v12, 16, v140
	v_and_b32_e32 v13, 0xffff0000, v140
	v_lshlrev_b32_e32 v20, 16, v172
	v_and_b32_e32 v21, 0xffff0000, v172
	v_lshlrev_b32_e32 v14, 16, v141
	v_and_b32_e32 v15, 0xffff0000, v141
	v_lshlrev_b32_e32 v22, 16, v173
	v_and_b32_e32 v23, 0xffff0000, v173
	v_lshlrev_b32_e32 v16, 16, v142
	v_and_b32_e32 v17, 0xffff0000, v142
	v_lshlrev_b32_e32 v24, 16, v174
	v_and_b32_e32 v25, 0xffff0000, v174
	v_lshlrev_b32_e32 v18, 16, v143
	v_and_b32_e32 v19, 0xffff0000, v143
	v_lshlrev_b32_e32 v26, 16, v175
	v_and_b32_e32 v27, 0xffff0000, v175
	v_pk_fma_f32 v[20:21], v[44:45], v[20:21], v[12:13] op_sel_hi:[0,1,1] neg_lo:[1,0,0] neg_hi:[1,0,0]
	v_pk_fma_f32 v[22:23], v[44:45], v[22:23], v[14:15] op_sel_hi:[0,1,1] neg_lo:[1,0,0] neg_hi:[1,0,0]
	v_pk_fma_f32 v[24:25], v[44:45], v[24:25], v[16:17] op_sel_hi:[0,1,1] neg_lo:[1,0,0] neg_hi:[1,0,0]
	v_pk_fma_f32 v[26:27], v[44:45], v[26:27], v[18:19] op_sel_hi:[0,1,1] neg_lo:[1,0,0] neg_hi:[1,0,0]
	v_pk_add_f32 v[4:5], v[4:5], v[20:21]
	v_pk_add_f32 v[6:7], v[6:7], v[22:23]
	v_pk_add_f32 v[8:9], v[8:9], v[24:25]
	v_pk_add_f32 v[10:11], v[10:11], v[26:27]
	v_mov_b32_e32 v46, v3
	v_pk_fma_f32 v[28:29], v[46:47], v[4:5], v[12:13] op_sel_hi:[0,1,1] neg_lo:[0,0,1] neg_hi:[0,0,1]
	v_pk_fma_f32 v[30:31], v[46:47], v[6:7], v[14:15] op_sel_hi:[0,1,1] neg_lo:[0,0,1] neg_hi:[0,0,1]
	v_pk_fma_f32 v[32:33], v[46:47], v[8:9], v[16:17] op_sel_hi:[0,1,1] neg_lo:[0,0,1] neg_hi:[0,0,1]
	v_pk_fma_f32 v[34:35], v[46:47], v[10:11], v[18:19] op_sel_hi:[0,1,1] neg_lo:[0,0,1] neg_hi:[0,0,1]
	v_cvt_pk_bf16_f32 v40, v28, v29
	v_cvt_pk_bf16_f32 v41, v30, v31
	v_cvt_pk_bf16_f32 v42, v32, v33
	v_cvt_pk_bf16_f32 v43, v34, v35
	global_store_dwordx4 v1, v[40:43], s[24:25]
	s_add_u32 s24, s24, 0x2000
	s_addc_u32 s25, s25, 0
	v_lshlrev_b32_e32 v12, 16, v144
	v_and_b32_e32 v13, 0xffff0000, v144
	v_lshlrev_b32_e32 v20, 16, v176
	v_and_b32_e32 v21, 0xffff0000, v176
	v_lshlrev_b32_e32 v14, 16, v145
	v_and_b32_e32 v15, 0xffff0000, v145
	v_lshlrev_b32_e32 v22, 16, v177
	v_and_b32_e32 v23, 0xffff0000, v177
	v_lshlrev_b32_e32 v16, 16, v146
	v_and_b32_e32 v17, 0xffff0000, v146
	v_lshlrev_b32_e32 v24, 16, v178
	v_and_b32_e32 v25, 0xffff0000, v178
	v_lshlrev_b32_e32 v18, 16, v147
	v_and_b32_e32 v19, 0xffff0000, v147
	v_lshlrev_b32_e32 v26, 16, v179
	v_and_b32_e32 v27, 0xffff0000, v179
	v_pk_fma_f32 v[20:21], v[44:45], v[20:21], v[12:13] op_sel_hi:[0,1,1] neg_lo:[1,0,0] neg_hi:[1,0,0]
	v_pk_fma_f32 v[22:23], v[44:45], v[22:23], v[14:15] op_sel_hi:[0,1,1] neg_lo:[1,0,0] neg_hi:[1,0,0]
	v_pk_fma_f32 v[24:25], v[44:45], v[24:25], v[16:17] op_sel_hi:[0,1,1] neg_lo:[1,0,0] neg_hi:[1,0,0]
	v_pk_fma_f32 v[26:27], v[44:45], v[26:27], v[18:19] op_sel_hi:[0,1,1] neg_lo:[1,0,0] neg_hi:[1,0,0]
	v_pk_add_f32 v[4:5], v[4:5], v[20:21]
	v_pk_add_f32 v[6:7], v[6:7], v[22:23]
	v_pk_add_f32 v[8:9], v[8:9], v[24:25]
	v_pk_add_f32 v[10:11], v[10:11], v[26:27]
	v_mov_b32_e32 v46, v3
	v_pk_fma_f32 v[28:29], v[46:47], v[4:5], v[12:13] op_sel_hi:[0,1,1] neg_lo:[0,0,1] neg_hi:[0,0,1]
	v_pk_fma_f32 v[30:31], v[46:47], v[6:7], v[14:15] op_sel_hi:[0,1,1] neg_lo:[0,0,1] neg_hi:[0,0,1]
	v_pk_fma_f32 v[32:33], v[46:47], v[8:9], v[16:17] op_sel_hi:[0,1,1] neg_lo:[0,0,1] neg_hi:[0,0,1]
	v_pk_fma_f32 v[34:35], v[46:47], v[10:11], v[18:19] op_sel_hi:[0,1,1] neg_lo:[0,0,1] neg_hi:[0,0,1]
	v_cvt_pk_bf16_f32 v36, v28, v29
	v_cvt_pk_bf16_f32 v37, v30, v31
	v_cvt_pk_bf16_f32 v38, v32, v33
	v_cvt_pk_bf16_f32 v39, v34, v35
	global_store_dwordx4 v1, v[36:39], s[24:25]
	s_add_u32 s24, s24, 0x2000
	s_addc_u32 s25, s25, 0
	v_lshlrev_b32_e32 v12, 16, v148
	v_and_b32_e32 v13, 0xffff0000, v148
	v_lshlrev_b32_e32 v20, 16, v180
	v_and_b32_e32 v21, 0xffff0000, v180
	v_lshlrev_b32_e32 v14, 16, v149
	v_and_b32_e32 v15, 0xffff0000, v149
	v_lshlrev_b32_e32 v22, 16, v181
	v_and_b32_e32 v23, 0xffff0000, v181
	v_lshlrev_b32_e32 v16, 16, v150
	v_and_b32_e32 v17, 0xffff0000, v150
	v_lshlrev_b32_e32 v24, 16, v182
	v_and_b32_e32 v25, 0xffff0000, v182
	v_lshlrev_b32_e32 v18, 16, v151
	v_and_b32_e32 v19, 0xffff0000, v151
	v_lshlrev_b32_e32 v26, 16, v183
	v_and_b32_e32 v27, 0xffff0000, v183
	v_pk_fma_f32 v[20:21], v[44:45], v[20:21], v[12:13] op_sel_hi:[0,1,1] neg_lo:[1,0,0] neg_hi:[1,0,0]
	v_pk_fma_f32 v[22:23], v[44:45], v[22:23], v[14:15] op_sel_hi:[0,1,1] neg_lo:[1,0,0] neg_hi:[1,0,0]
	v_pk_fma_f32 v[24:25], v[44:45], v[24:25], v[16:17] op_sel_hi:[0,1,1] neg_lo:[1,0,0] neg_hi:[1,0,0]
	v_pk_fma_f32 v[26:27], v[44:45], v[26:27], v[18:19] op_sel_hi:[0,1,1] neg_lo:[1,0,0] neg_hi:[1,0,0]
	v_pk_add_f32 v[4:5], v[4:5], v[20:21]
	v_pk_add_f32 v[6:7], v[6:7], v[22:23]
	v_pk_add_f32 v[8:9], v[8:9], v[24:25]
	v_pk_add_f32 v[10:11], v[10:11], v[26:27]
	v_mov_b32_e32 v46, v3
	v_pk_fma_f32 v[28:29], v[46:47], v[4:5], v[12:13] op_sel_hi:[0,1,1] neg_lo:[0,0,1] neg_hi:[0,0,1]
	v_pk_fma_f32 v[30:31], v[46:47], v[6:7], v[14:15] op_sel_hi:[0,1,1] neg_lo:[0,0,1] neg_hi:[0,0,1]
	v_pk_fma_f32 v[32:33], v[46:47], v[8:9], v[16:17] op_sel_hi:[0,1,1] neg_lo:[0,0,1] neg_hi:[0,0,1]
	v_pk_fma_f32 v[34:35], v[46:47], v[10:11], v[18:19] op_sel_hi:[0,1,1] neg_lo:[0,0,1] neg_hi:[0,0,1]
	v_cvt_pk_bf16_f32 v40, v28, v29
	v_cvt_pk_bf16_f32 v41, v30, v31
	v_cvt_pk_bf16_f32 v42, v32, v33
	v_cvt_pk_bf16_f32 v43, v34, v35
	global_store_dwordx4 v1, v[40:43], s[24:25]
	s_add_u32 s24, s24, 0x2000
	s_addc_u32 s25, s25, 0
	v_lshlrev_b32_e32 v12, 16, v152
	v_and_b32_e32 v13, 0xffff0000, v152
	v_lshlrev_b32_e32 v20, 16, v184
	v_and_b32_e32 v21, 0xffff0000, v184
	v_lshlrev_b32_e32 v14, 16, v153
	v_and_b32_e32 v15, 0xffff0000, v153
	v_lshlrev_b32_e32 v22, 16, v185
	v_and_b32_e32 v23, 0xffff0000, v185
	v_lshlrev_b32_e32 v16, 16, v154
	v_and_b32_e32 v17, 0xffff0000, v154
	v_lshlrev_b32_e32 v24, 16, v186
	v_and_b32_e32 v25, 0xffff0000, v186
	v_lshlrev_b32_e32 v18, 16, v155
	v_and_b32_e32 v19, 0xffff0000, v155
	v_lshlrev_b32_e32 v26, 16, v187
	v_and_b32_e32 v27, 0xffff0000, v187
	v_pk_fma_f32 v[20:21], v[44:45], v[20:21], v[12:13] op_sel_hi:[0,1,1] neg_lo:[1,0,0] neg_hi:[1,0,0]
	v_pk_fma_f32 v[22:23], v[44:45], v[22:23], v[14:15] op_sel_hi:[0,1,1] neg_lo:[1,0,0] neg_hi:[1,0,0]
	v_pk_fma_f32 v[24:25], v[44:45], v[24:25], v[16:17] op_sel_hi:[0,1,1] neg_lo:[1,0,0] neg_hi:[1,0,0]
	v_pk_fma_f32 v[26:27], v[44:45], v[26:27], v[18:19] op_sel_hi:[0,1,1] neg_lo:[1,0,0] neg_hi:[1,0,0]
	v_pk_add_f32 v[4:5], v[4:5], v[20:21]
	v_pk_add_f32 v[6:7], v[6:7], v[22:23]
	v_pk_add_f32 v[8:9], v[8:9], v[24:25]
	v_pk_add_f32 v[10:11], v[10:11], v[26:27]
	v_mov_b32_e32 v46, v3
	v_pk_fma_f32 v[28:29], v[46:47], v[4:5], v[12:13] op_sel_hi:[0,1,1] neg_lo:[0,0,1] neg_hi:[0,0,1]
	v_pk_fma_f32 v[30:31], v[46:47], v[6:7], v[14:15] op_sel_hi:[0,1,1] neg_lo:[0,0,1] neg_hi:[0,0,1]
	v_pk_fma_f32 v[32:33], v[46:47], v[8:9], v[16:17] op_sel_hi:[0,1,1] neg_lo:[0,0,1] neg_hi:[0,0,1]
	v_pk_fma_f32 v[34:35], v[46:47], v[10:11], v[18:19] op_sel_hi:[0,1,1] neg_lo:[0,0,1] neg_hi:[0,0,1]
	v_cvt_pk_bf16_f32 v36, v28, v29
	v_cvt_pk_bf16_f32 v37, v30, v31
	v_cvt_pk_bf16_f32 v38, v32, v33
	v_cvt_pk_bf16_f32 v39, v34, v35
	global_store_dwordx4 v1, v[36:39], s[24:25]
	s_add_u32 s24, s24, 0x2000
	s_addc_u32 s25, s25, 0
	v_lshlrev_b32_e32 v12, 16, v156
	v_and_b32_e32 v13, 0xffff0000, v156
	v_lshlrev_b32_e32 v20, 16, v188
	v_and_b32_e32 v21, 0xffff0000, v188
	v_lshlrev_b32_e32 v14, 16, v157
	v_and_b32_e32 v15, 0xffff0000, v157
	v_lshlrev_b32_e32 v22, 16, v189
	v_and_b32_e32 v23, 0xffff0000, v189
	v_lshlrev_b32_e32 v16, 16, v158
	v_and_b32_e32 v17, 0xffff0000, v158
	v_lshlrev_b32_e32 v24, 16, v190
	v_and_b32_e32 v25, 0xffff0000, v190
	v_lshlrev_b32_e32 v18, 16, v159
	v_and_b32_e32 v19, 0xffff0000, v159
	v_lshlrev_b32_e32 v26, 16, v191
	v_and_b32_e32 v27, 0xffff0000, v191
	v_pk_fma_f32 v[20:21], v[44:45], v[20:21], v[12:13] op_sel_hi:[0,1,1] neg_lo:[1,0,0] neg_hi:[1,0,0]
	v_pk_fma_f32 v[22:23], v[44:45], v[22:23], v[14:15] op_sel_hi:[0,1,1] neg_lo:[1,0,0] neg_hi:[1,0,0]
	v_pk_fma_f32 v[24:25], v[44:45], v[24:25], v[16:17] op_sel_hi:[0,1,1] neg_lo:[1,0,0] neg_hi:[1,0,0]
	v_pk_fma_f32 v[26:27], v[44:45], v[26:27], v[18:19] op_sel_hi:[0,1,1] neg_lo:[1,0,0] neg_hi:[1,0,0]
	v_pk_add_f32 v[4:5], v[4:5], v[20:21]
	v_pk_add_f32 v[6:7], v[6:7], v[22:23]
	v_pk_add_f32 v[8:9], v[8:9], v[24:25]
	v_pk_add_f32 v[10:11], v[10:11], v[26:27]
	v_mov_b32_e32 v46, v3
	v_pk_fma_f32 v[28:29], v[46:47], v[4:5], v[12:13] op_sel_hi:[0,1,1] neg_lo:[0,0,1] neg_hi:[0,0,1]
	v_pk_fma_f32 v[30:31], v[46:47], v[6:7], v[14:15] op_sel_hi:[0,1,1] neg_lo:[0,0,1] neg_hi:[0,0,1]
	v_pk_fma_f32 v[32:33], v[46:47], v[8:9], v[16:17] op_sel_hi:[0,1,1] neg_lo:[0,0,1] neg_hi:[0,0,1]
	v_pk_fma_f32 v[34:35], v[46:47], v[10:11], v[18:19] op_sel_hi:[0,1,1] neg_lo:[0,0,1] neg_hi:[0,0,1]
	v_cvt_pk_bf16_f32 v40, v28, v29
	v_cvt_pk_bf16_f32 v41, v30, v31
	v_cvt_pk_bf16_f32 v42, v32, v33
	v_cvt_pk_bf16_f32 v43, v34, v35
	global_store_dwordx4 v1, v[40:43], s[24:25]
	s_add_u32 s24, s24, 0x2000
	s_addc_u32 s25, s25, 0
	global_load_dwordx4 v[128:131], v1, s[20:21]
	global_load_dwordx4 v[160:163], v49, s[22:23]
	s_add_u32 s20, s20, 0x2000
	s_addc_u32 s21, s21, 0
	s_add_u32 s22, s22, 0x2000
	s_addc_u32 s23, s23, 0
	global_load_dwordx4 v[132:135], v1, s[20:21]
	global_load_dwordx4 v[164:167], v49, s[22:23]
	s_add_u32 s20, s20, 0x2000
	s_addc_u32 s21, s21, 0
	s_add_u32 s22, s22, 0x2000
	s_addc_u32 s23, s23, 0
	global_load_dwordx4 v[136:139], v1, s[20:21]
	global_load_dwordx4 v[168:171], v49, s[22:23]
	s_add_u32 s20, s20, 0x2000
	s_addc_u32 s21, s21, 0
	s_add_u32 s22, s22, 0x2000
	s_addc_u32 s23, s23, 0
	global_load_dwordx4 v[140:143], v1, s[20:21]
	global_load_dwordx4 v[172:175], v49, s[22:23]
	s_add_u32 s20, s20, 0x2000
	s_addc_u32 s21, s21, 0
	s_add_u32 s22, s22, 0x2000
	s_addc_u32 s23, s23, 0
	global_load_dwordx4 v[144:147], v1, s[20:21]
	global_load_dwordx4 v[176:179], v49, s[22:23]
	s_add_u32 s20, s20, 0x2000
	s_addc_u32 s21, s21, 0
	s_add_u32 s22, s22, 0x2000
	s_addc_u32 s23, s23, 0
	global_load_dwordx4 v[148:151], v1, s[20:21]
	global_load_dwordx4 v[180:183], v49, s[22:23]
	s_add_u32 s20, s20, 0x2000
	s_addc_u32 s21, s21, 0
	s_add_u32 s22, s22, 0x2000
	s_addc_u32 s23, s23, 0
	global_load_dwordx4 v[152:155], v1, s[20:21]
	global_load_dwordx4 v[184:187], v49, s[22:23]
	s_add_u32 s20, s20, 0x2000
	s_addc_u32 s21, s21, 0
	s_add_u32 s22, s22, 0x2000
	s_addc_u32 s23, s23, 0
	global_load_dwordx4 v[156:159], v1, s[20:21]
	global_load_dwordx4 v[188:191], v49, s[22:23]
	s_add_u32 s20, s20, 0x2000
	s_addc_u32 s21, s21, 0
	s_add_u32 s22, s22, 0x2000
	s_addc_u32 s23, s23, 0
	s_waitcnt vmcnt(24)
	v_mov_b32_e32 v44, 1.0
	v_lshlrev_b32_e32 v12, 16, v64
	v_and_b32_e32 v13, 0xffff0000, v64
	v_lshlrev_b32_e32 v20, 16, v96
	v_and_b32_e32 v21, 0xffff0000, v96
	v_lshlrev_b32_e32 v14, 16, v65
	v_and_b32_e32 v15, 0xffff0000, v65
	v_lshlrev_b32_e32 v22, 16, v97
	v_and_b32_e32 v23, 0xffff0000, v97
	v_lshlrev_b32_e32 v16, 16, v66
	v_and_b32_e32 v17, 0xffff0000, v66
	v_lshlrev_b32_e32 v24, 16, v98
	v_and_b32_e32 v25, 0xffff0000, v98
	v_lshlrev_b32_e32 v18, 16, v67
	v_and_b32_e32 v19, 0xffff0000, v67
	v_lshlrev_b32_e32 v26, 16, v99
	v_and_b32_e32 v27, 0xffff0000, v99
	v_pk_fma_f32 v[20:21], v[44:45], v[20:21], v[12:13] op_sel_hi:[0,1,1] neg_lo:[1,0,0] neg_hi:[1,0,0]
	v_pk_fma_f32 v[22:23], v[44:45], v[22:23], v[14:15] op_sel_hi:[0,1,1] neg_lo:[1,0,0] neg_hi:[1,0,0]
	v_pk_fma_f32 v[24:25], v[44:45], v[24:25], v[16:17] op_sel_hi:[0,1,1] neg_lo:[1,0,0] neg_hi:[1,0,0]
	v_pk_fma_f32 v[26:27], v[44:45], v[26:27], v[18:19] op_sel_hi:[0,1,1] neg_lo:[1,0,0] neg_hi:[1,0,0]
	v_pk_add_f32 v[4:5], v[4:5], v[20:21]
	v_pk_add_f32 v[6:7], v[6:7], v[22:23]
	v_pk_add_f32 v[8:9], v[8:9], v[24:25]
	v_pk_add_f32 v[10:11], v[10:11], v[26:27]
	v_mov_b32_e32 v46, v3
	v_pk_fma_f32 v[28:29], v[46:47], v[4:5], v[12:13] op_sel_hi:[0,1,1] neg_lo:[0,0,1] neg_hi:[0,0,1]
	v_pk_fma_f32 v[30:31], v[46:47], v[6:7], v[14:15] op_sel_hi:[0,1,1] neg_lo:[0,0,1] neg_hi:[0,0,1]
	v_pk_fma_f32 v[32:33], v[46:47], v[8:9], v[16:17] op_sel_hi:[0,1,1] neg_lo:[0,0,1] neg_hi:[0,0,1]
	v_pk_fma_f32 v[34:35], v[46:47], v[10:11], v[18:19] op_sel_hi:[0,1,1] neg_lo:[0,0,1] neg_hi:[0,0,1]
	v_cvt_pk_bf16_f32 v36, v28, v29
	v_cvt_pk_bf16_f32 v37, v30, v31
	v_cvt_pk_bf16_f32 v38, v32, v33
	v_cvt_pk_bf16_f32 v39, v34, v35
	global_store_dwordx4 v1, v[36:39], s[24:25]
	s_add_u32 s24, s24, 0x2000
	s_addc_u32 s25, s25, 0
	v_lshlrev_b32_e32 v12, 16, v68
	v_and_b32_e32 v13, 0xffff0000, v68
	v_lshlrev_b32_e32 v20, 16, v100
	v_and_b32_e32 v21, 0xffff0000, v100
	v_lshlrev_b32_e32 v14, 16, v69
	v_and_b32_e32 v15, 0xffff0000, v69
	v_lshlrev_b32_e32 v22, 16, v101
	v_and_b32_e32 v23, 0xffff0000, v101
	v_lshlrev_b32_e32 v16, 16, v70
	v_and_b32_e32 v17, 0xffff0000, v70
	v_lshlrev_b32_e32 v24, 16, v102
	v_and_b32_e32 v25, 0xffff0000, v102
	v_lshlrev_b32_e32 v18, 16, v71
	v_and_b32_e32 v19, 0xffff0000, v71
	v_lshlrev_b32_e32 v26, 16, v103
	v_and_b32_e32 v27, 0xffff0000, v103
	v_pk_fma_f32 v[20:21], v[44:45], v[20:21], v[12:13] op_sel_hi:[0,1,1] neg_lo:[1,0,0] neg_hi:[1,0,0]
	v_pk_fma_f32 v[22:23], v[44:45], v[22:23], v[14:15] op_sel_hi:[0,1,1] neg_lo:[1,0,0] neg_hi:[1,0,0]
	v_pk_fma_f32 v[24:25], v[44:45], v[24:25], v[16:17] op_sel_hi:[0,1,1] neg_lo:[1,0,0] neg_hi:[1,0,0]
	v_pk_fma_f32 v[26:27], v[44:45], v[26:27], v[18:19] op_sel_hi:[0,1,1] neg_lo:[1,0,0] neg_hi:[1,0,0]
	v_pk_add_f32 v[4:5], v[4:5], v[20:21]
	v_pk_add_f32 v[6:7], v[6:7], v[22:23]
	v_pk_add_f32 v[8:9], v[8:9], v[24:25]
	v_pk_add_f32 v[10:11], v[10:11], v[26:27]
	v_mov_b32_e32 v46, v3
	v_pk_fma_f32 v[28:29], v[46:47], v[4:5], v[12:13] op_sel_hi:[0,1,1] neg_lo:[0,0,1] neg_hi:[0,0,1]
	v_pk_fma_f32 v[30:31], v[46:47], v[6:7], v[14:15] op_sel_hi:[0,1,1] neg_lo:[0,0,1] neg_hi:[0,0,1]
	v_pk_fma_f32 v[32:33], v[46:47], v[8:9], v[16:17] op_sel_hi:[0,1,1] neg_lo:[0,0,1] neg_hi:[0,0,1]
	v_pk_fma_f32 v[34:35], v[46:47], v[10:11], v[18:19] op_sel_hi:[0,1,1] neg_lo:[0,0,1] neg_hi:[0,0,1]
	v_cvt_pk_bf16_f32 v40, v28, v29
	v_cvt_pk_bf16_f32 v41, v30, v31
	v_cvt_pk_bf16_f32 v42, v32, v33
	v_cvt_pk_bf16_f32 v43, v34, v35
	global_store_dwordx4 v1, v[40:43], s[24:25]
	s_add_u32 s24, s24, 0x2000
	s_addc_u32 s25, s25, 0
	v_lshlrev_b32_e32 v12, 16, v72
	v_and_b32_e32 v13, 0xffff0000, v72
	v_lshlrev_b32_e32 v20, 16, v104
	v_and_b32_e32 v21, 0xffff0000, v104
	v_lshlrev_b32_e32 v14, 16, v73
	v_and_b32_e32 v15, 0xffff0000, v73
	v_lshlrev_b32_e32 v22, 16, v105
	v_and_b32_e32 v23, 0xffff0000, v105
	v_lshlrev_b32_e32 v16, 16, v74
	v_and_b32_e32 v17, 0xffff0000, v74
	v_lshlrev_b32_e32 v24, 16, v106
	v_and_b32_e32 v25, 0xffff0000, v106
	v_lshlrev_b32_e32 v18, 16, v75
	v_and_b32_e32 v19, 0xffff0000, v75
	v_lshlrev_b32_e32 v26, 16, v107
	v_and_b32_e32 v27, 0xffff0000, v107
	v_pk_fma_f32 v[20:21], v[44:45], v[20:21], v[12:13] op_sel_hi:[0,1,1] neg_lo:[1,0,0] neg_hi:[1,0,0]
	v_pk_fma_f32 v[22:23], v[44:45], v[22:23], v[14:15] op_sel_hi:[0,1,1] neg_lo:[1,0,0] neg_hi:[1,0,0]
	v_pk_fma_f32 v[24:25], v[44:45], v[24:25], v[16:17] op_sel_hi:[0,1,1] neg_lo:[1,0,0] neg_hi:[1,0,0]
	v_pk_fma_f32 v[26:27], v[44:45], v[26:27], v[18:19] op_sel_hi:[0,1,1] neg_lo:[1,0,0] neg_hi:[1,0,0]
	v_pk_add_f32 v[4:5], v[4:5], v[20:21]
	v_pk_add_f32 v[6:7], v[6:7], v[22:23]
	v_pk_add_f32 v[8:9], v[8:9], v[24:25]
	v_pk_add_f32 v[10:11], v[10:11], v[26:27]
	v_mov_b32_e32 v46, v3
	v_pk_fma_f32 v[28:29], v[46:47], v[4:5], v[12:13] op_sel_hi:[0,1,1] neg_lo:[0,0,1] neg_hi:[0,0,1]
	v_pk_fma_f32 v[30:31], v[46:47], v[6:7], v[14:15] op_sel_hi:[0,1,1] neg_lo:[0,0,1] neg_hi:[0,0,1]
	v_pk_fma_f32 v[32:33], v[46:47], v[8:9], v[16:17] op_sel_hi:[0,1,1] neg_lo:[0,0,1] neg_hi:[0,0,1]
	v_pk_fma_f32 v[34:35], v[46:47], v[10:11], v[18:19] op_sel_hi:[0,1,1] neg_lo:[0,0,1] neg_hi:[0,0,1]
	v_cvt_pk_bf16_f32 v36, v28, v29
	v_cvt_pk_bf16_f32 v37, v30, v31
	v_cvt_pk_bf16_f32 v38, v32, v33
	v_cvt_pk_bf16_f32 v39, v34, v35
	global_store_dwordx4 v1, v[36:39], s[24:25]
	s_add_u32 s24, s24, 0x2000
	s_addc_u32 s25, s25, 0
	v_lshlrev_b32_e32 v12, 16, v76
	v_and_b32_e32 v13, 0xffff0000, v76
	v_lshlrev_b32_e32 v20, 16, v108
	v_and_b32_e32 v21, 0xffff0000, v108
	v_lshlrev_b32_e32 v14, 16, v77
	v_and_b32_e32 v15, 0xffff0000, v77
	v_lshlrev_b32_e32 v22, 16, v109
	v_and_b32_e32 v23, 0xffff0000, v109
	v_lshlrev_b32_e32 v16, 16, v78
	v_and_b32_e32 v17, 0xffff0000, v78
	v_lshlrev_b32_e32 v24, 16, v110
	v_and_b32_e32 v25, 0xffff0000, v110
	v_lshlrev_b32_e32 v18, 16, v79
	v_and_b32_e32 v19, 0xffff0000, v79
	v_lshlrev_b32_e32 v26, 16, v111
	v_and_b32_e32 v27, 0xffff0000, v111
	v_pk_fma_f32 v[20:21], v[44:45], v[20:21], v[12:13] op_sel_hi:[0,1,1] neg_lo:[1,0,0] neg_hi:[1,0,0]
	v_pk_fma_f32 v[22:23], v[44:45], v[22:23], v[14:15] op_sel_hi:[0,1,1] neg_lo:[1,0,0] neg_hi:[1,0,0]
	v_pk_fma_f32 v[24:25], v[44:45], v[24:25], v[16:17] op_sel_hi:[0,1,1] neg_lo:[1,0,0] neg_hi:[1,0,0]
	v_pk_fma_f32 v[26:27], v[44:45], v[26:27], v[18:19] op_sel_hi:[0,1,1] neg_lo:[1,0,0] neg_hi:[1,0,0]
	v_pk_add_f32 v[4:5], v[4:5], v[20:21]
	v_pk_add_f32 v[6:7], v[6:7], v[22:23]
	v_pk_add_f32 v[8:9], v[8:9], v[24:25]
	v_pk_add_f32 v[10:11], v[10:11], v[26:27]
	v_mov_b32_e32 v46, v3
	v_pk_fma_f32 v[28:29], v[46:47], v[4:5], v[12:13] op_sel_hi:[0,1,1] neg_lo:[0,0,1] neg_hi:[0,0,1]
	v_pk_fma_f32 v[30:31], v[46:47], v[6:7], v[14:15] op_sel_hi:[0,1,1] neg_lo:[0,0,1] neg_hi:[0,0,1]
	v_pk_fma_f32 v[32:33], v[46:47], v[8:9], v[16:17] op_sel_hi:[0,1,1] neg_lo:[0,0,1] neg_hi:[0,0,1]
	v_pk_fma_f32 v[34:35], v[46:47], v[10:11], v[18:19] op_sel_hi:[0,1,1] neg_lo:[0,0,1] neg_hi:[0,0,1]
	v_cvt_pk_bf16_f32 v40, v28, v29
	v_cvt_pk_bf16_f32 v41, v30, v31
	v_cvt_pk_bf16_f32 v42, v32, v33
	v_cvt_pk_bf16_f32 v43, v34, v35
	global_store_dwordx4 v1, v[40:43], s[24:25]
	s_add_u32 s24, s24, 0x2000
	s_addc_u32 s25, s25, 0
	v_lshlrev_b32_e32 v12, 16, v80
	v_and_b32_e32 v13, 0xffff0000, v80
	v_lshlrev_b32_e32 v20, 16, v112
	v_and_b32_e32 v21, 0xffff0000, v112
	v_lshlrev_b32_e32 v14, 16, v81
	v_and_b32_e32 v15, 0xffff0000, v81
	v_lshlrev_b32_e32 v22, 16, v113
	v_and_b32_e32 v23, 0xffff0000, v113
	v_lshlrev_b32_e32 v16, 16, v82
	v_and_b32_e32 v17, 0xffff0000, v82
	v_lshlrev_b32_e32 v24, 16, v114
	v_and_b32_e32 v25, 0xffff0000, v114
	v_lshlrev_b32_e32 v18, 16, v83
	v_and_b32_e32 v19, 0xffff0000, v83
	v_lshlrev_b32_e32 v26, 16, v115
	v_and_b32_e32 v27, 0xffff0000, v115
	v_pk_fma_f32 v[20:21], v[44:45], v[20:21], v[12:13] op_sel_hi:[0,1,1] neg_lo:[1,0,0] neg_hi:[1,0,0]
	v_pk_fma_f32 v[22:23], v[44:45], v[22:23], v[14:15] op_sel_hi:[0,1,1] neg_lo:[1,0,0] neg_hi:[1,0,0]
	v_pk_fma_f32 v[24:25], v[44:45], v[24:25], v[16:17] op_sel_hi:[0,1,1] neg_lo:[1,0,0] neg_hi:[1,0,0]
	v_pk_fma_f32 v[26:27], v[44:45], v[26:27], v[18:19] op_sel_hi:[0,1,1] neg_lo:[1,0,0] neg_hi:[1,0,0]
	v_pk_add_f32 v[4:5], v[4:5], v[20:21]
	v_pk_add_f32 v[6:7], v[6:7], v[22:23]
	v_pk_add_f32 v[8:9], v[8:9], v[24:25]
	v_pk_add_f32 v[10:11], v[10:11], v[26:27]
	v_mov_b32_e32 v46, v3
	v_pk_fma_f32 v[28:29], v[46:47], v[4:5], v[12:13] op_sel_hi:[0,1,1] neg_lo:[0,0,1] neg_hi:[0,0,1]
	v_pk_fma_f32 v[30:31], v[46:47], v[6:7], v[14:15] op_sel_hi:[0,1,1] neg_lo:[0,0,1] neg_hi:[0,0,1]
	v_pk_fma_f32 v[32:33], v[46:47], v[8:9], v[16:17] op_sel_hi:[0,1,1] neg_lo:[0,0,1] neg_hi:[0,0,1]
	v_pk_fma_f32 v[34:35], v[46:47], v[10:11], v[18:19] op_sel_hi:[0,1,1] neg_lo:[0,0,1] neg_hi:[0,0,1]
	v_cvt_pk_bf16_f32 v36, v28, v29
	v_cvt_pk_bf16_f32 v37, v30, v31
	v_cvt_pk_bf16_f32 v38, v32, v33
	v_cvt_pk_bf16_f32 v39, v34, v35
	global_store_dwordx4 v1, v[36:39], s[24:25]
	s_add_u32 s24, s24, 0x2000
	s_addc_u32 s25, s25, 0
	v_lshlrev_b32_e32 v12, 16, v84
	v_and_b32_e32 v13, 0xffff0000, v84
	v_lshlrev_b32_e32 v20, 16, v116
	v_and_b32_e32 v21, 0xffff0000, v116
	v_lshlrev_b32_e32 v14, 16, v85
	v_and_b32_e32 v15, 0xffff0000, v85
	v_lshlrev_b32_e32 v22, 16, v117
	v_and_b32_e32 v23, 0xffff0000, v117
	v_lshlrev_b32_e32 v16, 16, v86
	v_and_b32_e32 v17, 0xffff0000, v86
	v_lshlrev_b32_e32 v24, 16, v118
	v_and_b32_e32 v25, 0xffff0000, v118
	v_lshlrev_b32_e32 v18, 16, v87
	v_and_b32_e32 v19, 0xffff0000, v87
	v_lshlrev_b32_e32 v26, 16, v119
	v_and_b32_e32 v27, 0xffff0000, v119
	v_pk_fma_f32 v[20:21], v[44:45], v[20:21], v[12:13] op_sel_hi:[0,1,1] neg_lo:[1,0,0] neg_hi:[1,0,0]
	v_pk_fma_f32 v[22:23], v[44:45], v[22:23], v[14:15] op_sel_hi:[0,1,1] neg_lo:[1,0,0] neg_hi:[1,0,0]
	v_pk_fma_f32 v[24:25], v[44:45], v[24:25], v[16:17] op_sel_hi:[0,1,1] neg_lo:[1,0,0] neg_hi:[1,0,0]
	v_pk_fma_f32 v[26:27], v[44:45], v[26:27], v[18:19] op_sel_hi:[0,1,1] neg_lo:[1,0,0] neg_hi:[1,0,0]
	v_pk_add_f32 v[4:5], v[4:5], v[20:21]
	v_pk_add_f32 v[6:7], v[6:7], v[22:23]
	v_pk_add_f32 v[8:9], v[8:9], v[24:25]
	v_pk_add_f32 v[10:11], v[10:11], v[26:27]
	v_mov_b32_e32 v46, v3
	v_pk_fma_f32 v[28:29], v[46:47], v[4:5], v[12:13] op_sel_hi:[0,1,1] neg_lo:[0,0,1] neg_hi:[0,0,1]
	v_pk_fma_f32 v[30:31], v[46:47], v[6:7], v[14:15] op_sel_hi:[0,1,1] neg_lo:[0,0,1] neg_hi:[0,0,1]
	v_pk_fma_f32 v[32:33], v[46:47], v[8:9], v[16:17] op_sel_hi:[0,1,1] neg_lo:[0,0,1] neg_hi:[0,0,1]
	v_pk_fma_f32 v[34:35], v[46:47], v[10:11], v[18:19] op_sel_hi:[0,1,1] neg_lo:[0,0,1] neg_hi:[0,0,1]
	v_cvt_pk_bf16_f32 v40, v28, v29
	v_cvt_pk_bf16_f32 v41, v30, v31
	v_cvt_pk_bf16_f32 v42, v32, v33
	v_cvt_pk_bf16_f32 v43, v34, v35
	global_store_dwordx4 v1, v[40:43], s[24:25]
	s_add_u32 s24, s24, 0x2000
	s_addc_u32 s25, s25, 0
	v_lshlrev_b32_e32 v12, 16, v88
	v_and_b32_e32 v13, 0xffff0000, v88
	v_lshlrev_b32_e32 v20, 16, v120
	v_and_b32_e32 v21, 0xffff0000, v120
	v_lshlrev_b32_e32 v14, 16, v89
	v_and_b32_e32 v15, 0xffff0000, v89
	v_lshlrev_b32_e32 v22, 16, v121
	v_and_b32_e32 v23, 0xffff0000, v121
	v_lshlrev_b32_e32 v16, 16, v90
	v_and_b32_e32 v17, 0xffff0000, v90
	v_lshlrev_b32_e32 v24, 16, v122
	v_and_b32_e32 v25, 0xffff0000, v122
	v_lshlrev_b32_e32 v18, 16, v91
	v_and_b32_e32 v19, 0xffff0000, v91
	v_lshlrev_b32_e32 v26, 16, v123
	v_and_b32_e32 v27, 0xffff0000, v123
	v_pk_fma_f32 v[20:21], v[44:45], v[20:21], v[12:13] op_sel_hi:[0,1,1] neg_lo:[1,0,0] neg_hi:[1,0,0]
	v_pk_fma_f32 v[22:23], v[44:45], v[22:23], v[14:15] op_sel_hi:[0,1,1] neg_lo:[1,0,0] neg_hi:[1,0,0]
	v_pk_fma_f32 v[24:25], v[44:45], v[24:25], v[16:17] op_sel_hi:[0,1,1] neg_lo:[1,0,0] neg_hi:[1,0,0]
	v_pk_fma_f32 v[26:27], v[44:45], v[26:27], v[18:19] op_sel_hi:[0,1,1] neg_lo:[1,0,0] neg_hi:[1,0,0]
	v_pk_add_f32 v[4:5], v[4:5], v[20:21]
	v_pk_add_f32 v[6:7], v[6:7], v[22:23]
	v_pk_add_f32 v[8:9], v[8:9], v[24:25]
	v_pk_add_f32 v[10:11], v[10:11], v[26:27]
	v_mov_b32_e32 v46, v3
	v_pk_fma_f32 v[28:29], v[46:47], v[4:5], v[12:13] op_sel_hi:[0,1,1] neg_lo:[0,0,1] neg_hi:[0,0,1]
	v_pk_fma_f32 v[30:31], v[46:47], v[6:7], v[14:15] op_sel_hi:[0,1,1] neg_lo:[0,0,1] neg_hi:[0,0,1]
	v_pk_fma_f32 v[32:33], v[46:47], v[8:9], v[16:17] op_sel_hi:[0,1,1] neg_lo:[0,0,1] neg_hi:[0,0,1]
	v_pk_fma_f32 v[34:35], v[46:47], v[10:11], v[18:19] op_sel_hi:[0,1,1] neg_lo:[0,0,1] neg_hi:[0,0,1]
	v_cvt_pk_bf16_f32 v36, v28, v29
	v_cvt_pk_bf16_f32 v37, v30, v31
	v_cvt_pk_bf16_f32 v38, v32, v33
	v_cvt_pk_bf16_f32 v39, v34, v35
	global_store_dwordx4 v1, v[36:39], s[24:25]
	s_add_u32 s24, s24, 0x2000
	s_addc_u32 s25, s25, 0
	v_lshlrev_b32_e32 v12, 16, v92
	v_and_b32_e32 v13, 0xffff0000, v92
	v_lshlrev_b32_e32 v20, 16, v124
	v_and_b32_e32 v21, 0xffff0000, v124
	v_lshlrev_b32_e32 v14, 16, v93
	v_and_b32_e32 v15, 0xffff0000, v93
	v_lshlrev_b32_e32 v22, 16, v125
	v_and_b32_e32 v23, 0xffff0000, v125
	v_lshlrev_b32_e32 v16, 16, v94
	v_and_b32_e32 v17, 0xffff0000, v94
	v_lshlrev_b32_e32 v24, 16, v126
	v_and_b32_e32 v25, 0xffff0000, v126
	v_lshlrev_b32_e32 v18, 16, v95
	v_and_b32_e32 v19, 0xffff0000, v95
	v_lshlrev_b32_e32 v26, 16, v127
	v_and_b32_e32 v27, 0xffff0000, v127
	v_pk_fma_f32 v[20:21], v[44:45], v[20:21], v[12:13] op_sel_hi:[0,1,1] neg_lo:[1,0,0] neg_hi:[1,0,0]
	v_pk_fma_f32 v[22:23], v[44:45], v[22:23], v[14:15] op_sel_hi:[0,1,1] neg_lo:[1,0,0] neg_hi:[1,0,0]
	v_pk_fma_f32 v[24:25], v[44:45], v[24:25], v[16:17] op_sel_hi:[0,1,1] neg_lo:[1,0,0] neg_hi:[1,0,0]
	v_pk_fma_f32 v[26:27], v[44:45], v[26:27], v[18:19] op_sel_hi:[0,1,1] neg_lo:[1,0,0] neg_hi:[1,0,0]
	v_pk_add_f32 v[4:5], v[4:5], v[20:21]
	v_pk_add_f32 v[6:7], v[6:7], v[22:23]
	v_pk_add_f32 v[8:9], v[8:9], v[24:25]
	v_pk_add_f32 v[10:11], v[10:11], v[26:27]
	v_mov_b32_e32 v46, v3
	v_pk_fma_f32 v[28:29], v[46:47], v[4:5], v[12:13] op_sel_hi:[0,1,1] neg_lo:[0,0,1] neg_hi:[0,0,1]
	v_pk_fma_f32 v[30:31], v[46:47], v[6:7], v[14:15] op_sel_hi:[0,1,1] neg_lo:[0,0,1] neg_hi:[0,0,1]
	v_pk_fma_f32 v[32:33], v[46:47], v[8:9], v[16:17] op_sel_hi:[0,1,1] neg_lo:[0,0,1] neg_hi:[0,0,1]
	v_pk_fma_f32 v[34:35], v[46:47], v[10:11], v[18:19] op_sel_hi:[0,1,1] neg_lo:[0,0,1] neg_hi:[0,0,1]
	v_cvt_pk_bf16_f32 v40, v28, v29
	v_cvt_pk_bf16_f32 v41, v30, v31
	v_cvt_pk_bf16_f32 v42, v32, v33
	v_cvt_pk_bf16_f32 v43, v34, v35
	global_store_dwordx4 v1, v[40:43], s[24:25]
	s_add_u32 s24, s24, 0x2000
	s_addc_u32 s25, s25, 0
	global_load_dwordx4 v[64:67], v1, s[20:21]
	global_load_dwordx4 v[96:99], v49, s[22:23]
	s_add_u32 s20, s20, 0x2000
	s_addc_u32 s21, s21, 0
	s_add_u32 s22, s22, 0x2000
	s_addc_u32 s23, s23, 0
	global_load_dwordx4 v[68:71], v1, s[20:21]
	global_load_dwordx4 v[100:103], v49, s[22:23]
	s_add_u32 s20, s20, 0x2000
	s_addc_u32 s21, s21, 0
	s_add_u32 s22, s22, 0x2000
	s_addc_u32 s23, s23, 0
	global_load_dwordx4 v[72:75], v1, s[20:21]
	global_load_dwordx4 v[104:107], v49, s[22:23]
	s_add_u32 s20, s20, 0x2000
	s_addc_u32 s21, s21, 0
	s_add_u32 s22, s22, 0x2000
	s_addc_u32 s23, s23, 0
	global_load_dwordx4 v[76:79], v1, s[20:21]
	global_load_dwordx4 v[108:111], v49, s[22:23]
	s_add_u32 s20, s20, 0x2000
	s_addc_u32 s21, s21, 0
	s_add_u32 s22, s22, 0x2000
	s_addc_u32 s23, s23, 0
	global_load_dwordx4 v[80:83], v1, s[20:21]
	global_load_dwordx4 v[112:115], v49, s[22:23]
	s_add_u32 s20, s20, 0x2000
	s_addc_u32 s21, s21, 0
	s_add_u32 s22, s22, 0x2000
	s_addc_u32 s23, s23, 0
	global_load_dwordx4 v[84:87], v1, s[20:21]
	global_load_dwordx4 v[116:119], v49, s[22:23]
	s_add_u32 s20, s20, 0x2000
	s_addc_u32 s21, s21, 0
	s_add_u32 s22, s22, 0x2000
	s_addc_u32 s23, s23, 0
	global_load_dwordx4 v[88:91], v1, s[20:21]
	global_load_dwordx4 v[120:123], v49, s[22:23]
	s_add_u32 s20, s20, 0x2000
	s_addc_u32 s21, s21, 0
	s_add_u32 s22, s22, 0x2000
	s_addc_u32 s23, s23, 0
	global_load_dwordx4 v[92:95], v1, s[20:21]
	global_load_dwordx4 v[124:127], v49, s[22:23]
	s_add_u32 s20, s20, 0x2000
	s_addc_u32 s21, s21, 0
	s_add_u32 s22, s22, 0x2000
	s_addc_u32 s23, s23, 0
	s_waitcnt vmcnt(24)
	v_mov_b32_e32 v44, 1.0
	v_lshlrev_b32_e32 v12, 16, v128
	v_and_b32_e32 v13, 0xffff0000, v128
	v_lshlrev_b32_e32 v20, 16, v160
	v_and_b32_e32 v21, 0xffff0000, v160
	v_lshlrev_b32_e32 v14, 16, v129
	v_and_b32_e32 v15, 0xffff0000, v129
	v_lshlrev_b32_e32 v22, 16, v161
	v_and_b32_e32 v23, 0xffff0000, v161
	v_lshlrev_b32_e32 v16, 16, v130
	v_and_b32_e32 v17, 0xffff0000, v130
	v_lshlrev_b32_e32 v24, 16, v162
	v_and_b32_e32 v25, 0xffff0000, v162
	v_lshlrev_b32_e32 v18, 16, v131
	v_and_b32_e32 v19, 0xffff0000, v131
	v_lshlrev_b32_e32 v26, 16, v163
	v_and_b32_e32 v27, 0xffff0000, v163
	v_pk_fma_f32 v[20:21], v[44:45], v[20:21], v[12:13] op_sel_hi:[0,1,1] neg_lo:[1,0,0] neg_hi:[1,0,0]
	v_pk_fma_f32 v[22:23], v[44:45], v[22:23], v[14:15] op_sel_hi:[0,1,1] neg_lo:[1,0,0] neg_hi:[1,0,0]
	v_pk_fma_f32 v[24:25], v[44:45], v[24:25], v[16:17] op_sel_hi:[0,1,1] neg_lo:[1,0,0] neg_hi:[1,0,0]
	v_pk_fma_f32 v[26:27], v[44:45], v[26:27], v[18:19] op_sel_hi:[0,1,1] neg_lo:[1,0,0] neg_hi:[1,0,0]
	v_pk_add_f32 v[4:5], v[4:5], v[20:21]
	v_pk_add_f32 v[6:7], v[6:7], v[22:23]
	v_pk_add_f32 v[8:9], v[8:9], v[24:25]
	v_pk_add_f32 v[10:11], v[10:11], v[26:27]
	v_mov_b32_e32 v46, v3
	v_pk_fma_f32 v[28:29], v[46:47], v[4:5], v[12:13] op_sel_hi:[0,1,1] neg_lo:[0,0,1] neg_hi:[0,0,1]
	v_pk_fma_f32 v[30:31], v[46:47], v[6:7], v[14:15] op_sel_hi:[0,1,1] neg_lo:[0,0,1] neg_hi:[0,0,1]
	v_pk_fma_f32 v[32:33], v[46:47], v[8:9], v[16:17] op_sel_hi:[0,1,1] neg_lo:[0,0,1] neg_hi:[0,0,1]
	v_pk_fma_f32 v[34:35], v[46:47], v[10:11], v[18:19] op_sel_hi:[0,1,1] neg_lo:[0,0,1] neg_hi:[0,0,1]
	v_cvt_pk_bf16_f32 v36, v28, v29
	v_cvt_pk_bf16_f32 v37, v30, v31
	v_cvt_pk_bf16_f32 v38, v32, v33
	v_cvt_pk_bf16_f32 v39, v34, v35
	global_store_dwordx4 v1, v[36:39], s[24:25]
	s_add_u32 s24, s24, 0x2000
	s_addc_u32 s25, s25, 0
	v_lshlrev_b32_e32 v12, 16, v132
	v_and_b32_e32 v13, 0xffff0000, v132
	v_lshlrev_b32_e32 v20, 16, v164
	v_and_b32_e32 v21, 0xffff0000, v164
	v_lshlrev_b32_e32 v14, 16, v133
	v_and_b32_e32 v15, 0xffff0000, v133
	v_lshlrev_b32_e32 v22, 16, v165
	v_and_b32_e32 v23, 0xffff0000, v165
	v_lshlrev_b32_e32 v16, 16, v134
	v_and_b32_e32 v17, 0xffff0000, v134
	v_lshlrev_b32_e32 v24, 16, v166
	v_and_b32_e32 v25, 0xffff0000, v166
	v_lshlrev_b32_e32 v18, 16, v135
	v_and_b32_e32 v19, 0xffff0000, v135
	v_lshlrev_b32_e32 v26, 16, v167
	v_and_b32_e32 v27, 0xffff0000, v167
	v_pk_fma_f32 v[20:21], v[44:45], v[20:21], v[12:13] op_sel_hi:[0,1,1] neg_lo:[1,0,0] neg_hi:[1,0,0]
	v_pk_fma_f32 v[22:23], v[44:45], v[22:23], v[14:15] op_sel_hi:[0,1,1] neg_lo:[1,0,0] neg_hi:[1,0,0]
	v_pk_fma_f32 v[24:25], v[44:45], v[24:25], v[16:17] op_sel_hi:[0,1,1] neg_lo:[1,0,0] neg_hi:[1,0,0]
	v_pk_fma_f32 v[26:27], v[44:45], v[26:27], v[18:19] op_sel_hi:[0,1,1] neg_lo:[1,0,0] neg_hi:[1,0,0]
	v_pk_add_f32 v[4:5], v[4:5], v[20:21]
	v_pk_add_f32 v[6:7], v[6:7], v[22:23]
	v_pk_add_f32 v[8:9], v[8:9], v[24:25]
	v_pk_add_f32 v[10:11], v[10:11], v[26:27]
	v_mov_b32_e32 v46, v3
	v_pk_fma_f32 v[28:29], v[46:47], v[4:5], v[12:13] op_sel_hi:[0,1,1] neg_lo:[0,0,1] neg_hi:[0,0,1]
	v_pk_fma_f32 v[30:31], v[46:47], v[6:7], v[14:15] op_sel_hi:[0,1,1] neg_lo:[0,0,1] neg_hi:[0,0,1]
	v_pk_fma_f32 v[32:33], v[46:47], v[8:9], v[16:17] op_sel_hi:[0,1,1] neg_lo:[0,0,1] neg_hi:[0,0,1]
	v_pk_fma_f32 v[34:35], v[46:47], v[10:11], v[18:19] op_sel_hi:[0,1,1] neg_lo:[0,0,1] neg_hi:[0,0,1]
	v_cvt_pk_bf16_f32 v40, v28, v29
	v_cvt_pk_bf16_f32 v41, v30, v31
	v_cvt_pk_bf16_f32 v42, v32, v33
	v_cvt_pk_bf16_f32 v43, v34, v35
	global_store_dwordx4 v1, v[40:43], s[24:25]
	s_add_u32 s24, s24, 0x2000
	s_addc_u32 s25, s25, 0
	v_lshlrev_b32_e32 v12, 16, v136
	v_and_b32_e32 v13, 0xffff0000, v136
	v_lshlrev_b32_e32 v20, 16, v168
	v_and_b32_e32 v21, 0xffff0000, v168
	v_lshlrev_b32_e32 v14, 16, v137
	v_and_b32_e32 v15, 0xffff0000, v137
	v_lshlrev_b32_e32 v22, 16, v169
	v_and_b32_e32 v23, 0xffff0000, v169
	v_lshlrev_b32_e32 v16, 16, v138
	v_and_b32_e32 v17, 0xffff0000, v138
	v_lshlrev_b32_e32 v24, 16, v170
	v_and_b32_e32 v25, 0xffff0000, v170
	v_lshlrev_b32_e32 v18, 16, v139
	v_and_b32_e32 v19, 0xffff0000, v139
	v_lshlrev_b32_e32 v26, 16, v171
	v_and_b32_e32 v27, 0xffff0000, v171
	v_pk_fma_f32 v[20:21], v[44:45], v[20:21], v[12:13] op_sel_hi:[0,1,1] neg_lo:[1,0,0] neg_hi:[1,0,0]
	v_pk_fma_f32 v[22:23], v[44:45], v[22:23], v[14:15] op_sel_hi:[0,1,1] neg_lo:[1,0,0] neg_hi:[1,0,0]
	v_pk_fma_f32 v[24:25], v[44:45], v[24:25], v[16:17] op_sel_hi:[0,1,1] neg_lo:[1,0,0] neg_hi:[1,0,0]
	v_pk_fma_f32 v[26:27], v[44:45], v[26:27], v[18:19] op_sel_hi:[0,1,1] neg_lo:[1,0,0] neg_hi:[1,0,0]
	v_pk_add_f32 v[4:5], v[4:5], v[20:21]
	v_pk_add_f32 v[6:7], v[6:7], v[22:23]
	v_pk_add_f32 v[8:9], v[8:9], v[24:25]
	v_pk_add_f32 v[10:11], v[10:11], v[26:27]
	v_mov_b32_e32 v46, v3
	v_pk_fma_f32 v[28:29], v[46:47], v[4:5], v[12:13] op_sel_hi:[0,1,1] neg_lo:[0,0,1] neg_hi:[0,0,1]
	v_pk_fma_f32 v[30:31], v[46:47], v[6:7], v[14:15] op_sel_hi:[0,1,1] neg_lo:[0,0,1] neg_hi:[0,0,1]
	v_pk_fma_f32 v[32:33], v[46:47], v[8:9], v[16:17] op_sel_hi:[0,1,1] neg_lo:[0,0,1] neg_hi:[0,0,1]
	v_pk_fma_f32 v[34:35], v[46:47], v[10:11], v[18:19] op_sel_hi:[0,1,1] neg_lo:[0,0,1] neg_hi:[0,0,1]
	v_cvt_pk_bf16_f32 v36, v28, v29
	v_cvt_pk_bf16_f32 v37, v30, v31
	v_cvt_pk_bf16_f32 v38, v32, v33
	v_cvt_pk_bf16_f32 v39, v34, v35
	global_store_dwordx4 v1, v[36:39], s[24:25]
	s_add_u32 s24, s24, 0x2000
	s_addc_u32 s25, s25, 0
	v_lshlrev_b32_e32 v12, 16, v140
	v_and_b32_e32 v13, 0xffff0000, v140
	v_lshlrev_b32_e32 v20, 16, v172
	v_and_b32_e32 v21, 0xffff0000, v172
	v_lshlrev_b32_e32 v14, 16, v141
	v_and_b32_e32 v15, 0xffff0000, v141
	v_lshlrev_b32_e32 v22, 16, v173
	v_and_b32_e32 v23, 0xffff0000, v173
	v_lshlrev_b32_e32 v16, 16, v142
	v_and_b32_e32 v17, 0xffff0000, v142
	v_lshlrev_b32_e32 v24, 16, v174
	v_and_b32_e32 v25, 0xffff0000, v174
	v_lshlrev_b32_e32 v18, 16, v143
	v_and_b32_e32 v19, 0xffff0000, v143
	v_lshlrev_b32_e32 v26, 16, v175
	v_and_b32_e32 v27, 0xffff0000, v175
	v_pk_fma_f32 v[20:21], v[44:45], v[20:21], v[12:13] op_sel_hi:[0,1,1] neg_lo:[1,0,0] neg_hi:[1,0,0]
	v_pk_fma_f32 v[22:23], v[44:45], v[22:23], v[14:15] op_sel_hi:[0,1,1] neg_lo:[1,0,0] neg_hi:[1,0,0]
	v_pk_fma_f32 v[24:25], v[44:45], v[24:25], v[16:17] op_sel_hi:[0,1,1] neg_lo:[1,0,0] neg_hi:[1,0,0]
	v_pk_fma_f32 v[26:27], v[44:45], v[26:27], v[18:19] op_sel_hi:[0,1,1] neg_lo:[1,0,0] neg_hi:[1,0,0]
	v_pk_add_f32 v[4:5], v[4:5], v[20:21]
	v_pk_add_f32 v[6:7], v[6:7], v[22:23]
	v_pk_add_f32 v[8:9], v[8:9], v[24:25]
	v_pk_add_f32 v[10:11], v[10:11], v[26:27]
	v_mov_b32_e32 v46, v3
	v_pk_fma_f32 v[28:29], v[46:47], v[4:5], v[12:13] op_sel_hi:[0,1,1] neg_lo:[0,0,1] neg_hi:[0,0,1]
	v_pk_fma_f32 v[30:31], v[46:47], v[6:7], v[14:15] op_sel_hi:[0,1,1] neg_lo:[0,0,1] neg_hi:[0,0,1]
	v_pk_fma_f32 v[32:33], v[46:47], v[8:9], v[16:17] op_sel_hi:[0,1,1] neg_lo:[0,0,1] neg_hi:[0,0,1]
	v_pk_fma_f32 v[34:35], v[46:47], v[10:11], v[18:19] op_sel_hi:[0,1,1] neg_lo:[0,0,1] neg_hi:[0,0,1]
	v_cvt_pk_bf16_f32 v40, v28, v29
	v_cvt_pk_bf16_f32 v41, v30, v31
	v_cvt_pk_bf16_f32 v42, v32, v33
	v_cvt_pk_bf16_f32 v43, v34, v35
	global_store_dwordx4 v1, v[40:43], s[24:25]
	s_add_u32 s24, s24, 0x2000
	s_addc_u32 s25, s25, 0
	v_lshlrev_b32_e32 v12, 16, v144
	v_and_b32_e32 v13, 0xffff0000, v144
	v_lshlrev_b32_e32 v20, 16, v176
	v_and_b32_e32 v21, 0xffff0000, v176
	v_lshlrev_b32_e32 v14, 16, v145
	v_and_b32_e32 v15, 0xffff0000, v145
	v_lshlrev_b32_e32 v22, 16, v177
	v_and_b32_e32 v23, 0xffff0000, v177
	v_lshlrev_b32_e32 v16, 16, v146
	v_and_b32_e32 v17, 0xffff0000, v146
	v_lshlrev_b32_e32 v24, 16, v178
	v_and_b32_e32 v25, 0xffff0000, v178
	v_lshlrev_b32_e32 v18, 16, v147
	v_and_b32_e32 v19, 0xffff0000, v147
	v_lshlrev_b32_e32 v26, 16, v179
	v_and_b32_e32 v27, 0xffff0000, v179
	v_pk_fma_f32 v[20:21], v[44:45], v[20:21], v[12:13] op_sel_hi:[0,1,1] neg_lo:[1,0,0] neg_hi:[1,0,0]
	v_pk_fma_f32 v[22:23], v[44:45], v[22:23], v[14:15] op_sel_hi:[0,1,1] neg_lo:[1,0,0] neg_hi:[1,0,0]
	v_pk_fma_f32 v[24:25], v[44:45], v[24:25], v[16:17] op_sel_hi:[0,1,1] neg_lo:[1,0,0] neg_hi:[1,0,0]
	v_pk_fma_f32 v[26:27], v[44:45], v[26:27], v[18:19] op_sel_hi:[0,1,1] neg_lo:[1,0,0] neg_hi:[1,0,0]
	v_pk_add_f32 v[4:5], v[4:5], v[20:21]
	v_pk_add_f32 v[6:7], v[6:7], v[22:23]
	v_pk_add_f32 v[8:9], v[8:9], v[24:25]
	v_pk_add_f32 v[10:11], v[10:11], v[26:27]
	v_mov_b32_e32 v46, v3
	v_pk_fma_f32 v[28:29], v[46:47], v[4:5], v[12:13] op_sel_hi:[0,1,1] neg_lo:[0,0,1] neg_hi:[0,0,1]
	v_pk_fma_f32 v[30:31], v[46:47], v[6:7], v[14:15] op_sel_hi:[0,1,1] neg_lo:[0,0,1] neg_hi:[0,0,1]
	v_pk_fma_f32 v[32:33], v[46:47], v[8:9], v[16:17] op_sel_hi:[0,1,1] neg_lo:[0,0,1] neg_hi:[0,0,1]
	v_pk_fma_f32 v[34:35], v[46:47], v[10:11], v[18:19] op_sel_hi:[0,1,1] neg_lo:[0,0,1] neg_hi:[0,0,1]
	v_cvt_pk_bf16_f32 v36, v28, v29
	v_cvt_pk_bf16_f32 v37, v30, v31
	v_cvt_pk_bf16_f32 v38, v32, v33
	v_cvt_pk_bf16_f32 v39, v34, v35
	global_store_dwordx4 v1, v[36:39], s[24:25]
	s_add_u32 s24, s24, 0x2000
	s_addc_u32 s25, s25, 0
	v_lshlrev_b32_e32 v12, 16, v148
	v_and_b32_e32 v13, 0xffff0000, v148
	v_lshlrev_b32_e32 v20, 16, v180
	v_and_b32_e32 v21, 0xffff0000, v180
	v_lshlrev_b32_e32 v14, 16, v149
	v_and_b32_e32 v15, 0xffff0000, v149
	v_lshlrev_b32_e32 v22, 16, v181
	v_and_b32_e32 v23, 0xffff0000, v181
	v_lshlrev_b32_e32 v16, 16, v150
	v_and_b32_e32 v17, 0xffff0000, v150
	v_lshlrev_b32_e32 v24, 16, v182
	v_and_b32_e32 v25, 0xffff0000, v182
	v_lshlrev_b32_e32 v18, 16, v151
	v_and_b32_e32 v19, 0xffff0000, v151
	v_lshlrev_b32_e32 v26, 16, v183
	v_and_b32_e32 v27, 0xffff0000, v183
	v_pk_fma_f32 v[20:21], v[44:45], v[20:21], v[12:13] op_sel_hi:[0,1,1] neg_lo:[1,0,0] neg_hi:[1,0,0]
	v_pk_fma_f32 v[22:23], v[44:45], v[22:23], v[14:15] op_sel_hi:[0,1,1] neg_lo:[1,0,0] neg_hi:[1,0,0]
	v_pk_fma_f32 v[24:25], v[44:45], v[24:25], v[16:17] op_sel_hi:[0,1,1] neg_lo:[1,0,0] neg_hi:[1,0,0]
	v_pk_fma_f32 v[26:27], v[44:45], v[26:27], v[18:19] op_sel_hi:[0,1,1] neg_lo:[1,0,0] neg_hi:[1,0,0]
	v_pk_add_f32 v[4:5], v[4:5], v[20:21]
	v_pk_add_f32 v[6:7], v[6:7], v[22:23]
	v_pk_add_f32 v[8:9], v[8:9], v[24:25]
	v_pk_add_f32 v[10:11], v[10:11], v[26:27]
	v_mov_b32_e32 v46, v3
	v_pk_fma_f32 v[28:29], v[46:47], v[4:5], v[12:13] op_sel_hi:[0,1,1] neg_lo:[0,0,1] neg_hi:[0,0,1]
	v_pk_fma_f32 v[30:31], v[46:47], v[6:7], v[14:15] op_sel_hi:[0,1,1] neg_lo:[0,0,1] neg_hi:[0,0,1]
	v_pk_fma_f32 v[32:33], v[46:47], v[8:9], v[16:17] op_sel_hi:[0,1,1] neg_lo:[0,0,1] neg_hi:[0,0,1]
	v_pk_fma_f32 v[34:35], v[46:47], v[10:11], v[18:19] op_sel_hi:[0,1,1] neg_lo:[0,0,1] neg_hi:[0,0,1]
	v_cvt_pk_bf16_f32 v40, v28, v29
	v_cvt_pk_bf16_f32 v41, v30, v31
	v_cvt_pk_bf16_f32 v42, v32, v33
	v_cvt_pk_bf16_f32 v43, v34, v35
	global_store_dwordx4 v1, v[40:43], s[24:25]
	s_add_u32 s24, s24, 0x2000
	s_addc_u32 s25, s25, 0
	v_lshlrev_b32_e32 v12, 16, v152
	v_and_b32_e32 v13, 0xffff0000, v152
	v_lshlrev_b32_e32 v20, 16, v184
	v_and_b32_e32 v21, 0xffff0000, v184
	v_lshlrev_b32_e32 v14, 16, v153
	v_and_b32_e32 v15, 0xffff0000, v153
	v_lshlrev_b32_e32 v22, 16, v185
	v_and_b32_e32 v23, 0xffff0000, v185
	v_lshlrev_b32_e32 v16, 16, v154
	v_and_b32_e32 v17, 0xffff0000, v154
	v_lshlrev_b32_e32 v24, 16, v186
	v_and_b32_e32 v25, 0xffff0000, v186
	v_lshlrev_b32_e32 v18, 16, v155
	v_and_b32_e32 v19, 0xffff0000, v155
	v_lshlrev_b32_e32 v26, 16, v187
	v_and_b32_e32 v27, 0xffff0000, v187
	v_pk_fma_f32 v[20:21], v[44:45], v[20:21], v[12:13] op_sel_hi:[0,1,1] neg_lo:[1,0,0] neg_hi:[1,0,0]
	v_pk_fma_f32 v[22:23], v[44:45], v[22:23], v[14:15] op_sel_hi:[0,1,1] neg_lo:[1,0,0] neg_hi:[1,0,0]
	v_pk_fma_f32 v[24:25], v[44:45], v[24:25], v[16:17] op_sel_hi:[0,1,1] neg_lo:[1,0,0] neg_hi:[1,0,0]
	v_pk_fma_f32 v[26:27], v[44:45], v[26:27], v[18:19] op_sel_hi:[0,1,1] neg_lo:[1,0,0] neg_hi:[1,0,0]
	v_pk_add_f32 v[4:5], v[4:5], v[20:21]
	v_pk_add_f32 v[6:7], v[6:7], v[22:23]
	v_pk_add_f32 v[8:9], v[8:9], v[24:25]
	v_pk_add_f32 v[10:11], v[10:11], v[26:27]
	v_mov_b32_e32 v46, v3
	v_pk_fma_f32 v[28:29], v[46:47], v[4:5], v[12:13] op_sel_hi:[0,1,1] neg_lo:[0,0,1] neg_hi:[0,0,1]
	v_pk_fma_f32 v[30:31], v[46:47], v[6:7], v[14:15] op_sel_hi:[0,1,1] neg_lo:[0,0,1] neg_hi:[0,0,1]
	v_pk_fma_f32 v[32:33], v[46:47], v[8:9], v[16:17] op_sel_hi:[0,1,1] neg_lo:[0,0,1] neg_hi:[0,0,1]
	v_pk_fma_f32 v[34:35], v[46:47], v[10:11], v[18:19] op_sel_hi:[0,1,1] neg_lo:[0,0,1] neg_hi:[0,0,1]
	v_cvt_pk_bf16_f32 v36, v28, v29
	v_cvt_pk_bf16_f32 v37, v30, v31
	v_cvt_pk_bf16_f32 v38, v32, v33
	v_cvt_pk_bf16_f32 v39, v34, v35
	global_store_dwordx4 v1, v[36:39], s[24:25]
	s_add_u32 s24, s24, 0x2000
	s_addc_u32 s25, s25, 0
	v_lshlrev_b32_e32 v12, 16, v156
	v_and_b32_e32 v13, 0xffff0000, v156
	v_lshlrev_b32_e32 v20, 16, v188
	v_and_b32_e32 v21, 0xffff0000, v188
	v_lshlrev_b32_e32 v14, 16, v157
	v_and_b32_e32 v15, 0xffff0000, v157
	v_lshlrev_b32_e32 v22, 16, v189
	v_and_b32_e32 v23, 0xffff0000, v189
	v_lshlrev_b32_e32 v16, 16, v158
	v_and_b32_e32 v17, 0xffff0000, v158
	v_lshlrev_b32_e32 v24, 16, v190
	v_and_b32_e32 v25, 0xffff0000, v190
	v_lshlrev_b32_e32 v18, 16, v159
	v_and_b32_e32 v19, 0xffff0000, v159
	v_lshlrev_b32_e32 v26, 16, v191
	v_and_b32_e32 v27, 0xffff0000, v191
	v_pk_fma_f32 v[20:21], v[44:45], v[20:21], v[12:13] op_sel_hi:[0,1,1] neg_lo:[1,0,0] neg_hi:[1,0,0]
	v_pk_fma_f32 v[22:23], v[44:45], v[22:23], v[14:15] op_sel_hi:[0,1,1] neg_lo:[1,0,0] neg_hi:[1,0,0]
	v_pk_fma_f32 v[24:25], v[44:45], v[24:25], v[16:17] op_sel_hi:[0,1,1] neg_lo:[1,0,0] neg_hi:[1,0,0]
	v_pk_fma_f32 v[26:27], v[44:45], v[26:27], v[18:19] op_sel_hi:[0,1,1] neg_lo:[1,0,0] neg_hi:[1,0,0]
	v_pk_add_f32 v[4:5], v[4:5], v[20:21]
	v_pk_add_f32 v[6:7], v[6:7], v[22:23]
	v_pk_add_f32 v[8:9], v[8:9], v[24:25]
	v_pk_add_f32 v[10:11], v[10:11], v[26:27]
	v_mov_b32_e32 v46, v3
	v_pk_fma_f32 v[28:29], v[46:47], v[4:5], v[12:13] op_sel_hi:[0,1,1] neg_lo:[0,0,1] neg_hi:[0,0,1]
	v_pk_fma_f32 v[30:31], v[46:47], v[6:7], v[14:15] op_sel_hi:[0,1,1] neg_lo:[0,0,1] neg_hi:[0,0,1]
	v_pk_fma_f32 v[32:33], v[46:47], v[8:9], v[16:17] op_sel_hi:[0,1,1] neg_lo:[0,0,1] neg_hi:[0,0,1]
	v_pk_fma_f32 v[34:35], v[46:47], v[10:11], v[18:19] op_sel_hi:[0,1,1] neg_lo:[0,0,1] neg_hi:[0,0,1]
	v_cvt_pk_bf16_f32 v40, v28, v29
	v_cvt_pk_bf16_f32 v41, v30, v31
	v_cvt_pk_bf16_f32 v42, v32, v33
	v_cvt_pk_bf16_f32 v43, v34, v35
	global_store_dwordx4 v1, v[40:43], s[24:25]
	s_add_u32 s24, s24, 0x2000
	s_addc_u32 s25, s25, 0
	global_load_dwordx4 v[128:131], v1, s[20:21]
	global_load_dwordx4 v[160:163], v49, s[22:23]
	s_add_u32 s20, s20, 0x2000
	s_addc_u32 s21, s21, 0
	s_add_u32 s22, s22, 0x2000
	s_addc_u32 s23, s23, 0
	global_load_dwordx4 v[132:135], v1, s[20:21]
	global_load_dwordx4 v[164:167], v49, s[22:23]
	s_add_u32 s20, s20, 0x2000
	s_addc_u32 s21, s21, 0
	s_add_u32 s22, s22, 0x2000
	s_addc_u32 s23, s23, 0
	global_load_dwordx4 v[136:139], v1, s[20:21]
	global_load_dwordx4 v[168:171], v49, s[22:23]
	s_add_u32 s20, s20, 0x2000
	s_addc_u32 s21, s21, 0
	s_add_u32 s22, s22, 0x2000
	s_addc_u32 s23, s23, 0
	global_load_dwordx4 v[140:143], v1, s[20:21]
	global_load_dwordx4 v[172:175], v49, s[22:23]
	s_add_u32 s20, s20, 0x2000
	s_addc_u32 s21, s21, 0
	s_add_u32 s22, s22, 0x2000
	s_addc_u32 s23, s23, 0
	global_load_dwordx4 v[144:147], v1, s[20:21]
	global_load_dwordx4 v[176:179], v49, s[22:23]
	s_add_u32 s20, s20, 0x2000
	s_addc_u32 s21, s21, 0
	s_add_u32 s22, s22, 0x2000
	s_addc_u32 s23, s23, 0
	global_load_dwordx4 v[148:151], v1, s[20:21]
	global_load_dwordx4 v[180:183], v49, s[22:23]
	s_add_u32 s20, s20, 0x2000
	s_addc_u32 s21, s21, 0
	s_add_u32 s22, s22, 0x2000
	s_addc_u32 s23, s23, 0
	global_load_dwordx4 v[152:155], v1, s[20:21]
	global_load_dwordx4 v[184:187], v49, s[22:23]
	s_add_u32 s20, s20, 0x2000
	s_addc_u32 s21, s21, 0
	s_add_u32 s22, s22, 0x2000
	s_addc_u32 s23, s23, 0
	global_load_dwordx4 v[156:159], v1, s[20:21]
	global_load_dwordx4 v[188:191], v49, s[22:23]
	s_add_u32 s20, s20, 0x2000
	s_addc_u32 s21, s21, 0
	s_add_u32 s22, s22, 0x2000
	s_addc_u32 s23, s23, 0
	s_waitcnt vmcnt(24)
	v_mov_b32_e32 v44, 1.0
	v_lshlrev_b32_e32 v12, 16, v64
	v_and_b32_e32 v13, 0xffff0000, v64
	v_lshlrev_b32_e32 v20, 16, v96
	v_and_b32_e32 v21, 0xffff0000, v96
	v_lshlrev_b32_e32 v14, 16, v65
	v_and_b32_e32 v15, 0xffff0000, v65
	v_lshlrev_b32_e32 v22, 16, v97
	v_and_b32_e32 v23, 0xffff0000, v97
	v_lshlrev_b32_e32 v16, 16, v66
	v_and_b32_e32 v17, 0xffff0000, v66
	v_lshlrev_b32_e32 v24, 16, v98
	v_and_b32_e32 v25, 0xffff0000, v98
	v_lshlrev_b32_e32 v18, 16, v67
	v_and_b32_e32 v19, 0xffff0000, v67
	v_lshlrev_b32_e32 v26, 16, v99
	v_and_b32_e32 v27, 0xffff0000, v99
	v_pk_fma_f32 v[20:21], v[44:45], v[20:21], v[12:13] op_sel_hi:[0,1,1] neg_lo:[1,0,0] neg_hi:[1,0,0]
	v_pk_fma_f32 v[22:23], v[44:45], v[22:23], v[14:15] op_sel_hi:[0,1,1] neg_lo:[1,0,0] neg_hi:[1,0,0]
	v_pk_fma_f32 v[24:25], v[44:45], v[24:25], v[16:17] op_sel_hi:[0,1,1] neg_lo:[1,0,0] neg_hi:[1,0,0]
	v_pk_fma_f32 v[26:27], v[44:45], v[26:27], v[18:19] op_sel_hi:[0,1,1] neg_lo:[1,0,0] neg_hi:[1,0,0]
	v_pk_add_f32 v[4:5], v[4:5], v[20:21]
	v_pk_add_f32 v[6:7], v[6:7], v[22:23]
	v_pk_add_f32 v[8:9], v[8:9], v[24:25]
	v_pk_add_f32 v[10:11], v[10:11], v[26:27]
	v_mov_b32_e32 v46, v3
	v_pk_fma_f32 v[28:29], v[46:47], v[4:5], v[12:13] op_sel_hi:[0,1,1] neg_lo:[0,0,1] neg_hi:[0,0,1]
	v_pk_fma_f32 v[30:31], v[46:47], v[6:7], v[14:15] op_sel_hi:[0,1,1] neg_lo:[0,0,1] neg_hi:[0,0,1]
	v_pk_fma_f32 v[32:33], v[46:47], v[8:9], v[16:17] op_sel_hi:[0,1,1] neg_lo:[0,0,1] neg_hi:[0,0,1]
	v_pk_fma_f32 v[34:35], v[46:47], v[10:11], v[18:19] op_sel_hi:[0,1,1] neg_lo:[0,0,1] neg_hi:[0,0,1]
	v_cvt_pk_bf16_f32 v36, v28, v29
	v_cvt_pk_bf16_f32 v37, v30, v31
	v_cvt_pk_bf16_f32 v38, v32, v33
	v_cvt_pk_bf16_f32 v39, v34, v35
	global_store_dwordx4 v1, v[36:39], s[24:25]
	s_add_u32 s24, s24, 0x2000
	s_addc_u32 s25, s25, 0
	v_lshlrev_b32_e32 v12, 16, v68
	v_and_b32_e32 v13, 0xffff0000, v68
	v_lshlrev_b32_e32 v20, 16, v100
	v_and_b32_e32 v21, 0xffff0000, v100
	v_lshlrev_b32_e32 v14, 16, v69
	v_and_b32_e32 v15, 0xffff0000, v69
	v_lshlrev_b32_e32 v22, 16, v101
	v_and_b32_e32 v23, 0xffff0000, v101
	v_lshlrev_b32_e32 v16, 16, v70
	v_and_b32_e32 v17, 0xffff0000, v70
	v_lshlrev_b32_e32 v24, 16, v102
	v_and_b32_e32 v25, 0xffff0000, v102
	v_lshlrev_b32_e32 v18, 16, v71
	v_and_b32_e32 v19, 0xffff0000, v71
	v_lshlrev_b32_e32 v26, 16, v103
	v_and_b32_e32 v27, 0xffff0000, v103
	v_pk_fma_f32 v[20:21], v[44:45], v[20:21], v[12:13] op_sel_hi:[0,1,1] neg_lo:[1,0,0] neg_hi:[1,0,0]
	v_pk_fma_f32 v[22:23], v[44:45], v[22:23], v[14:15] op_sel_hi:[0,1,1] neg_lo:[1,0,0] neg_hi:[1,0,0]
	v_pk_fma_f32 v[24:25], v[44:45], v[24:25], v[16:17] op_sel_hi:[0,1,1] neg_lo:[1,0,0] neg_hi:[1,0,0]
	v_pk_fma_f32 v[26:27], v[44:45], v[26:27], v[18:19] op_sel_hi:[0,1,1] neg_lo:[1,0,0] neg_hi:[1,0,0]
	v_pk_add_f32 v[4:5], v[4:5], v[20:21]
	v_pk_add_f32 v[6:7], v[6:7], v[22:23]
	v_pk_add_f32 v[8:9], v[8:9], v[24:25]
	v_pk_add_f32 v[10:11], v[10:11], v[26:27]
	v_mov_b32_e32 v46, v3
	v_pk_fma_f32 v[28:29], v[46:47], v[4:5], v[12:13] op_sel_hi:[0,1,1] neg_lo:[0,0,1] neg_hi:[0,0,1]
	v_pk_fma_f32 v[30:31], v[46:47], v[6:7], v[14:15] op_sel_hi:[0,1,1] neg_lo:[0,0,1] neg_hi:[0,0,1]
	v_pk_fma_f32 v[32:33], v[46:47], v[8:9], v[16:17] op_sel_hi:[0,1,1] neg_lo:[0,0,1] neg_hi:[0,0,1]
	v_pk_fma_f32 v[34:35], v[46:47], v[10:11], v[18:19] op_sel_hi:[0,1,1] neg_lo:[0,0,1] neg_hi:[0,0,1]
	v_cvt_pk_bf16_f32 v40, v28, v29
	v_cvt_pk_bf16_f32 v41, v30, v31
	v_cvt_pk_bf16_f32 v42, v32, v33
	v_cvt_pk_bf16_f32 v43, v34, v35
	global_store_dwordx4 v1, v[40:43], s[24:25]
	s_add_u32 s24, s24, 0x2000
	s_addc_u32 s25, s25, 0
	v_lshlrev_b32_e32 v12, 16, v72
	v_and_b32_e32 v13, 0xffff0000, v72
	v_lshlrev_b32_e32 v20, 16, v104
	v_and_b32_e32 v21, 0xffff0000, v104
	v_lshlrev_b32_e32 v14, 16, v73
	v_and_b32_e32 v15, 0xffff0000, v73
	v_lshlrev_b32_e32 v22, 16, v105
	v_and_b32_e32 v23, 0xffff0000, v105
	v_lshlrev_b32_e32 v16, 16, v74
	v_and_b32_e32 v17, 0xffff0000, v74
	v_lshlrev_b32_e32 v24, 16, v106
	v_and_b32_e32 v25, 0xffff0000, v106
	v_lshlrev_b32_e32 v18, 16, v75
	v_and_b32_e32 v19, 0xffff0000, v75
	v_lshlrev_b32_e32 v26, 16, v107
	v_and_b32_e32 v27, 0xffff0000, v107
	v_pk_fma_f32 v[20:21], v[44:45], v[20:21], v[12:13] op_sel_hi:[0,1,1] neg_lo:[1,0,0] neg_hi:[1,0,0]
	v_pk_fma_f32 v[22:23], v[44:45], v[22:23], v[14:15] op_sel_hi:[0,1,1] neg_lo:[1,0,0] neg_hi:[1,0,0]
	v_pk_fma_f32 v[24:25], v[44:45], v[24:25], v[16:17] op_sel_hi:[0,1,1] neg_lo:[1,0,0] neg_hi:[1,0,0]
	v_pk_fma_f32 v[26:27], v[44:45], v[26:27], v[18:19] op_sel_hi:[0,1,1] neg_lo:[1,0,0] neg_hi:[1,0,0]
	v_pk_add_f32 v[4:5], v[4:5], v[20:21]
	v_pk_add_f32 v[6:7], v[6:7], v[22:23]
	v_pk_add_f32 v[8:9], v[8:9], v[24:25]
	v_pk_add_f32 v[10:11], v[10:11], v[26:27]
	v_mov_b32_e32 v46, v3
	v_pk_fma_f32 v[28:29], v[46:47], v[4:5], v[12:13] op_sel_hi:[0,1,1] neg_lo:[0,0,1] neg_hi:[0,0,1]
	v_pk_fma_f32 v[30:31], v[46:47], v[6:7], v[14:15] op_sel_hi:[0,1,1] neg_lo:[0,0,1] neg_hi:[0,0,1]
	v_pk_fma_f32 v[32:33], v[46:47], v[8:9], v[16:17] op_sel_hi:[0,1,1] neg_lo:[0,0,1] neg_hi:[0,0,1]
	v_pk_fma_f32 v[34:35], v[46:47], v[10:11], v[18:19] op_sel_hi:[0,1,1] neg_lo:[0,0,1] neg_hi:[0,0,1]
	v_cvt_pk_bf16_f32 v36, v28, v29
	v_cvt_pk_bf16_f32 v37, v30, v31
	v_cvt_pk_bf16_f32 v38, v32, v33
	v_cvt_pk_bf16_f32 v39, v34, v35
	global_store_dwordx4 v1, v[36:39], s[24:25]
	s_add_u32 s24, s24, 0x2000
	s_addc_u32 s25, s25, 0
	v_lshlrev_b32_e32 v12, 16, v76
	v_and_b32_e32 v13, 0xffff0000, v76
	v_lshlrev_b32_e32 v20, 16, v108
	v_and_b32_e32 v21, 0xffff0000, v108
	v_lshlrev_b32_e32 v14, 16, v77
	v_and_b32_e32 v15, 0xffff0000, v77
	v_lshlrev_b32_e32 v22, 16, v109
	v_and_b32_e32 v23, 0xffff0000, v109
	v_lshlrev_b32_e32 v16, 16, v78
	v_and_b32_e32 v17, 0xffff0000, v78
	v_lshlrev_b32_e32 v24, 16, v110
	v_and_b32_e32 v25, 0xffff0000, v110
	v_lshlrev_b32_e32 v18, 16, v79
	v_and_b32_e32 v19, 0xffff0000, v79
	v_lshlrev_b32_e32 v26, 16, v111
	v_and_b32_e32 v27, 0xffff0000, v111
	v_pk_fma_f32 v[20:21], v[44:45], v[20:21], v[12:13] op_sel_hi:[0,1,1] neg_lo:[1,0,0] neg_hi:[1,0,0]
	v_pk_fma_f32 v[22:23], v[44:45], v[22:23], v[14:15] op_sel_hi:[0,1,1] neg_lo:[1,0,0] neg_hi:[1,0,0]
	v_pk_fma_f32 v[24:25], v[44:45], v[24:25], v[16:17] op_sel_hi:[0,1,1] neg_lo:[1,0,0] neg_hi:[1,0,0]
	v_pk_fma_f32 v[26:27], v[44:45], v[26:27], v[18:19] op_sel_hi:[0,1,1] neg_lo:[1,0,0] neg_hi:[1,0,0]
	v_pk_add_f32 v[4:5], v[4:5], v[20:21]
	v_pk_add_f32 v[6:7], v[6:7], v[22:23]
	v_pk_add_f32 v[8:9], v[8:9], v[24:25]
	v_pk_add_f32 v[10:11], v[10:11], v[26:27]
	v_mov_b32_e32 v46, v3
	v_pk_fma_f32 v[28:29], v[46:47], v[4:5], v[12:13] op_sel_hi:[0,1,1] neg_lo:[0,0,1] neg_hi:[0,0,1]
	v_pk_fma_f32 v[30:31], v[46:47], v[6:7], v[14:15] op_sel_hi:[0,1,1] neg_lo:[0,0,1] neg_hi:[0,0,1]
	v_pk_fma_f32 v[32:33], v[46:47], v[8:9], v[16:17] op_sel_hi:[0,1,1] neg_lo:[0,0,1] neg_hi:[0,0,1]
	v_pk_fma_f32 v[34:35], v[46:47], v[10:11], v[18:19] op_sel_hi:[0,1,1] neg_lo:[0,0,1] neg_hi:[0,0,1]
	v_cvt_pk_bf16_f32 v40, v28, v29
	v_cvt_pk_bf16_f32 v41, v30, v31
	v_cvt_pk_bf16_f32 v42, v32, v33
	v_cvt_pk_bf16_f32 v43, v34, v35
	global_store_dwordx4 v1, v[40:43], s[24:25]
	s_add_u32 s24, s24, 0x2000
	s_addc_u32 s25, s25, 0
	v_lshlrev_b32_e32 v12, 16, v80
	v_and_b32_e32 v13, 0xffff0000, v80
	v_lshlrev_b32_e32 v20, 16, v112
	v_and_b32_e32 v21, 0xffff0000, v112
	v_lshlrev_b32_e32 v14, 16, v81
	v_and_b32_e32 v15, 0xffff0000, v81
	v_lshlrev_b32_e32 v22, 16, v113
	v_and_b32_e32 v23, 0xffff0000, v113
	v_lshlrev_b32_e32 v16, 16, v82
	v_and_b32_e32 v17, 0xffff0000, v82
	v_lshlrev_b32_e32 v24, 16, v114
	v_and_b32_e32 v25, 0xffff0000, v114
	v_lshlrev_b32_e32 v18, 16, v83
	v_and_b32_e32 v19, 0xffff0000, v83
	v_lshlrev_b32_e32 v26, 16, v115
	v_and_b32_e32 v27, 0xffff0000, v115
	v_pk_fma_f32 v[20:21], v[44:45], v[20:21], v[12:13] op_sel_hi:[0,1,1] neg_lo:[1,0,0] neg_hi:[1,0,0]
	v_pk_fma_f32 v[22:23], v[44:45], v[22:23], v[14:15] op_sel_hi:[0,1,1] neg_lo:[1,0,0] neg_hi:[1,0,0]
	v_pk_fma_f32 v[24:25], v[44:45], v[24:25], v[16:17] op_sel_hi:[0,1,1] neg_lo:[1,0,0] neg_hi:[1,0,0]
	v_pk_fma_f32 v[26:27], v[44:45], v[26:27], v[18:19] op_sel_hi:[0,1,1] neg_lo:[1,0,0] neg_hi:[1,0,0]
	v_pk_add_f32 v[4:5], v[4:5], v[20:21]
	v_pk_add_f32 v[6:7], v[6:7], v[22:23]
	v_pk_add_f32 v[8:9], v[8:9], v[24:25]
	v_pk_add_f32 v[10:11], v[10:11], v[26:27]
	v_mov_b32_e32 v46, v3
	v_pk_fma_f32 v[28:29], v[46:47], v[4:5], v[12:13] op_sel_hi:[0,1,1] neg_lo:[0,0,1] neg_hi:[0,0,1]
	v_pk_fma_f32 v[30:31], v[46:47], v[6:7], v[14:15] op_sel_hi:[0,1,1] neg_lo:[0,0,1] neg_hi:[0,0,1]
	v_pk_fma_f32 v[32:33], v[46:47], v[8:9], v[16:17] op_sel_hi:[0,1,1] neg_lo:[0,0,1] neg_hi:[0,0,1]
	v_pk_fma_f32 v[34:35], v[46:47], v[10:11], v[18:19] op_sel_hi:[0,1,1] neg_lo:[0,0,1] neg_hi:[0,0,1]
	v_cvt_pk_bf16_f32 v36, v28, v29
	v_cvt_pk_bf16_f32 v37, v30, v31
	v_cvt_pk_bf16_f32 v38, v32, v33
	v_cvt_pk_bf16_f32 v39, v34, v35
	global_store_dwordx4 v1, v[36:39], s[24:25]
	s_add_u32 s24, s24, 0x2000
	s_addc_u32 s25, s25, 0
	v_lshlrev_b32_e32 v12, 16, v84
	v_and_b32_e32 v13, 0xffff0000, v84
	v_lshlrev_b32_e32 v20, 16, v116
	v_and_b32_e32 v21, 0xffff0000, v116
	v_lshlrev_b32_e32 v14, 16, v85
	v_and_b32_e32 v15, 0xffff0000, v85
	v_lshlrev_b32_e32 v22, 16, v117
	v_and_b32_e32 v23, 0xffff0000, v117
	v_lshlrev_b32_e32 v16, 16, v86
	v_and_b32_e32 v17, 0xffff0000, v86
	v_lshlrev_b32_e32 v24, 16, v118
	v_and_b32_e32 v25, 0xffff0000, v118
	v_lshlrev_b32_e32 v18, 16, v87
	v_and_b32_e32 v19, 0xffff0000, v87
	v_lshlrev_b32_e32 v26, 16, v119
	v_and_b32_e32 v27, 0xffff0000, v119
	v_pk_fma_f32 v[20:21], v[44:45], v[20:21], v[12:13] op_sel_hi:[0,1,1] neg_lo:[1,0,0] neg_hi:[1,0,0]
	v_pk_fma_f32 v[22:23], v[44:45], v[22:23], v[14:15] op_sel_hi:[0,1,1] neg_lo:[1,0,0] neg_hi:[1,0,0]
	v_pk_fma_f32 v[24:25], v[44:45], v[24:25], v[16:17] op_sel_hi:[0,1,1] neg_lo:[1,0,0] neg_hi:[1,0,0]
	v_pk_fma_f32 v[26:27], v[44:45], v[26:27], v[18:19] op_sel_hi:[0,1,1] neg_lo:[1,0,0] neg_hi:[1,0,0]
	v_pk_add_f32 v[4:5], v[4:5], v[20:21]
	v_pk_add_f32 v[6:7], v[6:7], v[22:23]
	v_pk_add_f32 v[8:9], v[8:9], v[24:25]
	v_pk_add_f32 v[10:11], v[10:11], v[26:27]
	v_mov_b32_e32 v46, v3
	v_pk_fma_f32 v[28:29], v[46:47], v[4:5], v[12:13] op_sel_hi:[0,1,1] neg_lo:[0,0,1] neg_hi:[0,0,1]
	v_pk_fma_f32 v[30:31], v[46:47], v[6:7], v[14:15] op_sel_hi:[0,1,1] neg_lo:[0,0,1] neg_hi:[0,0,1]
	v_pk_fma_f32 v[32:33], v[46:47], v[8:9], v[16:17] op_sel_hi:[0,1,1] neg_lo:[0,0,1] neg_hi:[0,0,1]
	v_pk_fma_f32 v[34:35], v[46:47], v[10:11], v[18:19] op_sel_hi:[0,1,1] neg_lo:[0,0,1] neg_hi:[0,0,1]
	v_cvt_pk_bf16_f32 v40, v28, v29
	v_cvt_pk_bf16_f32 v41, v30, v31
	v_cvt_pk_bf16_f32 v42, v32, v33
	v_cvt_pk_bf16_f32 v43, v34, v35
	global_store_dwordx4 v1, v[40:43], s[24:25]
	s_add_u32 s24, s24, 0x2000
	s_addc_u32 s25, s25, 0
	v_lshlrev_b32_e32 v12, 16, v88
	v_and_b32_e32 v13, 0xffff0000, v88
	v_lshlrev_b32_e32 v20, 16, v120
	v_and_b32_e32 v21, 0xffff0000, v120
	v_lshlrev_b32_e32 v14, 16, v89
	v_and_b32_e32 v15, 0xffff0000, v89
	v_lshlrev_b32_e32 v22, 16, v121
	v_and_b32_e32 v23, 0xffff0000, v121
	v_lshlrev_b32_e32 v16, 16, v90
	v_and_b32_e32 v17, 0xffff0000, v90
	v_lshlrev_b32_e32 v24, 16, v122
	v_and_b32_e32 v25, 0xffff0000, v122
	v_lshlrev_b32_e32 v18, 16, v91
	v_and_b32_e32 v19, 0xffff0000, v91
	v_lshlrev_b32_e32 v26, 16, v123
	v_and_b32_e32 v27, 0xffff0000, v123
	v_pk_fma_f32 v[20:21], v[44:45], v[20:21], v[12:13] op_sel_hi:[0,1,1] neg_lo:[1,0,0] neg_hi:[1,0,0]
	v_pk_fma_f32 v[22:23], v[44:45], v[22:23], v[14:15] op_sel_hi:[0,1,1] neg_lo:[1,0,0] neg_hi:[1,0,0]
	v_pk_fma_f32 v[24:25], v[44:45], v[24:25], v[16:17] op_sel_hi:[0,1,1] neg_lo:[1,0,0] neg_hi:[1,0,0]
	v_pk_fma_f32 v[26:27], v[44:45], v[26:27], v[18:19] op_sel_hi:[0,1,1] neg_lo:[1,0,0] neg_hi:[1,0,0]
	v_pk_add_f32 v[4:5], v[4:5], v[20:21]
	v_pk_add_f32 v[6:7], v[6:7], v[22:23]
	v_pk_add_f32 v[8:9], v[8:9], v[24:25]
	v_pk_add_f32 v[10:11], v[10:11], v[26:27]
	v_mov_b32_e32 v46, v3
	v_pk_fma_f32 v[28:29], v[46:47], v[4:5], v[12:13] op_sel_hi:[0,1,1] neg_lo:[0,0,1] neg_hi:[0,0,1]
	v_pk_fma_f32 v[30:31], v[46:47], v[6:7], v[14:15] op_sel_hi:[0,1,1] neg_lo:[0,0,1] neg_hi:[0,0,1]
	v_pk_fma_f32 v[32:33], v[46:47], v[8:9], v[16:17] op_sel_hi:[0,1,1] neg_lo:[0,0,1] neg_hi:[0,0,1]
	v_pk_fma_f32 v[34:35], v[46:47], v[10:11], v[18:19] op_sel_hi:[0,1,1] neg_lo:[0,0,1] neg_hi:[0,0,1]
	v_cvt_pk_bf16_f32 v36, v28, v29
	v_cvt_pk_bf16_f32 v37, v30, v31
	v_cvt_pk_bf16_f32 v38, v32, v33
	v_cvt_pk_bf16_f32 v39, v34, v35
	global_store_dwordx4 v1, v[36:39], s[24:25]
	s_add_u32 s24, s24, 0x2000
	s_addc_u32 s25, s25, 0
	v_lshlrev_b32_e32 v12, 16, v92
	v_and_b32_e32 v13, 0xffff0000, v92
	v_lshlrev_b32_e32 v20, 16, v124
	v_and_b32_e32 v21, 0xffff0000, v124
	v_lshlrev_b32_e32 v14, 16, v93
	v_and_b32_e32 v15, 0xffff0000, v93
	v_lshlrev_b32_e32 v22, 16, v125
	v_and_b32_e32 v23, 0xffff0000, v125
	v_lshlrev_b32_e32 v16, 16, v94
	v_and_b32_e32 v17, 0xffff0000, v94
	v_lshlrev_b32_e32 v24, 16, v126
	v_and_b32_e32 v25, 0xffff0000, v126
	v_lshlrev_b32_e32 v18, 16, v95
	v_and_b32_e32 v19, 0xffff0000, v95
	v_lshlrev_b32_e32 v26, 16, v127
	v_and_b32_e32 v27, 0xffff0000, v127
	v_pk_fma_f32 v[20:21], v[44:45], v[20:21], v[12:13] op_sel_hi:[0,1,1] neg_lo:[1,0,0] neg_hi:[1,0,0]
	v_pk_fma_f32 v[22:23], v[44:45], v[22:23], v[14:15] op_sel_hi:[0,1,1] neg_lo:[1,0,0] neg_hi:[1,0,0]
	v_pk_fma_f32 v[24:25], v[44:45], v[24:25], v[16:17] op_sel_hi:[0,1,1] neg_lo:[1,0,0] neg_hi:[1,0,0]
	v_pk_fma_f32 v[26:27], v[44:45], v[26:27], v[18:19] op_sel_hi:[0,1,1] neg_lo:[1,0,0] neg_hi:[1,0,0]
	v_pk_add_f32 v[4:5], v[4:5], v[20:21]
	v_pk_add_f32 v[6:7], v[6:7], v[22:23]
	v_pk_add_f32 v[8:9], v[8:9], v[24:25]
	v_pk_add_f32 v[10:11], v[10:11], v[26:27]
	v_mov_b32_e32 v46, v3
	v_pk_fma_f32 v[28:29], v[46:47], v[4:5], v[12:13] op_sel_hi:[0,1,1] neg_lo:[0,0,1] neg_hi:[0,0,1]
	v_pk_fma_f32 v[30:31], v[46:47], v[6:7], v[14:15] op_sel_hi:[0,1,1] neg_lo:[0,0,1] neg_hi:[0,0,1]
	v_pk_fma_f32 v[32:33], v[46:47], v[8:9], v[16:17] op_sel_hi:[0,1,1] neg_lo:[0,0,1] neg_hi:[0,0,1]
	v_pk_fma_f32 v[34:35], v[46:47], v[10:11], v[18:19] op_sel_hi:[0,1,1] neg_lo:[0,0,1] neg_hi:[0,0,1]
	v_cvt_pk_bf16_f32 v40, v28, v29
	v_cvt_pk_bf16_f32 v41, v30, v31
	v_cvt_pk_bf16_f32 v42, v32, v33
	v_cvt_pk_bf16_f32 v43, v34, v35
	global_store_dwordx4 v1, v[40:43], s[24:25]
	s_add_u32 s24, s24, 0x2000
	s_addc_u32 s25, s25, 0
	global_load_dwordx4 v[64:67], v1, s[20:21]
	global_load_dwordx4 v[96:99], v49, s[22:23]
	s_add_u32 s20, s20, 0x2000
	s_addc_u32 s21, s21, 0
	s_add_u32 s22, s22, 0x2000
	s_addc_u32 s23, s23, 0
	global_load_dwordx4 v[68:71], v1, s[20:21]
	global_load_dwordx4 v[100:103], v49, s[22:23]
	s_add_u32 s20, s20, 0x2000
	s_addc_u32 s21, s21, 0
	s_add_u32 s22, s22, 0x2000
	s_addc_u32 s23, s23, 0
	global_load_dwordx4 v[72:75], v1, s[20:21]
	global_load_dwordx4 v[104:107], v49, s[22:23]
	s_add_u32 s20, s20, 0x2000
	s_addc_u32 s21, s21, 0
	s_add_u32 s22, s22, 0x2000
	s_addc_u32 s23, s23, 0
	global_load_dwordx4 v[76:79], v1, s[20:21]
	global_load_dwordx4 v[108:111], v49, s[22:23]
	s_add_u32 s20, s20, 0x2000
	s_addc_u32 s21, s21, 0
	s_add_u32 s22, s22, 0x2000
	s_addc_u32 s23, s23, 0
	global_load_dwordx4 v[80:83], v1, s[20:21]
	global_load_dwordx4 v[112:115], v49, s[22:23]
	s_add_u32 s20, s20, 0x2000
	s_addc_u32 s21, s21, 0
	s_add_u32 s22, s22, 0x2000
	s_addc_u32 s23, s23, 0
	global_load_dwordx4 v[84:87], v1, s[20:21]
	global_load_dwordx4 v[116:119], v49, s[22:23]
	s_add_u32 s20, s20, 0x2000
	s_addc_u32 s21, s21, 0
	s_add_u32 s22, s22, 0x2000
	s_addc_u32 s23, s23, 0
	global_load_dwordx4 v[88:91], v1, s[20:21]
	global_load_dwordx4 v[120:123], v49, s[22:23]
	s_add_u32 s20, s20, 0x2000
	s_addc_u32 s21, s21, 0
	s_add_u32 s22, s22, 0x2000
	s_addc_u32 s23, s23, 0
	global_load_dwordx4 v[92:95], v1, s[20:21]
	global_load_dwordx4 v[124:127], v49, s[22:23]
	s_add_u32 s20, s20, 0x2000
	s_addc_u32 s21, s21, 0
	s_add_u32 s22, s22, 0x2000
	s_addc_u32 s23, s23, 0
	s_waitcnt vmcnt(24)
	v_mov_b32_e32 v44, 1.0
	v_lshlrev_b32_e32 v12, 16, v128
	v_and_b32_e32 v13, 0xffff0000, v128
	v_lshlrev_b32_e32 v20, 16, v160
	v_and_b32_e32 v21, 0xffff0000, v160
	v_lshlrev_b32_e32 v14, 16, v129
	v_and_b32_e32 v15, 0xffff0000, v129
	v_lshlrev_b32_e32 v22, 16, v161
	v_and_b32_e32 v23, 0xffff0000, v161
	v_lshlrev_b32_e32 v16, 16, v130
	v_and_b32_e32 v17, 0xffff0000, v130
	v_lshlrev_b32_e32 v24, 16, v162
	v_and_b32_e32 v25, 0xffff0000, v162
	v_lshlrev_b32_e32 v18, 16, v131
	v_and_b32_e32 v19, 0xffff0000, v131
	v_lshlrev_b32_e32 v26, 16, v163
	v_and_b32_e32 v27, 0xffff0000, v163
	v_pk_fma_f32 v[20:21], v[44:45], v[20:21], v[12:13] op_sel_hi:[0,1,1] neg_lo:[1,0,0] neg_hi:[1,0,0]
	v_pk_fma_f32 v[22:23], v[44:45], v[22:23], v[14:15] op_sel_hi:[0,1,1] neg_lo:[1,0,0] neg_hi:[1,0,0]
	v_pk_fma_f32 v[24:25], v[44:45], v[24:25], v[16:17] op_sel_hi:[0,1,1] neg_lo:[1,0,0] neg_hi:[1,0,0]
	v_pk_fma_f32 v[26:27], v[44:45], v[26:27], v[18:19] op_sel_hi:[0,1,1] neg_lo:[1,0,0] neg_hi:[1,0,0]
	v_pk_add_f32 v[4:5], v[4:5], v[20:21]
	v_pk_add_f32 v[6:7], v[6:7], v[22:23]
	v_pk_add_f32 v[8:9], v[8:9], v[24:25]
	v_pk_add_f32 v[10:11], v[10:11], v[26:27]
	v_mov_b32_e32 v46, v3
	v_pk_fma_f32 v[28:29], v[46:47], v[4:5], v[12:13] op_sel_hi:[0,1,1] neg_lo:[0,0,1] neg_hi:[0,0,1]
	v_pk_fma_f32 v[30:31], v[46:47], v[6:7], v[14:15] op_sel_hi:[0,1,1] neg_lo:[0,0,1] neg_hi:[0,0,1]
	v_pk_fma_f32 v[32:33], v[46:47], v[8:9], v[16:17] op_sel_hi:[0,1,1] neg_lo:[0,0,1] neg_hi:[0,0,1]
	v_pk_fma_f32 v[34:35], v[46:47], v[10:11], v[18:19] op_sel_hi:[0,1,1] neg_lo:[0,0,1] neg_hi:[0,0,1]
	v_cvt_pk_bf16_f32 v36, v28, v29
	v_cvt_pk_bf16_f32 v37, v30, v31
	v_cvt_pk_bf16_f32 v38, v32, v33
	v_cvt_pk_bf16_f32 v39, v34, v35
	global_store_dwordx4 v1, v[36:39], s[24:25]
	s_add_u32 s24, s24, 0x2000
	s_addc_u32 s25, s25, 0
	v_lshlrev_b32_e32 v12, 16, v132
	v_and_b32_e32 v13, 0xffff0000, v132
	v_lshlrev_b32_e32 v20, 16, v164
	v_and_b32_e32 v21, 0xffff0000, v164
	v_lshlrev_b32_e32 v14, 16, v133
	v_and_b32_e32 v15, 0xffff0000, v133
	v_lshlrev_b32_e32 v22, 16, v165
	v_and_b32_e32 v23, 0xffff0000, v165
	v_lshlrev_b32_e32 v16, 16, v134
	v_and_b32_e32 v17, 0xffff0000, v134
	v_lshlrev_b32_e32 v24, 16, v166
	v_and_b32_e32 v25, 0xffff0000, v166
	v_lshlrev_b32_e32 v18, 16, v135
	v_and_b32_e32 v19, 0xffff0000, v135
	v_lshlrev_b32_e32 v26, 16, v167
	v_and_b32_e32 v27, 0xffff0000, v167
	v_pk_fma_f32 v[20:21], v[44:45], v[20:21], v[12:13] op_sel_hi:[0,1,1] neg_lo:[1,0,0] neg_hi:[1,0,0]
	v_pk_fma_f32 v[22:23], v[44:45], v[22:23], v[14:15] op_sel_hi:[0,1,1] neg_lo:[1,0,0] neg_hi:[1,0,0]
	v_pk_fma_f32 v[24:25], v[44:45], v[24:25], v[16:17] op_sel_hi:[0,1,1] neg_lo:[1,0,0] neg_hi:[1,0,0]
	v_pk_fma_f32 v[26:27], v[44:45], v[26:27], v[18:19] op_sel_hi:[0,1,1] neg_lo:[1,0,0] neg_hi:[1,0,0]
	v_pk_add_f32 v[4:5], v[4:5], v[20:21]
	v_pk_add_f32 v[6:7], v[6:7], v[22:23]
	v_pk_add_f32 v[8:9], v[8:9], v[24:25]
	v_pk_add_f32 v[10:11], v[10:11], v[26:27]
	v_mov_b32_e32 v46, v3
	v_pk_fma_f32 v[28:29], v[46:47], v[4:5], v[12:13] op_sel_hi:[0,1,1] neg_lo:[0,0,1] neg_hi:[0,0,1]
	v_pk_fma_f32 v[30:31], v[46:47], v[6:7], v[14:15] op_sel_hi:[0,1,1] neg_lo:[0,0,1] neg_hi:[0,0,1]
	v_pk_fma_f32 v[32:33], v[46:47], v[8:9], v[16:17] op_sel_hi:[0,1,1] neg_lo:[0,0,1] neg_hi:[0,0,1]
	v_pk_fma_f32 v[34:35], v[46:47], v[10:11], v[18:19] op_sel_hi:[0,1,1] neg_lo:[0,0,1] neg_hi:[0,0,1]
	v_cvt_pk_bf16_f32 v40, v28, v29
	v_cvt_pk_bf16_f32 v41, v30, v31
	v_cvt_pk_bf16_f32 v42, v32, v33
	v_cvt_pk_bf16_f32 v43, v34, v35
	global_store_dwordx4 v1, v[40:43], s[24:25]
	s_add_u32 s24, s24, 0x2000
	s_addc_u32 s25, s25, 0
	v_lshlrev_b32_e32 v12, 16, v136
	v_and_b32_e32 v13, 0xffff0000, v136
	v_lshlrev_b32_e32 v20, 16, v168
	v_and_b32_e32 v21, 0xffff0000, v168
	v_lshlrev_b32_e32 v14, 16, v137
	v_and_b32_e32 v15, 0xffff0000, v137
	v_lshlrev_b32_e32 v22, 16, v169
	v_and_b32_e32 v23, 0xffff0000, v169
	v_lshlrev_b32_e32 v16, 16, v138
	v_and_b32_e32 v17, 0xffff0000, v138
	v_lshlrev_b32_e32 v24, 16, v170
	v_and_b32_e32 v25, 0xffff0000, v170
	v_lshlrev_b32_e32 v18, 16, v139
	v_and_b32_e32 v19, 0xffff0000, v139
	v_lshlrev_b32_e32 v26, 16, v171
	v_and_b32_e32 v27, 0xffff0000, v171
	v_pk_fma_f32 v[20:21], v[44:45], v[20:21], v[12:13] op_sel_hi:[0,1,1] neg_lo:[1,0,0] neg_hi:[1,0,0]
	v_pk_fma_f32 v[22:23], v[44:45], v[22:23], v[14:15] op_sel_hi:[0,1,1] neg_lo:[1,0,0] neg_hi:[1,0,0]
	v_pk_fma_f32 v[24:25], v[44:45], v[24:25], v[16:17] op_sel_hi:[0,1,1] neg_lo:[1,0,0] neg_hi:[1,0,0]
	v_pk_fma_f32 v[26:27], v[44:45], v[26:27], v[18:19] op_sel_hi:[0,1,1] neg_lo:[1,0,0] neg_hi:[1,0,0]
	v_pk_add_f32 v[4:5], v[4:5], v[20:21]
	v_pk_add_f32 v[6:7], v[6:7], v[22:23]
	v_pk_add_f32 v[8:9], v[8:9], v[24:25]
	v_pk_add_f32 v[10:11], v[10:11], v[26:27]
	v_mov_b32_e32 v46, v3
	v_pk_fma_f32 v[28:29], v[46:47], v[4:5], v[12:13] op_sel_hi:[0,1,1] neg_lo:[0,0,1] neg_hi:[0,0,1]
	v_pk_fma_f32 v[30:31], v[46:47], v[6:7], v[14:15] op_sel_hi:[0,1,1] neg_lo:[0,0,1] neg_hi:[0,0,1]
	v_pk_fma_f32 v[32:33], v[46:47], v[8:9], v[16:17] op_sel_hi:[0,1,1] neg_lo:[0,0,1] neg_hi:[0,0,1]
	v_pk_fma_f32 v[34:35], v[46:47], v[10:11], v[18:19] op_sel_hi:[0,1,1] neg_lo:[0,0,1] neg_hi:[0,0,1]
	v_cvt_pk_bf16_f32 v36, v28, v29
	v_cvt_pk_bf16_f32 v37, v30, v31
	v_cvt_pk_bf16_f32 v38, v32, v33
	v_cvt_pk_bf16_f32 v39, v34, v35
	global_store_dwordx4 v1, v[36:39], s[24:25]
	s_add_u32 s24, s24, 0x2000
	s_addc_u32 s25, s25, 0
	v_lshlrev_b32_e32 v12, 16, v140
	v_and_b32_e32 v13, 0xffff0000, v140
	v_lshlrev_b32_e32 v20, 16, v172
	v_and_b32_e32 v21, 0xffff0000, v172
	v_lshlrev_b32_e32 v14, 16, v141
	v_and_b32_e32 v15, 0xffff0000, v141
	v_lshlrev_b32_e32 v22, 16, v173
	v_and_b32_e32 v23, 0xffff0000, v173
	v_lshlrev_b32_e32 v16, 16, v142
	v_and_b32_e32 v17, 0xffff0000, v142
	v_lshlrev_b32_e32 v24, 16, v174
	v_and_b32_e32 v25, 0xffff0000, v174
	v_lshlrev_b32_e32 v18, 16, v143
	v_and_b32_e32 v19, 0xffff0000, v143
	v_lshlrev_b32_e32 v26, 16, v175
	v_and_b32_e32 v27, 0xffff0000, v175
	v_pk_fma_f32 v[20:21], v[44:45], v[20:21], v[12:13] op_sel_hi:[0,1,1] neg_lo:[1,0,0] neg_hi:[1,0,0]
	v_pk_fma_f32 v[22:23], v[44:45], v[22:23], v[14:15] op_sel_hi:[0,1,1] neg_lo:[1,0,0] neg_hi:[1,0,0]
	v_pk_fma_f32 v[24:25], v[44:45], v[24:25], v[16:17] op_sel_hi:[0,1,1] neg_lo:[1,0,0] neg_hi:[1,0,0]
	v_pk_fma_f32 v[26:27], v[44:45], v[26:27], v[18:19] op_sel_hi:[0,1,1] neg_lo:[1,0,0] neg_hi:[1,0,0]
	v_pk_add_f32 v[4:5], v[4:5], v[20:21]
	v_pk_add_f32 v[6:7], v[6:7], v[22:23]
	v_pk_add_f32 v[8:9], v[8:9], v[24:25]
	v_pk_add_f32 v[10:11], v[10:11], v[26:27]
	v_mov_b32_e32 v46, v3
	v_pk_fma_f32 v[28:29], v[46:47], v[4:5], v[12:13] op_sel_hi:[0,1,1] neg_lo:[0,0,1] neg_hi:[0,0,1]
	v_pk_fma_f32 v[30:31], v[46:47], v[6:7], v[14:15] op_sel_hi:[0,1,1] neg_lo:[0,0,1] neg_hi:[0,0,1]
	v_pk_fma_f32 v[32:33], v[46:47], v[8:9], v[16:17] op_sel_hi:[0,1,1] neg_lo:[0,0,1] neg_hi:[0,0,1]
	v_pk_fma_f32 v[34:35], v[46:47], v[10:11], v[18:19] op_sel_hi:[0,1,1] neg_lo:[0,0,1] neg_hi:[0,0,1]
	v_cvt_pk_bf16_f32 v40, v28, v29
	v_cvt_pk_bf16_f32 v41, v30, v31
	v_cvt_pk_bf16_f32 v42, v32, v33
	v_cvt_pk_bf16_f32 v43, v34, v35
	global_store_dwordx4 v1, v[40:43], s[24:25]
	s_add_u32 s24, s24, 0x2000
	s_addc_u32 s25, s25, 0
	v_lshlrev_b32_e32 v12, 16, v144
	v_and_b32_e32 v13, 0xffff0000, v144
	v_lshlrev_b32_e32 v20, 16, v176
	v_and_b32_e32 v21, 0xffff0000, v176
	v_lshlrev_b32_e32 v14, 16, v145
	v_and_b32_e32 v15, 0xffff0000, v145
	v_lshlrev_b32_e32 v22, 16, v177
	v_and_b32_e32 v23, 0xffff0000, v177
	v_lshlrev_b32_e32 v16, 16, v146
	v_and_b32_e32 v17, 0xffff0000, v146
	v_lshlrev_b32_e32 v24, 16, v178
	v_and_b32_e32 v25, 0xffff0000, v178
	v_lshlrev_b32_e32 v18, 16, v147
	v_and_b32_e32 v19, 0xffff0000, v147
	v_lshlrev_b32_e32 v26, 16, v179
	v_and_b32_e32 v27, 0xffff0000, v179
	v_pk_fma_f32 v[20:21], v[44:45], v[20:21], v[12:13] op_sel_hi:[0,1,1] neg_lo:[1,0,0] neg_hi:[1,0,0]
	v_pk_fma_f32 v[22:23], v[44:45], v[22:23], v[14:15] op_sel_hi:[0,1,1] neg_lo:[1,0,0] neg_hi:[1,0,0]
	v_pk_fma_f32 v[24:25], v[44:45], v[24:25], v[16:17] op_sel_hi:[0,1,1] neg_lo:[1,0,0] neg_hi:[1,0,0]
	v_pk_fma_f32 v[26:27], v[44:45], v[26:27], v[18:19] op_sel_hi:[0,1,1] neg_lo:[1,0,0] neg_hi:[1,0,0]
	v_pk_add_f32 v[4:5], v[4:5], v[20:21]
	v_pk_add_f32 v[6:7], v[6:7], v[22:23]
	v_pk_add_f32 v[8:9], v[8:9], v[24:25]
	v_pk_add_f32 v[10:11], v[10:11], v[26:27]
	v_mov_b32_e32 v46, v3
	v_pk_fma_f32 v[28:29], v[46:47], v[4:5], v[12:13] op_sel_hi:[0,1,1] neg_lo:[0,0,1] neg_hi:[0,0,1]
	v_pk_fma_f32 v[30:31], v[46:47], v[6:7], v[14:15] op_sel_hi:[0,1,1] neg_lo:[0,0,1] neg_hi:[0,0,1]
	v_pk_fma_f32 v[32:33], v[46:47], v[8:9], v[16:17] op_sel_hi:[0,1,1] neg_lo:[0,0,1] neg_hi:[0,0,1]
	v_pk_fma_f32 v[34:35], v[46:47], v[10:11], v[18:19] op_sel_hi:[0,1,1] neg_lo:[0,0,1] neg_hi:[0,0,1]
	v_cvt_pk_bf16_f32 v36, v28, v29
	v_cvt_pk_bf16_f32 v37, v30, v31
	v_cvt_pk_bf16_f32 v38, v32, v33
	v_cvt_pk_bf16_f32 v39, v34, v35
	global_store_dwordx4 v1, v[36:39], s[24:25]
	s_add_u32 s24, s24, 0x2000
	s_addc_u32 s25, s25, 0
	v_lshlrev_b32_e32 v12, 16, v148
	v_and_b32_e32 v13, 0xffff0000, v148
	v_lshlrev_b32_e32 v20, 16, v180
	v_and_b32_e32 v21, 0xffff0000, v180
	v_lshlrev_b32_e32 v14, 16, v149
	v_and_b32_e32 v15, 0xffff0000, v149
	v_lshlrev_b32_e32 v22, 16, v181
	v_and_b32_e32 v23, 0xffff0000, v181
	v_lshlrev_b32_e32 v16, 16, v150
	v_and_b32_e32 v17, 0xffff0000, v150
	v_lshlrev_b32_e32 v24, 16, v182
	v_and_b32_e32 v25, 0xffff0000, v182
	v_lshlrev_b32_e32 v18, 16, v151
	v_and_b32_e32 v19, 0xffff0000, v151
	v_lshlrev_b32_e32 v26, 16, v183
	v_and_b32_e32 v27, 0xffff0000, v183
	v_pk_fma_f32 v[20:21], v[44:45], v[20:21], v[12:13] op_sel_hi:[0,1,1] neg_lo:[1,0,0] neg_hi:[1,0,0]
	v_pk_fma_f32 v[22:23], v[44:45], v[22:23], v[14:15] op_sel_hi:[0,1,1] neg_lo:[1,0,0] neg_hi:[1,0,0]
	v_pk_fma_f32 v[24:25], v[44:45], v[24:25], v[16:17] op_sel_hi:[0,1,1] neg_lo:[1,0,0] neg_hi:[1,0,0]
	v_pk_fma_f32 v[26:27], v[44:45], v[26:27], v[18:19] op_sel_hi:[0,1,1] neg_lo:[1,0,0] neg_hi:[1,0,0]
	v_pk_add_f32 v[4:5], v[4:5], v[20:21]
	v_pk_add_f32 v[6:7], v[6:7], v[22:23]
	v_pk_add_f32 v[8:9], v[8:9], v[24:25]
	v_pk_add_f32 v[10:11], v[10:11], v[26:27]
	v_mov_b32_e32 v46, v3
	v_pk_fma_f32 v[28:29], v[46:47], v[4:5], v[12:13] op_sel_hi:[0,1,1] neg_lo:[0,0,1] neg_hi:[0,0,1]
	v_pk_fma_f32 v[30:31], v[46:47], v[6:7], v[14:15] op_sel_hi:[0,1,1] neg_lo:[0,0,1] neg_hi:[0,0,1]
	v_pk_fma_f32 v[32:33], v[46:47], v[8:9], v[16:17] op_sel_hi:[0,1,1] neg_lo:[0,0,1] neg_hi:[0,0,1]
	v_pk_fma_f32 v[34:35], v[46:47], v[10:11], v[18:19] op_sel_hi:[0,1,1] neg_lo:[0,0,1] neg_hi:[0,0,1]
	v_cvt_pk_bf16_f32 v40, v28, v29
	v_cvt_pk_bf16_f32 v41, v30, v31
	v_cvt_pk_bf16_f32 v42, v32, v33
	v_cvt_pk_bf16_f32 v43, v34, v35
	global_store_dwordx4 v1, v[40:43], s[24:25]
	s_add_u32 s24, s24, 0x2000
	s_addc_u32 s25, s25, 0
	v_lshlrev_b32_e32 v12, 16, v152
	v_and_b32_e32 v13, 0xffff0000, v152
	v_lshlrev_b32_e32 v20, 16, v184
	v_and_b32_e32 v21, 0xffff0000, v184
	v_lshlrev_b32_e32 v14, 16, v153
	v_and_b32_e32 v15, 0xffff0000, v153
	v_lshlrev_b32_e32 v22, 16, v185
	v_and_b32_e32 v23, 0xffff0000, v185
	v_lshlrev_b32_e32 v16, 16, v154
	v_and_b32_e32 v17, 0xffff0000, v154
	v_lshlrev_b32_e32 v24, 16, v186
	v_and_b32_e32 v25, 0xffff0000, v186
	v_lshlrev_b32_e32 v18, 16, v155
	v_and_b32_e32 v19, 0xffff0000, v155
	v_lshlrev_b32_e32 v26, 16, v187
	v_and_b32_e32 v27, 0xffff0000, v187
	v_pk_fma_f32 v[20:21], v[44:45], v[20:21], v[12:13] op_sel_hi:[0,1,1] neg_lo:[1,0,0] neg_hi:[1,0,0]
	v_pk_fma_f32 v[22:23], v[44:45], v[22:23], v[14:15] op_sel_hi:[0,1,1] neg_lo:[1,0,0] neg_hi:[1,0,0]
	v_pk_fma_f32 v[24:25], v[44:45], v[24:25], v[16:17] op_sel_hi:[0,1,1] neg_lo:[1,0,0] neg_hi:[1,0,0]
	v_pk_fma_f32 v[26:27], v[44:45], v[26:27], v[18:19] op_sel_hi:[0,1,1] neg_lo:[1,0,0] neg_hi:[1,0,0]
	v_pk_add_f32 v[4:5], v[4:5], v[20:21]
	v_pk_add_f32 v[6:7], v[6:7], v[22:23]
	v_pk_add_f32 v[8:9], v[8:9], v[24:25]
	v_pk_add_f32 v[10:11], v[10:11], v[26:27]
	v_mov_b32_e32 v46, v3
	v_pk_fma_f32 v[28:29], v[46:47], v[4:5], v[12:13] op_sel_hi:[0,1,1] neg_lo:[0,0,1] neg_hi:[0,0,1]
	v_pk_fma_f32 v[30:31], v[46:47], v[6:7], v[14:15] op_sel_hi:[0,1,1] neg_lo:[0,0,1] neg_hi:[0,0,1]
	v_pk_fma_f32 v[32:33], v[46:47], v[8:9], v[16:17] op_sel_hi:[0,1,1] neg_lo:[0,0,1] neg_hi:[0,0,1]
	v_pk_fma_f32 v[34:35], v[46:47], v[10:11], v[18:19] op_sel_hi:[0,1,1] neg_lo:[0,0,1] neg_hi:[0,0,1]
	v_cvt_pk_bf16_f32 v36, v28, v29
	v_cvt_pk_bf16_f32 v37, v30, v31
	v_cvt_pk_bf16_f32 v38, v32, v33
	v_cvt_pk_bf16_f32 v39, v34, v35
	global_store_dwordx4 v1, v[36:39], s[24:25]
	s_add_u32 s24, s24, 0x2000
	s_addc_u32 s25, s25, 0
	v_lshlrev_b32_e32 v12, 16, v156
	v_and_b32_e32 v13, 0xffff0000, v156
	v_lshlrev_b32_e32 v20, 16, v188
	v_and_b32_e32 v21, 0xffff0000, v188
	v_lshlrev_b32_e32 v14, 16, v157
	v_and_b32_e32 v15, 0xffff0000, v157
	v_lshlrev_b32_e32 v22, 16, v189
	v_and_b32_e32 v23, 0xffff0000, v189
	v_lshlrev_b32_e32 v16, 16, v158
	v_and_b32_e32 v17, 0xffff0000, v158
	v_lshlrev_b32_e32 v24, 16, v190
	v_and_b32_e32 v25, 0xffff0000, v190
	v_lshlrev_b32_e32 v18, 16, v159
	v_and_b32_e32 v19, 0xffff0000, v159
	v_lshlrev_b32_e32 v26, 16, v191
	v_and_b32_e32 v27, 0xffff0000, v191
	v_pk_fma_f32 v[20:21], v[44:45], v[20:21], v[12:13] op_sel_hi:[0,1,1] neg_lo:[1,0,0] neg_hi:[1,0,0]
	v_pk_fma_f32 v[22:23], v[44:45], v[22:23], v[14:15] op_sel_hi:[0,1,1] neg_lo:[1,0,0] neg_hi:[1,0,0]
	v_pk_fma_f32 v[24:25], v[44:45], v[24:25], v[16:17] op_sel_hi:[0,1,1] neg_lo:[1,0,0] neg_hi:[1,0,0]
	v_pk_fma_f32 v[26:27], v[44:45], v[26:27], v[18:19] op_sel_hi:[0,1,1] neg_lo:[1,0,0] neg_hi:[1,0,0]
	v_pk_add_f32 v[4:5], v[4:5], v[20:21]
	v_pk_add_f32 v[6:7], v[6:7], v[22:23]
	v_pk_add_f32 v[8:9], v[8:9], v[24:25]
	v_pk_add_f32 v[10:11], v[10:11], v[26:27]
	v_mov_b32_e32 v46, v3
	v_pk_fma_f32 v[28:29], v[46:47], v[4:5], v[12:13] op_sel_hi:[0,1,1] neg_lo:[0,0,1] neg_hi:[0,0,1]
	v_pk_fma_f32 v[30:31], v[46:47], v[6:7], v[14:15] op_sel_hi:[0,1,1] neg_lo:[0,0,1] neg_hi:[0,0,1]
	v_pk_fma_f32 v[32:33], v[46:47], v[8:9], v[16:17] op_sel_hi:[0,1,1] neg_lo:[0,0,1] neg_hi:[0,0,1]
	v_pk_fma_f32 v[34:35], v[46:47], v[10:11], v[18:19] op_sel_hi:[0,1,1] neg_lo:[0,0,1] neg_hi:[0,0,1]
	v_cvt_pk_bf16_f32 v40, v28, v29
	v_cvt_pk_bf16_f32 v41, v30, v31
	v_cvt_pk_bf16_f32 v42, v32, v33
	v_cvt_pk_bf16_f32 v43, v34, v35
	global_store_dwordx4 v1, v[40:43], s[24:25]
	s_add_u32 s24, s24, 0x2000
	s_addc_u32 s25, s25, 0
	global_load_dwordx4 v[128:131], v1, s[20:21]
	global_load_dwordx4 v[160:163], v49, s[22:23]
	s_add_u32 s20, s20, 0x2000
	s_addc_u32 s21, s21, 0
	s_add_u32 s22, s22, 0x2000
	s_addc_u32 s23, s23, 0
	global_load_dwordx4 v[132:135], v1, s[20:21]
	global_load_dwordx4 v[164:167], v49, s[22:23]
	s_add_u32 s20, s20, 0x2000
	s_addc_u32 s21, s21, 0
	s_add_u32 s22, s22, 0x2000
	s_addc_u32 s23, s23, 0
	global_load_dwordx4 v[136:139], v1, s[20:21]
	global_load_dwordx4 v[168:171], v49, s[22:23]
	s_add_u32 s20, s20, 0x2000
	s_addc_u32 s21, s21, 0
	s_add_u32 s22, s22, 0x2000
	s_addc_u32 s23, s23, 0
	global_load_dwordx4 v[140:143], v1, s[20:21]
	global_load_dwordx4 v[172:175], v49, s[22:23]
	s_add_u32 s20, s20, 0x2000
	s_addc_u32 s21, s21, 0
	s_add_u32 s22, s22, 0x2000
	s_addc_u32 s23, s23, 0
	global_load_dwordx4 v[144:147], v1, s[20:21]
	global_load_dwordx4 v[176:179], v49, s[22:23]
	s_add_u32 s20, s20, 0x2000
	s_addc_u32 s21, s21, 0
	s_add_u32 s22, s22, 0x2000
	s_addc_u32 s23, s23, 0
	global_load_dwordx4 v[148:151], v1, s[20:21]
	global_load_dwordx4 v[180:183], v49, s[22:23]
	s_add_u32 s20, s20, 0x2000
	s_addc_u32 s21, s21, 0
	s_add_u32 s22, s22, 0x2000
	s_addc_u32 s23, s23, 0
	global_load_dwordx4 v[152:155], v1, s[20:21]
	global_load_dwordx4 v[184:187], v49, s[22:23]
	s_add_u32 s20, s20, 0x2000
	s_addc_u32 s21, s21, 0
	s_add_u32 s22, s22, 0x2000
	s_addc_u32 s23, s23, 0
	global_load_dwordx4 v[156:159], v1, s[20:21]
	global_load_dwordx4 v[188:191], v49, s[22:23]
	s_add_u32 s20, s20, 0x2000
	s_addc_u32 s21, s21, 0
	s_add_u32 s22, s22, 0x2000
	s_addc_u32 s23, s23, 0
	s_waitcnt vmcnt(24)
	v_mov_b32_e32 v44, 1.0
	v_lshlrev_b32_e32 v12, 16, v64
	v_and_b32_e32 v13, 0xffff0000, v64
	v_lshlrev_b32_e32 v20, 16, v96
	v_and_b32_e32 v21, 0xffff0000, v96
	v_lshlrev_b32_e32 v14, 16, v65
	v_and_b32_e32 v15, 0xffff0000, v65
	v_lshlrev_b32_e32 v22, 16, v97
	v_and_b32_e32 v23, 0xffff0000, v97
	v_lshlrev_b32_e32 v16, 16, v66
	v_and_b32_e32 v17, 0xffff0000, v66
	v_lshlrev_b32_e32 v24, 16, v98
	v_and_b32_e32 v25, 0xffff0000, v98
	v_lshlrev_b32_e32 v18, 16, v67
	v_and_b32_e32 v19, 0xffff0000, v67
	v_lshlrev_b32_e32 v26, 16, v99
	v_and_b32_e32 v27, 0xffff0000, v99
	v_pk_fma_f32 v[20:21], v[44:45], v[20:21], v[12:13] op_sel_hi:[0,1,1] neg_lo:[1,0,0] neg_hi:[1,0,0]
	v_pk_fma_f32 v[22:23], v[44:45], v[22:23], v[14:15] op_sel_hi:[0,1,1] neg_lo:[1,0,0] neg_hi:[1,0,0]
	v_pk_fma_f32 v[24:25], v[44:45], v[24:25], v[16:17] op_sel_hi:[0,1,1] neg_lo:[1,0,0] neg_hi:[1,0,0]
	v_pk_fma_f32 v[26:27], v[44:45], v[26:27], v[18:19] op_sel_hi:[0,1,1] neg_lo:[1,0,0] neg_hi:[1,0,0]
	v_pk_add_f32 v[4:5], v[4:5], v[20:21]
	v_pk_add_f32 v[6:7], v[6:7], v[22:23]
	v_pk_add_f32 v[8:9], v[8:9], v[24:25]
	v_pk_add_f32 v[10:11], v[10:11], v[26:27]
	v_mov_b32_e32 v46, v3
	v_pk_fma_f32 v[28:29], v[46:47], v[4:5], v[12:13] op_sel_hi:[0,1,1] neg_lo:[0,0,1] neg_hi:[0,0,1]
	v_pk_fma_f32 v[30:31], v[46:47], v[6:7], v[14:15] op_sel_hi:[0,1,1] neg_lo:[0,0,1] neg_hi:[0,0,1]
	v_pk_fma_f32 v[32:33], v[46:47], v[8:9], v[16:17] op_sel_hi:[0,1,1] neg_lo:[0,0,1] neg_hi:[0,0,1]
	v_pk_fma_f32 v[34:35], v[46:47], v[10:11], v[18:19] op_sel_hi:[0,1,1] neg_lo:[0,0,1] neg_hi:[0,0,1]
	v_cvt_pk_bf16_f32 v36, v28, v29
	v_cvt_pk_bf16_f32 v37, v30, v31
	v_cvt_pk_bf16_f32 v38, v32, v33
	v_cvt_pk_bf16_f32 v39, v34, v35
	global_store_dwordx4 v1, v[36:39], s[24:25]
	s_add_u32 s24, s24, 0x2000
	s_addc_u32 s25, s25, 0
	v_lshlrev_b32_e32 v12, 16, v68
	v_and_b32_e32 v13, 0xffff0000, v68
	v_lshlrev_b32_e32 v20, 16, v100
	v_and_b32_e32 v21, 0xffff0000, v100
	v_lshlrev_b32_e32 v14, 16, v69
	v_and_b32_e32 v15, 0xffff0000, v69
	v_lshlrev_b32_e32 v22, 16, v101
	v_and_b32_e32 v23, 0xffff0000, v101
	v_lshlrev_b32_e32 v16, 16, v70
	v_and_b32_e32 v17, 0xffff0000, v70
	v_lshlrev_b32_e32 v24, 16, v102
	v_and_b32_e32 v25, 0xffff0000, v102
	v_lshlrev_b32_e32 v18, 16, v71
	v_and_b32_e32 v19, 0xffff0000, v71
	v_lshlrev_b32_e32 v26, 16, v103
	v_and_b32_e32 v27, 0xffff0000, v103
	v_pk_fma_f32 v[20:21], v[44:45], v[20:21], v[12:13] op_sel_hi:[0,1,1] neg_lo:[1,0,0] neg_hi:[1,0,0]
	v_pk_fma_f32 v[22:23], v[44:45], v[22:23], v[14:15] op_sel_hi:[0,1,1] neg_lo:[1,0,0] neg_hi:[1,0,0]
	v_pk_fma_f32 v[24:25], v[44:45], v[24:25], v[16:17] op_sel_hi:[0,1,1] neg_lo:[1,0,0] neg_hi:[1,0,0]
	v_pk_fma_f32 v[26:27], v[44:45], v[26:27], v[18:19] op_sel_hi:[0,1,1] neg_lo:[1,0,0] neg_hi:[1,0,0]
	v_pk_add_f32 v[4:5], v[4:5], v[20:21]
	v_pk_add_f32 v[6:7], v[6:7], v[22:23]
	v_pk_add_f32 v[8:9], v[8:9], v[24:25]
	v_pk_add_f32 v[10:11], v[10:11], v[26:27]
	v_mov_b32_e32 v46, v3
	v_pk_fma_f32 v[28:29], v[46:47], v[4:5], v[12:13] op_sel_hi:[0,1,1] neg_lo:[0,0,1] neg_hi:[0,0,1]
	v_pk_fma_f32 v[30:31], v[46:47], v[6:7], v[14:15] op_sel_hi:[0,1,1] neg_lo:[0,0,1] neg_hi:[0,0,1]
	v_pk_fma_f32 v[32:33], v[46:47], v[8:9], v[16:17] op_sel_hi:[0,1,1] neg_lo:[0,0,1] neg_hi:[0,0,1]
	v_pk_fma_f32 v[34:35], v[46:47], v[10:11], v[18:19] op_sel_hi:[0,1,1] neg_lo:[0,0,1] neg_hi:[0,0,1]
	v_cvt_pk_bf16_f32 v40, v28, v29
	v_cvt_pk_bf16_f32 v41, v30, v31
	v_cvt_pk_bf16_f32 v42, v32, v33
	v_cvt_pk_bf16_f32 v43, v34, v35
	global_store_dwordx4 v1, v[40:43], s[24:25]
	s_add_u32 s24, s24, 0x2000
	s_addc_u32 s25, s25, 0
	v_lshlrev_b32_e32 v12, 16, v72
	v_and_b32_e32 v13, 0xffff0000, v72
	v_lshlrev_b32_e32 v20, 16, v104
	v_and_b32_e32 v21, 0xffff0000, v104
	v_lshlrev_b32_e32 v14, 16, v73
	v_and_b32_e32 v15, 0xffff0000, v73
	v_lshlrev_b32_e32 v22, 16, v105
	v_and_b32_e32 v23, 0xffff0000, v105
	v_lshlrev_b32_e32 v16, 16, v74
	v_and_b32_e32 v17, 0xffff0000, v74
	v_lshlrev_b32_e32 v24, 16, v106
	v_and_b32_e32 v25, 0xffff0000, v106
	v_lshlrev_b32_e32 v18, 16, v75
	v_and_b32_e32 v19, 0xffff0000, v75
	v_lshlrev_b32_e32 v26, 16, v107
	v_and_b32_e32 v27, 0xffff0000, v107
	v_pk_fma_f32 v[20:21], v[44:45], v[20:21], v[12:13] op_sel_hi:[0,1,1] neg_lo:[1,0,0] neg_hi:[1,0,0]
	v_pk_fma_f32 v[22:23], v[44:45], v[22:23], v[14:15] op_sel_hi:[0,1,1] neg_lo:[1,0,0] neg_hi:[1,0,0]
	v_pk_fma_f32 v[24:25], v[44:45], v[24:25], v[16:17] op_sel_hi:[0,1,1] neg_lo:[1,0,0] neg_hi:[1,0,0]
	v_pk_fma_f32 v[26:27], v[44:45], v[26:27], v[18:19] op_sel_hi:[0,1,1] neg_lo:[1,0,0] neg_hi:[1,0,0]
	v_pk_add_f32 v[4:5], v[4:5], v[20:21]
	v_pk_add_f32 v[6:7], v[6:7], v[22:23]
	v_pk_add_f32 v[8:9], v[8:9], v[24:25]
	v_pk_add_f32 v[10:11], v[10:11], v[26:27]
	v_mov_b32_e32 v46, v3
	v_pk_fma_f32 v[28:29], v[46:47], v[4:5], v[12:13] op_sel_hi:[0,1,1] neg_lo:[0,0,1] neg_hi:[0,0,1]
	v_pk_fma_f32 v[30:31], v[46:47], v[6:7], v[14:15] op_sel_hi:[0,1,1] neg_lo:[0,0,1] neg_hi:[0,0,1]
	v_pk_fma_f32 v[32:33], v[46:47], v[8:9], v[16:17] op_sel_hi:[0,1,1] neg_lo:[0,0,1] neg_hi:[0,0,1]
	v_pk_fma_f32 v[34:35], v[46:47], v[10:11], v[18:19] op_sel_hi:[0,1,1] neg_lo:[0,0,1] neg_hi:[0,0,1]
	v_cvt_pk_bf16_f32 v36, v28, v29
	v_cvt_pk_bf16_f32 v37, v30, v31
	v_cvt_pk_bf16_f32 v38, v32, v33
	v_cvt_pk_bf16_f32 v39, v34, v35
	global_store_dwordx4 v1, v[36:39], s[24:25]
	s_add_u32 s24, s24, 0x2000
	s_addc_u32 s25, s25, 0
	v_lshlrev_b32_e32 v12, 16, v76
	v_and_b32_e32 v13, 0xffff0000, v76
	v_lshlrev_b32_e32 v20, 16, v108
	v_and_b32_e32 v21, 0xffff0000, v108
	v_lshlrev_b32_e32 v14, 16, v77
	v_and_b32_e32 v15, 0xffff0000, v77
	v_lshlrev_b32_e32 v22, 16, v109
	v_and_b32_e32 v23, 0xffff0000, v109
	v_lshlrev_b32_e32 v16, 16, v78
	v_and_b32_e32 v17, 0xffff0000, v78
	v_lshlrev_b32_e32 v24, 16, v110
	v_and_b32_e32 v25, 0xffff0000, v110
	v_lshlrev_b32_e32 v18, 16, v79
	v_and_b32_e32 v19, 0xffff0000, v79
	v_lshlrev_b32_e32 v26, 16, v111
	v_and_b32_e32 v27, 0xffff0000, v111
	v_pk_fma_f32 v[20:21], v[44:45], v[20:21], v[12:13] op_sel_hi:[0,1,1] neg_lo:[1,0,0] neg_hi:[1,0,0]
	v_pk_fma_f32 v[22:23], v[44:45], v[22:23], v[14:15] op_sel_hi:[0,1,1] neg_lo:[1,0,0] neg_hi:[1,0,0]
	v_pk_fma_f32 v[24:25], v[44:45], v[24:25], v[16:17] op_sel_hi:[0,1,1] neg_lo:[1,0,0] neg_hi:[1,0,0]
	v_pk_fma_f32 v[26:27], v[44:45], v[26:27], v[18:19] op_sel_hi:[0,1,1] neg_lo:[1,0,0] neg_hi:[1,0,0]
	v_pk_add_f32 v[4:5], v[4:5], v[20:21]
	v_pk_add_f32 v[6:7], v[6:7], v[22:23]
	v_pk_add_f32 v[8:9], v[8:9], v[24:25]
	v_pk_add_f32 v[10:11], v[10:11], v[26:27]
	v_mov_b32_e32 v46, v3
	v_pk_fma_f32 v[28:29], v[46:47], v[4:5], v[12:13] op_sel_hi:[0,1,1] neg_lo:[0,0,1] neg_hi:[0,0,1]
	v_pk_fma_f32 v[30:31], v[46:47], v[6:7], v[14:15] op_sel_hi:[0,1,1] neg_lo:[0,0,1] neg_hi:[0,0,1]
	v_pk_fma_f32 v[32:33], v[46:47], v[8:9], v[16:17] op_sel_hi:[0,1,1] neg_lo:[0,0,1] neg_hi:[0,0,1]
	v_pk_fma_f32 v[34:35], v[46:47], v[10:11], v[18:19] op_sel_hi:[0,1,1] neg_lo:[0,0,1] neg_hi:[0,0,1]
	v_cvt_pk_bf16_f32 v40, v28, v29
	v_cvt_pk_bf16_f32 v41, v30, v31
	v_cvt_pk_bf16_f32 v42, v32, v33
	v_cvt_pk_bf16_f32 v43, v34, v35
	global_store_dwordx4 v1, v[40:43], s[24:25]
	s_add_u32 s24, s24, 0x2000
	s_addc_u32 s25, s25, 0
	v_lshlrev_b32_e32 v12, 16, v80
	v_and_b32_e32 v13, 0xffff0000, v80
	v_lshlrev_b32_e32 v20, 16, v112
	v_and_b32_e32 v21, 0xffff0000, v112
	v_lshlrev_b32_e32 v14, 16, v81
	v_and_b32_e32 v15, 0xffff0000, v81
	v_lshlrev_b32_e32 v22, 16, v113
	v_and_b32_e32 v23, 0xffff0000, v113
	v_lshlrev_b32_e32 v16, 16, v82
	v_and_b32_e32 v17, 0xffff0000, v82
	v_lshlrev_b32_e32 v24, 16, v114
	v_and_b32_e32 v25, 0xffff0000, v114
	v_lshlrev_b32_e32 v18, 16, v83
	v_and_b32_e32 v19, 0xffff0000, v83
	v_lshlrev_b32_e32 v26, 16, v115
	v_and_b32_e32 v27, 0xffff0000, v115
	v_pk_fma_f32 v[20:21], v[44:45], v[20:21], v[12:13] op_sel_hi:[0,1,1] neg_lo:[1,0,0] neg_hi:[1,0,0]
	v_pk_fma_f32 v[22:23], v[44:45], v[22:23], v[14:15] op_sel_hi:[0,1,1] neg_lo:[1,0,0] neg_hi:[1,0,0]
	v_pk_fma_f32 v[24:25], v[44:45], v[24:25], v[16:17] op_sel_hi:[0,1,1] neg_lo:[1,0,0] neg_hi:[1,0,0]
	v_pk_fma_f32 v[26:27], v[44:45], v[26:27], v[18:19] op_sel_hi:[0,1,1] neg_lo:[1,0,0] neg_hi:[1,0,0]
	v_pk_add_f32 v[4:5], v[4:5], v[20:21]
	v_pk_add_f32 v[6:7], v[6:7], v[22:23]
	v_pk_add_f32 v[8:9], v[8:9], v[24:25]
	v_pk_add_f32 v[10:11], v[10:11], v[26:27]
	v_mov_b32_e32 v46, v3
	v_pk_fma_f32 v[28:29], v[46:47], v[4:5], v[12:13] op_sel_hi:[0,1,1] neg_lo:[0,0,1] neg_hi:[0,0,1]
	v_pk_fma_f32 v[30:31], v[46:47], v[6:7], v[14:15] op_sel_hi:[0,1,1] neg_lo:[0,0,1] neg_hi:[0,0,1]
	v_pk_fma_f32 v[32:33], v[46:47], v[8:9], v[16:17] op_sel_hi:[0,1,1] neg_lo:[0,0,1] neg_hi:[0,0,1]
	v_pk_fma_f32 v[34:35], v[46:47], v[10:11], v[18:19] op_sel_hi:[0,1,1] neg_lo:[0,0,1] neg_hi:[0,0,1]
	v_cvt_pk_bf16_f32 v36, v28, v29
	v_cvt_pk_bf16_f32 v37, v30, v31
	v_cvt_pk_bf16_f32 v38, v32, v33
	v_cvt_pk_bf16_f32 v39, v34, v35
	global_store_dwordx4 v1, v[36:39], s[24:25]
	s_add_u32 s24, s24, 0x2000
	s_addc_u32 s25, s25, 0
	v_lshlrev_b32_e32 v12, 16, v84
	v_and_b32_e32 v13, 0xffff0000, v84
	v_lshlrev_b32_e32 v20, 16, v116
	v_and_b32_e32 v21, 0xffff0000, v116
	v_lshlrev_b32_e32 v14, 16, v85
	v_and_b32_e32 v15, 0xffff0000, v85
	v_lshlrev_b32_e32 v22, 16, v117
	v_and_b32_e32 v23, 0xffff0000, v117
	v_lshlrev_b32_e32 v16, 16, v86
	v_and_b32_e32 v17, 0xffff0000, v86
	v_lshlrev_b32_e32 v24, 16, v118
	v_and_b32_e32 v25, 0xffff0000, v118
	v_lshlrev_b32_e32 v18, 16, v87
	v_and_b32_e32 v19, 0xffff0000, v87
	v_lshlrev_b32_e32 v26, 16, v119
	v_and_b32_e32 v27, 0xffff0000, v119
	v_pk_fma_f32 v[20:21], v[44:45], v[20:21], v[12:13] op_sel_hi:[0,1,1] neg_lo:[1,0,0] neg_hi:[1,0,0]
	v_pk_fma_f32 v[22:23], v[44:45], v[22:23], v[14:15] op_sel_hi:[0,1,1] neg_lo:[1,0,0] neg_hi:[1,0,0]
	v_pk_fma_f32 v[24:25], v[44:45], v[24:25], v[16:17] op_sel_hi:[0,1,1] neg_lo:[1,0,0] neg_hi:[1,0,0]
	v_pk_fma_f32 v[26:27], v[44:45], v[26:27], v[18:19] op_sel_hi:[0,1,1] neg_lo:[1,0,0] neg_hi:[1,0,0]
	v_pk_add_f32 v[4:5], v[4:5], v[20:21]
	v_pk_add_f32 v[6:7], v[6:7], v[22:23]
	v_pk_add_f32 v[8:9], v[8:9], v[24:25]
	v_pk_add_f32 v[10:11], v[10:11], v[26:27]
	v_mov_b32_e32 v46, v3
	v_pk_fma_f32 v[28:29], v[46:47], v[4:5], v[12:13] op_sel_hi:[0,1,1] neg_lo:[0,0,1] neg_hi:[0,0,1]
	v_pk_fma_f32 v[30:31], v[46:47], v[6:7], v[14:15] op_sel_hi:[0,1,1] neg_lo:[0,0,1] neg_hi:[0,0,1]
	v_pk_fma_f32 v[32:33], v[46:47], v[8:9], v[16:17] op_sel_hi:[0,1,1] neg_lo:[0,0,1] neg_hi:[0,0,1]
	v_pk_fma_f32 v[34:35], v[46:47], v[10:11], v[18:19] op_sel_hi:[0,1,1] neg_lo:[0,0,1] neg_hi:[0,0,1]
	v_cvt_pk_bf16_f32 v40, v28, v29
	v_cvt_pk_bf16_f32 v41, v30, v31
	v_cvt_pk_bf16_f32 v42, v32, v33
	v_cvt_pk_bf16_f32 v43, v34, v35
	global_store_dwordx4 v1, v[40:43], s[24:25]
	s_add_u32 s24, s24, 0x2000
	s_addc_u32 s25, s25, 0
	v_lshlrev_b32_e32 v12, 16, v88
	v_and_b32_e32 v13, 0xffff0000, v88
	v_lshlrev_b32_e32 v20, 16, v120
	v_and_b32_e32 v21, 0xffff0000, v120
	v_lshlrev_b32_e32 v14, 16, v89
	v_and_b32_e32 v15, 0xffff0000, v89
	v_lshlrev_b32_e32 v22, 16, v121
	v_and_b32_e32 v23, 0xffff0000, v121
	v_lshlrev_b32_e32 v16, 16, v90
	v_and_b32_e32 v17, 0xffff0000, v90
	v_lshlrev_b32_e32 v24, 16, v122
	v_and_b32_e32 v25, 0xffff0000, v122
	v_lshlrev_b32_e32 v18, 16, v91
	v_and_b32_e32 v19, 0xffff0000, v91
	v_lshlrev_b32_e32 v26, 16, v123
	v_and_b32_e32 v27, 0xffff0000, v123
	v_pk_fma_f32 v[20:21], v[44:45], v[20:21], v[12:13] op_sel_hi:[0,1,1] neg_lo:[1,0,0] neg_hi:[1,0,0]
	v_pk_fma_f32 v[22:23], v[44:45], v[22:23], v[14:15] op_sel_hi:[0,1,1] neg_lo:[1,0,0] neg_hi:[1,0,0]
	v_pk_fma_f32 v[24:25], v[44:45], v[24:25], v[16:17] op_sel_hi:[0,1,1] neg_lo:[1,0,0] neg_hi:[1,0,0]
	v_pk_fma_f32 v[26:27], v[44:45], v[26:27], v[18:19] op_sel_hi:[0,1,1] neg_lo:[1,0,0] neg_hi:[1,0,0]
	v_pk_add_f32 v[4:5], v[4:5], v[20:21]
	v_pk_add_f32 v[6:7], v[6:7], v[22:23]
	v_pk_add_f32 v[8:9], v[8:9], v[24:25]
	v_pk_add_f32 v[10:11], v[10:11], v[26:27]
	v_mov_b32_e32 v46, v3
	v_pk_fma_f32 v[28:29], v[46:47], v[4:5], v[12:13] op_sel_hi:[0,1,1] neg_lo:[0,0,1] neg_hi:[0,0,1]
	v_pk_fma_f32 v[30:31], v[46:47], v[6:7], v[14:15] op_sel_hi:[0,1,1] neg_lo:[0,0,1] neg_hi:[0,0,1]
	v_pk_fma_f32 v[32:33], v[46:47], v[8:9], v[16:17] op_sel_hi:[0,1,1] neg_lo:[0,0,1] neg_hi:[0,0,1]
	v_pk_fma_f32 v[34:35], v[46:47], v[10:11], v[18:19] op_sel_hi:[0,1,1] neg_lo:[0,0,1] neg_hi:[0,0,1]
	v_cvt_pk_bf16_f32 v36, v28, v29
	v_cvt_pk_bf16_f32 v37, v30, v31
	v_cvt_pk_bf16_f32 v38, v32, v33
	v_cvt_pk_bf16_f32 v39, v34, v35
	global_store_dwordx4 v1, v[36:39], s[24:25]
	s_add_u32 s24, s24, 0x2000
	s_addc_u32 s25, s25, 0
	v_lshlrev_b32_e32 v12, 16, v92
	v_and_b32_e32 v13, 0xffff0000, v92
	v_lshlrev_b32_e32 v20, 16, v124
	v_and_b32_e32 v21, 0xffff0000, v124
	v_lshlrev_b32_e32 v14, 16, v93
	v_and_b32_e32 v15, 0xffff0000, v93
	v_lshlrev_b32_e32 v22, 16, v125
	v_and_b32_e32 v23, 0xffff0000, v125
	v_lshlrev_b32_e32 v16, 16, v94
	v_and_b32_e32 v17, 0xffff0000, v94
	v_lshlrev_b32_e32 v24, 16, v126
	v_and_b32_e32 v25, 0xffff0000, v126
	v_lshlrev_b32_e32 v18, 16, v95
	v_and_b32_e32 v19, 0xffff0000, v95
	v_lshlrev_b32_e32 v26, 16, v127
	v_and_b32_e32 v27, 0xffff0000, v127
	v_pk_fma_f32 v[20:21], v[44:45], v[20:21], v[12:13] op_sel_hi:[0,1,1] neg_lo:[1,0,0] neg_hi:[1,0,0]
	v_pk_fma_f32 v[22:23], v[44:45], v[22:23], v[14:15] op_sel_hi:[0,1,1] neg_lo:[1,0,0] neg_hi:[1,0,0]
	v_pk_fma_f32 v[24:25], v[44:45], v[24:25], v[16:17] op_sel_hi:[0,1,1] neg_lo:[1,0,0] neg_hi:[1,0,0]
	v_pk_fma_f32 v[26:27], v[44:45], v[26:27], v[18:19] op_sel_hi:[0,1,1] neg_lo:[1,0,0] neg_hi:[1,0,0]
	v_pk_add_f32 v[4:5], v[4:5], v[20:21]
	v_pk_add_f32 v[6:7], v[6:7], v[22:23]
	v_pk_add_f32 v[8:9], v[8:9], v[24:25]
	v_pk_add_f32 v[10:11], v[10:11], v[26:27]
	v_mov_b32_e32 v46, v3
	v_pk_fma_f32 v[28:29], v[46:47], v[4:5], v[12:13] op_sel_hi:[0,1,1] neg_lo:[0,0,1] neg_hi:[0,0,1]
	v_pk_fma_f32 v[30:31], v[46:47], v[6:7], v[14:15] op_sel_hi:[0,1,1] neg_lo:[0,0,1] neg_hi:[0,0,1]
	v_pk_fma_f32 v[32:33], v[46:47], v[8:9], v[16:17] op_sel_hi:[0,1,1] neg_lo:[0,0,1] neg_hi:[0,0,1]
	v_pk_fma_f32 v[34:35], v[46:47], v[10:11], v[18:19] op_sel_hi:[0,1,1] neg_lo:[0,0,1] neg_hi:[0,0,1]
	v_cvt_pk_bf16_f32 v40, v28, v29
	v_cvt_pk_bf16_f32 v41, v30, v31
	v_cvt_pk_bf16_f32 v42, v32, v33
	v_cvt_pk_bf16_f32 v43, v34, v35
	global_store_dwordx4 v1, v[40:43], s[24:25]
	s_add_u32 s24, s24, 0x2000
	s_addc_u32 s25, s25, 0
	s_waitcnt vmcnt(8)
	v_mov_b32_e32 v44, 1.0
	v_lshlrev_b32_e32 v12, 16, v128
	v_and_b32_e32 v13, 0xffff0000, v128
	v_lshlrev_b32_e32 v20, 16, v160
	v_and_b32_e32 v21, 0xffff0000, v160
	v_lshlrev_b32_e32 v14, 16, v129
	v_and_b32_e32 v15, 0xffff0000, v129
	v_lshlrev_b32_e32 v22, 16, v161
	v_and_b32_e32 v23, 0xffff0000, v161
	v_lshlrev_b32_e32 v16, 16, v130
	v_and_b32_e32 v17, 0xffff0000, v130
	v_lshlrev_b32_e32 v24, 16, v162
	v_and_b32_e32 v25, 0xffff0000, v162
	v_lshlrev_b32_e32 v18, 16, v131
	v_and_b32_e32 v19, 0xffff0000, v131
	v_lshlrev_b32_e32 v26, 16, v163
	v_and_b32_e32 v27, 0xffff0000, v163
	v_pk_fma_f32 v[20:21], v[44:45], v[20:21], v[12:13] op_sel_hi:[0,1,1] neg_lo:[1,0,0] neg_hi:[1,0,0]
	v_pk_fma_f32 v[22:23], v[44:45], v[22:23], v[14:15] op_sel_hi:[0,1,1] neg_lo:[1,0,0] neg_hi:[1,0,0]
	v_pk_fma_f32 v[24:25], v[44:45], v[24:25], v[16:17] op_sel_hi:[0,1,1] neg_lo:[1,0,0] neg_hi:[1,0,0]
	v_pk_fma_f32 v[26:27], v[44:45], v[26:27], v[18:19] op_sel_hi:[0,1,1] neg_lo:[1,0,0] neg_hi:[1,0,0]
	v_pk_add_f32 v[4:5], v[4:5], v[20:21]
	v_pk_add_f32 v[6:7], v[6:7], v[22:23]
	v_pk_add_f32 v[8:9], v[8:9], v[24:25]
	v_pk_add_f32 v[10:11], v[10:11], v[26:27]
	v_mov_b32_e32 v46, v3
	v_pk_fma_f32 v[28:29], v[46:47], v[4:5], v[12:13] op_sel_hi:[0,1,1] neg_lo:[0,0,1] neg_hi:[0,0,1]
	v_pk_fma_f32 v[30:31], v[46:47], v[6:7], v[14:15] op_sel_hi:[0,1,1] neg_lo:[0,0,1] neg_hi:[0,0,1]
	v_pk_fma_f32 v[32:33], v[46:47], v[8:9], v[16:17] op_sel_hi:[0,1,1] neg_lo:[0,0,1] neg_hi:[0,0,1]
	v_pk_fma_f32 v[34:35], v[46:47], v[10:11], v[18:19] op_sel_hi:[0,1,1] neg_lo:[0,0,1] neg_hi:[0,0,1]
	v_cvt_pk_bf16_f32 v36, v28, v29
	v_cvt_pk_bf16_f32 v37, v30, v31
	v_cvt_pk_bf16_f32 v38, v32, v33
	v_cvt_pk_bf16_f32 v39, v34, v35
	global_store_dwordx4 v1, v[36:39], s[24:25]
	s_add_u32 s24, s24, 0x2000
	s_addc_u32 s25, s25, 0
	v_lshlrev_b32_e32 v12, 16, v132
	v_and_b32_e32 v13, 0xffff0000, v132
	v_lshlrev_b32_e32 v20, 16, v164
	v_and_b32_e32 v21, 0xffff0000, v164
	v_lshlrev_b32_e32 v14, 16, v133
	v_and_b32_e32 v15, 0xffff0000, v133
	v_lshlrev_b32_e32 v22, 16, v165
	v_and_b32_e32 v23, 0xffff0000, v165
	v_lshlrev_b32_e32 v16, 16, v134
	v_and_b32_e32 v17, 0xffff0000, v134
	v_lshlrev_b32_e32 v24, 16, v166
	v_and_b32_e32 v25, 0xffff0000, v166
	v_lshlrev_b32_e32 v18, 16, v135
	v_and_b32_e32 v19, 0xffff0000, v135
	v_lshlrev_b32_e32 v26, 16, v167
	v_and_b32_e32 v27, 0xffff0000, v167
	v_pk_fma_f32 v[20:21], v[44:45], v[20:21], v[12:13] op_sel_hi:[0,1,1] neg_lo:[1,0,0] neg_hi:[1,0,0]
	v_pk_fma_f32 v[22:23], v[44:45], v[22:23], v[14:15] op_sel_hi:[0,1,1] neg_lo:[1,0,0] neg_hi:[1,0,0]
	v_pk_fma_f32 v[24:25], v[44:45], v[24:25], v[16:17] op_sel_hi:[0,1,1] neg_lo:[1,0,0] neg_hi:[1,0,0]
	v_pk_fma_f32 v[26:27], v[44:45], v[26:27], v[18:19] op_sel_hi:[0,1,1] neg_lo:[1,0,0] neg_hi:[1,0,0]
	v_pk_add_f32 v[4:5], v[4:5], v[20:21]
	v_pk_add_f32 v[6:7], v[6:7], v[22:23]
	v_pk_add_f32 v[8:9], v[8:9], v[24:25]
	v_pk_add_f32 v[10:11], v[10:11], v[26:27]
	v_mov_b32_e32 v46, v3
	v_pk_fma_f32 v[28:29], v[46:47], v[4:5], v[12:13] op_sel_hi:[0,1,1] neg_lo:[0,0,1] neg_hi:[0,0,1]
	v_pk_fma_f32 v[30:31], v[46:47], v[6:7], v[14:15] op_sel_hi:[0,1,1] neg_lo:[0,0,1] neg_hi:[0,0,1]
	v_pk_fma_f32 v[32:33], v[46:47], v[8:9], v[16:17] op_sel_hi:[0,1,1] neg_lo:[0,0,1] neg_hi:[0,0,1]
	v_pk_fma_f32 v[34:35], v[46:47], v[10:11], v[18:19] op_sel_hi:[0,1,1] neg_lo:[0,0,1] neg_hi:[0,0,1]
	v_cvt_pk_bf16_f32 v40, v28, v29
	v_cvt_pk_bf16_f32 v41, v30, v31
	v_cvt_pk_bf16_f32 v42, v32, v33
	v_cvt_pk_bf16_f32 v43, v34, v35
	global_store_dwordx4 v1, v[40:43], s[24:25]
	s_add_u32 s24, s24, 0x2000
	s_addc_u32 s25, s25, 0
	v_lshlrev_b32_e32 v12, 16, v136
	v_and_b32_e32 v13, 0xffff0000, v136
	v_lshlrev_b32_e32 v20, 16, v168
	v_and_b32_e32 v21, 0xffff0000, v168
	v_lshlrev_b32_e32 v14, 16, v137
	v_and_b32_e32 v15, 0xffff0000, v137
	v_lshlrev_b32_e32 v22, 16, v169
	v_and_b32_e32 v23, 0xffff0000, v169
	v_lshlrev_b32_e32 v16, 16, v138
	v_and_b32_e32 v17, 0xffff0000, v138
	v_lshlrev_b32_e32 v24, 16, v170
	v_and_b32_e32 v25, 0xffff0000, v170
	v_lshlrev_b32_e32 v18, 16, v139
	v_and_b32_e32 v19, 0xffff0000, v139
	v_lshlrev_b32_e32 v26, 16, v171
	v_and_b32_e32 v27, 0xffff0000, v171
	v_pk_fma_f32 v[20:21], v[44:45], v[20:21], v[12:13] op_sel_hi:[0,1,1] neg_lo:[1,0,0] neg_hi:[1,0,0]
	v_pk_fma_f32 v[22:23], v[44:45], v[22:23], v[14:15] op_sel_hi:[0,1,1] neg_lo:[1,0,0] neg_hi:[1,0,0]
	v_pk_fma_f32 v[24:25], v[44:45], v[24:25], v[16:17] op_sel_hi:[0,1,1] neg_lo:[1,0,0] neg_hi:[1,0,0]
	v_pk_fma_f32 v[26:27], v[44:45], v[26:27], v[18:19] op_sel_hi:[0,1,1] neg_lo:[1,0,0] neg_hi:[1,0,0]
	v_pk_add_f32 v[4:5], v[4:5], v[20:21]
	v_pk_add_f32 v[6:7], v[6:7], v[22:23]
	v_pk_add_f32 v[8:9], v[8:9], v[24:25]
	v_pk_add_f32 v[10:11], v[10:11], v[26:27]
	v_mov_b32_e32 v46, v3
	v_pk_fma_f32 v[28:29], v[46:47], v[4:5], v[12:13] op_sel_hi:[0,1,1] neg_lo:[0,0,1] neg_hi:[0,0,1]
	v_pk_fma_f32 v[30:31], v[46:47], v[6:7], v[14:15] op_sel_hi:[0,1,1] neg_lo:[0,0,1] neg_hi:[0,0,1]
	v_pk_fma_f32 v[32:33], v[46:47], v[8:9], v[16:17] op_sel_hi:[0,1,1] neg_lo:[0,0,1] neg_hi:[0,0,1]
	v_pk_fma_f32 v[34:35], v[46:47], v[10:11], v[18:19] op_sel_hi:[0,1,1] neg_lo:[0,0,1] neg_hi:[0,0,1]
	v_cvt_pk_bf16_f32 v36, v28, v29
	v_cvt_pk_bf16_f32 v37, v30, v31
	v_cvt_pk_bf16_f32 v38, v32, v33
	v_cvt_pk_bf16_f32 v39, v34, v35
	global_store_dwordx4 v1, v[36:39], s[24:25]
	s_add_u32 s24, s24, 0x2000
	s_addc_u32 s25, s25, 0
	v_lshlrev_b32_e32 v12, 16, v140
	v_and_b32_e32 v13, 0xffff0000, v140
	v_lshlrev_b32_e32 v20, 16, v172
	v_and_b32_e32 v21, 0xffff0000, v172
	v_lshlrev_b32_e32 v14, 16, v141
	v_and_b32_e32 v15, 0xffff0000, v141
	v_lshlrev_b32_e32 v22, 16, v173
	v_and_b32_e32 v23, 0xffff0000, v173
	v_lshlrev_b32_e32 v16, 16, v142
	v_and_b32_e32 v17, 0xffff0000, v142
	v_lshlrev_b32_e32 v24, 16, v174
	v_and_b32_e32 v25, 0xffff0000, v174
	v_lshlrev_b32_e32 v18, 16, v143
	v_and_b32_e32 v19, 0xffff0000, v143
	v_lshlrev_b32_e32 v26, 16, v175
	v_and_b32_e32 v27, 0xffff0000, v175
	v_pk_fma_f32 v[20:21], v[44:45], v[20:21], v[12:13] op_sel_hi:[0,1,1] neg_lo:[1,0,0] neg_hi:[1,0,0]
	v_pk_fma_f32 v[22:23], v[44:45], v[22:23], v[14:15] op_sel_hi:[0,1,1] neg_lo:[1,0,0] neg_hi:[1,0,0]
	v_pk_fma_f32 v[24:25], v[44:45], v[24:25], v[16:17] op_sel_hi:[0,1,1] neg_lo:[1,0,0] neg_hi:[1,0,0]
	v_pk_fma_f32 v[26:27], v[44:45], v[26:27], v[18:19] op_sel_hi:[0,1,1] neg_lo:[1,0,0] neg_hi:[1,0,0]
	v_pk_add_f32 v[4:5], v[4:5], v[20:21]
	v_pk_add_f32 v[6:7], v[6:7], v[22:23]
	v_pk_add_f32 v[8:9], v[8:9], v[24:25]
	v_pk_add_f32 v[10:11], v[10:11], v[26:27]
	v_mov_b32_e32 v46, v3
	v_pk_fma_f32 v[28:29], v[46:47], v[4:5], v[12:13] op_sel_hi:[0,1,1] neg_lo:[0,0,1] neg_hi:[0,0,1]
	v_pk_fma_f32 v[30:31], v[46:47], v[6:7], v[14:15] op_sel_hi:[0,1,1] neg_lo:[0,0,1] neg_hi:[0,0,1]
	v_pk_fma_f32 v[32:33], v[46:47], v[8:9], v[16:17] op_sel_hi:[0,1,1] neg_lo:[0,0,1] neg_hi:[0,0,1]
	v_pk_fma_f32 v[34:35], v[46:47], v[10:11], v[18:19] op_sel_hi:[0,1,1] neg_lo:[0,0,1] neg_hi:[0,0,1]
	v_cvt_pk_bf16_f32 v40, v28, v29
	v_cvt_pk_bf16_f32 v41, v30, v31
	v_cvt_pk_bf16_f32 v42, v32, v33
	v_cvt_pk_bf16_f32 v43, v34, v35
	global_store_dwordx4 v1, v[40:43], s[24:25]
	s_add_u32 s24, s24, 0x2000
	s_addc_u32 s25, s25, 0
	v_lshlrev_b32_e32 v12, 16, v144
	v_and_b32_e32 v13, 0xffff0000, v144
	v_lshlrev_b32_e32 v20, 16, v176
	v_and_b32_e32 v21, 0xffff0000, v176
	v_lshlrev_b32_e32 v14, 16, v145
	v_and_b32_e32 v15, 0xffff0000, v145
	v_lshlrev_b32_e32 v22, 16, v177
	v_and_b32_e32 v23, 0xffff0000, v177
	v_lshlrev_b32_e32 v16, 16, v146
	v_and_b32_e32 v17, 0xffff0000, v146
	v_lshlrev_b32_e32 v24, 16, v178
	v_and_b32_e32 v25, 0xffff0000, v178
	v_lshlrev_b32_e32 v18, 16, v147
	v_and_b32_e32 v19, 0xffff0000, v147
	v_lshlrev_b32_e32 v26, 16, v179
	v_and_b32_e32 v27, 0xffff0000, v179
	v_pk_fma_f32 v[20:21], v[44:45], v[20:21], v[12:13] op_sel_hi:[0,1,1] neg_lo:[1,0,0] neg_hi:[1,0,0]
	v_pk_fma_f32 v[22:23], v[44:45], v[22:23], v[14:15] op_sel_hi:[0,1,1] neg_lo:[1,0,0] neg_hi:[1,0,0]
	v_pk_fma_f32 v[24:25], v[44:45], v[24:25], v[16:17] op_sel_hi:[0,1,1] neg_lo:[1,0,0] neg_hi:[1,0,0]
	v_pk_fma_f32 v[26:27], v[44:45], v[26:27], v[18:19] op_sel_hi:[0,1,1] neg_lo:[1,0,0] neg_hi:[1,0,0]
	v_pk_add_f32 v[4:5], v[4:5], v[20:21]
	v_pk_add_f32 v[6:7], v[6:7], v[22:23]
	v_pk_add_f32 v[8:9], v[8:9], v[24:25]
	v_pk_add_f32 v[10:11], v[10:11], v[26:27]
	v_mov_b32_e32 v46, v3
	v_pk_fma_f32 v[28:29], v[46:47], v[4:5], v[12:13] op_sel_hi:[0,1,1] neg_lo:[0,0,1] neg_hi:[0,0,1]
	v_pk_fma_f32 v[30:31], v[46:47], v[6:7], v[14:15] op_sel_hi:[0,1,1] neg_lo:[0,0,1] neg_hi:[0,0,1]
	v_pk_fma_f32 v[32:33], v[46:47], v[8:9], v[16:17] op_sel_hi:[0,1,1] neg_lo:[0,0,1] neg_hi:[0,0,1]
	v_pk_fma_f32 v[34:35], v[46:47], v[10:11], v[18:19] op_sel_hi:[0,1,1] neg_lo:[0,0,1] neg_hi:[0,0,1]
	v_cvt_pk_bf16_f32 v36, v28, v29
	v_cvt_pk_bf16_f32 v37, v30, v31
	v_cvt_pk_bf16_f32 v38, v32, v33
	v_cvt_pk_bf16_f32 v39, v34, v35
	global_store_dwordx4 v1, v[36:39], s[24:25]
	s_add_u32 s24, s24, 0x2000
	s_addc_u32 s25, s25, 0
	v_lshlrev_b32_e32 v12, 16, v148
	v_and_b32_e32 v13, 0xffff0000, v148
	v_lshlrev_b32_e32 v20, 16, v180
	v_and_b32_e32 v21, 0xffff0000, v180
	v_lshlrev_b32_e32 v14, 16, v149
	v_and_b32_e32 v15, 0xffff0000, v149
	v_lshlrev_b32_e32 v22, 16, v181
	v_and_b32_e32 v23, 0xffff0000, v181
	v_lshlrev_b32_e32 v16, 16, v150
	v_and_b32_e32 v17, 0xffff0000, v150
	v_lshlrev_b32_e32 v24, 16, v182
	v_and_b32_e32 v25, 0xffff0000, v182
	v_lshlrev_b32_e32 v18, 16, v151
	v_and_b32_e32 v19, 0xffff0000, v151
	v_lshlrev_b32_e32 v26, 16, v183
	v_and_b32_e32 v27, 0xffff0000, v183
	v_pk_fma_f32 v[20:21], v[44:45], v[20:21], v[12:13] op_sel_hi:[0,1,1] neg_lo:[1,0,0] neg_hi:[1,0,0]
	v_pk_fma_f32 v[22:23], v[44:45], v[22:23], v[14:15] op_sel_hi:[0,1,1] neg_lo:[1,0,0] neg_hi:[1,0,0]
	v_pk_fma_f32 v[24:25], v[44:45], v[24:25], v[16:17] op_sel_hi:[0,1,1] neg_lo:[1,0,0] neg_hi:[1,0,0]
	v_pk_fma_f32 v[26:27], v[44:45], v[26:27], v[18:19] op_sel_hi:[0,1,1] neg_lo:[1,0,0] neg_hi:[1,0,0]
	v_pk_add_f32 v[4:5], v[4:5], v[20:21]
	v_pk_add_f32 v[6:7], v[6:7], v[22:23]
	v_pk_add_f32 v[8:9], v[8:9], v[24:25]
	v_pk_add_f32 v[10:11], v[10:11], v[26:27]
	v_mov_b32_e32 v46, v3
	v_pk_fma_f32 v[28:29], v[46:47], v[4:5], v[12:13] op_sel_hi:[0,1,1] neg_lo:[0,0,1] neg_hi:[0,0,1]
	v_pk_fma_f32 v[30:31], v[46:47], v[6:7], v[14:15] op_sel_hi:[0,1,1] neg_lo:[0,0,1] neg_hi:[0,0,1]
	v_pk_fma_f32 v[32:33], v[46:47], v[8:9], v[16:17] op_sel_hi:[0,1,1] neg_lo:[0,0,1] neg_hi:[0,0,1]
	v_pk_fma_f32 v[34:35], v[46:47], v[10:11], v[18:19] op_sel_hi:[0,1,1] neg_lo:[0,0,1] neg_hi:[0,0,1]
	v_cvt_pk_bf16_f32 v40, v28, v29
	v_cvt_pk_bf16_f32 v41, v30, v31
	v_cvt_pk_bf16_f32 v42, v32, v33
	v_cvt_pk_bf16_f32 v43, v34, v35
	global_store_dwordx4 v1, v[40:43], s[24:25]
	s_add_u32 s24, s24, 0x2000
	s_addc_u32 s25, s25, 0
	v_lshlrev_b32_e32 v12, 16, v152
	v_and_b32_e32 v13, 0xffff0000, v152
	v_lshlrev_b32_e32 v20, 16, v184
	v_and_b32_e32 v21, 0xffff0000, v184
	v_lshlrev_b32_e32 v14, 16, v153
	v_and_b32_e32 v15, 0xffff0000, v153
	v_lshlrev_b32_e32 v22, 16, v185
	v_and_b32_e32 v23, 0xffff0000, v185
	v_lshlrev_b32_e32 v16, 16, v154
	v_and_b32_e32 v17, 0xffff0000, v154
	v_lshlrev_b32_e32 v24, 16, v186
	v_and_b32_e32 v25, 0xffff0000, v186
	v_lshlrev_b32_e32 v18, 16, v155
	v_and_b32_e32 v19, 0xffff0000, v155
	v_lshlrev_b32_e32 v26, 16, v187
	v_and_b32_e32 v27, 0xffff0000, v187
	v_pk_fma_f32 v[20:21], v[44:45], v[20:21], v[12:13] op_sel_hi:[0,1,1] neg_lo:[1,0,0] neg_hi:[1,0,0]
	v_pk_fma_f32 v[22:23], v[44:45], v[22:23], v[14:15] op_sel_hi:[0,1,1] neg_lo:[1,0,0] neg_hi:[1,0,0]
	v_pk_fma_f32 v[24:25], v[44:45], v[24:25], v[16:17] op_sel_hi:[0,1,1] neg_lo:[1,0,0] neg_hi:[1,0,0]
	v_pk_fma_f32 v[26:27], v[44:45], v[26:27], v[18:19] op_sel_hi:[0,1,1] neg_lo:[1,0,0] neg_hi:[1,0,0]
	v_pk_add_f32 v[4:5], v[4:5], v[20:21]
	v_pk_add_f32 v[6:7], v[6:7], v[22:23]
	v_pk_add_f32 v[8:9], v[8:9], v[24:25]
	v_pk_add_f32 v[10:11], v[10:11], v[26:27]
	v_mov_b32_e32 v46, v3
	v_pk_fma_f32 v[28:29], v[46:47], v[4:5], v[12:13] op_sel_hi:[0,1,1] neg_lo:[0,0,1] neg_hi:[0,0,1]
	v_pk_fma_f32 v[30:31], v[46:47], v[6:7], v[14:15] op_sel_hi:[0,1,1] neg_lo:[0,0,1] neg_hi:[0,0,1]
	v_pk_fma_f32 v[32:33], v[46:47], v[8:9], v[16:17] op_sel_hi:[0,1,1] neg_lo:[0,0,1] neg_hi:[0,0,1]
	v_pk_fma_f32 v[34:35], v[46:47], v[10:11], v[18:19] op_sel_hi:[0,1,1] neg_lo:[0,0,1] neg_hi:[0,0,1]
	v_cvt_pk_bf16_f32 v36, v28, v29
	v_cvt_pk_bf16_f32 v37, v30, v31
	v_cvt_pk_bf16_f32 v38, v32, v33
	v_cvt_pk_bf16_f32 v39, v34, v35
	global_store_dwordx4 v1, v[36:39], s[24:25]
	s_add_u32 s24, s24, 0x2000
	s_addc_u32 s25, s25, 0
	v_lshlrev_b32_e32 v12, 16, v156
	v_and_b32_e32 v13, 0xffff0000, v156
	v_lshlrev_b32_e32 v20, 16, v188
	v_and_b32_e32 v21, 0xffff0000, v188
	v_lshlrev_b32_e32 v14, 16, v157
	v_and_b32_e32 v15, 0xffff0000, v157
	v_lshlrev_b32_e32 v22, 16, v189
	v_and_b32_e32 v23, 0xffff0000, v189
	v_lshlrev_b32_e32 v16, 16, v158
	v_and_b32_e32 v17, 0xffff0000, v158
	v_lshlrev_b32_e32 v24, 16, v190
	v_and_b32_e32 v25, 0xffff0000, v190
	v_lshlrev_b32_e32 v18, 16, v159
	v_and_b32_e32 v19, 0xffff0000, v159
	v_lshlrev_b32_e32 v26, 16, v191
	v_and_b32_e32 v27, 0xffff0000, v191
	v_pk_fma_f32 v[20:21], v[44:45], v[20:21], v[12:13] op_sel_hi:[0,1,1] neg_lo:[1,0,0] neg_hi:[1,0,0]
	v_pk_fma_f32 v[22:23], v[44:45], v[22:23], v[14:15] op_sel_hi:[0,1,1] neg_lo:[1,0,0] neg_hi:[1,0,0]
	v_pk_fma_f32 v[24:25], v[44:45], v[24:25], v[16:17] op_sel_hi:[0,1,1] neg_lo:[1,0,0] neg_hi:[1,0,0]
	v_pk_fma_f32 v[26:27], v[44:45], v[26:27], v[18:19] op_sel_hi:[0,1,1] neg_lo:[1,0,0] neg_hi:[1,0,0]
	v_pk_add_f32 v[4:5], v[4:5], v[20:21]
	v_pk_add_f32 v[6:7], v[6:7], v[22:23]
	v_pk_add_f32 v[8:9], v[8:9], v[24:25]
	v_pk_add_f32 v[10:11], v[10:11], v[26:27]
	v_mov_b32_e32 v46, v3
	v_pk_fma_f32 v[28:29], v[46:47], v[4:5], v[12:13] op_sel_hi:[0,1,1] neg_lo:[0,0,1] neg_hi:[0,0,1]
	v_pk_fma_f32 v[30:31], v[46:47], v[6:7], v[14:15] op_sel_hi:[0,1,1] neg_lo:[0,0,1] neg_hi:[0,0,1]
	v_pk_fma_f32 v[32:33], v[46:47], v[8:9], v[16:17] op_sel_hi:[0,1,1] neg_lo:[0,0,1] neg_hi:[0,0,1]
	v_pk_fma_f32 v[34:35], v[46:47], v[10:11], v[18:19] op_sel_hi:[0,1,1] neg_lo:[0,0,1] neg_hi:[0,0,1]
	v_cvt_pk_bf16_f32 v40, v28, v29
	v_cvt_pk_bf16_f32 v41, v30, v31
	v_cvt_pk_bf16_f32 v42, v32, v33
	v_cvt_pk_bf16_f32 v43, v34, v35
	global_store_dwordx4 v1, v[40:43], s[24:25]
	s_add_u32 s24, s24, 0x2000
	s_addc_u32 s25, s25, 0
	s_branch .Lpool_next
.Lpool_tc0:
	global_load_dwordx4 v[64:67], v1, s[20:21]
	global_load_dwordx4 v[96:99], v50, s[22:23]
	s_add_u32 s20, s20, 0x2000
	s_addc_u32 s21, s21, 0
	s_add_u32 s22, s22, 0x2000
	s_addc_u32 s23, s23, 0
	global_load_dwordx4 v[68:71], v1, s[20:21]
	global_load_dwordx4 v[100:103], v50, s[22:23]
	s_add_u32 s20, s20, 0x2000
	s_addc_u32 s21, s21, 0
	s_add_u32 s22, s22, 0x2000
	s_addc_u32 s23, s23, 0
	global_load_dwordx4 v[72:75], v1, s[20:21]
	v_cmp_ge_u32_e32 vcc, 2, v2
	s_nop 1
	v_cndmask_b32_e32 v55, v50, v49, vcc
	global_load_dwordx4 v[104:107], v55, s[22:23]
	s_add_u32 s20, s20, 0x2000
	s_addc_u32 s21, s21, 0
	s_add_u32 s22, s22, 0x2000
	s_addc_u32 s23, s23, 0
	global_load_dwordx4 v[76:79], v1, s[20:21]
	v_cmp_ge_u32_e32 vcc, 3, v2
	s_nop 1
	v_cndmask_b32_e32 v55, v50, v49, vcc
	global_load_dwordx4 v[108:111], v55, s[22:23]
	s_add_u32 s20, s20, 0x2000
	s_addc_u32 s21, s21, 0
	s_add_u32 s22, s22, 0x2000
	s_addc_u32 s23, s23, 0
	global_load_dwordx4 v[80:83], v1, s[20:21]
	v_cmp_ge_u32_e32 vcc, 4, v2
	s_nop 1
	v_cndmask_b32_e32 v55, v50, v49, vcc
	global_load_dwordx4 v[112:115], v55, s[22:23]
	s_add_u32 s20, s20, 0x2000
	s_addc_u32 s21, s21, 0
	s_add_u32 s22, s22, 0x2000
	s_addc_u32 s23, s23, 0
	global_load_dwordx4 v[84:87], v1, s[20:21]
	v_cmp_ge_u32_e32 vcc, 5, v2
	s_nop 1
	v_cndmask_b32_e32 v55, v50, v49, vcc
	global_load_dwordx4 v[116:119], v55, s[22:23]
	s_add_u32 s20, s20, 0x2000
	s_addc_u32 s21, s21, 0
	s_add_u32 s22, s22, 0x2000
	s_addc_u32 s23, s23, 0
	global_load_dwordx4 v[88:91], v1, s[20:21]
	v_cmp_ge_u32_e32 vcc, 6, v2
	s_nop 1
	v_cndmask_b32_e32 v55, v50, v49, vcc
	global_load_dwordx4 v[120:123], v55, s[22:23]
	s_add_u32 s20, s20, 0x2000
	s_addc_u32 s21, s21, 0
	s_add_u32 s22, s22, 0x2000
	s_addc_u32 s23, s23, 0
	global_load_dwordx4 v[92:95], v1, s[20:21]
	v_cmp_ge_u32_e32 vcc, 7, v2
	s_nop 1
	v_cndmask_b32_e32 v55, v50, v49, vcc
	global_load_dwordx4 v[124:127], v55, s[22:23]
	s_add_u32 s20, s20, 0x2000
	s_addc_u32 s21, s21, 0
	s_add_u32 s22, s22, 0x2000
	s_addc_u32 s23, s23, 0
	global_load_dwordx4 v[128:131], v1, s[20:21]
	v_cmp_ge_u32_e32 vcc, 8, v2
	s_nop 1
	v_cndmask_b32_e32 v55, v50, v49, vcc
	global_load_dwordx4 v[160:163], v55, s[22:23]
	s_add_u32 s20, s20, 0x2000
	s_addc_u32 s21, s21, 0
	s_add_u32 s22, s22, 0x2000
	s_addc_u32 s23, s23, 0
	global_load_dwordx4 v[132:135], v1, s[20:21]
	v_cmp_ge_u32_e32 vcc, 9, v2
	s_nop 1
	v_cndmask_b32_e32 v55, v50, v49, vcc
	global_load_dwordx4 v[164:167], v55, s[22:23]
	s_add_u32 s20, s20, 0x2000
	s_addc_u32 s21, s21, 0
	s_add_u32 s22, s22, 0x2000
	s_addc_u32 s23, s23, 0
	global_load_dwordx4 v[136:139], v1, s[20:21]
	v_cmp_ge_u32_e32 vcc, 10, v2
	s_nop 1
	v_cndmask_b32_e32 v55, v50, v49, vcc
	global_load_dwordx4 v[168:171], v55, s[22:23]
	s_add_u32 s20, s20, 0x2000
	s_addc_u32 s21, s21, 0
	s_add_u32 s22, s22, 0x2000
	s_addc_u32 s23, s23, 0
	global_load_dwordx4 v[140:143], v1, s[20:21]
	v_cmp_ge_u32_e32 vcc, 11, v2
	s_nop 1
	v_cndmask_b32_e32 v55, v50, v49, vcc
	global_load_dwordx4 v[172:175], v55, s[22:23]
	s_add_u32 s20, s20, 0x2000
	s_addc_u32 s21, s21, 0
	s_add_u32 s22, s22, 0x2000
	s_addc_u32 s23, s23, 0
	global_load_dwordx4 v[144:147], v1, s[20:21]
	v_cmp_ge_u32_e32 vcc, 12, v2
	s_nop 1
	v_cndmask_b32_e32 v55, v50, v49, vcc
	global_load_dwordx4 v[176:179], v55, s[22:23]
	s_add_u32 s20, s20, 0x2000
	s_addc_u32 s21, s21, 0
	s_add_u32 s22, s22, 0x2000
	s_addc_u32 s23, s23, 0
	global_load_dwordx4 v[148:151], v1, s[20:21]
	v_cmp_ge_u32_e32 vcc, 13, v2
	s_nop 1
	v_cndmask_b32_e32 v55, v50, v49, vcc
	global_load_dwordx4 v[180:183], v55, s[22:23]
	s_add_u32 s20, s20, 0x2000
	s_addc_u32 s21, s21, 0
	s_add_u32 s22, s22, 0x2000
	s_addc_u32 s23, s23, 0
	global_load_dwordx4 v[152:155], v1, s[20:21]
	v_cmp_ge_u32_e32 vcc, 14, v2
	s_nop 1
	v_cndmask_b32_e32 v55, v50, v49, vcc
	global_load_dwordx4 v[184:187], v55, s[22:23]
	s_add_u32 s20, s20, 0x2000
	s_addc_u32 s21, s21, 0
	s_add_u32 s22, s22, 0x2000
	s_addc_u32 s23, s23, 0
	global_load_dwordx4 v[156:159], v1, s[20:21]
	v_cmp_ge_u32_e32 vcc, 15, v2
	s_nop 1
	v_cndmask_b32_e32 v55, v50, v49, vcc
	global_load_dwordx4 v[188:191], v55, s[22:23]
	s_add_u32 s20, s20, 0x2000
	s_addc_u32 s21, s21, 0
	s_add_u32 s22, s22, 0x2000
	s_addc_u32 s23, s23, 0
	s_waitcnt vmcnt(16)
	v_lshlrev_b32_e32 v12, 16, v64
	v_and_b32_e32 v13, 0xffff0000, v64
	v_lshlrev_b32_e32 v20, 16, v96
	v_and_b32_e32 v21, 0xffff0000, v96
	v_lshlrev_b32_e32 v14, 16, v65
	v_and_b32_e32 v15, 0xffff0000, v65
	v_lshlrev_b32_e32 v22, 16, v97
	v_and_b32_e32 v23, 0xffff0000, v97
	v_lshlrev_b32_e32 v16, 16, v66
	v_and_b32_e32 v17, 0xffff0000, v66
	v_lshlrev_b32_e32 v24, 16, v98
	v_and_b32_e32 v25, 0xffff0000, v98
	v_lshlrev_b32_e32 v18, 16, v67
	v_and_b32_e32 v19, 0xffff0000, v67
	v_lshlrev_b32_e32 v26, 16, v99
	v_and_b32_e32 v27, 0xffff0000, v99
	v_mov_b32_e32 v44, 0
	v_pk_fma_f32 v[20:21], v[44:45], v[20:21], v[12:13] op_sel_hi:[0,1,1] neg_lo:[1,0,0] neg_hi:[1,0,0]
	v_pk_fma_f32 v[22:23], v[44:45], v[22:23], v[14:15] op_sel_hi:[0,1,1] neg_lo:[1,0,0] neg_hi:[1,0,0]
	v_pk_fma_f32 v[24:25], v[44:45], v[24:25], v[16:17] op_sel_hi:[0,1,1] neg_lo:[1,0,0] neg_hi:[1,0,0]
	v_pk_fma_f32 v[26:27], v[44:45], v[26:27], v[18:19] op_sel_hi:[0,1,1] neg_lo:[1,0,0] neg_hi:[1,0,0]
	v_pk_add_f32 v[4:5], v[4:5], v[20:21]
	v_pk_add_f32 v[6:7], v[6:7], v[22:23]
	v_pk_add_f32 v[8:9], v[8:9], v[24:25]
	v_pk_add_f32 v[10:11], v[10:11], v[26:27]
	v_max_f32_e32 v46, 0x3f800000, v3
	v_pk_fma_f32 v[28:29], v[46:47], v[4:5], v[12:13] op_sel_hi:[0,1,1] neg_lo:[0,0,1] neg_hi:[0,0,1]
	v_pk_fma_f32 v[30:31], v[46:47], v[6:7], v[14:15] op_sel_hi:[0,1,1] neg_lo:[0,0,1] neg_hi:[0,0,1]
	v_pk_fma_f32 v[32:33], v[46:47], v[8:9], v[16:17] op_sel_hi:[0,1,1] neg_lo:[0,0,1] neg_hi:[0,0,1]
	v_pk_fma_f32 v[34:35], v[46:47], v[10:11], v[18:19] op_sel_hi:[0,1,1] neg_lo:[0,0,1] neg_hi:[0,0,1]
	v_cvt_pk_bf16_f32 v36, v28, v29
	v_cvt_pk_bf16_f32 v37, v30, v31
	v_cvt_pk_bf16_f32 v38, v32, v33
	v_cvt_pk_bf16_f32 v39, v34, v35
	global_store_dwordx4 v1, v[36:39], s[24:25]
	s_add_u32 s24, s24, 0x2000
	s_addc_u32 s25, s25, 0
	v_lshlrev_b32_e32 v12, 16, v68
	v_and_b32_e32 v13, 0xffff0000, v68
	v_lshlrev_b32_e32 v20, 16, v100
	v_and_b32_e32 v21, 0xffff0000, v100
	v_lshlrev_b32_e32 v14, 16, v69
	v_and_b32_e32 v15, 0xffff0000, v69
	v_lshlrev_b32_e32 v22, 16, v101
	v_and_b32_e32 v23, 0xffff0000, v101
	v_lshlrev_b32_e32 v16, 16, v70
	v_and_b32_e32 v17, 0xffff0000, v70
	v_lshlrev_b32_e32 v24, 16, v102
	v_and_b32_e32 v25, 0xffff0000, v102
	v_lshlrev_b32_e32 v18, 16, v71
	v_and_b32_e32 v19, 0xffff0000, v71
	v_lshlrev_b32_e32 v26, 16, v103
	v_and_b32_e32 v27, 0xffff0000, v103
	v_mov_b32_e32 v44, 0
	v_pk_fma_f32 v[20:21], v[44:45], v[20:21], v[12:13] op_sel_hi:[0,1,1] neg_lo:[1,0,0] neg_hi:[1,0,0]
	v_pk_fma_f32 v[22:23], v[44:45], v[22:23], v[14:15] op_sel_hi:[0,1,1] neg_lo:[1,0,0] neg_hi:[1,0,0]
	v_pk_fma_f32 v[24:25], v[44:45], v[24:25], v[16:17] op_sel_hi:[0,1,1] neg_lo:[1,0,0] neg_hi:[1,0,0]
	v_pk_fma_f32 v[26:27], v[44:45], v[26:27], v[18:19] op_sel_hi:[0,1,1] neg_lo:[1,0,0] neg_hi:[1,0,0]
	v_pk_add_f32 v[4:5], v[4:5], v[20:21]
	v_pk_add_f32 v[6:7], v[6:7], v[22:23]
	v_pk_add_f32 v[8:9], v[8:9], v[24:25]
	v_pk_add_f32 v[10:11], v[10:11], v[26:27]
	v_max_f32_e32 v46, 0x3f000000, v3
	v_pk_fma_f32 v[28:29], v[46:47], v[4:5], v[12:13] op_sel_hi:[0,1,1] neg_lo:[0,0,1] neg_hi:[0,0,1]
	v_pk_fma_f32 v[30:31], v[46:47], v[6:7], v[14:15] op_sel_hi:[0,1,1] neg_lo:[0,0,1] neg_hi:[0,0,1]
	v_pk_fma_f32 v[32:33], v[46:47], v[8:9], v[16:17] op_sel_hi:[0,1,1] neg_lo:[0,0,1] neg_hi:[0,0,1]
	v_pk_fma_f32 v[34:35], v[46:47], v[10:11], v[18:19] op_sel_hi:[0,1,1] neg_lo:[0,0,1] neg_hi:[0,0,1]
	v_cvt_pk_bf16_f32 v40, v28, v29
	v_cvt_pk_bf16_f32 v41, v30, v31
	v_cvt_pk_bf16_f32 v42, v32, v33
	v_cvt_pk_bf16_f32 v43, v34, v35
	global_store_dwordx4 v1, v[40:43], s[24:25]
	s_add_u32 s24, s24, 0x2000
	s_addc_u32 s25, s25, 0
	v_lshlrev_b32_e32 v12, 16, v72
	v_and_b32_e32 v13, 0xffff0000, v72
	v_lshlrev_b32_e32 v20, 16, v104
	v_and_b32_e32 v21, 0xffff0000, v104
	v_lshlrev_b32_e32 v14, 16, v73
	v_and_b32_e32 v15, 0xffff0000, v73
	v_lshlrev_b32_e32 v22, 16, v105
	v_and_b32_e32 v23, 0xffff0000, v105
	v_lshlrev_b32_e32 v16, 16, v74
	v_and_b32_e32 v17, 0xffff0000, v74
	v_lshlrev_b32_e32 v24, 16, v106
	v_and_b32_e32 v25, 0xffff0000, v106
	v_lshlrev_b32_e32 v18, 16, v75
	v_and_b32_e32 v19, 0xffff0000, v75
	v_lshlrev_b32_e32 v26, 16, v107
	v_and_b32_e32 v27, 0xffff0000, v107
	v_cmp_ge_u32_e32 vcc, 2, v2
	s_nop 1
	v_cndmask_b32_e64 v44, 0, 1.0, vcc
	v_pk_fma_f32 v[20:21], v[44:45], v[20:21], v[12:13] op_sel_hi:[0,1,1] neg_lo:[1,0,0] neg_hi:[1,0,0]
	v_pk_fma_f32 v[22:23], v[44:45], v[22:23], v[14:15] op_sel_hi:[0,1,1] neg_lo:[1,0,0] neg_hi:[1,0,0]
	v_pk_fma_f32 v[24:25], v[44:45], v[24:25], v[16:17] op_sel_hi:[0,1,1] neg_lo:[1,0,0] neg_hi:[1,0,0]
	v_pk_fma_f32 v[26:27], v[44:45], v[26:27], v[18:19] op_sel_hi:[0,1,1] neg_lo:[1,0,0] neg_hi:[1,0,0]
	v_pk_add_f32 v[4:5], v[4:5], v[20:21]
	v_pk_add_f32 v[6:7], v[6:7], v[22:23]
	v_pk_add_f32 v[8:9], v[8:9], v[24:25]
	v_pk_add_f32 v[10:11], v[10:11], v[26:27]
	v_max_f32_e32 v46, 0x3eaaaaab, v3
	v_pk_fma_f32 v[28:29], v[46:47], v[4:5], v[12:13] op_sel_hi:[0,1,1] neg_lo:[0,0,1] neg_hi:[0,0,1]
	v_pk_fma_f32 v[30:31], v[46:47], v[6:7], v[14:15] op_sel_hi:[0,1,1] neg_lo:[0,0,1] neg_hi:[0,0,1]
	v_pk_fma_f32 v[32:33], v[46:47], v[8:9], v[16:17] op_sel_hi:[0,1,1] neg_lo:[0,0,1] neg_hi:[0,0,1]
	v_pk_fma_f32 v[34:35], v[46:47], v[10:11], v[18:19] op_sel_hi:[0,1,1] neg_lo:[0,0,1] neg_hi:[0,0,1]
	v_cvt_pk_bf16_f32 v36, v28, v29
	v_cvt_pk_bf16_f32 v37, v30, v31
	v_cvt_pk_bf16_f32 v38, v32, v33
	v_cvt_pk_bf16_f32 v39, v34, v35
	global_store_dwordx4 v1, v[36:39], s[24:25]
	s_add_u32 s24, s24, 0x2000
	s_addc_u32 s25, s25, 0
	v_lshlrev_b32_e32 v12, 16, v76
	v_and_b32_e32 v13, 0xffff0000, v76
	v_lshlrev_b32_e32 v20, 16, v108
	v_and_b32_e32 v21, 0xffff0000, v108
	v_lshlrev_b32_e32 v14, 16, v77
	v_and_b32_e32 v15, 0xffff0000, v77
	v_lshlrev_b32_e32 v22, 16, v109
	v_and_b32_e32 v23, 0xffff0000, v109
	v_lshlrev_b32_e32 v16, 16, v78
	v_and_b32_e32 v17, 0xffff0000, v78
	v_lshlrev_b32_e32 v24, 16, v110
	v_and_b32_e32 v25, 0xffff0000, v110
	v_lshlrev_b32_e32 v18, 16, v79
	v_and_b32_e32 v19, 0xffff0000, v79
	v_lshlrev_b32_e32 v26, 16, v111
	v_and_b32_e32 v27, 0xffff0000, v111
	v_cmp_ge_u32_e32 vcc, 3, v2
	s_nop 1
	v_cndmask_b32_e64 v44, 0, 1.0, vcc
	v_pk_fma_f32 v[20:21], v[44:45], v[20:21], v[12:13] op_sel_hi:[0,1,1] neg_lo:[1,0,0] neg_hi:[1,0,0]
	v_pk_fma_f32 v[22:23], v[44:45], v[22:23], v[14:15] op_sel_hi:[0,1,1] neg_lo:[1,0,0] neg_hi:[1,0,0]
	v_pk_fma_f32 v[24:25], v[44:45], v[24:25], v[16:17] op_sel_hi:[0,1,1] neg_lo:[1,0,0] neg_hi:[1,0,0]
	v_pk_fma_f32 v[26:27], v[44:45], v[26:27], v[18:19] op_sel_hi:[0,1,1] neg_lo:[1,0,0] neg_hi:[1,0,0]
	v_pk_add_f32 v[4:5], v[4:5], v[20:21]
	v_pk_add_f32 v[6:7], v[6:7], v[22:23]
	v_pk_add_f32 v[8:9], v[8:9], v[24:25]
	v_pk_add_f32 v[10:11], v[10:11], v[26:27]
	v_max_f32_e32 v46, 0x3e800000, v3
	v_pk_fma_f32 v[28:29], v[46:47], v[4:5], v[12:13] op_sel_hi:[0,1,1] neg_lo:[0,0,1] neg_hi:[0,0,1]
	v_pk_fma_f32 v[30:31], v[46:47], v[6:7], v[14:15] op_sel_hi:[0,1,1] neg_lo:[0,0,1] neg_hi:[0,0,1]
	v_pk_fma_f32 v[32:33], v[46:47], v[8:9], v[16:17] op_sel_hi:[0,1,1] neg_lo:[0,0,1] neg_hi:[0,0,1]
	v_pk_fma_f32 v[34:35], v[46:47], v[10:11], v[18:19] op_sel_hi:[0,1,1] neg_lo:[0,0,1] neg_hi:[0,0,1]
	v_cvt_pk_bf16_f32 v40, v28, v29
	v_cvt_pk_bf16_f32 v41, v30, v31
	v_cvt_pk_bf16_f32 v42, v32, v33
	v_cvt_pk_bf16_f32 v43, v34, v35
	global_store_dwordx4 v1, v[40:43], s[24:25]
	s_add_u32 s24, s24, 0x2000
	s_addc_u32 s25, s25, 0
	v_lshlrev_b32_e32 v12, 16, v80
	v_and_b32_e32 v13, 0xffff0000, v80
	v_lshlrev_b32_e32 v20, 16, v112
	v_and_b32_e32 v21, 0xffff0000, v112
	v_lshlrev_b32_e32 v14, 16, v81
	v_and_b32_e32 v15, 0xffff0000, v81
	v_lshlrev_b32_e32 v22, 16, v113
	v_and_b32_e32 v23, 0xffff0000, v113
	v_lshlrev_b32_e32 v16, 16, v82
	v_and_b32_e32 v17, 0xffff0000, v82
	v_lshlrev_b32_e32 v24, 16, v114
	v_and_b32_e32 v25, 0xffff0000, v114
	v_lshlrev_b32_e32 v18, 16, v83
	v_and_b32_e32 v19, 0xffff0000, v83
	v_lshlrev_b32_e32 v26, 16, v115
	v_and_b32_e32 v27, 0xffff0000, v115
	v_cmp_ge_u32_e32 vcc, 4, v2
	s_nop 1
	v_cndmask_b32_e64 v44, 0, 1.0, vcc
	v_pk_fma_f32 v[20:21], v[44:45], v[20:21], v[12:13] op_sel_hi:[0,1,1] neg_lo:[1,0,0] neg_hi:[1,0,0]
	v_pk_fma_f32 v[22:23], v[44:45], v[22:23], v[14:15] op_sel_hi:[0,1,1] neg_lo:[1,0,0] neg_hi:[1,0,0]
	v_pk_fma_f32 v[24:25], v[44:45], v[24:25], v[16:17] op_sel_hi:[0,1,1] neg_lo:[1,0,0] neg_hi:[1,0,0]
	v_pk_fma_f32 v[26:27], v[44:45], v[26:27], v[18:19] op_sel_hi:[0,1,1] neg_lo:[1,0,0] neg_hi:[1,0,0]
	v_pk_add_f32 v[4:5], v[4:5], v[20:21]
	v_pk_add_f32 v[6:7], v[6:7], v[22:23]
	v_pk_add_f32 v[8:9], v[8:9], v[24:25]
	v_pk_add_f32 v[10:11], v[10:11], v[26:27]
	v_max_f32_e32 v46, 0x3e4ccccd, v3
	v_pk_fma_f32 v[28:29], v[46:47], v[4:5], v[12:13] op_sel_hi:[0,1,1] neg_lo:[0,0,1] neg_hi:[0,0,1]
	v_pk_fma_f32 v[30:31], v[46:47], v[6:7], v[14:15] op_sel_hi:[0,1,1] neg_lo:[0,0,1] neg_hi:[0,0,1]
	v_pk_fma_f32 v[32:33], v[46:47], v[8:9], v[16:17] op_sel_hi:[0,1,1] neg_lo:[0,0,1] neg_hi:[0,0,1]
	v_pk_fma_f32 v[34:35], v[46:47], v[10:11], v[18:19] op_sel_hi:[0,1,1] neg_lo:[0,0,1] neg_hi:[0,0,1]
	v_cvt_pk_bf16_f32 v36, v28, v29
	v_cvt_pk_bf16_f32 v37, v30, v31
	v_cvt_pk_bf16_f32 v38, v32, v33
	v_cvt_pk_bf16_f32 v39, v34, v35
	global_store_dwordx4 v1, v[36:39], s[24:25]
	s_add_u32 s24, s24, 0x2000
	s_addc_u32 s25, s25, 0
	v_lshlrev_b32_e32 v12, 16, v84
	v_and_b32_e32 v13, 0xffff0000, v84
	v_lshlrev_b32_e32 v20, 16, v116
	v_and_b32_e32 v21, 0xffff0000, v116
	v_lshlrev_b32_e32 v14, 16, v85
	v_and_b32_e32 v15, 0xffff0000, v85
	v_lshlrev_b32_e32 v22, 16, v117
	v_and_b32_e32 v23, 0xffff0000, v117
	v_lshlrev_b32_e32 v16, 16, v86
	v_and_b32_e32 v17, 0xffff0000, v86
	v_lshlrev_b32_e32 v24, 16, v118
	v_and_b32_e32 v25, 0xffff0000, v118
	v_lshlrev_b32_e32 v18, 16, v87
	v_and_b32_e32 v19, 0xffff0000, v87
	v_lshlrev_b32_e32 v26, 16, v119
	v_and_b32_e32 v27, 0xffff0000, v119
	v_cmp_ge_u32_e32 vcc, 5, v2
	s_nop 1
	v_cndmask_b32_e64 v44, 0, 1.0, vcc
	v_pk_fma_f32 v[20:21], v[44:45], v[20:21], v[12:13] op_sel_hi:[0,1,1] neg_lo:[1,0,0] neg_hi:[1,0,0]
	v_pk_fma_f32 v[22:23], v[44:45], v[22:23], v[14:15] op_sel_hi:[0,1,1] neg_lo:[1,0,0] neg_hi:[1,0,0]
	v_pk_fma_f32 v[24:25], v[44:45], v[24:25], v[16:17] op_sel_hi:[0,1,1] neg_lo:[1,0,0] neg_hi:[1,0,0]
	v_pk_fma_f32 v[26:27], v[44:45], v[26:27], v[18:19] op_sel_hi:[0,1,1] neg_lo:[1,0,0] neg_hi:[1,0,0]
	v_pk_add_f32 v[4:5], v[4:5], v[20:21]
	v_pk_add_f32 v[6:7], v[6:7], v[22:23]
	v_pk_add_f32 v[8:9], v[8:9], v[24:25]
	v_pk_add_f32 v[10:11], v[10:11], v[26:27]
	v_max_f32_e32 v46, 0x3e2aaaab, v3
	v_pk_fma_f32 v[28:29], v[46:47], v[4:5], v[12:13] op_sel_hi:[0,1,1] neg_lo:[0,0,1] neg_hi:[0,0,1]
	v_pk_fma_f32 v[30:31], v[46:47], v[6:7], v[14:15] op_sel_hi:[0,1,1] neg_lo:[0,0,1] neg_hi:[0,0,1]
	v_pk_fma_f32 v[32:33], v[46:47], v[8:9], v[16:17] op_sel_hi:[0,1,1] neg_lo:[0,0,1] neg_hi:[0,0,1]
	v_pk_fma_f32 v[34:35], v[46:47], v[10:11], v[18:19] op_sel_hi:[0,1,1] neg_lo:[0,0,1] neg_hi:[0,0,1]
	v_cvt_pk_bf16_f32 v40, v28, v29
	v_cvt_pk_bf16_f32 v41, v30, v31
	v_cvt_pk_bf16_f32 v42, v32, v33
	v_cvt_pk_bf16_f32 v43, v34, v35
	global_store_dwordx4 v1, v[40:43], s[24:25]
	s_add_u32 s24, s24, 0x2000
	s_addc_u32 s25, s25, 0
	v_lshlrev_b32_e32 v12, 16, v88
	v_and_b32_e32 v13, 0xffff0000, v88
	v_lshlrev_b32_e32 v20, 16, v120
	v_and_b32_e32 v21, 0xffff0000, v120
	v_lshlrev_b32_e32 v14, 16, v89
	v_and_b32_e32 v15, 0xffff0000, v89
	v_lshlrev_b32_e32 v22, 16, v121
	v_and_b32_e32 v23, 0xffff0000, v121
	v_lshlrev_b32_e32 v16, 16, v90
	v_and_b32_e32 v17, 0xffff0000, v90
	v_lshlrev_b32_e32 v24, 16, v122
	v_and_b32_e32 v25, 0xffff0000, v122
	v_lshlrev_b32_e32 v18, 16, v91
	v_and_b32_e32 v19, 0xffff0000, v91
	v_lshlrev_b32_e32 v26, 16, v123
	v_and_b32_e32 v27, 0xffff0000, v123
	v_cmp_ge_u32_e32 vcc, 6, v2
	s_nop 1
	v_cndmask_b32_e64 v44, 0, 1.0, vcc
	v_pk_fma_f32 v[20:21], v[44:45], v[20:21], v[12:13] op_sel_hi:[0,1,1] neg_lo:[1,0,0] neg_hi:[1,0,0]
	v_pk_fma_f32 v[22:23], v[44:45], v[22:23], v[14:15] op_sel_hi:[0,1,1] neg_lo:[1,0,0] neg_hi:[1,0,0]
	v_pk_fma_f32 v[24:25], v[44:45], v[24:25], v[16:17] op_sel_hi:[0,1,1] neg_lo:[1,0,0] neg_hi:[1,0,0]
	v_pk_fma_f32 v[26:27], v[44:45], v[26:27], v[18:19] op_sel_hi:[0,1,1] neg_lo:[1,0,0] neg_hi:[1,0,0]
	v_pk_add_f32 v[4:5], v[4:5], v[20:21]
	v_pk_add_f32 v[6:7], v[6:7], v[22:23]
	v_pk_add_f32 v[8:9], v[8:9], v[24:25]
	v_pk_add_f32 v[10:11], v[10:11], v[26:27]
	v_max_f32_e32 v46, 0x3e124925, v3
	v_pk_fma_f32 v[28:29], v[46:47], v[4:5], v[12:13] op_sel_hi:[0,1,1] neg_lo:[0,0,1] neg_hi:[0,0,1]
	v_pk_fma_f32 v[30:31], v[46:47], v[6:7], v[14:15] op_sel_hi:[0,1,1] neg_lo:[0,0,1] neg_hi:[0,0,1]
	v_pk_fma_f32 v[32:33], v[46:47], v[8:9], v[16:17] op_sel_hi:[0,1,1] neg_lo:[0,0,1] neg_hi:[0,0,1]
	v_pk_fma_f32 v[34:35], v[46:47], v[10:11], v[18:19] op_sel_hi:[0,1,1] neg_lo:[0,0,1] neg_hi:[0,0,1]
	v_cvt_pk_bf16_f32 v36, v28, v29
	v_cvt_pk_bf16_f32 v37, v30, v31
	v_cvt_pk_bf16_f32 v38, v32, v33
	v_cvt_pk_bf16_f32 v39, v34, v35
	global_store_dwordx4 v1, v[36:39], s[24:25]
	s_add_u32 s24, s24, 0x2000
	s_addc_u32 s25, s25, 0
	v_lshlrev_b32_e32 v12, 16, v92
	v_and_b32_e32 v13, 0xffff0000, v92
	v_lshlrev_b32_e32 v20, 16, v124
	v_and_b32_e32 v21, 0xffff0000, v124
	v_lshlrev_b32_e32 v14, 16, v93
	v_and_b32_e32 v15, 0xffff0000, v93
	v_lshlrev_b32_e32 v22, 16, v125
	v_and_b32_e32 v23, 0xffff0000, v125
	v_lshlrev_b32_e32 v16, 16, v94
	v_and_b32_e32 v17, 0xffff0000, v94
	v_lshlrev_b32_e32 v24, 16, v126
	v_and_b32_e32 v25, 0xffff0000, v126
	v_lshlrev_b32_e32 v18, 16, v95
	v_and_b32_e32 v19, 0xffff0000, v95
	v_lshlrev_b32_e32 v26, 16, v127
	v_and_b32_e32 v27, 0xffff0000, v127
	v_cmp_ge_u32_e32 vcc, 7, v2
	s_nop 1
	v_cndmask_b32_e64 v44, 0, 1.0, vcc
	v_pk_fma_f32 v[20:21], v[44:45], v[20:21], v[12:13] op_sel_hi:[0,1,1] neg_lo:[1,0,0] neg_hi:[1,0,0]
	v_pk_fma_f32 v[22:23], v[44:45], v[22:23], v[14:15] op_sel_hi:[0,1,1] neg_lo:[1,0,0] neg_hi:[1,0,0]
	v_pk_fma_f32 v[24:25], v[44:45], v[24:25], v[16:17] op_sel_hi:[0,1,1] neg_lo:[1,0,0] neg_hi:[1,0,0]
	v_pk_fma_f32 v[26:27], v[44:45], v[26:27], v[18:19] op_sel_hi:[0,1,1] neg_lo:[1,0,0] neg_hi:[1,0,0]
	v_pk_add_f32 v[4:5], v[4:5], v[20:21]
	v_pk_add_f32 v[6:7], v[6:7], v[22:23]
	v_pk_add_f32 v[8:9], v[8:9], v[24:25]
	v_pk_add_f32 v[10:11], v[10:11], v[26:27]
	v_max_f32_e32 v46, 0x3e000000, v3
	v_pk_fma_f32 v[28:29], v[46:47], v[4:5], v[12:13] op_sel_hi:[0,1,1] neg_lo:[0,0,1] neg_hi:[0,0,1]
	v_pk_fma_f32 v[30:31], v[46:47], v[6:7], v[14:15] op_sel_hi:[0,1,1] neg_lo:[0,0,1] neg_hi:[0,0,1]
	v_pk_fma_f32 v[32:33], v[46:47], v[8:9], v[16:17] op_sel_hi:[0,1,1] neg_lo:[0,0,1] neg_hi:[0,0,1]
	v_pk_fma_f32 v[34:35], v[46:47], v[10:11], v[18:19] op_sel_hi:[0,1,1] neg_lo:[0,0,1] neg_hi:[0,0,1]
	v_cvt_pk_bf16_f32 v40, v28, v29
	v_cvt_pk_bf16_f32 v41, v30, v31
	v_cvt_pk_bf16_f32 v42, v32, v33
	v_cvt_pk_bf16_f32 v43, v34, v35
	global_store_dwordx4 v1, v[40:43], s[24:25]
	s_add_u32 s24, s24, 0x2000
	s_addc_u32 s25, s25, 0
	global_load_dwordx4 v[64:67], v1, s[20:21]
	global_load_dwordx4 v[96:99], v49, s[22:23]
	s_add_u32 s20, s20, 0x2000
	s_addc_u32 s21, s21, 0
	s_add_u32 s22, s22, 0x2000
	s_addc_u32 s23, s23, 0
	global_load_dwordx4 v[68:71], v1, s[20:21]
	global_load_dwordx4 v[100:103], v49, s[22:23]
	s_add_u32 s20, s20, 0x2000
	s_addc_u32 s21, s21, 0
	s_add_u32 s22, s22, 0x2000
	s_addc_u32 s23, s23, 0
	global_load_dwordx4 v[72:75], v1, s[20:21]
	global_load_dwordx4 v[104:107], v49, s[22:23]
	s_add_u32 s20, s20, 0x2000
	s_addc_u32 s21, s21, 0
	s_add_u32 s22, s22, 0x2000
	s_addc_u32 s23, s23, 0
	global_load_dwordx4 v[76:79], v1, s[20:21]
	global_load_dwordx4 v[108:111], v49, s[22:23]
	s_add_u32 s20, s20, 0x2000
	s_addc_u32 s21, s21, 0
	s_add_u32 s22, s22, 0x2000
	s_addc_u32 s23, s23, 0
	global_load_dwordx4 v[80:83], v1, s[20:21]
	global_load_dwordx4 v[112:115], v49, s[22:23]
	s_add_u32 s20, s20, 0x2000
	s_addc_u32 s21, s21, 0
	s_add_u32 s22, s22, 0x2000
	s_addc_u32 s23, s23, 0
	global_load_dwordx4 v[84:87], v1, s[20:21]
	global_load_dwordx4 v[116:119], v49, s[22:23]
	s_add_u32 s20, s20, 0x2000
	s_addc_u32 s21, s21, 0
	s_add_u32 s22, s22, 0x2000
	s_addc_u32 s23, s23, 0
	global_load_dwordx4 v[88:91], v1, s[20:21]
	global_load_dwordx4 v[120:123], v49, s[22:23]
	s_add_u32 s20, s20, 0x2000
	s_addc_u32 s21, s21, 0
	s_add_u32 s22, s22, 0x2000
	s_addc_u32 s23, s23, 0
	global_load_dwordx4 v[92:95], v1, s[20:21]
	global_load_dwordx4 v[124:127], v49, s[22:23]
	s_add_u32 s20, s20, 0x2000
	s_addc_u32 s21, s21, 0
	s_add_u32 s22, s22, 0x2000
	s_addc_u32 s23, s23, 0
	s_waitcnt vmcnt(24)
	v_lshlrev_b32_e32 v12, 16, v128
	v_and_b32_e32 v13, 0xffff0000, v128
	v_lshlrev_b32_e32 v20, 16, v160
	v_and_b32_e32 v21, 0xffff0000, v160
	v_lshlrev_b32_e32 v14, 16, v129
	v_and_b32_e32 v15, 0xffff0000, v129
	v_lshlrev_b32_e32 v22, 16, v161
	v_and_b32_e32 v23, 0xffff0000, v161
	v_lshlrev_b32_e32 v16, 16, v130
	v_and_b32_e32 v17, 0xffff0000, v130
	v_lshlrev_b32_e32 v24, 16, v162
	v_and_b32_e32 v25, 0xffff0000, v162
	v_lshlrev_b32_e32 v18, 16, v131
	v_and_b32_e32 v19, 0xffff0000, v131
	v_lshlrev_b32_e32 v26, 16, v163
	v_and_b32_e32 v27, 0xffff0000, v163
	v_cmp_ge_u32_e32 vcc, 8, v2
	s_nop 1
	v_cndmask_b32_e64 v44, 0, 1.0, vcc
	v_pk_fma_f32 v[20:21], v[44:45], v[20:21], v[12:13] op_sel_hi:[0,1,1] neg_lo:[1,0,0] neg_hi:[1,0,0]
	v_pk_fma_f32 v[22:23], v[44:45], v[22:23], v[14:15] op_sel_hi:[0,1,1] neg_lo:[1,0,0] neg_hi:[1,0,0]
	v_pk_fma_f32 v[24:25], v[44:45], v[24:25], v[16:17] op_sel_hi:[0,1,1] neg_lo:[1,0,0] neg_hi:[1,0,0]
	v_pk_fma_f32 v[26:27], v[44:45], v[26:27], v[18:19] op_sel_hi:[0,1,1] neg_lo:[1,0,0] neg_hi:[1,0,0]
	v_pk_add_f32 v[4:5], v[4:5], v[20:21]
	v_pk_add_f32 v[6:7], v[6:7], v[22:23]
	v_pk_add_f32 v[8:9], v[8:9], v[24:25]
	v_pk_add_f32 v[10:11], v[10:11], v[26:27]
	v_max_f32_e32 v46, 0x3de38e39, v3
	v_pk_fma_f32 v[28:29], v[46:47], v[4:5], v[12:13] op_sel_hi:[0,1,1] neg_lo:[0,0,1] neg_hi:[0,0,1]
	v_pk_fma_f32 v[30:31], v[46:47], v[6:7], v[14:15] op_sel_hi:[0,1,1] neg_lo:[0,0,1] neg_hi:[0,0,1]
	v_pk_fma_f32 v[32:33], v[46:47], v[8:9], v[16:17] op_sel_hi:[0,1,1] neg_lo:[0,0,1] neg_hi:[0,0,1]
	v_pk_fma_f32 v[34:35], v[46:47], v[10:11], v[18:19] op_sel_hi:[0,1,1] neg_lo:[0,0,1] neg_hi:[0,0,1]
	v_cvt_pk_bf16_f32 v36, v28, v29
	v_cvt_pk_bf16_f32 v37, v30, v31
	v_cvt_pk_bf16_f32 v38, v32, v33
	v_cvt_pk_bf16_f32 v39, v34, v35
	global_store_dwordx4 v1, v[36:39], s[24:25]
	s_add_u32 s24, s24, 0x2000
	s_addc_u32 s25, s25, 0
	v_lshlrev_b32_e32 v12, 16, v132
	v_and_b32_e32 v13, 0xffff0000, v132
	v_lshlrev_b32_e32 v20, 16, v164
	v_and_b32_e32 v21, 0xffff0000, v164
	v_lshlrev_b32_e32 v14, 16, v133
	v_and_b32_e32 v15, 0xffff0000, v133
	v_lshlrev_b32_e32 v22, 16, v165
	v_and_b32_e32 v23, 0xffff0000, v165
	v_lshlrev_b32_e32 v16, 16, v134
	v_and_b32_e32 v17, 0xffff0000, v134
	v_lshlrev_b32_e32 v24, 16, v166
	v_and_b32_e32 v25, 0xffff0000, v166
	v_lshlrev_b32_e32 v18, 16, v135
	v_and_b32_e32 v19, 0xffff0000, v135
	v_lshlrev_b32_e32 v26, 16, v167
	v_and_b32_e32 v27, 0xffff0000, v167
	v_cmp_ge_u32_e32 vcc, 9, v2
	s_nop 1
	v_cndmask_b32_e64 v44, 0, 1.0, vcc
	v_pk_fma_f32 v[20:21], v[44:45], v[20:21], v[12:13] op_sel_hi:[0,1,1] neg_lo:[1,0,0] neg_hi:[1,0,0]
	v_pk_fma_f32 v[22:23], v[44:45], v[22:23], v[14:15] op_sel_hi:[0,1,1] neg_lo:[1,0,0] neg_hi:[1,0,0]
	v_pk_fma_f32 v[24:25], v[44:45], v[24:25], v[16:17] op_sel_hi:[0,1,1] neg_lo:[1,0,0] neg_hi:[1,0,0]
	v_pk_fma_f32 v[26:27], v[44:45], v[26:27], v[18:19] op_sel_hi:[0,1,1] neg_lo:[1,0,0] neg_hi:[1,0,0]
	v_pk_add_f32 v[4:5], v[4:5], v[20:21]
	v_pk_add_f32 v[6:7], v[6:7], v[22:23]
	v_pk_add_f32 v[8:9], v[8:9], v[24:25]
	v_pk_add_f32 v[10:11], v[10:11], v[26:27]
	v_max_f32_e32 v46, 0x3dcccccd, v3
	v_pk_fma_f32 v[28:29], v[46:47], v[4:5], v[12:13] op_sel_hi:[0,1,1] neg_lo:[0,0,1] neg_hi:[0,0,1]
	v_pk_fma_f32 v[30:31], v[46:47], v[6:7], v[14:15] op_sel_hi:[0,1,1] neg_lo:[0,0,1] neg_hi:[0,0,1]
	v_pk_fma_f32 v[32:33], v[46:47], v[8:9], v[16:17] op_sel_hi:[0,1,1] neg_lo:[0,0,1] neg_hi:[0,0,1]
	v_pk_fma_f32 v[34:35], v[46:47], v[10:11], v[18:19] op_sel_hi:[0,1,1] neg_lo:[0,0,1] neg_hi:[0,0,1]
	v_cvt_pk_bf16_f32 v40, v28, v29
	v_cvt_pk_bf16_f32 v41, v30, v31
	v_cvt_pk_bf16_f32 v42, v32, v33
	v_cvt_pk_bf16_f32 v43, v34, v35
	global_store_dwordx4 v1, v[40:43], s[24:25]
	s_add_u32 s24, s24, 0x2000
	s_addc_u32 s25, s25, 0
	v_lshlrev_b32_e32 v12, 16, v136
	v_and_b32_e32 v13, 0xffff0000, v136
	v_lshlrev_b32_e32 v20, 16, v168
	v_and_b32_e32 v21, 0xffff0000, v168
	v_lshlrev_b32_e32 v14, 16, v137
	v_and_b32_e32 v15, 0xffff0000, v137
	v_lshlrev_b32_e32 v22, 16, v169
	v_and_b32_e32 v23, 0xffff0000, v169
	v_lshlrev_b32_e32 v16, 16, v138
	v_and_b32_e32 v17, 0xffff0000, v138
	v_lshlrev_b32_e32 v24, 16, v170
	v_and_b32_e32 v25, 0xffff0000, v170
	v_lshlrev_b32_e32 v18, 16, v139
	v_and_b32_e32 v19, 0xffff0000, v139
	v_lshlrev_b32_e32 v26, 16, v171
	v_and_b32_e32 v27, 0xffff0000, v171
	v_cmp_ge_u32_e32 vcc, 10, v2
	s_nop 1
	v_cndmask_b32_e64 v44, 0, 1.0, vcc
	v_pk_fma_f32 v[20:21], v[44:45], v[20:21], v[12:13] op_sel_hi:[0,1,1] neg_lo:[1,0,0] neg_hi:[1,0,0]
	v_pk_fma_f32 v[22:23], v[44:45], v[22:23], v[14:15] op_sel_hi:[0,1,1] neg_lo:[1,0,0] neg_hi:[1,0,0]
	v_pk_fma_f32 v[24:25], v[44:45], v[24:25], v[16:17] op_sel_hi:[0,1,1] neg_lo:[1,0,0] neg_hi:[1,0,0]
	v_pk_fma_f32 v[26:27], v[44:45], v[26:27], v[18:19] op_sel_hi:[0,1,1] neg_lo:[1,0,0] neg_hi:[1,0,0]
	v_pk_add_f32 v[4:5], v[4:5], v[20:21]
	v_pk_add_f32 v[6:7], v[6:7], v[22:23]
	v_pk_add_f32 v[8:9], v[8:9], v[24:25]
	v_pk_add_f32 v[10:11], v[10:11], v[26:27]
	v_max_f32_e32 v46, 0x3dba2e8c, v3
	v_pk_fma_f32 v[28:29], v[46:47], v[4:5], v[12:13] op_sel_hi:[0,1,1] neg_lo:[0,0,1] neg_hi:[0,0,1]
	v_pk_fma_f32 v[30:31], v[46:47], v[6:7], v[14:15] op_sel_hi:[0,1,1] neg_lo:[0,0,1] neg_hi:[0,0,1]
	v_pk_fma_f32 v[32:33], v[46:47], v[8:9], v[16:17] op_sel_hi:[0,1,1] neg_lo:[0,0,1] neg_hi:[0,0,1]
	v_pk_fma_f32 v[34:35], v[46:47], v[10:11], v[18:19] op_sel_hi:[0,1,1] neg_lo:[0,0,1] neg_hi:[0,0,1]
	v_cvt_pk_bf16_f32 v36, v28, v29
	v_cvt_pk_bf16_f32 v37, v30, v31
	v_cvt_pk_bf16_f32 v38, v32, v33
	v_cvt_pk_bf16_f32 v39, v34, v35
	global_store_dwordx4 v1, v[36:39], s[24:25]
	s_add_u32 s24, s24, 0x2000
	s_addc_u32 s25, s25, 0
	v_lshlrev_b32_e32 v12, 16, v140
	v_and_b32_e32 v13, 0xffff0000, v140
	v_lshlrev_b32_e32 v20, 16, v172
	v_and_b32_e32 v21, 0xffff0000, v172
	v_lshlrev_b32_e32 v14, 16, v141
	v_and_b32_e32 v15, 0xffff0000, v141
	v_lshlrev_b32_e32 v22, 16, v173
	v_and_b32_e32 v23, 0xffff0000, v173
	v_lshlrev_b32_e32 v16, 16, v142
	v_and_b32_e32 v17, 0xffff0000, v142
	v_lshlrev_b32_e32 v24, 16, v174
	v_and_b32_e32 v25, 0xffff0000, v174
	v_lshlrev_b32_e32 v18, 16, v143
	v_and_b32_e32 v19, 0xffff0000, v143
	v_lshlrev_b32_e32 v26, 16, v175
	v_and_b32_e32 v27, 0xffff0000, v175
	v_cmp_ge_u32_e32 vcc, 11, v2
	s_nop 1
	v_cndmask_b32_e64 v44, 0, 1.0, vcc
	v_pk_fma_f32 v[20:21], v[44:45], v[20:21], v[12:13] op_sel_hi:[0,1,1] neg_lo:[1,0,0] neg_hi:[1,0,0]
	v_pk_fma_f32 v[22:23], v[44:45], v[22:23], v[14:15] op_sel_hi:[0,1,1] neg_lo:[1,0,0] neg_hi:[1,0,0]
	v_pk_fma_f32 v[24:25], v[44:45], v[24:25], v[16:17] op_sel_hi:[0,1,1] neg_lo:[1,0,0] neg_hi:[1,0,0]
	v_pk_fma_f32 v[26:27], v[44:45], v[26:27], v[18:19] op_sel_hi:[0,1,1] neg_lo:[1,0,0] neg_hi:[1,0,0]
	v_pk_add_f32 v[4:5], v[4:5], v[20:21]
	v_pk_add_f32 v[6:7], v[6:7], v[22:23]
	v_pk_add_f32 v[8:9], v[8:9], v[24:25]
	v_pk_add_f32 v[10:11], v[10:11], v[26:27]
	v_max_f32_e32 v46, 0x3daaaaab, v3
	v_pk_fma_f32 v[28:29], v[46:47], v[4:5], v[12:13] op_sel_hi:[0,1,1] neg_lo:[0,0,1] neg_hi:[0,0,1]
	v_pk_fma_f32 v[30:31], v[46:47], v[6:7], v[14:15] op_sel_hi:[0,1,1] neg_lo:[0,0,1] neg_hi:[0,0,1]
	v_pk_fma_f32 v[32:33], v[46:47], v[8:9], v[16:17] op_sel_hi:[0,1,1] neg_lo:[0,0,1] neg_hi:[0,0,1]
	v_pk_fma_f32 v[34:35], v[46:47], v[10:11], v[18:19] op_sel_hi:[0,1,1] neg_lo:[0,0,1] neg_hi:[0,0,1]
	v_cvt_pk_bf16_f32 v40, v28, v29
	v_cvt_pk_bf16_f32 v41, v30, v31
	v_cvt_pk_bf16_f32 v42, v32, v33
	v_cvt_pk_bf16_f32 v43, v34, v35
	global_store_dwordx4 v1, v[40:43], s[24:25]
	s_add_u32 s24, s24, 0x2000
	s_addc_u32 s25, s25, 0
	v_lshlrev_b32_e32 v12, 16, v144
	v_and_b32_e32 v13, 0xffff0000, v144
	v_lshlrev_b32_e32 v20, 16, v176
	v_and_b32_e32 v21, 0xffff0000, v176
	v_lshlrev_b32_e32 v14, 16, v145
	v_and_b32_e32 v15, 0xffff0000, v145
	v_lshlrev_b32_e32 v22, 16, v177
	v_and_b32_e32 v23, 0xffff0000, v177
	v_lshlrev_b32_e32 v16, 16, v146
	v_and_b32_e32 v17, 0xffff0000, v146
	v_lshlrev_b32_e32 v24, 16, v178
	v_and_b32_e32 v25, 0xffff0000, v178
	v_lshlrev_b32_e32 v18, 16, v147
	v_and_b32_e32 v19, 0xffff0000, v147
	v_lshlrev_b32_e32 v26, 16, v179
	v_and_b32_e32 v27, 0xffff0000, v179
	v_cmp_ge_u32_e32 vcc, 12, v2
	s_nop 1
	v_cndmask_b32_e64 v44, 0, 1.0, vcc
	v_pk_fma_f32 v[20:21], v[44:45], v[20:21], v[12:13] op_sel_hi:[0,1,1] neg_lo:[1,0,0] neg_hi:[1,0,0]
	v_pk_fma_f32 v[22:23], v[44:45], v[22:23], v[14:15] op_sel_hi:[0,1,1] neg_lo:[1,0,0] neg_hi:[1,0,0]
	v_pk_fma_f32 v[24:25], v[44:45], v[24:25], v[16:17] op_sel_hi:[0,1,1] neg_lo:[1,0,0] neg_hi:[1,0,0]
	v_pk_fma_f32 v[26:27], v[44:45], v[26:27], v[18:19] op_sel_hi:[0,1,1] neg_lo:[1,0,0] neg_hi:[1,0,0]
	v_pk_add_f32 v[4:5], v[4:5], v[20:21]
	v_pk_add_f32 v[6:7], v[6:7], v[22:23]
	v_pk_add_f32 v[8:9], v[8:9], v[24:25]
	v_pk_add_f32 v[10:11], v[10:11], v[26:27]
	v_max_f32_e32 v46, 0x3d9d89d9, v3
	v_pk_fma_f32 v[28:29], v[46:47], v[4:5], v[12:13] op_sel_hi:[0,1,1] neg_lo:[0,0,1] neg_hi:[0,0,1]
	v_pk_fma_f32 v[30:31], v[46:47], v[6:7], v[14:15] op_sel_hi:[0,1,1] neg_lo:[0,0,1] neg_hi:[0,0,1]
	v_pk_fma_f32 v[32:33], v[46:47], v[8:9], v[16:17] op_sel_hi:[0,1,1] neg_lo:[0,0,1] neg_hi:[0,0,1]
	v_pk_fma_f32 v[34:35], v[46:47], v[10:11], v[18:19] op_sel_hi:[0,1,1] neg_lo:[0,0,1] neg_hi:[0,0,1]
	v_cvt_pk_bf16_f32 v36, v28, v29
	v_cvt_pk_bf16_f32 v37, v30, v31
	v_cvt_pk_bf16_f32 v38, v32, v33
	v_cvt_pk_bf16_f32 v39, v34, v35
	global_store_dwordx4 v1, v[36:39], s[24:25]
	s_add_u32 s24, s24, 0x2000
	s_addc_u32 s25, s25, 0
	v_lshlrev_b32_e32 v12, 16, v148
	v_and_b32_e32 v13, 0xffff0000, v148
	v_lshlrev_b32_e32 v20, 16, v180
	v_and_b32_e32 v21, 0xffff0000, v180
	v_lshlrev_b32_e32 v14, 16, v149
	v_and_b32_e32 v15, 0xffff0000, v149
	v_lshlrev_b32_e32 v22, 16, v181
	v_and_b32_e32 v23, 0xffff0000, v181
	v_lshlrev_b32_e32 v16, 16, v150
	v_and_b32_e32 v17, 0xffff0000, v150
	v_lshlrev_b32_e32 v24, 16, v182
	v_and_b32_e32 v25, 0xffff0000, v182
	v_lshlrev_b32_e32 v18, 16, v151
	v_and_b32_e32 v19, 0xffff0000, v151
	v_lshlrev_b32_e32 v26, 16, v183
	v_and_b32_e32 v27, 0xffff0000, v183
	v_cmp_ge_u32_e32 vcc, 13, v2
	s_nop 1
	v_cndmask_b32_e64 v44, 0, 1.0, vcc
	v_pk_fma_f32 v[20:21], v[44:45], v[20:21], v[12:13] op_sel_hi:[0,1,1] neg_lo:[1,0,0] neg_hi:[1,0,0]
	v_pk_fma_f32 v[22:23], v[44:45], v[22:23], v[14:15] op_sel_hi:[0,1,1] neg_lo:[1,0,0] neg_hi:[1,0,0]
	v_pk_fma_f32 v[24:25], v[44:45], v[24:25], v[16:17] op_sel_hi:[0,1,1] neg_lo:[1,0,0] neg_hi:[1,0,0]
	v_pk_fma_f32 v[26:27], v[44:45], v[26:27], v[18:19] op_sel_hi:[0,1,1] neg_lo:[1,0,0] neg_hi:[1,0,0]
	v_pk_add_f32 v[4:5], v[4:5], v[20:21]
	v_pk_add_f32 v[6:7], v[6:7], v[22:23]
	v_pk_add_f32 v[8:9], v[8:9], v[24:25]
	v_pk_add_f32 v[10:11], v[10:11], v[26:27]
	v_max_f32_e32 v46, 0x3d924925, v3
	v_pk_fma_f32 v[28:29], v[46:47], v[4:5], v[12:13] op_sel_hi:[0,1,1] neg_lo:[0,0,1] neg_hi:[0,0,1]
	v_pk_fma_f32 v[30:31], v[46:47], v[6:7], v[14:15] op_sel_hi:[0,1,1] neg_lo:[0,0,1] neg_hi:[0,0,1]
	v_pk_fma_f32 v[32:33], v[46:47], v[8:9], v[16:17] op_sel_hi:[0,1,1] neg_lo:[0,0,1] neg_hi:[0,0,1]
	v_pk_fma_f32 v[34:35], v[46:47], v[10:11], v[18:19] op_sel_hi:[0,1,1] neg_lo:[0,0,1] neg_hi:[0,0,1]
	v_cvt_pk_bf16_f32 v40, v28, v29
	v_cvt_pk_bf16_f32 v41, v30, v31
	v_cvt_pk_bf16_f32 v42, v32, v33
	v_cvt_pk_bf16_f32 v43, v34, v35
	global_store_dwordx4 v1, v[40:43], s[24:25]
	s_add_u32 s24, s24, 0x2000
	s_addc_u32 s25, s25, 0
	v_lshlrev_b32_e32 v12, 16, v152
	v_and_b32_e32 v13, 0xffff0000, v152
	v_lshlrev_b32_e32 v20, 16, v184
	v_and_b32_e32 v21, 0xffff0000, v184
	v_lshlrev_b32_e32 v14, 16, v153
	v_and_b32_e32 v15, 0xffff0000, v153
	v_lshlrev_b32_e32 v22, 16, v185
	v_and_b32_e32 v23, 0xffff0000, v185
	v_lshlrev_b32_e32 v16, 16, v154
	v_and_b32_e32 v17, 0xffff0000, v154
	v_lshlrev_b32_e32 v24, 16, v186
	v_and_b32_e32 v25, 0xffff0000, v186
	v_lshlrev_b32_e32 v18, 16, v155
	v_and_b32_e32 v19, 0xffff0000, v155
	v_lshlrev_b32_e32 v26, 16, v187
	v_and_b32_e32 v27, 0xffff0000, v187
	v_cmp_ge_u32_e32 vcc, 14, v2
	s_nop 1
	v_cndmask_b32_e64 v44, 0, 1.0, vcc
	v_pk_fma_f32 v[20:21], v[44:45], v[20:21], v[12:13] op_sel_hi:[0,1,1] neg_lo:[1,0,0] neg_hi:[1,0,0]
	v_pk_fma_f32 v[22:23], v[44:45], v[22:23], v[14:15] op_sel_hi:[0,1,1] neg_lo:[1,0,0] neg_hi:[1,0,0]
	v_pk_fma_f32 v[24:25], v[44:45], v[24:25], v[16:17] op_sel_hi:[0,1,1] neg_lo:[1,0,0] neg_hi:[1,0,0]
	v_pk_fma_f32 v[26:27], v[44:45], v[26:27], v[18:19] op_sel_hi:[0,1,1] neg_lo:[1,0,0] neg_hi:[1,0,0]
	v_pk_add_f32 v[4:5], v[4:5], v[20:21]
	v_pk_add_f32 v[6:7], v[6:7], v[22:23]
	v_pk_add_f32 v[8:9], v[8:9], v[24:25]
	v_pk_add_f32 v[10:11], v[10:11], v[26:27]
	v_max_f32_e32 v46, 0x3d888889, v3
	v_pk_fma_f32 v[28:29], v[46:47], v[4:5], v[12:13] op_sel_hi:[0,1,1] neg_lo:[0,0,1] neg_hi:[0,0,1]
	v_pk_fma_f32 v[30:31], v[46:47], v[6:7], v[14:15] op_sel_hi:[0,1,1] neg_lo:[0,0,1] neg_hi:[0,0,1]
	v_pk_fma_f32 v[32:33], v[46:47], v[8:9], v[16:17] op_sel_hi:[0,1,1] neg_lo:[0,0,1] neg_hi:[0,0,1]
	v_pk_fma_f32 v[34:35], v[46:47], v[10:11], v[18:19] op_sel_hi:[0,1,1] neg_lo:[0,0,1] neg_hi:[0,0,1]
	v_cvt_pk_bf16_f32 v36, v28, v29
	v_cvt_pk_bf16_f32 v37, v30, v31
	v_cvt_pk_bf16_f32 v38, v32, v33
	v_cvt_pk_bf16_f32 v39, v34, v35
	global_store_dwordx4 v1, v[36:39], s[24:25]
	s_add_u32 s24, s24, 0x2000
	s_addc_u32 s25, s25, 0
	v_lshlrev_b32_e32 v12, 16, v156
	v_and_b32_e32 v13, 0xffff0000, v156
	v_lshlrev_b32_e32 v20, 16, v188
	v_and_b32_e32 v21, 0xffff0000, v188
	v_lshlrev_b32_e32 v14, 16, v157
	v_and_b32_e32 v15, 0xffff0000, v157
	v_lshlrev_b32_e32 v22, 16, v189
	v_and_b32_e32 v23, 0xffff0000, v189
	v_lshlrev_b32_e32 v16, 16, v158
	v_and_b32_e32 v17, 0xffff0000, v158
	v_lshlrev_b32_e32 v24, 16, v190
	v_and_b32_e32 v25, 0xffff0000, v190
	v_lshlrev_b32_e32 v18, 16, v159
	v_and_b32_e32 v19, 0xffff0000, v159
	v_lshlrev_b32_e32 v26, 16, v191
	v_and_b32_e32 v27, 0xffff0000, v191
	v_cmp_ge_u32_e32 vcc, 15, v2
	s_nop 1
	v_cndmask_b32_e64 v44, 0, 1.0, vcc
	v_pk_fma_f32 v[20:21], v[44:45], v[20:21], v[12:13] op_sel_hi:[0,1,1] neg_lo:[1,0,0] neg_hi:[1,0,0]
	v_pk_fma_f32 v[22:23], v[44:45], v[22:23], v[14:15] op_sel_hi:[0,1,1] neg_lo:[1,0,0] neg_hi:[1,0,0]
	v_pk_fma_f32 v[24:25], v[44:45], v[24:25], v[16:17] op_sel_hi:[0,1,1] neg_lo:[1,0,0] neg_hi:[1,0,0]
	v_pk_fma_f32 v[26:27], v[44:45], v[26:27], v[18:19] op_sel_hi:[0,1,1] neg_lo:[1,0,0] neg_hi:[1,0,0]
	v_pk_add_f32 v[4:5], v[4:5], v[20:21]
	v_pk_add_f32 v[6:7], v[6:7], v[22:23]
	v_pk_add_f32 v[8:9], v[8:9], v[24:25]
	v_pk_add_f32 v[10:11], v[10:11], v[26:27]
	v_max_f32_e32 v46, 0x3d800000, v3
	v_pk_fma_f32 v[28:29], v[46:47], v[4:5], v[12:13] op_sel_hi:[0,1,1] neg_lo:[0,0,1] neg_hi:[0,0,1]
	v_pk_fma_f32 v[30:31], v[46:47], v[6:7], v[14:15] op_sel_hi:[0,1,1] neg_lo:[0,0,1] neg_hi:[0,0,1]
	v_pk_fma_f32 v[32:33], v[46:47], v[8:9], v[16:17] op_sel_hi:[0,1,1] neg_lo:[0,0,1] neg_hi:[0,0,1]
	v_pk_fma_f32 v[34:35], v[46:47], v[10:11], v[18:19] op_sel_hi:[0,1,1] neg_lo:[0,0,1] neg_hi:[0,0,1]
	v_cvt_pk_bf16_f32 v40, v28, v29
	v_cvt_pk_bf16_f32 v41, v30, v31
	v_cvt_pk_bf16_f32 v42, v32, v33
	v_cvt_pk_bf16_f32 v43, v34, v35
	global_store_dwordx4 v1, v[40:43], s[24:25]
	s_add_u32 s24, s24, 0x2000
	s_addc_u32 s25, s25, 0
	global_load_dwordx4 v[128:131], v1, s[20:21]
	global_load_dwordx4 v[160:163], v49, s[22:23]
	s_add_u32 s20, s20, 0x2000
	s_addc_u32 s21, s21, 0
	s_add_u32 s22, s22, 0x2000
	s_addc_u32 s23, s23, 0
	global_load_dwordx4 v[132:135], v1, s[20:21]
	global_load_dwordx4 v[164:167], v49, s[22:23]
	s_add_u32 s20, s20, 0x2000
	s_addc_u32 s21, s21, 0
	s_add_u32 s22, s22, 0x2000
	s_addc_u32 s23, s23, 0
	global_load_dwordx4 v[136:139], v1, s[20:21]
	global_load_dwordx4 v[168:171], v49, s[22:23]
	s_add_u32 s20, s20, 0x2000
	s_addc_u32 s21, s21, 0
	s_add_u32 s22, s22, 0x2000
	s_addc_u32 s23, s23, 0
	global_load_dwordx4 v[140:143], v1, s[20:21]
	global_load_dwordx4 v[172:175], v49, s[22:23]
	s_add_u32 s20, s20, 0x2000
	s_addc_u32 s21, s21, 0
	s_add_u32 s22, s22, 0x2000
	s_addc_u32 s23, s23, 0
	global_load_dwordx4 v[144:147], v1, s[20:21]
	global_load_dwordx4 v[176:179], v49, s[22:23]
	s_add_u32 s20, s20, 0x2000
	s_addc_u32 s21, s21, 0
	s_add_u32 s22, s22, 0x2000
	s_addc_u32 s23, s23, 0
	global_load_dwordx4 v[148:151], v1, s[20:21]
	global_load_dwordx4 v[180:183], v49, s[22:23]
	s_add_u32 s20, s20, 0x2000
	s_addc_u32 s21, s21, 0
	s_add_u32 s22, s22, 0x2000
	s_addc_u32 s23, s23, 0
	global_load_dwordx4 v[152:155], v1, s[20:21]
	global_load_dwordx4 v[184:187], v49, s[22:23]
	s_add_u32 s20, s20, 0x2000
	s_addc_u32 s21, s21, 0
	s_add_u32 s22, s22, 0x2000
	s_addc_u32 s23, s23, 0
	global_load_dwordx4 v[156:159], v1, s[20:21]
	global_load_dwordx4 v[188:191], v49, s[22:23]
	s_add_u32 s20, s20, 0x2000
	s_addc_u32 s21, s21, 0
	s_add_u32 s22, s22, 0x2000
	s_addc_u32 s23, s23, 0
	s_waitcnt vmcnt(24)
	v_mov_b32_e32 v44, 1.0
	v_lshlrev_b32_e32 v12, 16, v64
	v_and_b32_e32 v13, 0xffff0000, v64
	v_lshlrev_b32_e32 v20, 16, v96
	v_and_b32_e32 v21, 0xffff0000, v96
	v_lshlrev_b32_e32 v14, 16, v65
	v_and_b32_e32 v15, 0xffff0000, v65
	v_lshlrev_b32_e32 v22, 16, v97
	v_and_b32_e32 v23, 0xffff0000, v97
	v_lshlrev_b32_e32 v16, 16, v66
	v_and_b32_e32 v17, 0xffff0000, v66
	v_lshlrev_b32_e32 v24, 16, v98
	v_and_b32_e32 v25, 0xffff0000, v98
	v_lshlrev_b32_e32 v18, 16, v67
	v_and_b32_e32 v19, 0xffff0000, v67
	v_lshlrev_b32_e32 v26, 16, v99
	v_and_b32_e32 v27, 0xffff0000, v99
	v_pk_fma_f32 v[20:21], v[44:45], v[20:21], v[12:13] op_sel_hi:[0,1,1] neg_lo:[1,0,0] neg_hi:[1,0,0]
	v_pk_fma_f32 v[22:23], v[44:45], v[22:23], v[14:15] op_sel_hi:[0,1,1] neg_lo:[1,0,0] neg_hi:[1,0,0]
	v_pk_fma_f32 v[24:25], v[44:45], v[24:25], v[16:17] op_sel_hi:[0,1,1] neg_lo:[1,0,0] neg_hi:[1,0,0]
	v_pk_fma_f32 v[26:27], v[44:45], v[26:27], v[18:19] op_sel_hi:[0,1,1] neg_lo:[1,0,0] neg_hi:[1,0,0]
	v_pk_add_f32 v[4:5], v[4:5], v[20:21]
	v_pk_add_f32 v[6:7], v[6:7], v[22:23]
	v_pk_add_f32 v[8:9], v[8:9], v[24:25]
	v_pk_add_f32 v[10:11], v[10:11], v[26:27]
	v_mov_b32_e32 v46, v3
	v_pk_fma_f32 v[28:29], v[46:47], v[4:5], v[12:13] op_sel_hi:[0,1,1] neg_lo:[0,0,1] neg_hi:[0,0,1]
	v_pk_fma_f32 v[30:31], v[46:47], v[6:7], v[14:15] op_sel_hi:[0,1,1] neg_lo:[0,0,1] neg_hi:[0,0,1]
	v_pk_fma_f32 v[32:33], v[46:47], v[8:9], v[16:17] op_sel_hi:[0,1,1] neg_lo:[0,0,1] neg_hi:[0,0,1]
	v_pk_fma_f32 v[34:35], v[46:47], v[10:11], v[18:19] op_sel_hi:[0,1,1] neg_lo:[0,0,1] neg_hi:[0,0,1]
	v_cvt_pk_bf16_f32 v36, v28, v29
	v_cvt_pk_bf16_f32 v37, v30, v31
	v_cvt_pk_bf16_f32 v38, v32, v33
	v_cvt_pk_bf16_f32 v39, v34, v35
	global_store_dwordx4 v1, v[36:39], s[24:25]
	s_add_u32 s24, s24, 0x2000
	s_addc_u32 s25, s25, 0
	v_lshlrev_b32_e32 v12, 16, v68
	v_and_b32_e32 v13, 0xffff0000, v68
	v_lshlrev_b32_e32 v20, 16, v100
	v_and_b32_e32 v21, 0xffff0000, v100
	v_lshlrev_b32_e32 v14, 16, v69
	v_and_b32_e32 v15, 0xffff0000, v69
	v_lshlrev_b32_e32 v22, 16, v101
	v_and_b32_e32 v23, 0xffff0000, v101
	v_lshlrev_b32_e32 v16, 16, v70
	v_and_b32_e32 v17, 0xffff0000, v70
	v_lshlrev_b32_e32 v24, 16, v102
	v_and_b32_e32 v25, 0xffff0000, v102
	v_lshlrev_b32_e32 v18, 16, v71
	v_and_b32_e32 v19, 0xffff0000, v71
	v_lshlrev_b32_e32 v26, 16, v103
	v_and_b32_e32 v27, 0xffff0000, v103
	v_pk_fma_f32 v[20:21], v[44:45], v[20:21], v[12:13] op_sel_hi:[0,1,1] neg_lo:[1,0,0] neg_hi:[1,0,0]
	v_pk_fma_f32 v[22:23], v[44:45], v[22:23], v[14:15] op_sel_hi:[0,1,1] neg_lo:[1,0,0] neg_hi:[1,0,0]
	v_pk_fma_f32 v[24:25], v[44:45], v[24:25], v[16:17] op_sel_hi:[0,1,1] neg_lo:[1,0,0] neg_hi:[1,0,0]
	v_pk_fma_f32 v[26:27], v[44:45], v[26:27], v[18:19] op_sel_hi:[0,1,1] neg_lo:[1,0,0] neg_hi:[1,0,0]
	v_pk_add_f32 v[4:5], v[4:5], v[20:21]
	v_pk_add_f32 v[6:7], v[6:7], v[22:23]
	v_pk_add_f32 v[8:9], v[8:9], v[24:25]
	v_pk_add_f32 v[10:11], v[10:11], v[26:27]
	v_mov_b32_e32 v46, v3
	v_pk_fma_f32 v[28:29], v[46:47], v[4:5], v[12:13] op_sel_hi:[0,1,1] neg_lo:[0,0,1] neg_hi:[0,0,1]
	v_pk_fma_f32 v[30:31], v[46:47], v[6:7], v[14:15] op_sel_hi:[0,1,1] neg_lo:[0,0,1] neg_hi:[0,0,1]
	v_pk_fma_f32 v[32:33], v[46:47], v[8:9], v[16:17] op_sel_hi:[0,1,1] neg_lo:[0,0,1] neg_hi:[0,0,1]
	v_pk_fma_f32 v[34:35], v[46:47], v[10:11], v[18:19] op_sel_hi:[0,1,1] neg_lo:[0,0,1] neg_hi:[0,0,1]
	v_cvt_pk_bf16_f32 v40, v28, v29
	v_cvt_pk_bf16_f32 v41, v30, v31
	v_cvt_pk_bf16_f32 v42, v32, v33
	v_cvt_pk_bf16_f32 v43, v34, v35
	global_store_dwordx4 v1, v[40:43], s[24:25]
	s_add_u32 s24, s24, 0x2000
	s_addc_u32 s25, s25, 0
	v_lshlrev_b32_e32 v12, 16, v72
	v_and_b32_e32 v13, 0xffff0000, v72
	v_lshlrev_b32_e32 v20, 16, v104
	v_and_b32_e32 v21, 0xffff0000, v104
	v_lshlrev_b32_e32 v14, 16, v73
	v_and_b32_e32 v15, 0xffff0000, v73
	v_lshlrev_b32_e32 v22, 16, v105
	v_and_b32_e32 v23, 0xffff0000, v105
	v_lshlrev_b32_e32 v16, 16, v74
	v_and_b32_e32 v17, 0xffff0000, v74
	v_lshlrev_b32_e32 v24, 16, v106
	v_and_b32_e32 v25, 0xffff0000, v106
	v_lshlrev_b32_e32 v18, 16, v75
	v_and_b32_e32 v19, 0xffff0000, v75
	v_lshlrev_b32_e32 v26, 16, v107
	v_and_b32_e32 v27, 0xffff0000, v107
	v_pk_fma_f32 v[20:21], v[44:45], v[20:21], v[12:13] op_sel_hi:[0,1,1] neg_lo:[1,0,0] neg_hi:[1,0,0]
	v_pk_fma_f32 v[22:23], v[44:45], v[22:23], v[14:15] op_sel_hi:[0,1,1] neg_lo:[1,0,0] neg_hi:[1,0,0]
	v_pk_fma_f32 v[24:25], v[44:45], v[24:25], v[16:17] op_sel_hi:[0,1,1] neg_lo:[1,0,0] neg_hi:[1,0,0]
	v_pk_fma_f32 v[26:27], v[44:45], v[26:27], v[18:19] op_sel_hi:[0,1,1] neg_lo:[1,0,0] neg_hi:[1,0,0]
	v_pk_add_f32 v[4:5], v[4:5], v[20:21]
	v_pk_add_f32 v[6:7], v[6:7], v[22:23]
	v_pk_add_f32 v[8:9], v[8:9], v[24:25]
	v_pk_add_f32 v[10:11], v[10:11], v[26:27]
	v_mov_b32_e32 v46, v3
	v_pk_fma_f32 v[28:29], v[46:47], v[4:5], v[12:13] op_sel_hi:[0,1,1] neg_lo:[0,0,1] neg_hi:[0,0,1]
	v_pk_fma_f32 v[30:31], v[46:47], v[6:7], v[14:15] op_sel_hi:[0,1,1] neg_lo:[0,0,1] neg_hi:[0,0,1]
	v_pk_fma_f32 v[32:33], v[46:47], v[8:9], v[16:17] op_sel_hi:[0,1,1] neg_lo:[0,0,1] neg_hi:[0,0,1]
	v_pk_fma_f32 v[34:35], v[46:47], v[10:11], v[18:19] op_sel_hi:[0,1,1] neg_lo:[0,0,1] neg_hi:[0,0,1]
	v_cvt_pk_bf16_f32 v36, v28, v29
	v_cvt_pk_bf16_f32 v37, v30, v31
	v_cvt_pk_bf16_f32 v38, v32, v33
	v_cvt_pk_bf16_f32 v39, v34, v35
	global_store_dwordx4 v1, v[36:39], s[24:25]
	s_add_u32 s24, s24, 0x2000
	s_addc_u32 s25, s25, 0
	v_lshlrev_b32_e32 v12, 16, v76
	v_and_b32_e32 v13, 0xffff0000, v76
	v_lshlrev_b32_e32 v20, 16, v108
	v_and_b32_e32 v21, 0xffff0000, v108
	v_lshlrev_b32_e32 v14, 16, v77
	v_and_b32_e32 v15, 0xffff0000, v77
	v_lshlrev_b32_e32 v22, 16, v109
	v_and_b32_e32 v23, 0xffff0000, v109
	v_lshlrev_b32_e32 v16, 16, v78
	v_and_b32_e32 v17, 0xffff0000, v78
	v_lshlrev_b32_e32 v24, 16, v110
	v_and_b32_e32 v25, 0xffff0000, v110
	v_lshlrev_b32_e32 v18, 16, v79
	v_and_b32_e32 v19, 0xffff0000, v79
	v_lshlrev_b32_e32 v26, 16, v111
	v_and_b32_e32 v27, 0xffff0000, v111
	v_pk_fma_f32 v[20:21], v[44:45], v[20:21], v[12:13] op_sel_hi:[0,1,1] neg_lo:[1,0,0] neg_hi:[1,0,0]
	v_pk_fma_f32 v[22:23], v[44:45], v[22:23], v[14:15] op_sel_hi:[0,1,1] neg_lo:[1,0,0] neg_hi:[1,0,0]
	v_pk_fma_f32 v[24:25], v[44:45], v[24:25], v[16:17] op_sel_hi:[0,1,1] neg_lo:[1,0,0] neg_hi:[1,0,0]
	v_pk_fma_f32 v[26:27], v[44:45], v[26:27], v[18:19] op_sel_hi:[0,1,1] neg_lo:[1,0,0] neg_hi:[1,0,0]
	v_pk_add_f32 v[4:5], v[4:5], v[20:21]
	v_pk_add_f32 v[6:7], v[6:7], v[22:23]
	v_pk_add_f32 v[8:9], v[8:9], v[24:25]
	v_pk_add_f32 v[10:11], v[10:11], v[26:27]
	v_mov_b32_e32 v46, v3
	v_pk_fma_f32 v[28:29], v[46:47], v[4:5], v[12:13] op_sel_hi:[0,1,1] neg_lo:[0,0,1] neg_hi:[0,0,1]
	v_pk_fma_f32 v[30:31], v[46:47], v[6:7], v[14:15] op_sel_hi:[0,1,1] neg_lo:[0,0,1] neg_hi:[0,0,1]
	v_pk_fma_f32 v[32:33], v[46:47], v[8:9], v[16:17] op_sel_hi:[0,1,1] neg_lo:[0,0,1] neg_hi:[0,0,1]
	v_pk_fma_f32 v[34:35], v[46:47], v[10:11], v[18:19] op_sel_hi:[0,1,1] neg_lo:[0,0,1] neg_hi:[0,0,1]
	v_cvt_pk_bf16_f32 v40, v28, v29
	v_cvt_pk_bf16_f32 v41, v30, v31
	v_cvt_pk_bf16_f32 v42, v32, v33
	v_cvt_pk_bf16_f32 v43, v34, v35
	global_store_dwordx4 v1, v[40:43], s[24:25]
	s_add_u32 s24, s24, 0x2000
	s_addc_u32 s25, s25, 0
	v_lshlrev_b32_e32 v12, 16, v80
	v_and_b32_e32 v13, 0xffff0000, v80
	v_lshlrev_b32_e32 v20, 16, v112
	v_and_b32_e32 v21, 0xffff0000, v112
	v_lshlrev_b32_e32 v14, 16, v81
	v_and_b32_e32 v15, 0xffff0000, v81
	v_lshlrev_b32_e32 v22, 16, v113
	v_and_b32_e32 v23, 0xffff0000, v113
	v_lshlrev_b32_e32 v16, 16, v82
	v_and_b32_e32 v17, 0xffff0000, v82
	v_lshlrev_b32_e32 v24, 16, v114
	v_and_b32_e32 v25, 0xffff0000, v114
	v_lshlrev_b32_e32 v18, 16, v83
	v_and_b32_e32 v19, 0xffff0000, v83
	v_lshlrev_b32_e32 v26, 16, v115
	v_and_b32_e32 v27, 0xffff0000, v115
	v_pk_fma_f32 v[20:21], v[44:45], v[20:21], v[12:13] op_sel_hi:[0,1,1] neg_lo:[1,0,0] neg_hi:[1,0,0]
	v_pk_fma_f32 v[22:23], v[44:45], v[22:23], v[14:15] op_sel_hi:[0,1,1] neg_lo:[1,0,0] neg_hi:[1,0,0]
	v_pk_fma_f32 v[24:25], v[44:45], v[24:25], v[16:17] op_sel_hi:[0,1,1] neg_lo:[1,0,0] neg_hi:[1,0,0]
	v_pk_fma_f32 v[26:27], v[44:45], v[26:27], v[18:19] op_sel_hi:[0,1,1] neg_lo:[1,0,0] neg_hi:[1,0,0]
	v_pk_add_f32 v[4:5], v[4:5], v[20:21]
	v_pk_add_f32 v[6:7], v[6:7], v[22:23]
	v_pk_add_f32 v[8:9], v[8:9], v[24:25]
	v_pk_add_f32 v[10:11], v[10:11], v[26:27]
	v_mov_b32_e32 v46, v3
	v_pk_fma_f32 v[28:29], v[46:47], v[4:5], v[12:13] op_sel_hi:[0,1,1] neg_lo:[0,0,1] neg_hi:[0,0,1]
	v_pk_fma_f32 v[30:31], v[46:47], v[6:7], v[14:15] op_sel_hi:[0,1,1] neg_lo:[0,0,1] neg_hi:[0,0,1]
	v_pk_fma_f32 v[32:33], v[46:47], v[8:9], v[16:17] op_sel_hi:[0,1,1] neg_lo:[0,0,1] neg_hi:[0,0,1]
	v_pk_fma_f32 v[34:35], v[46:47], v[10:11], v[18:19] op_sel_hi:[0,1,1] neg_lo:[0,0,1] neg_hi:[0,0,1]
	v_cvt_pk_bf16_f32 v36, v28, v29
	v_cvt_pk_bf16_f32 v37, v30, v31
	v_cvt_pk_bf16_f32 v38, v32, v33
	v_cvt_pk_bf16_f32 v39, v34, v35
	global_store_dwordx4 v1, v[36:39], s[24:25]
	s_add_u32 s24, s24, 0x2000
	s_addc_u32 s25, s25, 0
	v_lshlrev_b32_e32 v12, 16, v84
	v_and_b32_e32 v13, 0xffff0000, v84
	v_lshlrev_b32_e32 v20, 16, v116
	v_and_b32_e32 v21, 0xffff0000, v116
	v_lshlrev_b32_e32 v14, 16, v85
	v_and_b32_e32 v15, 0xffff0000, v85
	v_lshlrev_b32_e32 v22, 16, v117
	v_and_b32_e32 v23, 0xffff0000, v117
	v_lshlrev_b32_e32 v16, 16, v86
	v_and_b32_e32 v17, 0xffff0000, v86
	v_lshlrev_b32_e32 v24, 16, v118
	v_and_b32_e32 v25, 0xffff0000, v118
	v_lshlrev_b32_e32 v18, 16, v87
	v_and_b32_e32 v19, 0xffff0000, v87
	v_lshlrev_b32_e32 v26, 16, v119
	v_and_b32_e32 v27, 0xffff0000, v119
	v_pk_fma_f32 v[20:21], v[44:45], v[20:21], v[12:13] op_sel_hi:[0,1,1] neg_lo:[1,0,0] neg_hi:[1,0,0]
	v_pk_fma_f32 v[22:23], v[44:45], v[22:23], v[14:15] op_sel_hi:[0,1,1] neg_lo:[1,0,0] neg_hi:[1,0,0]
	v_pk_fma_f32 v[24:25], v[44:45], v[24:25], v[16:17] op_sel_hi:[0,1,1] neg_lo:[1,0,0] neg_hi:[1,0,0]
	v_pk_fma_f32 v[26:27], v[44:45], v[26:27], v[18:19] op_sel_hi:[0,1,1] neg_lo:[1,0,0] neg_hi:[1,0,0]
	v_pk_add_f32 v[4:5], v[4:5], v[20:21]
	v_pk_add_f32 v[6:7], v[6:7], v[22:23]
	v_pk_add_f32 v[8:9], v[8:9], v[24:25]
	v_pk_add_f32 v[10:11], v[10:11], v[26:27]
	v_mov_b32_e32 v46, v3
	v_pk_fma_f32 v[28:29], v[46:47], v[4:5], v[12:13] op_sel_hi:[0,1,1] neg_lo:[0,0,1] neg_hi:[0,0,1]
	v_pk_fma_f32 v[30:31], v[46:47], v[6:7], v[14:15] op_sel_hi:[0,1,1] neg_lo:[0,0,1] neg_hi:[0,0,1]
	v_pk_fma_f32 v[32:33], v[46:47], v[8:9], v[16:17] op_sel_hi:[0,1,1] neg_lo:[0,0,1] neg_hi:[0,0,1]
	v_pk_fma_f32 v[34:35], v[46:47], v[10:11], v[18:19] op_sel_hi:[0,1,1] neg_lo:[0,0,1] neg_hi:[0,0,1]
	v_cvt_pk_bf16_f32 v40, v28, v29
	v_cvt_pk_bf16_f32 v41, v30, v31
	v_cvt_pk_bf16_f32 v42, v32, v33
	v_cvt_pk_bf16_f32 v43, v34, v35
	global_store_dwordx4 v1, v[40:43], s[24:25]
	s_add_u32 s24, s24, 0x2000
	s_addc_u32 s25, s25, 0
	v_lshlrev_b32_e32 v12, 16, v88
	v_and_b32_e32 v13, 0xffff0000, v88
	v_lshlrev_b32_e32 v20, 16, v120
	v_and_b32_e32 v21, 0xffff0000, v120
	v_lshlrev_b32_e32 v14, 16, v89
	v_and_b32_e32 v15, 0xffff0000, v89
	v_lshlrev_b32_e32 v22, 16, v121
	v_and_b32_e32 v23, 0xffff0000, v121
	v_lshlrev_b32_e32 v16, 16, v90
	v_and_b32_e32 v17, 0xffff0000, v90
	v_lshlrev_b32_e32 v24, 16, v122
	v_and_b32_e32 v25, 0xffff0000, v122
	v_lshlrev_b32_e32 v18, 16, v91
	v_and_b32_e32 v19, 0xffff0000, v91
	v_lshlrev_b32_e32 v26, 16, v123
	v_and_b32_e32 v27, 0xffff0000, v123
	v_pk_fma_f32 v[20:21], v[44:45], v[20:21], v[12:13] op_sel_hi:[0,1,1] neg_lo:[1,0,0] neg_hi:[1,0,0]
	v_pk_fma_f32 v[22:23], v[44:45], v[22:23], v[14:15] op_sel_hi:[0,1,1] neg_lo:[1,0,0] neg_hi:[1,0,0]
	v_pk_fma_f32 v[24:25], v[44:45], v[24:25], v[16:17] op_sel_hi:[0,1,1] neg_lo:[1,0,0] neg_hi:[1,0,0]
	v_pk_fma_f32 v[26:27], v[44:45], v[26:27], v[18:19] op_sel_hi:[0,1,1] neg_lo:[1,0,0] neg_hi:[1,0,0]
	v_pk_add_f32 v[4:5], v[4:5], v[20:21]
	v_pk_add_f32 v[6:7], v[6:7], v[22:23]
	v_pk_add_f32 v[8:9], v[8:9], v[24:25]
	v_pk_add_f32 v[10:11], v[10:11], v[26:27]
	v_mov_b32_e32 v46, v3
	v_pk_fma_f32 v[28:29], v[46:47], v[4:5], v[12:13] op_sel_hi:[0,1,1] neg_lo:[0,0,1] neg_hi:[0,0,1]
	v_pk_fma_f32 v[30:31], v[46:47], v[6:7], v[14:15] op_sel_hi:[0,1,1] neg_lo:[0,0,1] neg_hi:[0,0,1]
	v_pk_fma_f32 v[32:33], v[46:47], v[8:9], v[16:17] op_sel_hi:[0,1,1] neg_lo:[0,0,1] neg_hi:[0,0,1]
	v_pk_fma_f32 v[34:35], v[46:47], v[10:11], v[18:19] op_sel_hi:[0,1,1] neg_lo:[0,0,1] neg_hi:[0,0,1]
	v_cvt_pk_bf16_f32 v36, v28, v29
	v_cvt_pk_bf16_f32 v37, v30, v31
	v_cvt_pk_bf16_f32 v38, v32, v33
	v_cvt_pk_bf16_f32 v39, v34, v35
	global_store_dwordx4 v1, v[36:39], s[24:25]
	s_add_u32 s24, s24, 0x2000
	s_addc_u32 s25, s25, 0
	v_lshlrev_b32_e32 v12, 16, v92
	v_and_b32_e32 v13, 0xffff0000, v92
	v_lshlrev_b32_e32 v20, 16, v124
	v_and_b32_e32 v21, 0xffff0000, v124
	v_lshlrev_b32_e32 v14, 16, v93
	v_and_b32_e32 v15, 0xffff0000, v93
	v_lshlrev_b32_e32 v22, 16, v125
	v_and_b32_e32 v23, 0xffff0000, v125
	v_lshlrev_b32_e32 v16, 16, v94
	v_and_b32_e32 v17, 0xffff0000, v94
	v_lshlrev_b32_e32 v24, 16, v126
	v_and_b32_e32 v25, 0xffff0000, v126
	v_lshlrev_b32_e32 v18, 16, v95
	v_and_b32_e32 v19, 0xffff0000, v95
	v_lshlrev_b32_e32 v26, 16, v127
	v_and_b32_e32 v27, 0xffff0000, v127
	v_pk_fma_f32 v[20:21], v[44:45], v[20:21], v[12:13] op_sel_hi:[0,1,1] neg_lo:[1,0,0] neg_hi:[1,0,0]
	v_pk_fma_f32 v[22:23], v[44:45], v[22:23], v[14:15] op_sel_hi:[0,1,1] neg_lo:[1,0,0] neg_hi:[1,0,0]
	v_pk_fma_f32 v[24:25], v[44:45], v[24:25], v[16:17] op_sel_hi:[0,1,1] neg_lo:[1,0,0] neg_hi:[1,0,0]
	v_pk_fma_f32 v[26:27], v[44:45], v[26:27], v[18:19] op_sel_hi:[0,1,1] neg_lo:[1,0,0] neg_hi:[1,0,0]
	v_pk_add_f32 v[4:5], v[4:5], v[20:21]
	v_pk_add_f32 v[6:7], v[6:7], v[22:23]
	v_pk_add_f32 v[8:9], v[8:9], v[24:25]
	v_pk_add_f32 v[10:11], v[10:11], v[26:27]
	v_mov_b32_e32 v46, v3
	v_pk_fma_f32 v[28:29], v[46:47], v[4:5], v[12:13] op_sel_hi:[0,1,1] neg_lo:[0,0,1] neg_hi:[0,0,1]
	v_pk_fma_f32 v[30:31], v[46:47], v[6:7], v[14:15] op_sel_hi:[0,1,1] neg_lo:[0,0,1] neg_hi:[0,0,1]
	v_pk_fma_f32 v[32:33], v[46:47], v[8:9], v[16:17] op_sel_hi:[0,1,1] neg_lo:[0,0,1] neg_hi:[0,0,1]
	v_pk_fma_f32 v[34:35], v[46:47], v[10:11], v[18:19] op_sel_hi:[0,1,1] neg_lo:[0,0,1] neg_hi:[0,0,1]
	v_cvt_pk_bf16_f32 v40, v28, v29
	v_cvt_pk_bf16_f32 v41, v30, v31
	v_cvt_pk_bf16_f32 v42, v32, v33
	v_cvt_pk_bf16_f32 v43, v34, v35
	global_store_dwordx4 v1, v[40:43], s[24:25]
	s_add_u32 s24, s24, 0x2000
	s_addc_u32 s25, s25, 0
	global_load_dwordx4 v[64:67], v1, s[20:21]
	global_load_dwordx4 v[96:99], v49, s[22:23]
	s_add_u32 s20, s20, 0x2000
	s_addc_u32 s21, s21, 0
	s_add_u32 s22, s22, 0x2000
	s_addc_u32 s23, s23, 0
	global_load_dwordx4 v[68:71], v1, s[20:21]
	global_load_dwordx4 v[100:103], v49, s[22:23]
	s_add_u32 s20, s20, 0x2000
	s_addc_u32 s21, s21, 0
	s_add_u32 s22, s22, 0x2000
	s_addc_u32 s23, s23, 0
	global_load_dwordx4 v[72:75], v1, s[20:21]
	global_load_dwordx4 v[104:107], v49, s[22:23]
	s_add_u32 s20, s20, 0x2000
	s_addc_u32 s21, s21, 0
	s_add_u32 s22, s22, 0x2000
	s_addc_u32 s23, s23, 0
	global_load_dwordx4 v[76:79], v1, s[20:21]
	global_load_dwordx4 v[108:111], v49, s[22:23]
	s_add_u32 s20, s20, 0x2000
	s_addc_u32 s21, s21, 0
	s_add_u32 s22, s22, 0x2000
	s_addc_u32 s23, s23, 0
	global_load_dwordx4 v[80:83], v1, s[20:21]
	global_load_dwordx4 v[112:115], v49, s[22:23]
	s_add_u32 s20, s20, 0x2000
	s_addc_u32 s21, s21, 0
	s_add_u32 s22, s22, 0x2000
	s_addc_u32 s23, s23, 0
	global_load_dwordx4 v[84:87], v1, s[20:21]
	global_load_dwordx4 v[116:119], v49, s[22:23]
	s_add_u32 s20, s20, 0x2000
	s_addc_u32 s21, s21, 0
	s_add_u32 s22, s22, 0x2000
	s_addc_u32 s23, s23, 0
	global_load_dwordx4 v[88:91], v1, s[20:21]
	global_load_dwordx4 v[120:123], v49, s[22:23]
	s_add_u32 s20, s20, 0x2000
	s_addc_u32 s21, s21, 0
	s_add_u32 s22, s22, 0x2000
	s_addc_u32 s23, s23, 0
	global_load_dwordx4 v[92:95], v1, s[20:21]
	global_load_dwordx4 v[124:127], v49, s[22:23]
	s_add_u32 s20, s20, 0x2000
	s_addc_u32 s21, s21, 0
	s_add_u32 s22, s22, 0x2000
	s_addc_u32 s23, s23, 0
	s_waitcnt vmcnt(24)
	v_mov_b32_e32 v44, 1.0
	v_lshlrev_b32_e32 v12, 16, v128
	v_and_b32_e32 v13, 0xffff0000, v128
	v_lshlrev_b32_e32 v20, 16, v160
	v_and_b32_e32 v21, 0xffff0000, v160
	v_lshlrev_b32_e32 v14, 16, v129
	v_and_b32_e32 v15, 0xffff0000, v129
	v_lshlrev_b32_e32 v22, 16, v161
	v_and_b32_e32 v23, 0xffff0000, v161
	v_lshlrev_b32_e32 v16, 16, v130
	v_and_b32_e32 v17, 0xffff0000, v130
	v_lshlrev_b32_e32 v24, 16, v162
	v_and_b32_e32 v25, 0xffff0000, v162
	v_lshlrev_b32_e32 v18, 16, v131
	v_and_b32_e32 v19, 0xffff0000, v131
	v_lshlrev_b32_e32 v26, 16, v163
	v_and_b32_e32 v27, 0xffff0000, v163
	v_pk_fma_f32 v[20:21], v[44:45], v[20:21], v[12:13] op_sel_hi:[0,1,1] neg_lo:[1,0,0] neg_hi:[1,0,0]
	v_pk_fma_f32 v[22:23], v[44:45], v[22:23], v[14:15] op_sel_hi:[0,1,1] neg_lo:[1,0,0] neg_hi:[1,0,0]
	v_pk_fma_f32 v[24:25], v[44:45], v[24:25], v[16:17] op_sel_hi:[0,1,1] neg_lo:[1,0,0] neg_hi:[1,0,0]
	v_pk_fma_f32 v[26:27], v[44:45], v[26:27], v[18:19] op_sel_hi:[0,1,1] neg_lo:[1,0,0] neg_hi:[1,0,0]
	v_pk_add_f32 v[4:5], v[4:5], v[20:21]
	v_pk_add_f32 v[6:7], v[6:7], v[22:23]
	v_pk_add_f32 v[8:9], v[8:9], v[24:25]
	v_pk_add_f32 v[10:11], v[10:11], v[26:27]
	v_mov_b32_e32 v46, v3
	v_pk_fma_f32 v[28:29], v[46:47], v[4:5], v[12:13] op_sel_hi:[0,1,1] neg_lo:[0,0,1] neg_hi:[0,0,1]
	v_pk_fma_f32 v[30:31], v[46:47], v[6:7], v[14:15] op_sel_hi:[0,1,1] neg_lo:[0,0,1] neg_hi:[0,0,1]
	v_pk_fma_f32 v[32:33], v[46:47], v[8:9], v[16:17] op_sel_hi:[0,1,1] neg_lo:[0,0,1] neg_hi:[0,0,1]
	v_pk_fma_f32 v[34:35], v[46:47], v[10:11], v[18:19] op_sel_hi:[0,1,1] neg_lo:[0,0,1] neg_hi:[0,0,1]
	v_cvt_pk_bf16_f32 v36, v28, v29
	v_cvt_pk_bf16_f32 v37, v30, v31
	v_cvt_pk_bf16_f32 v38, v32, v33
	v_cvt_pk_bf16_f32 v39, v34, v35
	global_store_dwordx4 v1, v[36:39], s[24:25]
	s_add_u32 s24, s24, 0x2000
	s_addc_u32 s25, s25, 0
	v_lshlrev_b32_e32 v12, 16, v132
	v_and_b32_e32 v13, 0xffff0000, v132
	v_lshlrev_b32_e32 v20, 16, v164
	v_and_b32_e32 v21, 0xffff0000, v164
	v_lshlrev_b32_e32 v14, 16, v133
	v_and_b32_e32 v15, 0xffff0000, v133
	v_lshlrev_b32_e32 v22, 16, v165
	v_and_b32_e32 v23, 0xffff0000, v165
	v_lshlrev_b32_e32 v16, 16, v134
	v_and_b32_e32 v17, 0xffff0000, v134
	v_lshlrev_b32_e32 v24, 16, v166
	v_and_b32_e32 v25, 0xffff0000, v166
	v_lshlrev_b32_e32 v18, 16, v135
	v_and_b32_e32 v19, 0xffff0000, v135
	v_lshlrev_b32_e32 v26, 16, v167
	v_and_b32_e32 v27, 0xffff0000, v167
	v_pk_fma_f32 v[20:21], v[44:45], v[20:21], v[12:13] op_sel_hi:[0,1,1] neg_lo:[1,0,0] neg_hi:[1,0,0]
	v_pk_fma_f32 v[22:23], v[44:45], v[22:23], v[14:15] op_sel_hi:[0,1,1] neg_lo:[1,0,0] neg_hi:[1,0,0]
	v_pk_fma_f32 v[24:25], v[44:45], v[24:25], v[16:17] op_sel_hi:[0,1,1] neg_lo:[1,0,0] neg_hi:[1,0,0]
	v_pk_fma_f32 v[26:27], v[44:45], v[26:27], v[18:19] op_sel_hi:[0,1,1] neg_lo:[1,0,0] neg_hi:[1,0,0]
	v_pk_add_f32 v[4:5], v[4:5], v[20:21]
	v_pk_add_f32 v[6:7], v[6:7], v[22:23]
	v_pk_add_f32 v[8:9], v[8:9], v[24:25]
	v_pk_add_f32 v[10:11], v[10:11], v[26:27]
	v_mov_b32_e32 v46, v3
	v_pk_fma_f32 v[28:29], v[46:47], v[4:5], v[12:13] op_sel_hi:[0,1,1] neg_lo:[0,0,1] neg_hi:[0,0,1]
	v_pk_fma_f32 v[30:31], v[46:47], v[6:7], v[14:15] op_sel_hi:[0,1,1] neg_lo:[0,0,1] neg_hi:[0,0,1]
	v_pk_fma_f32 v[32:33], v[46:47], v[8:9], v[16:17] op_sel_hi:[0,1,1] neg_lo:[0,0,1] neg_hi:[0,0,1]
	v_pk_fma_f32 v[34:35], v[46:47], v[10:11], v[18:19] op_sel_hi:[0,1,1] neg_lo:[0,0,1] neg_hi:[0,0,1]
	v_cvt_pk_bf16_f32 v40, v28, v29
	v_cvt_pk_bf16_f32 v41, v30, v31
	v_cvt_pk_bf16_f32 v42, v32, v33
	v_cvt_pk_bf16_f32 v43, v34, v35
	global_store_dwordx4 v1, v[40:43], s[24:25]
	s_add_u32 s24, s24, 0x2000
	s_addc_u32 s25, s25, 0
	v_lshlrev_b32_e32 v12, 16, v136
	v_and_b32_e32 v13, 0xffff0000, v136
	v_lshlrev_b32_e32 v20, 16, v168
	v_and_b32_e32 v21, 0xffff0000, v168
	v_lshlrev_b32_e32 v14, 16, v137
	v_and_b32_e32 v15, 0xffff0000, v137
	v_lshlrev_b32_e32 v22, 16, v169
	v_and_b32_e32 v23, 0xffff0000, v169
	v_lshlrev_b32_e32 v16, 16, v138
	v_and_b32_e32 v17, 0xffff0000, v138
	v_lshlrev_b32_e32 v24, 16, v170
	v_and_b32_e32 v25, 0xffff0000, v170
	v_lshlrev_b32_e32 v18, 16, v139
	v_and_b32_e32 v19, 0xffff0000, v139
	v_lshlrev_b32_e32 v26, 16, v171
	v_and_b32_e32 v27, 0xffff0000, v171
	v_pk_fma_f32 v[20:21], v[44:45], v[20:21], v[12:13] op_sel_hi:[0,1,1] neg_lo:[1,0,0] neg_hi:[1,0,0]
	v_pk_fma_f32 v[22:23], v[44:45], v[22:23], v[14:15] op_sel_hi:[0,1,1] neg_lo:[1,0,0] neg_hi:[1,0,0]
	v_pk_fma_f32 v[24:25], v[44:45], v[24:25], v[16:17] op_sel_hi:[0,1,1] neg_lo:[1,0,0] neg_hi:[1,0,0]
	v_pk_fma_f32 v[26:27], v[44:45], v[26:27], v[18:19] op_sel_hi:[0,1,1] neg_lo:[1,0,0] neg_hi:[1,0,0]
	v_pk_add_f32 v[4:5], v[4:5], v[20:21]
	v_pk_add_f32 v[6:7], v[6:7], v[22:23]
	v_pk_add_f32 v[8:9], v[8:9], v[24:25]
	v_pk_add_f32 v[10:11], v[10:11], v[26:27]
	v_mov_b32_e32 v46, v3
	v_pk_fma_f32 v[28:29], v[46:47], v[4:5], v[12:13] op_sel_hi:[0,1,1] neg_lo:[0,0,1] neg_hi:[0,0,1]
	v_pk_fma_f32 v[30:31], v[46:47], v[6:7], v[14:15] op_sel_hi:[0,1,1] neg_lo:[0,0,1] neg_hi:[0,0,1]
	v_pk_fma_f32 v[32:33], v[46:47], v[8:9], v[16:17] op_sel_hi:[0,1,1] neg_lo:[0,0,1] neg_hi:[0,0,1]
	v_pk_fma_f32 v[34:35], v[46:47], v[10:11], v[18:19] op_sel_hi:[0,1,1] neg_lo:[0,0,1] neg_hi:[0,0,1]
	v_cvt_pk_bf16_f32 v36, v28, v29
	v_cvt_pk_bf16_f32 v37, v30, v31
	v_cvt_pk_bf16_f32 v38, v32, v33
	v_cvt_pk_bf16_f32 v39, v34, v35
	global_store_dwordx4 v1, v[36:39], s[24:25]
	s_add_u32 s24, s24, 0x2000
	s_addc_u32 s25, s25, 0
	v_lshlrev_b32_e32 v12, 16, v140
	v_and_b32_e32 v13, 0xffff0000, v140
	v_lshlrev_b32_e32 v20, 16, v172
	v_and_b32_e32 v21, 0xffff0000, v172
	v_lshlrev_b32_e32 v14, 16, v141
	v_and_b32_e32 v15, 0xffff0000, v141
	v_lshlrev_b32_e32 v22, 16, v173
	v_and_b32_e32 v23, 0xffff0000, v173
	v_lshlrev_b32_e32 v16, 16, v142
	v_and_b32_e32 v17, 0xffff0000, v142
	v_lshlrev_b32_e32 v24, 16, v174
	v_and_b32_e32 v25, 0xffff0000, v174
	v_lshlrev_b32_e32 v18, 16, v143
	v_and_b32_e32 v19, 0xffff0000, v143
	v_lshlrev_b32_e32 v26, 16, v175
	v_and_b32_e32 v27, 0xffff0000, v175
	v_pk_fma_f32 v[20:21], v[44:45], v[20:21], v[12:13] op_sel_hi:[0,1,1] neg_lo:[1,0,0] neg_hi:[1,0,0]
	v_pk_fma_f32 v[22:23], v[44:45], v[22:23], v[14:15] op_sel_hi:[0,1,1] neg_lo:[1,0,0] neg_hi:[1,0,0]
	v_pk_fma_f32 v[24:25], v[44:45], v[24:25], v[16:17] op_sel_hi:[0,1,1] neg_lo:[1,0,0] neg_hi:[1,0,0]
	v_pk_fma_f32 v[26:27], v[44:45], v[26:27], v[18:19] op_sel_hi:[0,1,1] neg_lo:[1,0,0] neg_hi:[1,0,0]
	v_pk_add_f32 v[4:5], v[4:5], v[20:21]
	v_pk_add_f32 v[6:7], v[6:7], v[22:23]
	v_pk_add_f32 v[8:9], v[8:9], v[24:25]
	v_pk_add_f32 v[10:11], v[10:11], v[26:27]
	v_mov_b32_e32 v46, v3
	v_pk_fma_f32 v[28:29], v[46:47], v[4:5], v[12:13] op_sel_hi:[0,1,1] neg_lo:[0,0,1] neg_hi:[0,0,1]
	v_pk_fma_f32 v[30:31], v[46:47], v[6:7], v[14:15] op_sel_hi:[0,1,1] neg_lo:[0,0,1] neg_hi:[0,0,1]
	v_pk_fma_f32 v[32:33], v[46:47], v[8:9], v[16:17] op_sel_hi:[0,1,1] neg_lo:[0,0,1] neg_hi:[0,0,1]
	v_pk_fma_f32 v[34:35], v[46:47], v[10:11], v[18:19] op_sel_hi:[0,1,1] neg_lo:[0,0,1] neg_hi:[0,0,1]
	v_cvt_pk_bf16_f32 v40, v28, v29
	v_cvt_pk_bf16_f32 v41, v30, v31
	v_cvt_pk_bf16_f32 v42, v32, v33
	v_cvt_pk_bf16_f32 v43, v34, v35
	global_store_dwordx4 v1, v[40:43], s[24:25]
	s_add_u32 s24, s24, 0x2000
	s_addc_u32 s25, s25, 0
	v_lshlrev_b32_e32 v12, 16, v144
	v_and_b32_e32 v13, 0xffff0000, v144
	v_lshlrev_b32_e32 v20, 16, v176
	v_and_b32_e32 v21, 0xffff0000, v176
	v_lshlrev_b32_e32 v14, 16, v145
	v_and_b32_e32 v15, 0xffff0000, v145
	v_lshlrev_b32_e32 v22, 16, v177
	v_and_b32_e32 v23, 0xffff0000, v177
	v_lshlrev_b32_e32 v16, 16, v146
	v_and_b32_e32 v17, 0xffff0000, v146
	v_lshlrev_b32_e32 v24, 16, v178
	v_and_b32_e32 v25, 0xffff0000, v178
	v_lshlrev_b32_e32 v18, 16, v147
	v_and_b32_e32 v19, 0xffff0000, v147
	v_lshlrev_b32_e32 v26, 16, v179
	v_and_b32_e32 v27, 0xffff0000, v179
	v_pk_fma_f32 v[20:21], v[44:45], v[20:21], v[12:13] op_sel_hi:[0,1,1] neg_lo:[1,0,0] neg_hi:[1,0,0]
	v_pk_fma_f32 v[22:23], v[44:45], v[22:23], v[14:15] op_sel_hi:[0,1,1] neg_lo:[1,0,0] neg_hi:[1,0,0]
	v_pk_fma_f32 v[24:25], v[44:45], v[24:25], v[16:17] op_sel_hi:[0,1,1] neg_lo:[1,0,0] neg_hi:[1,0,0]
	v_pk_fma_f32 v[26:27], v[44:45], v[26:27], v[18:19] op_sel_hi:[0,1,1] neg_lo:[1,0,0] neg_hi:[1,0,0]
	v_pk_add_f32 v[4:5], v[4:5], v[20:21]
	v_pk_add_f32 v[6:7], v[6:7], v[22:23]
	v_pk_add_f32 v[8:9], v[8:9], v[24:25]
	v_pk_add_f32 v[10:11], v[10:11], v[26:27]
	v_mov_b32_e32 v46, v3
	v_pk_fma_f32 v[28:29], v[46:47], v[4:5], v[12:13] op_sel_hi:[0,1,1] neg_lo:[0,0,1] neg_hi:[0,0,1]
	v_pk_fma_f32 v[30:31], v[46:47], v[6:7], v[14:15] op_sel_hi:[0,1,1] neg_lo:[0,0,1] neg_hi:[0,0,1]
	v_pk_fma_f32 v[32:33], v[46:47], v[8:9], v[16:17] op_sel_hi:[0,1,1] neg_lo:[0,0,1] neg_hi:[0,0,1]
	v_pk_fma_f32 v[34:35], v[46:47], v[10:11], v[18:19] op_sel_hi:[0,1,1] neg_lo:[0,0,1] neg_hi:[0,0,1]
	v_cvt_pk_bf16_f32 v36, v28, v29
	v_cvt_pk_bf16_f32 v37, v30, v31
	v_cvt_pk_bf16_f32 v38, v32, v33
	v_cvt_pk_bf16_f32 v39, v34, v35
	global_store_dwordx4 v1, v[36:39], s[24:25]
	s_add_u32 s24, s24, 0x2000
	s_addc_u32 s25, s25, 0
	v_lshlrev_b32_e32 v12, 16, v148
	v_and_b32_e32 v13, 0xffff0000, v148
	v_lshlrev_b32_e32 v20, 16, v180
	v_and_b32_e32 v21, 0xffff0000, v180
	v_lshlrev_b32_e32 v14, 16, v149
	v_and_b32_e32 v15, 0xffff0000, v149
	v_lshlrev_b32_e32 v22, 16, v181
	v_and_b32_e32 v23, 0xffff0000, v181
	v_lshlrev_b32_e32 v16, 16, v150
	v_and_b32_e32 v17, 0xffff0000, v150
	v_lshlrev_b32_e32 v24, 16, v182
	v_and_b32_e32 v25, 0xffff0000, v182
	v_lshlrev_b32_e32 v18, 16, v151
	v_and_b32_e32 v19, 0xffff0000, v151
	v_lshlrev_b32_e32 v26, 16, v183
	v_and_b32_e32 v27, 0xffff0000, v183
	v_pk_fma_f32 v[20:21], v[44:45], v[20:21], v[12:13] op_sel_hi:[0,1,1] neg_lo:[1,0,0] neg_hi:[1,0,0]
	v_pk_fma_f32 v[22:23], v[44:45], v[22:23], v[14:15] op_sel_hi:[0,1,1] neg_lo:[1,0,0] neg_hi:[1,0,0]
	v_pk_fma_f32 v[24:25], v[44:45], v[24:25], v[16:17] op_sel_hi:[0,1,1] neg_lo:[1,0,0] neg_hi:[1,0,0]
	v_pk_fma_f32 v[26:27], v[44:45], v[26:27], v[18:19] op_sel_hi:[0,1,1] neg_lo:[1,0,0] neg_hi:[1,0,0]
	v_pk_add_f32 v[4:5], v[4:5], v[20:21]
	v_pk_add_f32 v[6:7], v[6:7], v[22:23]
	v_pk_add_f32 v[8:9], v[8:9], v[24:25]
	v_pk_add_f32 v[10:11], v[10:11], v[26:27]
	v_mov_b32_e32 v46, v3
	v_pk_fma_f32 v[28:29], v[46:47], v[4:5], v[12:13] op_sel_hi:[0,1,1] neg_lo:[0,0,1] neg_hi:[0,0,1]
	v_pk_fma_f32 v[30:31], v[46:47], v[6:7], v[14:15] op_sel_hi:[0,1,1] neg_lo:[0,0,1] neg_hi:[0,0,1]
	v_pk_fma_f32 v[32:33], v[46:47], v[8:9], v[16:17] op_sel_hi:[0,1,1] neg_lo:[0,0,1] neg_hi:[0,0,1]
	v_pk_fma_f32 v[34:35], v[46:47], v[10:11], v[18:19] op_sel_hi:[0,1,1] neg_lo:[0,0,1] neg_hi:[0,0,1]
	v_cvt_pk_bf16_f32 v40, v28, v29
	v_cvt_pk_bf16_f32 v41, v30, v31
	v_cvt_pk_bf16_f32 v42, v32, v33
	v_cvt_pk_bf16_f32 v43, v34, v35
	global_store_dwordx4 v1, v[40:43], s[24:25]
	s_add_u32 s24, s24, 0x2000
	s_addc_u32 s25, s25, 0
	v_lshlrev_b32_e32 v12, 16, v152
	v_and_b32_e32 v13, 0xffff0000, v152
	v_lshlrev_b32_e32 v20, 16, v184
	v_and_b32_e32 v21, 0xffff0000, v184
	v_lshlrev_b32_e32 v14, 16, v153
	v_and_b32_e32 v15, 0xffff0000, v153
	v_lshlrev_b32_e32 v22, 16, v185
	v_and_b32_e32 v23, 0xffff0000, v185
	v_lshlrev_b32_e32 v16, 16, v154
	v_and_b32_e32 v17, 0xffff0000, v154
	v_lshlrev_b32_e32 v24, 16, v186
	v_and_b32_e32 v25, 0xffff0000, v186
	v_lshlrev_b32_e32 v18, 16, v155
	v_and_b32_e32 v19, 0xffff0000, v155
	v_lshlrev_b32_e32 v26, 16, v187
	v_and_b32_e32 v27, 0xffff0000, v187
	v_pk_fma_f32 v[20:21], v[44:45], v[20:21], v[12:13] op_sel_hi:[0,1,1] neg_lo:[1,0,0] neg_hi:[1,0,0]
	v_pk_fma_f32 v[22:23], v[44:45], v[22:23], v[14:15] op_sel_hi:[0,1,1] neg_lo:[1,0,0] neg_hi:[1,0,0]
	v_pk_fma_f32 v[24:25], v[44:45], v[24:25], v[16:17] op_sel_hi:[0,1,1] neg_lo:[1,0,0] neg_hi:[1,0,0]
	v_pk_fma_f32 v[26:27], v[44:45], v[26:27], v[18:19] op_sel_hi:[0,1,1] neg_lo:[1,0,0] neg_hi:[1,0,0]
	v_pk_add_f32 v[4:5], v[4:5], v[20:21]
	v_pk_add_f32 v[6:7], v[6:7], v[22:23]
	v_pk_add_f32 v[8:9], v[8:9], v[24:25]
	v_pk_add_f32 v[10:11], v[10:11], v[26:27]
	v_mov_b32_e32 v46, v3
	v_pk_fma_f32 v[28:29], v[46:47], v[4:5], v[12:13] op_sel_hi:[0,1,1] neg_lo:[0,0,1] neg_hi:[0,0,1]
	v_pk_fma_f32 v[30:31], v[46:47], v[6:7], v[14:15] op_sel_hi:[0,1,1] neg_lo:[0,0,1] neg_hi:[0,0,1]
	v_pk_fma_f32 v[32:33], v[46:47], v[8:9], v[16:17] op_sel_hi:[0,1,1] neg_lo:[0,0,1] neg_hi:[0,0,1]
	v_pk_fma_f32 v[34:35], v[46:47], v[10:11], v[18:19] op_sel_hi:[0,1,1] neg_lo:[0,0,1] neg_hi:[0,0,1]
	v_cvt_pk_bf16_f32 v36, v28, v29
	v_cvt_pk_bf16_f32 v37, v30, v31
	v_cvt_pk_bf16_f32 v38, v32, v33
	v_cvt_pk_bf16_f32 v39, v34, v35
	global_store_dwordx4 v1, v[36:39], s[24:25]
	s_add_u32 s24, s24, 0x2000
	s_addc_u32 s25, s25, 0
	v_lshlrev_b32_e32 v12, 16, v156
	v_and_b32_e32 v13, 0xffff0000, v156
	v_lshlrev_b32_e32 v20, 16, v188
	v_and_b32_e32 v21, 0xffff0000, v188
	v_lshlrev_b32_e32 v14, 16, v157
	v_and_b32_e32 v15, 0xffff0000, v157
	v_lshlrev_b32_e32 v22, 16, v189
	v_and_b32_e32 v23, 0xffff0000, v189
	v_lshlrev_b32_e32 v16, 16, v158
	v_and_b32_e32 v17, 0xffff0000, v158
	v_lshlrev_b32_e32 v24, 16, v190
	v_and_b32_e32 v25, 0xffff0000, v190
	v_lshlrev_b32_e32 v18, 16, v159
	v_and_b32_e32 v19, 0xffff0000, v159
	v_lshlrev_b32_e32 v26, 16, v191
	v_and_b32_e32 v27, 0xffff0000, v191
	v_pk_fma_f32 v[20:21], v[44:45], v[20:21], v[12:13] op_sel_hi:[0,1,1] neg_lo:[1,0,0] neg_hi:[1,0,0]
	v_pk_fma_f32 v[22:23], v[44:45], v[22:23], v[14:15] op_sel_hi:[0,1,1] neg_lo:[1,0,0] neg_hi:[1,0,0]
	v_pk_fma_f32 v[24:25], v[44:45], v[24:25], v[16:17] op_sel_hi:[0,1,1] neg_lo:[1,0,0] neg_hi:[1,0,0]
	v_pk_fma_f32 v[26:27], v[44:45], v[26:27], v[18:19] op_sel_hi:[0,1,1] neg_lo:[1,0,0] neg_hi:[1,0,0]
	v_pk_add_f32 v[4:5], v[4:5], v[20:21]
	v_pk_add_f32 v[6:7], v[6:7], v[22:23]
	v_pk_add_f32 v[8:9], v[8:9], v[24:25]
	v_pk_add_f32 v[10:11], v[10:11], v[26:27]
	v_mov_b32_e32 v46, v3
	v_pk_fma_f32 v[28:29], v[46:47], v[4:5], v[12:13] op_sel_hi:[0,1,1] neg_lo:[0,0,1] neg_hi:[0,0,1]
	v_pk_fma_f32 v[30:31], v[46:47], v[6:7], v[14:15] op_sel_hi:[0,1,1] neg_lo:[0,0,1] neg_hi:[0,0,1]
	v_pk_fma_f32 v[32:33], v[46:47], v[8:9], v[16:17] op_sel_hi:[0,1,1] neg_lo:[0,0,1] neg_hi:[0,0,1]
	v_pk_fma_f32 v[34:35], v[46:47], v[10:11], v[18:19] op_sel_hi:[0,1,1] neg_lo:[0,0,1] neg_hi:[0,0,1]
	v_cvt_pk_bf16_f32 v40, v28, v29
	v_cvt_pk_bf16_f32 v41, v30, v31
	v_cvt_pk_bf16_f32 v42, v32, v33
	v_cvt_pk_bf16_f32 v43, v34, v35
	global_store_dwordx4 v1, v[40:43], s[24:25]
	s_add_u32 s24, s24, 0x2000
	s_addc_u32 s25, s25, 0
	global_load_dwordx4 v[128:131], v1, s[20:21]
	global_load_dwordx4 v[160:163], v49, s[22:23]
	s_add_u32 s20, s20, 0x2000
	s_addc_u32 s21, s21, 0
	s_add_u32 s22, s22, 0x2000
	s_addc_u32 s23, s23, 0
	global_load_dwordx4 v[132:135], v1, s[20:21]
	global_load_dwordx4 v[164:167], v49, s[22:23]
	s_add_u32 s20, s20, 0x2000
	s_addc_u32 s21, s21, 0
	s_add_u32 s22, s22, 0x2000
	s_addc_u32 s23, s23, 0
	global_load_dwordx4 v[136:139], v1, s[20:21]
	global_load_dwordx4 v[168:171], v49, s[22:23]
	s_add_u32 s20, s20, 0x2000
	s_addc_u32 s21, s21, 0
	s_add_u32 s22, s22, 0x2000
	s_addc_u32 s23, s23, 0
	global_load_dwordx4 v[140:143], v1, s[20:21]
	global_load_dwordx4 v[172:175], v49, s[22:23]
	s_add_u32 s20, s20, 0x2000
	s_addc_u32 s21, s21, 0
	s_add_u32 s22, s22, 0x2000
	s_addc_u32 s23, s23, 0
	global_load_dwordx4 v[144:147], v1, s[20:21]
	global_load_dwordx4 v[176:179], v49, s[22:23]
	s_add_u32 s20, s20, 0x2000
	s_addc_u32 s21, s21, 0
	s_add_u32 s22, s22, 0x2000
	s_addc_u32 s23, s23, 0
	global_load_dwordx4 v[148:151], v1, s[20:21]
	global_load_dwordx4 v[180:183], v49, s[22:23]
	s_add_u32 s20, s20, 0x2000
	s_addc_u32 s21, s21, 0
	s_add_u32 s22, s22, 0x2000
	s_addc_u32 s23, s23, 0
	global_load_dwordx4 v[152:155], v1, s[20:21]
	global_load_dwordx4 v[184:187], v49, s[22:23]
	s_add_u32 s20, s20, 0x2000
	s_addc_u32 s21, s21, 0
	s_add_u32 s22, s22, 0x2000
	s_addc_u32 s23, s23, 0
	global_load_dwordx4 v[156:159], v1, s[20:21]
	global_load_dwordx4 v[188:191], v49, s[22:23]
	s_add_u32 s20, s20, 0x2000
	s_addc_u32 s21, s21, 0
	s_add_u32 s22, s22, 0x2000
	s_addc_u32 s23, s23, 0
	s_waitcnt vmcnt(24)
	v_mov_b32_e32 v44, 1.0
	v_lshlrev_b32_e32 v12, 16, v64
	v_and_b32_e32 v13, 0xffff0000, v64
	v_lshlrev_b32_e32 v20, 16, v96
	v_and_b32_e32 v21, 0xffff0000, v96
	v_lshlrev_b32_e32 v14, 16, v65
	v_and_b32_e32 v15, 0xffff0000, v65
	v_lshlrev_b32_e32 v22, 16, v97
	v_and_b32_e32 v23, 0xffff0000, v97
	v_lshlrev_b32_e32 v16, 16, v66
	v_and_b32_e32 v17, 0xffff0000, v66
	v_lshlrev_b32_e32 v24, 16, v98
	v_and_b32_e32 v25, 0xffff0000, v98
	v_lshlrev_b32_e32 v18, 16, v67
	v_and_b32_e32 v19, 0xffff0000, v67
	v_lshlrev_b32_e32 v26, 16, v99
	v_and_b32_e32 v27, 0xffff0000, v99
	v_pk_fma_f32 v[20:21], v[44:45], v[20:21], v[12:13] op_sel_hi:[0,1,1] neg_lo:[1,0,0] neg_hi:[1,0,0]
	v_pk_fma_f32 v[22:23], v[44:45], v[22:23], v[14:15] op_sel_hi:[0,1,1] neg_lo:[1,0,0] neg_hi:[1,0,0]
	v_pk_fma_f32 v[24:25], v[44:45], v[24:25], v[16:17] op_sel_hi:[0,1,1] neg_lo:[1,0,0] neg_hi:[1,0,0]
	v_pk_fma_f32 v[26:27], v[44:45], v[26:27], v[18:19] op_sel_hi:[0,1,1] neg_lo:[1,0,0] neg_hi:[1,0,0]
	v_pk_add_f32 v[4:5], v[4:5], v[20:21]
	v_pk_add_f32 v[6:7], v[6:7], v[22:23]
	v_pk_add_f32 v[8:9], v[8:9], v[24:25]
	v_pk_add_f32 v[10:11], v[10:11], v[26:27]
	v_mov_b32_e32 v46, v3
	v_pk_fma_f32 v[28:29], v[46:47], v[4:5], v[12:13] op_sel_hi:[0,1,1] neg_lo:[0,0,1] neg_hi:[0,0,1]
	v_pk_fma_f32 v[30:31], v[46:47], v[6:7], v[14:15] op_sel_hi:[0,1,1] neg_lo:[0,0,1] neg_hi:[0,0,1]
	v_pk_fma_f32 v[32:33], v[46:47], v[8:9], v[16:17] op_sel_hi:[0,1,1] neg_lo:[0,0,1] neg_hi:[0,0,1]
	v_pk_fma_f32 v[34:35], v[46:47], v[10:11], v[18:19] op_sel_hi:[0,1,1] neg_lo:[0,0,1] neg_hi:[0,0,1]
	v_cvt_pk_bf16_f32 v36, v28, v29
	v_cvt_pk_bf16_f32 v37, v30, v31
	v_cvt_pk_bf16_f32 v38, v32, v33
	v_cvt_pk_bf16_f32 v39, v34, v35
	global_store_dwordx4 v1, v[36:39], s[24:25]
	s_add_u32 s24, s24, 0x2000
	s_addc_u32 s25, s25, 0
	v_lshlrev_b32_e32 v12, 16, v68
	v_and_b32_e32 v13, 0xffff0000, v68
	v_lshlrev_b32_e32 v20, 16, v100
	v_and_b32_e32 v21, 0xffff0000, v100
	v_lshlrev_b32_e32 v14, 16, v69
	v_and_b32_e32 v15, 0xffff0000, v69
	v_lshlrev_b32_e32 v22, 16, v101
	v_and_b32_e32 v23, 0xffff0000, v101
	v_lshlrev_b32_e32 v16, 16, v70
	v_and_b32_e32 v17, 0xffff0000, v70
	v_lshlrev_b32_e32 v24, 16, v102
	v_and_b32_e32 v25, 0xffff0000, v102
	v_lshlrev_b32_e32 v18, 16, v71
	v_and_b32_e32 v19, 0xffff0000, v71
	v_lshlrev_b32_e32 v26, 16, v103
	v_and_b32_e32 v27, 0xffff0000, v103
	v_pk_fma_f32 v[20:21], v[44:45], v[20:21], v[12:13] op_sel_hi:[0,1,1] neg_lo:[1,0,0] neg_hi:[1,0,0]
	v_pk_fma_f32 v[22:23], v[44:45], v[22:23], v[14:15] op_sel_hi:[0,1,1] neg_lo:[1,0,0] neg_hi:[1,0,0]
	v_pk_fma_f32 v[24:25], v[44:45], v[24:25], v[16:17] op_sel_hi:[0,1,1] neg_lo:[1,0,0] neg_hi:[1,0,0]
	v_pk_fma_f32 v[26:27], v[44:45], v[26:27], v[18:19] op_sel_hi:[0,1,1] neg_lo:[1,0,0] neg_hi:[1,0,0]
	v_pk_add_f32 v[4:5], v[4:5], v[20:21]
	v_pk_add_f32 v[6:7], v[6:7], v[22:23]
	v_pk_add_f32 v[8:9], v[8:9], v[24:25]
	v_pk_add_f32 v[10:11], v[10:11], v[26:27]
	v_mov_b32_e32 v46, v3
	v_pk_fma_f32 v[28:29], v[46:47], v[4:5], v[12:13] op_sel_hi:[0,1,1] neg_lo:[0,0,1] neg_hi:[0,0,1]
	v_pk_fma_f32 v[30:31], v[46:47], v[6:7], v[14:15] op_sel_hi:[0,1,1] neg_lo:[0,0,1] neg_hi:[0,0,1]
	v_pk_fma_f32 v[32:33], v[46:47], v[8:9], v[16:17] op_sel_hi:[0,1,1] neg_lo:[0,0,1] neg_hi:[0,0,1]
	v_pk_fma_f32 v[34:35], v[46:47], v[10:11], v[18:19] op_sel_hi:[0,1,1] neg_lo:[0,0,1] neg_hi:[0,0,1]
	v_cvt_pk_bf16_f32 v40, v28, v29
	v_cvt_pk_bf16_f32 v41, v30, v31
	v_cvt_pk_bf16_f32 v42, v32, v33
	v_cvt_pk_bf16_f32 v43, v34, v35
	global_store_dwordx4 v1, v[40:43], s[24:25]
	s_add_u32 s24, s24, 0x2000
	s_addc_u32 s25, s25, 0
	v_lshlrev_b32_e32 v12, 16, v72
	v_and_b32_e32 v13, 0xffff0000, v72
	v_lshlrev_b32_e32 v20, 16, v104
	v_and_b32_e32 v21, 0xffff0000, v104
	v_lshlrev_b32_e32 v14, 16, v73
	v_and_b32_e32 v15, 0xffff0000, v73
	v_lshlrev_b32_e32 v22, 16, v105
	v_and_b32_e32 v23, 0xffff0000, v105
	v_lshlrev_b32_e32 v16, 16, v74
	v_and_b32_e32 v17, 0xffff0000, v74
	v_lshlrev_b32_e32 v24, 16, v106
	v_and_b32_e32 v25, 0xffff0000, v106
	v_lshlrev_b32_e32 v18, 16, v75
	v_and_b32_e32 v19, 0xffff0000, v75
	v_lshlrev_b32_e32 v26, 16, v107
	v_and_b32_e32 v27, 0xffff0000, v107
	v_pk_fma_f32 v[20:21], v[44:45], v[20:21], v[12:13] op_sel_hi:[0,1,1] neg_lo:[1,0,0] neg_hi:[1,0,0]
	v_pk_fma_f32 v[22:23], v[44:45], v[22:23], v[14:15] op_sel_hi:[0,1,1] neg_lo:[1,0,0] neg_hi:[1,0,0]
	v_pk_fma_f32 v[24:25], v[44:45], v[24:25], v[16:17] op_sel_hi:[0,1,1] neg_lo:[1,0,0] neg_hi:[1,0,0]
	v_pk_fma_f32 v[26:27], v[44:45], v[26:27], v[18:19] op_sel_hi:[0,1,1] neg_lo:[1,0,0] neg_hi:[1,0,0]
	v_pk_add_f32 v[4:5], v[4:5], v[20:21]
	v_pk_add_f32 v[6:7], v[6:7], v[22:23]
	v_pk_add_f32 v[8:9], v[8:9], v[24:25]
	v_pk_add_f32 v[10:11], v[10:11], v[26:27]
	v_mov_b32_e32 v46, v3
	v_pk_fma_f32 v[28:29], v[46:47], v[4:5], v[12:13] op_sel_hi:[0,1,1] neg_lo:[0,0,1] neg_hi:[0,0,1]
	v_pk_fma_f32 v[30:31], v[46:47], v[6:7], v[14:15] op_sel_hi:[0,1,1] neg_lo:[0,0,1] neg_hi:[0,0,1]
	v_pk_fma_f32 v[32:33], v[46:47], v[8:9], v[16:17] op_sel_hi:[0,1,1] neg_lo:[0,0,1] neg_hi:[0,0,1]
	v_pk_fma_f32 v[34:35], v[46:47], v[10:11], v[18:19] op_sel_hi:[0,1,1] neg_lo:[0,0,1] neg_hi:[0,0,1]
	v_cvt_pk_bf16_f32 v36, v28, v29
	v_cvt_pk_bf16_f32 v37, v30, v31
	v_cvt_pk_bf16_f32 v38, v32, v33
	v_cvt_pk_bf16_f32 v39, v34, v35
	global_store_dwordx4 v1, v[36:39], s[24:25]
	s_add_u32 s24, s24, 0x2000
	s_addc_u32 s25, s25, 0
	v_lshlrev_b32_e32 v12, 16, v76
	v_and_b32_e32 v13, 0xffff0000, v76
	v_lshlrev_b32_e32 v20, 16, v108
	v_and_b32_e32 v21, 0xffff0000, v108
	v_lshlrev_b32_e32 v14, 16, v77
	v_and_b32_e32 v15, 0xffff0000, v77
	v_lshlrev_b32_e32 v22, 16, v109
	v_and_b32_e32 v23, 0xffff0000, v109
	v_lshlrev_b32_e32 v16, 16, v78
	v_and_b32_e32 v17, 0xffff0000, v78
	v_lshlrev_b32_e32 v24, 16, v110
	v_and_b32_e32 v25, 0xffff0000, v110
	v_lshlrev_b32_e32 v18, 16, v79
	v_and_b32_e32 v19, 0xffff0000, v79
	v_lshlrev_b32_e32 v26, 16, v111
	v_and_b32_e32 v27, 0xffff0000, v111
	v_pk_fma_f32 v[20:21], v[44:45], v[20:21], v[12:13] op_sel_hi:[0,1,1] neg_lo:[1,0,0] neg_hi:[1,0,0]
	v_pk_fma_f32 v[22:23], v[44:45], v[22:23], v[14:15] op_sel_hi:[0,1,1] neg_lo:[1,0,0] neg_hi:[1,0,0]
	v_pk_fma_f32 v[24:25], v[44:45], v[24:25], v[16:17] op_sel_hi:[0,1,1] neg_lo:[1,0,0] neg_hi:[1,0,0]
	v_pk_fma_f32 v[26:27], v[44:45], v[26:27], v[18:19] op_sel_hi:[0,1,1] neg_lo:[1,0,0] neg_hi:[1,0,0]
	v_pk_add_f32 v[4:5], v[4:5], v[20:21]
	v_pk_add_f32 v[6:7], v[6:7], v[22:23]
	v_pk_add_f32 v[8:9], v[8:9], v[24:25]
	v_pk_add_f32 v[10:11], v[10:11], v[26:27]
	v_mov_b32_e32 v46, v3
	v_pk_fma_f32 v[28:29], v[46:47], v[4:5], v[12:13] op_sel_hi:[0,1,1] neg_lo:[0,0,1] neg_hi:[0,0,1]
	v_pk_fma_f32 v[30:31], v[46:47], v[6:7], v[14:15] op_sel_hi:[0,1,1] neg_lo:[0,0,1] neg_hi:[0,0,1]
	v_pk_fma_f32 v[32:33], v[46:47], v[8:9], v[16:17] op_sel_hi:[0,1,1] neg_lo:[0,0,1] neg_hi:[0,0,1]
	v_pk_fma_f32 v[34:35], v[46:47], v[10:11], v[18:19] op_sel_hi:[0,1,1] neg_lo:[0,0,1] neg_hi:[0,0,1]
	v_cvt_pk_bf16_f32 v40, v28, v29
	v_cvt_pk_bf16_f32 v41, v30, v31
	v_cvt_pk_bf16_f32 v42, v32, v33
	v_cvt_pk_bf16_f32 v43, v34, v35
	global_store_dwordx4 v1, v[40:43], s[24:25]
	s_add_u32 s24, s24, 0x2000
	s_addc_u32 s25, s25, 0
	v_lshlrev_b32_e32 v12, 16, v80
	v_and_b32_e32 v13, 0xffff0000, v80
	v_lshlrev_b32_e32 v20, 16, v112
	v_and_b32_e32 v21, 0xffff0000, v112
	v_lshlrev_b32_e32 v14, 16, v81
	v_and_b32_e32 v15, 0xffff0000, v81
	v_lshlrev_b32_e32 v22, 16, v113
	v_and_b32_e32 v23, 0xffff0000, v113
	v_lshlrev_b32_e32 v16, 16, v82
	v_and_b32_e32 v17, 0xffff0000, v82
	v_lshlrev_b32_e32 v24, 16, v114
	v_and_b32_e32 v25, 0xffff0000, v114
	v_lshlrev_b32_e32 v18, 16, v83
	v_and_b32_e32 v19, 0xffff0000, v83
	v_lshlrev_b32_e32 v26, 16, v115
	v_and_b32_e32 v27, 0xffff0000, v115
	v_pk_fma_f32 v[20:21], v[44:45], v[20:21], v[12:13] op_sel_hi:[0,1,1] neg_lo:[1,0,0] neg_hi:[1,0,0]
	v_pk_fma_f32 v[22:23], v[44:45], v[22:23], v[14:15] op_sel_hi:[0,1,1] neg_lo:[1,0,0] neg_hi:[1,0,0]
	v_pk_fma_f32 v[24:25], v[44:45], v[24:25], v[16:17] op_sel_hi:[0,1,1] neg_lo:[1,0,0] neg_hi:[1,0,0]
	v_pk_fma_f32 v[26:27], v[44:45], v[26:27], v[18:19] op_sel_hi:[0,1,1] neg_lo:[1,0,0] neg_hi:[1,0,0]
	v_pk_add_f32 v[4:5], v[4:5], v[20:21]
	v_pk_add_f32 v[6:7], v[6:7], v[22:23]
	v_pk_add_f32 v[8:9], v[8:9], v[24:25]
	v_pk_add_f32 v[10:11], v[10:11], v[26:27]
	v_mov_b32_e32 v46, v3
	v_pk_fma_f32 v[28:29], v[46:47], v[4:5], v[12:13] op_sel_hi:[0,1,1] neg_lo:[0,0,1] neg_hi:[0,0,1]
	v_pk_fma_f32 v[30:31], v[46:47], v[6:7], v[14:15] op_sel_hi:[0,1,1] neg_lo:[0,0,1] neg_hi:[0,0,1]
	v_pk_fma_f32 v[32:33], v[46:47], v[8:9], v[16:17] op_sel_hi:[0,1,1] neg_lo:[0,0,1] neg_hi:[0,0,1]
	v_pk_fma_f32 v[34:35], v[46:47], v[10:11], v[18:19] op_sel_hi:[0,1,1] neg_lo:[0,0,1] neg_hi:[0,0,1]
	v_cvt_pk_bf16_f32 v36, v28, v29
	v_cvt_pk_bf16_f32 v37, v30, v31
	v_cvt_pk_bf16_f32 v38, v32, v33
	v_cvt_pk_bf16_f32 v39, v34, v35
	global_store_dwordx4 v1, v[36:39], s[24:25]
	s_add_u32 s24, s24, 0x2000
	s_addc_u32 s25, s25, 0
	v_lshlrev_b32_e32 v12, 16, v84
	v_and_b32_e32 v13, 0xffff0000, v84
	v_lshlrev_b32_e32 v20, 16, v116
	v_and_b32_e32 v21, 0xffff0000, v116
	v_lshlrev_b32_e32 v14, 16, v85
	v_and_b32_e32 v15, 0xffff0000, v85
	v_lshlrev_b32_e32 v22, 16, v117
	v_and_b32_e32 v23, 0xffff0000, v117
	v_lshlrev_b32_e32 v16, 16, v86
	v_and_b32_e32 v17, 0xffff0000, v86
	v_lshlrev_b32_e32 v24, 16, v118
	v_and_b32_e32 v25, 0xffff0000, v118
	v_lshlrev_b32_e32 v18, 16, v87
	v_and_b32_e32 v19, 0xffff0000, v87
	v_lshlrev_b32_e32 v26, 16, v119
	v_and_b32_e32 v27, 0xffff0000, v119
	v_pk_fma_f32 v[20:21], v[44:45], v[20:21], v[12:13] op_sel_hi:[0,1,1] neg_lo:[1,0,0] neg_hi:[1,0,0]
	v_pk_fma_f32 v[22:23], v[44:45], v[22:23], v[14:15] op_sel_hi:[0,1,1] neg_lo:[1,0,0] neg_hi:[1,0,0]
	v_pk_fma_f32 v[24:25], v[44:45], v[24:25], v[16:17] op_sel_hi:[0,1,1] neg_lo:[1,0,0] neg_hi:[1,0,0]
	v_pk_fma_f32 v[26:27], v[44:45], v[26:27], v[18:19] op_sel_hi:[0,1,1] neg_lo:[1,0,0] neg_hi:[1,0,0]
	v_pk_add_f32 v[4:5], v[4:5], v[20:21]
	v_pk_add_f32 v[6:7], v[6:7], v[22:23]
	v_pk_add_f32 v[8:9], v[8:9], v[24:25]
	v_pk_add_f32 v[10:11], v[10:11], v[26:27]
	v_mov_b32_e32 v46, v3
	v_pk_fma_f32 v[28:29], v[46:47], v[4:5], v[12:13] op_sel_hi:[0,1,1] neg_lo:[0,0,1] neg_hi:[0,0,1]
	v_pk_fma_f32 v[30:31], v[46:47], v[6:7], v[14:15] op_sel_hi:[0,1,1] neg_lo:[0,0,1] neg_hi:[0,0,1]
	v_pk_fma_f32 v[32:33], v[46:47], v[8:9], v[16:17] op_sel_hi:[0,1,1] neg_lo:[0,0,1] neg_hi:[0,0,1]
	v_pk_fma_f32 v[34:35], v[46:47], v[10:11], v[18:19] op_sel_hi:[0,1,1] neg_lo:[0,0,1] neg_hi:[0,0,1]
	v_cvt_pk_bf16_f32 v40, v28, v29
	v_cvt_pk_bf16_f32 v41, v30, v31
	v_cvt_pk_bf16_f32 v42, v32, v33
	v_cvt_pk_bf16_f32 v43, v34, v35
	global_store_dwordx4 v1, v[40:43], s[24:25]
	s_add_u32 s24, s24, 0x2000
	s_addc_u32 s25, s25, 0
	v_lshlrev_b32_e32 v12, 16, v88
	v_and_b32_e32 v13, 0xffff0000, v88
	v_lshlrev_b32_e32 v20, 16, v120
	v_and_b32_e32 v21, 0xffff0000, v120
	v_lshlrev_b32_e32 v14, 16, v89
	v_and_b32_e32 v15, 0xffff0000, v89
	v_lshlrev_b32_e32 v22, 16, v121
	v_and_b32_e32 v23, 0xffff0000, v121
	v_lshlrev_b32_e32 v16, 16, v90
	v_and_b32_e32 v17, 0xffff0000, v90
	v_lshlrev_b32_e32 v24, 16, v122
	v_and_b32_e32 v25, 0xffff0000, v122
	v_lshlrev_b32_e32 v18, 16, v91
	v_and_b32_e32 v19, 0xffff0000, v91
	v_lshlrev_b32_e32 v26, 16, v123
	v_and_b32_e32 v27, 0xffff0000, v123
	v_pk_fma_f32 v[20:21], v[44:45], v[20:21], v[12:13] op_sel_hi:[0,1,1] neg_lo:[1,0,0] neg_hi:[1,0,0]
	v_pk_fma_f32 v[22:23], v[44:45], v[22:23], v[14:15] op_sel_hi:[0,1,1] neg_lo:[1,0,0] neg_hi:[1,0,0]
	v_pk_fma_f32 v[24:25], v[44:45], v[24:25], v[16:17] op_sel_hi:[0,1,1] neg_lo:[1,0,0] neg_hi:[1,0,0]
	v_pk_fma_f32 v[26:27], v[44:45], v[26:27], v[18:19] op_sel_hi:[0,1,1] neg_lo:[1,0,0] neg_hi:[1,0,0]
	v_pk_add_f32 v[4:5], v[4:5], v[20:21]
	v_pk_add_f32 v[6:7], v[6:7], v[22:23]
	v_pk_add_f32 v[8:9], v[8:9], v[24:25]
	v_pk_add_f32 v[10:11], v[10:11], v[26:27]
	v_mov_b32_e32 v46, v3
	v_pk_fma_f32 v[28:29], v[46:47], v[4:5], v[12:13] op_sel_hi:[0,1,1] neg_lo:[0,0,1] neg_hi:[0,0,1]
	v_pk_fma_f32 v[30:31], v[46:47], v[6:7], v[14:15] op_sel_hi:[0,1,1] neg_lo:[0,0,1] neg_hi:[0,0,1]
	v_pk_fma_f32 v[32:33], v[46:47], v[8:9], v[16:17] op_sel_hi:[0,1,1] neg_lo:[0,0,1] neg_hi:[0,0,1]
	v_pk_fma_f32 v[34:35], v[46:47], v[10:11], v[18:19] op_sel_hi:[0,1,1] neg_lo:[0,0,1] neg_hi:[0,0,1]
	v_cvt_pk_bf16_f32 v36, v28, v29
	v_cvt_pk_bf16_f32 v37, v30, v31
	v_cvt_pk_bf16_f32 v38, v32, v33
	v_cvt_pk_bf16_f32 v39, v34, v35
	global_store_dwordx4 v1, v[36:39], s[24:25]
	s_add_u32 s24, s24, 0x2000
	s_addc_u32 s25, s25, 0
	v_lshlrev_b32_e32 v12, 16, v92
	v_and_b32_e32 v13, 0xffff0000, v92
	v_lshlrev_b32_e32 v20, 16, v124
	v_and_b32_e32 v21, 0xffff0000, v124
	v_lshlrev_b32_e32 v14, 16, v93
	v_and_b32_e32 v15, 0xffff0000, v93
	v_lshlrev_b32_e32 v22, 16, v125
	v_and_b32_e32 v23, 0xffff0000, v125
	v_lshlrev_b32_e32 v16, 16, v94
	v_and_b32_e32 v17, 0xffff0000, v94
	v_lshlrev_b32_e32 v24, 16, v126
	v_and_b32_e32 v25, 0xffff0000, v126
	v_lshlrev_b32_e32 v18, 16, v95
	v_and_b32_e32 v19, 0xffff0000, v95
	v_lshlrev_b32_e32 v26, 16, v127
	v_and_b32_e32 v27, 0xffff0000, v127
	v_pk_fma_f32 v[20:21], v[44:45], v[20:21], v[12:13] op_sel_hi:[0,1,1] neg_lo:[1,0,0] neg_hi:[1,0,0]
	v_pk_fma_f32 v[22:23], v[44:45], v[22:23], v[14:15] op_sel_hi:[0,1,1] neg_lo:[1,0,0] neg_hi:[1,0,0]
	v_pk_fma_f32 v[24:25], v[44:45], v[24:25], v[16:17] op_sel_hi:[0,1,1] neg_lo:[1,0,0] neg_hi:[1,0,0]
	v_pk_fma_f32 v[26:27], v[44:45], v[26:27], v[18:19] op_sel_hi:[0,1,1] neg_lo:[1,0,0] neg_hi:[1,0,0]
	v_pk_add_f32 v[4:5], v[4:5], v[20:21]
	v_pk_add_f32 v[6:7], v[6:7], v[22:23]
	v_pk_add_f32 v[8:9], v[8:9], v[24:25]
	v_pk_add_f32 v[10:11], v[10:11], v[26:27]
	v_mov_b32_e32 v46, v3
	v_pk_fma_f32 v[28:29], v[46:47], v[4:5], v[12:13] op_sel_hi:[0,1,1] neg_lo:[0,0,1] neg_hi:[0,0,1]
	v_pk_fma_f32 v[30:31], v[46:47], v[6:7], v[14:15] op_sel_hi:[0,1,1] neg_lo:[0,0,1] neg_hi:[0,0,1]
	v_pk_fma_f32 v[32:33], v[46:47], v[8:9], v[16:17] op_sel_hi:[0,1,1] neg_lo:[0,0,1] neg_hi:[0,0,1]
	v_pk_fma_f32 v[34:35], v[46:47], v[10:11], v[18:19] op_sel_hi:[0,1,1] neg_lo:[0,0,1] neg_hi:[0,0,1]
	v_cvt_pk_bf16_f32 v40, v28, v29
	v_cvt_pk_bf16_f32 v41, v30, v31
	v_cvt_pk_bf16_f32 v42, v32, v33
	v_cvt_pk_bf16_f32 v43, v34, v35
	global_store_dwordx4 v1, v[40:43], s[24:25]
	s_add_u32 s24, s24, 0x2000
	s_addc_u32 s25, s25, 0
	global_load_dwordx4 v[64:67], v1, s[20:21]
	global_load_dwordx4 v[96:99], v49, s[22:23]
	s_add_u32 s20, s20, 0x2000
	s_addc_u32 s21, s21, 0
	s_add_u32 s22, s22, 0x2000
	s_addc_u32 s23, s23, 0
	global_load_dwordx4 v[68:71], v1, s[20:21]
	global_load_dwordx4 v[100:103], v49, s[22:23]
	s_add_u32 s20, s20, 0x2000
	s_addc_u32 s21, s21, 0
	s_add_u32 s22, s22, 0x2000
	s_addc_u32 s23, s23, 0
	global_load_dwordx4 v[72:75], v1, s[20:21]
	global_load_dwordx4 v[104:107], v49, s[22:23]
	s_add_u32 s20, s20, 0x2000
	s_addc_u32 s21, s21, 0
	s_add_u32 s22, s22, 0x2000
	s_addc_u32 s23, s23, 0
	global_load_dwordx4 v[76:79], v1, s[20:21]
	global_load_dwordx4 v[108:111], v49, s[22:23]
	s_add_u32 s20, s20, 0x2000
	s_addc_u32 s21, s21, 0
	s_add_u32 s22, s22, 0x2000
	s_addc_u32 s23, s23, 0
	global_load_dwordx4 v[80:83], v1, s[20:21]
	global_load_dwordx4 v[112:115], v49, s[22:23]
	s_add_u32 s20, s20, 0x2000
	s_addc_u32 s21, s21, 0
	s_add_u32 s22, s22, 0x2000
	s_addc_u32 s23, s23, 0
	global_load_dwordx4 v[84:87], v1, s[20:21]
	global_load_dwordx4 v[116:119], v49, s[22:23]
	s_add_u32 s20, s20, 0x2000
	s_addc_u32 s21, s21, 0
	s_add_u32 s22, s22, 0x2000
	s_addc_u32 s23, s23, 0
	global_load_dwordx4 v[88:91], v1, s[20:21]
	global_load_dwordx4 v[120:123], v49, s[22:23]
	s_add_u32 s20, s20, 0x2000
	s_addc_u32 s21, s21, 0
	s_add_u32 s22, s22, 0x2000
	s_addc_u32 s23, s23, 0
	global_load_dwordx4 v[92:95], v1, s[20:21]
	global_load_dwordx4 v[124:127], v49, s[22:23]
	s_add_u32 s20, s20, 0x2000
	s_addc_u32 s21, s21, 0
	s_add_u32 s22, s22, 0x2000
	s_addc_u32 s23, s23, 0
	s_waitcnt vmcnt(24)
	v_mov_b32_e32 v44, 1.0
	v_lshlrev_b32_e32 v12, 16, v128
	v_and_b32_e32 v13, 0xffff0000, v128
	v_lshlrev_b32_e32 v20, 16, v160
	v_and_b32_e32 v21, 0xffff0000, v160
	v_lshlrev_b32_e32 v14, 16, v129
	v_and_b32_e32 v15, 0xffff0000, v129
	v_lshlrev_b32_e32 v22, 16, v161
	v_and_b32_e32 v23, 0xffff0000, v161
	v_lshlrev_b32_e32 v16, 16, v130
	v_and_b32_e32 v17, 0xffff0000, v130
	v_lshlrev_b32_e32 v24, 16, v162
	v_and_b32_e32 v25, 0xffff0000, v162
	v_lshlrev_b32_e32 v18, 16, v131
	v_and_b32_e32 v19, 0xffff0000, v131
	v_lshlrev_b32_e32 v26, 16, v163
	v_and_b32_e32 v27, 0xffff0000, v163
	v_pk_fma_f32 v[20:21], v[44:45], v[20:21], v[12:13] op_sel_hi:[0,1,1] neg_lo:[1,0,0] neg_hi:[1,0,0]
	v_pk_fma_f32 v[22:23], v[44:45], v[22:23], v[14:15] op_sel_hi:[0,1,1] neg_lo:[1,0,0] neg_hi:[1,0,0]
	v_pk_fma_f32 v[24:25], v[44:45], v[24:25], v[16:17] op_sel_hi:[0,1,1] neg_lo:[1,0,0] neg_hi:[1,0,0]
	v_pk_fma_f32 v[26:27], v[44:45], v[26:27], v[18:19] op_sel_hi:[0,1,1] neg_lo:[1,0,0] neg_hi:[1,0,0]
	v_pk_add_f32 v[4:5], v[4:5], v[20:21]
	v_pk_add_f32 v[6:7], v[6:7], v[22:23]
	v_pk_add_f32 v[8:9], v[8:9], v[24:25]
	v_pk_add_f32 v[10:11], v[10:11], v[26:27]
	v_mov_b32_e32 v46, v3
	v_pk_fma_f32 v[28:29], v[46:47], v[4:5], v[12:13] op_sel_hi:[0,1,1] neg_lo:[0,0,1] neg_hi:[0,0,1]
	v_pk_fma_f32 v[30:31], v[46:47], v[6:7], v[14:15] op_sel_hi:[0,1,1] neg_lo:[0,0,1] neg_hi:[0,0,1]
	v_pk_fma_f32 v[32:33], v[46:47], v[8:9], v[16:17] op_sel_hi:[0,1,1] neg_lo:[0,0,1] neg_hi:[0,0,1]
	v_pk_fma_f32 v[34:35], v[46:47], v[10:11], v[18:19] op_sel_hi:[0,1,1] neg_lo:[0,0,1] neg_hi:[0,0,1]
	v_cvt_pk_bf16_f32 v36, v28, v29
	v_cvt_pk_bf16_f32 v37, v30, v31
	v_cvt_pk_bf16_f32 v38, v32, v33
	v_cvt_pk_bf16_f32 v39, v34, v35
	global_store_dwordx4 v1, v[36:39], s[24:25]
	s_add_u32 s24, s24, 0x2000
	s_addc_u32 s25, s25, 0
	v_lshlrev_b32_e32 v12, 16, v132
	v_and_b32_e32 v13, 0xffff0000, v132
	v_lshlrev_b32_e32 v20, 16, v164
	v_and_b32_e32 v21, 0xffff0000, v164
	v_lshlrev_b32_e32 v14, 16, v133
	v_and_b32_e32 v15, 0xffff0000, v133
	v_lshlrev_b32_e32 v22, 16, v165
	v_and_b32_e32 v23, 0xffff0000, v165
	v_lshlrev_b32_e32 v16, 16, v134
	v_and_b32_e32 v17, 0xffff0000, v134
	v_lshlrev_b32_e32 v24, 16, v166
	v_and_b32_e32 v25, 0xffff0000, v166
	v_lshlrev_b32_e32 v18, 16, v135
	v_and_b32_e32 v19, 0xffff0000, v135
	v_lshlrev_b32_e32 v26, 16, v167
	v_and_b32_e32 v27, 0xffff0000, v167
	v_pk_fma_f32 v[20:21], v[44:45], v[20:21], v[12:13] op_sel_hi:[0,1,1] neg_lo:[1,0,0] neg_hi:[1,0,0]
	v_pk_fma_f32 v[22:23], v[44:45], v[22:23], v[14:15] op_sel_hi:[0,1,1] neg_lo:[1,0,0] neg_hi:[1,0,0]
	v_pk_fma_f32 v[24:25], v[44:45], v[24:25], v[16:17] op_sel_hi:[0,1,1] neg_lo:[1,0,0] neg_hi:[1,0,0]
	v_pk_fma_f32 v[26:27], v[44:45], v[26:27], v[18:19] op_sel_hi:[0,1,1] neg_lo:[1,0,0] neg_hi:[1,0,0]
	v_pk_add_f32 v[4:5], v[4:5], v[20:21]
	v_pk_add_f32 v[6:7], v[6:7], v[22:23]
	v_pk_add_f32 v[8:9], v[8:9], v[24:25]
	v_pk_add_f32 v[10:11], v[10:11], v[26:27]
	v_mov_b32_e32 v46, v3
	v_pk_fma_f32 v[28:29], v[46:47], v[4:5], v[12:13] op_sel_hi:[0,1,1] neg_lo:[0,0,1] neg_hi:[0,0,1]
	v_pk_fma_f32 v[30:31], v[46:47], v[6:7], v[14:15] op_sel_hi:[0,1,1] neg_lo:[0,0,1] neg_hi:[0,0,1]
	v_pk_fma_f32 v[32:33], v[46:47], v[8:9], v[16:17] op_sel_hi:[0,1,1] neg_lo:[0,0,1] neg_hi:[0,0,1]
	v_pk_fma_f32 v[34:35], v[46:47], v[10:11], v[18:19] op_sel_hi:[0,1,1] neg_lo:[0,0,1] neg_hi:[0,0,1]
	v_cvt_pk_bf16_f32 v40, v28, v29
	v_cvt_pk_bf16_f32 v41, v30, v31
	v_cvt_pk_bf16_f32 v42, v32, v33
	v_cvt_pk_bf16_f32 v43, v34, v35
	global_store_dwordx4 v1, v[40:43], s[24:25]
	s_add_u32 s24, s24, 0x2000
	s_addc_u32 s25, s25, 0
	v_lshlrev_b32_e32 v12, 16, v136
	v_and_b32_e32 v13, 0xffff0000, v136
	v_lshlrev_b32_e32 v20, 16, v168
	v_and_b32_e32 v21, 0xffff0000, v168
	v_lshlrev_b32_e32 v14, 16, v137
	v_and_b32_e32 v15, 0xffff0000, v137
	v_lshlrev_b32_e32 v22, 16, v169
	v_and_b32_e32 v23, 0xffff0000, v169
	v_lshlrev_b32_e32 v16, 16, v138
	v_and_b32_e32 v17, 0xffff0000, v138
	v_lshlrev_b32_e32 v24, 16, v170
	v_and_b32_e32 v25, 0xffff0000, v170
	v_lshlrev_b32_e32 v18, 16, v139
	v_and_b32_e32 v19, 0xffff0000, v139
	v_lshlrev_b32_e32 v26, 16, v171
	v_and_b32_e32 v27, 0xffff0000, v171
	v_pk_fma_f32 v[20:21], v[44:45], v[20:21], v[12:13] op_sel_hi:[0,1,1] neg_lo:[1,0,0] neg_hi:[1,0,0]
	v_pk_fma_f32 v[22:23], v[44:45], v[22:23], v[14:15] op_sel_hi:[0,1,1] neg_lo:[1,0,0] neg_hi:[1,0,0]
	v_pk_fma_f32 v[24:25], v[44:45], v[24:25], v[16:17] op_sel_hi:[0,1,1] neg_lo:[1,0,0] neg_hi:[1,0,0]
	v_pk_fma_f32 v[26:27], v[44:45], v[26:27], v[18:19] op_sel_hi:[0,1,1] neg_lo:[1,0,0] neg_hi:[1,0,0]
	v_pk_add_f32 v[4:5], v[4:5], v[20:21]
	v_pk_add_f32 v[6:7], v[6:7], v[22:23]
	v_pk_add_f32 v[8:9], v[8:9], v[24:25]
	v_pk_add_f32 v[10:11], v[10:11], v[26:27]
	v_mov_b32_e32 v46, v3
	v_pk_fma_f32 v[28:29], v[46:47], v[4:5], v[12:13] op_sel_hi:[0,1,1] neg_lo:[0,0,1] neg_hi:[0,0,1]
	v_pk_fma_f32 v[30:31], v[46:47], v[6:7], v[14:15] op_sel_hi:[0,1,1] neg_lo:[0,0,1] neg_hi:[0,0,1]
	v_pk_fma_f32 v[32:33], v[46:47], v[8:9], v[16:17] op_sel_hi:[0,1,1] neg_lo:[0,0,1] neg_hi:[0,0,1]
	v_pk_fma_f32 v[34:35], v[46:47], v[10:11], v[18:19] op_sel_hi:[0,1,1] neg_lo:[0,0,1] neg_hi:[0,0,1]
	v_cvt_pk_bf16_f32 v36, v28, v29
	v_cvt_pk_bf16_f32 v37, v30, v31
	v_cvt_pk_bf16_f32 v38, v32, v33
	v_cvt_pk_bf16_f32 v39, v34, v35
	global_store_dwordx4 v1, v[36:39], s[24:25]
	s_add_u32 s24, s24, 0x2000
	s_addc_u32 s25, s25, 0
	v_lshlrev_b32_e32 v12, 16, v140
	v_and_b32_e32 v13, 0xffff0000, v140
	v_lshlrev_b32_e32 v20, 16, v172
	v_and_b32_e32 v21, 0xffff0000, v172
	v_lshlrev_b32_e32 v14, 16, v141
	v_and_b32_e32 v15, 0xffff0000, v141
	v_lshlrev_b32_e32 v22, 16, v173
	v_and_b32_e32 v23, 0xffff0000, v173
	v_lshlrev_b32_e32 v16, 16, v142
	v_and_b32_e32 v17, 0xffff0000, v142
	v_lshlrev_b32_e32 v24, 16, v174
	v_and_b32_e32 v25, 0xffff0000, v174
	v_lshlrev_b32_e32 v18, 16, v143
	v_and_b32_e32 v19, 0xffff0000, v143
	v_lshlrev_b32_e32 v26, 16, v175
	v_and_b32_e32 v27, 0xffff0000, v175
	v_pk_fma_f32 v[20:21], v[44:45], v[20:21], v[12:13] op_sel_hi:[0,1,1] neg_lo:[1,0,0] neg_hi:[1,0,0]
	v_pk_fma_f32 v[22:23], v[44:45], v[22:23], v[14:15] op_sel_hi:[0,1,1] neg_lo:[1,0,0] neg_hi:[1,0,0]
	v_pk_fma_f32 v[24:25], v[44:45], v[24:25], v[16:17] op_sel_hi:[0,1,1] neg_lo:[1,0,0] neg_hi:[1,0,0]
	v_pk_fma_f32 v[26:27], v[44:45], v[26:27], v[18:19] op_sel_hi:[0,1,1] neg_lo:[1,0,0] neg_hi:[1,0,0]
	v_pk_add_f32 v[4:5], v[4:5], v[20:21]
	v_pk_add_f32 v[6:7], v[6:7], v[22:23]
	v_pk_add_f32 v[8:9], v[8:9], v[24:25]
	v_pk_add_f32 v[10:11], v[10:11], v[26:27]
	v_mov_b32_e32 v46, v3
	v_pk_fma_f32 v[28:29], v[46:47], v[4:5], v[12:13] op_sel_hi:[0,1,1] neg_lo:[0,0,1] neg_hi:[0,0,1]
	v_pk_fma_f32 v[30:31], v[46:47], v[6:7], v[14:15] op_sel_hi:[0,1,1] neg_lo:[0,0,1] neg_hi:[0,0,1]
	v_pk_fma_f32 v[32:33], v[46:47], v[8:9], v[16:17] op_sel_hi:[0,1,1] neg_lo:[0,0,1] neg_hi:[0,0,1]
	v_pk_fma_f32 v[34:35], v[46:47], v[10:11], v[18:19] op_sel_hi:[0,1,1] neg_lo:[0,0,1] neg_hi:[0,0,1]
	v_cvt_pk_bf16_f32 v40, v28, v29
	v_cvt_pk_bf16_f32 v41, v30, v31
	v_cvt_pk_bf16_f32 v42, v32, v33
	v_cvt_pk_bf16_f32 v43, v34, v35
	global_store_dwordx4 v1, v[40:43], s[24:25]
	s_add_u32 s24, s24, 0x2000
	s_addc_u32 s25, s25, 0
	v_lshlrev_b32_e32 v12, 16, v144
	v_and_b32_e32 v13, 0xffff0000, v144
	v_lshlrev_b32_e32 v20, 16, v176
	v_and_b32_e32 v21, 0xffff0000, v176
	v_lshlrev_b32_e32 v14, 16, v145
	v_and_b32_e32 v15, 0xffff0000, v145
	v_lshlrev_b32_e32 v22, 16, v177
	v_and_b32_e32 v23, 0xffff0000, v177
	v_lshlrev_b32_e32 v16, 16, v146
	v_and_b32_e32 v17, 0xffff0000, v146
	v_lshlrev_b32_e32 v24, 16, v178
	v_and_b32_e32 v25, 0xffff0000, v178
	v_lshlrev_b32_e32 v18, 16, v147
	v_and_b32_e32 v19, 0xffff0000, v147
	v_lshlrev_b32_e32 v26, 16, v179
	v_and_b32_e32 v27, 0xffff0000, v179
	v_pk_fma_f32 v[20:21], v[44:45], v[20:21], v[12:13] op_sel_hi:[0,1,1] neg_lo:[1,0,0] neg_hi:[1,0,0]
	v_pk_fma_f32 v[22:23], v[44:45], v[22:23], v[14:15] op_sel_hi:[0,1,1] neg_lo:[1,0,0] neg_hi:[1,0,0]
	v_pk_fma_f32 v[24:25], v[44:45], v[24:25], v[16:17] op_sel_hi:[0,1,1] neg_lo:[1,0,0] neg_hi:[1,0,0]
	v_pk_fma_f32 v[26:27], v[44:45], v[26:27], v[18:19] op_sel_hi:[0,1,1] neg_lo:[1,0,0] neg_hi:[1,0,0]
	v_pk_add_f32 v[4:5], v[4:5], v[20:21]
	v_pk_add_f32 v[6:7], v[6:7], v[22:23]
	v_pk_add_f32 v[8:9], v[8:9], v[24:25]
	v_pk_add_f32 v[10:11], v[10:11], v[26:27]
	v_mov_b32_e32 v46, v3
	v_pk_fma_f32 v[28:29], v[46:47], v[4:5], v[12:13] op_sel_hi:[0,1,1] neg_lo:[0,0,1] neg_hi:[0,0,1]
	v_pk_fma_f32 v[30:31], v[46:47], v[6:7], v[14:15] op_sel_hi:[0,1,1] neg_lo:[0,0,1] neg_hi:[0,0,1]
	v_pk_fma_f32 v[32:33], v[46:47], v[8:9], v[16:17] op_sel_hi:[0,1,1] neg_lo:[0,0,1] neg_hi:[0,0,1]
	v_pk_fma_f32 v[34:35], v[46:47], v[10:11], v[18:19] op_sel_hi:[0,1,1] neg_lo:[0,0,1] neg_hi:[0,0,1]
	v_cvt_pk_bf16_f32 v36, v28, v29
	v_cvt_pk_bf16_f32 v37, v30, v31
	v_cvt_pk_bf16_f32 v38, v32, v33
	v_cvt_pk_bf16_f32 v39, v34, v35
	global_store_dwordx4 v1, v[36:39], s[24:25]
	s_add_u32 s24, s24, 0x2000
	s_addc_u32 s25, s25, 0
	v_lshlrev_b32_e32 v12, 16, v148
	v_and_b32_e32 v13, 0xffff0000, v148
	v_lshlrev_b32_e32 v20, 16, v180
	v_and_b32_e32 v21, 0xffff0000, v180
	v_lshlrev_b32_e32 v14, 16, v149
	v_and_b32_e32 v15, 0xffff0000, v149
	v_lshlrev_b32_e32 v22, 16, v181
	v_and_b32_e32 v23, 0xffff0000, v181
	v_lshlrev_b32_e32 v16, 16, v150
	v_and_b32_e32 v17, 0xffff0000, v150
	v_lshlrev_b32_e32 v24, 16, v182
	v_and_b32_e32 v25, 0xffff0000, v182
	v_lshlrev_b32_e32 v18, 16, v151
	v_and_b32_e32 v19, 0xffff0000, v151
	v_lshlrev_b32_e32 v26, 16, v183
	v_and_b32_e32 v27, 0xffff0000, v183
	v_pk_fma_f32 v[20:21], v[44:45], v[20:21], v[12:13] op_sel_hi:[0,1,1] neg_lo:[1,0,0] neg_hi:[1,0,0]
	v_pk_fma_f32 v[22:23], v[44:45], v[22:23], v[14:15] op_sel_hi:[0,1,1] neg_lo:[1,0,0] neg_hi:[1,0,0]
	v_pk_fma_f32 v[24:25], v[44:45], v[24:25], v[16:17] op_sel_hi:[0,1,1] neg_lo:[1,0,0] neg_hi:[1,0,0]
	v_pk_fma_f32 v[26:27], v[44:45], v[26:27], v[18:19] op_sel_hi:[0,1,1] neg_lo:[1,0,0] neg_hi:[1,0,0]
	v_pk_add_f32 v[4:5], v[4:5], v[20:21]
	v_pk_add_f32 v[6:7], v[6:7], v[22:23]
	v_pk_add_f32 v[8:9], v[8:9], v[24:25]
	v_pk_add_f32 v[10:11], v[10:11], v[26:27]
	v_mov_b32_e32 v46, v3
	v_pk_fma_f32 v[28:29], v[46:47], v[4:5], v[12:13] op_sel_hi:[0,1,1] neg_lo:[0,0,1] neg_hi:[0,0,1]
	v_pk_fma_f32 v[30:31], v[46:47], v[6:7], v[14:15] op_sel_hi:[0,1,1] neg_lo:[0,0,1] neg_hi:[0,0,1]
	v_pk_fma_f32 v[32:33], v[46:47], v[8:9], v[16:17] op_sel_hi:[0,1,1] neg_lo:[0,0,1] neg_hi:[0,0,1]
	v_pk_fma_f32 v[34:35], v[46:47], v[10:11], v[18:19] op_sel_hi:[0,1,1] neg_lo:[0,0,1] neg_hi:[0,0,1]
	v_cvt_pk_bf16_f32 v40, v28, v29
	v_cvt_pk_bf16_f32 v41, v30, v31
	v_cvt_pk_bf16_f32 v42, v32, v33
	v_cvt_pk_bf16_f32 v43, v34, v35
	global_store_dwordx4 v1, v[40:43], s[24:25]
	s_add_u32 s24, s24, 0x2000
	s_addc_u32 s25, s25, 0
	v_lshlrev_b32_e32 v12, 16, v152
	v_and_b32_e32 v13, 0xffff0000, v152
	v_lshlrev_b32_e32 v20, 16, v184
	v_and_b32_e32 v21, 0xffff0000, v184
	v_lshlrev_b32_e32 v14, 16, v153
	v_and_b32_e32 v15, 0xffff0000, v153
	v_lshlrev_b32_e32 v22, 16, v185
	v_and_b32_e32 v23, 0xffff0000, v185
	v_lshlrev_b32_e32 v16, 16, v154
	v_and_b32_e32 v17, 0xffff0000, v154
	v_lshlrev_b32_e32 v24, 16, v186
	v_and_b32_e32 v25, 0xffff0000, v186
	v_lshlrev_b32_e32 v18, 16, v155
	v_and_b32_e32 v19, 0xffff0000, v155
	v_lshlrev_b32_e32 v26, 16, v187
	v_and_b32_e32 v27, 0xffff0000, v187
	v_pk_fma_f32 v[20:21], v[44:45], v[20:21], v[12:13] op_sel_hi:[0,1,1] neg_lo:[1,0,0] neg_hi:[1,0,0]
	v_pk_fma_f32 v[22:23], v[44:45], v[22:23], v[14:15] op_sel_hi:[0,1,1] neg_lo:[1,0,0] neg_hi:[1,0,0]
	v_pk_fma_f32 v[24:25], v[44:45], v[24:25], v[16:17] op_sel_hi:[0,1,1] neg_lo:[1,0,0] neg_hi:[1,0,0]
	v_pk_fma_f32 v[26:27], v[44:45], v[26:27], v[18:19] op_sel_hi:[0,1,1] neg_lo:[1,0,0] neg_hi:[1,0,0]
	v_pk_add_f32 v[4:5], v[4:5], v[20:21]
	v_pk_add_f32 v[6:7], v[6:7], v[22:23]
	v_pk_add_f32 v[8:9], v[8:9], v[24:25]
	v_pk_add_f32 v[10:11], v[10:11], v[26:27]
	v_mov_b32_e32 v46, v3
	v_pk_fma_f32 v[28:29], v[46:47], v[4:5], v[12:13] op_sel_hi:[0,1,1] neg_lo:[0,0,1] neg_hi:[0,0,1]
	v_pk_fma_f32 v[30:31], v[46:47], v[6:7], v[14:15] op_sel_hi:[0,1,1] neg_lo:[0,0,1] neg_hi:[0,0,1]
	v_pk_fma_f32 v[32:33], v[46:47], v[8:9], v[16:17] op_sel_hi:[0,1,1] neg_lo:[0,0,1] neg_hi:[0,0,1]
	v_pk_fma_f32 v[34:35], v[46:47], v[10:11], v[18:19] op_sel_hi:[0,1,1] neg_lo:[0,0,1] neg_hi:[0,0,1]
	v_cvt_pk_bf16_f32 v36, v28, v29
	v_cvt_pk_bf16_f32 v37, v30, v31
	v_cvt_pk_bf16_f32 v38, v32, v33
	v_cvt_pk_bf16_f32 v39, v34, v35
	global_store_dwordx4 v1, v[36:39], s[24:25]
	s_add_u32 s24, s24, 0x2000
	s_addc_u32 s25, s25, 0
	v_lshlrev_b32_e32 v12, 16, v156
	v_and_b32_e32 v13, 0xffff0000, v156
	v_lshlrev_b32_e32 v20, 16, v188
	v_and_b32_e32 v21, 0xffff0000, v188
	v_lshlrev_b32_e32 v14, 16, v157
	v_and_b32_e32 v15, 0xffff0000, v157
	v_lshlrev_b32_e32 v22, 16, v189
	v_and_b32_e32 v23, 0xffff0000, v189
	v_lshlrev_b32_e32 v16, 16, v158
	v_and_b32_e32 v17, 0xffff0000, v158
	v_lshlrev_b32_e32 v24, 16, v190
	v_and_b32_e32 v25, 0xffff0000, v190
	v_lshlrev_b32_e32 v18, 16, v159
	v_and_b32_e32 v19, 0xffff0000, v159
	v_lshlrev_b32_e32 v26, 16, v191
	v_and_b32_e32 v27, 0xffff0000, v191
	v_pk_fma_f32 v[20:21], v[44:45], v[20:21], v[12:13] op_sel_hi:[0,1,1] neg_lo:[1,0,0] neg_hi:[1,0,0]
	v_pk_fma_f32 v[22:23], v[44:45], v[22:23], v[14:15] op_sel_hi:[0,1,1] neg_lo:[1,0,0] neg_hi:[1,0,0]
	v_pk_fma_f32 v[24:25], v[44:45], v[24:25], v[16:17] op_sel_hi:[0,1,1] neg_lo:[1,0,0] neg_hi:[1,0,0]
	v_pk_fma_f32 v[26:27], v[44:45], v[26:27], v[18:19] op_sel_hi:[0,1,1] neg_lo:[1,0,0] neg_hi:[1,0,0]
	v_pk_add_f32 v[4:5], v[4:5], v[20:21]
	v_pk_add_f32 v[6:7], v[6:7], v[22:23]
	v_pk_add_f32 v[8:9], v[8:9], v[24:25]
	v_pk_add_f32 v[10:11], v[10:11], v[26:27]
	v_mov_b32_e32 v46, v3
	v_pk_fma_f32 v[28:29], v[46:47], v[4:5], v[12:13] op_sel_hi:[0,1,1] neg_lo:[0,0,1] neg_hi:[0,0,1]
	v_pk_fma_f32 v[30:31], v[46:47], v[6:7], v[14:15] op_sel_hi:[0,1,1] neg_lo:[0,0,1] neg_hi:[0,0,1]
	v_pk_fma_f32 v[32:33], v[46:47], v[8:9], v[16:17] op_sel_hi:[0,1,1] neg_lo:[0,0,1] neg_hi:[0,0,1]
	v_pk_fma_f32 v[34:35], v[46:47], v[10:11], v[18:19] op_sel_hi:[0,1,1] neg_lo:[0,0,1] neg_hi:[0,0,1]
	v_cvt_pk_bf16_f32 v40, v28, v29
	v_cvt_pk_bf16_f32 v41, v30, v31
	v_cvt_pk_bf16_f32 v42, v32, v33
	v_cvt_pk_bf16_f32 v43, v34, v35
	global_store_dwordx4 v1, v[40:43], s[24:25]
	s_add_u32 s24, s24, 0x2000
	s_addc_u32 s25, s25, 0
	global_load_dwordx4 v[128:131], v1, s[20:21]
	global_load_dwordx4 v[160:163], v49, s[22:23]
	s_add_u32 s20, s20, 0x2000
	s_addc_u32 s21, s21, 0
	s_add_u32 s22, s22, 0x2000
	s_addc_u32 s23, s23, 0
	global_load_dwordx4 v[132:135], v1, s[20:21]
	global_load_dwordx4 v[164:167], v49, s[22:23]
	s_add_u32 s20, s20, 0x2000
	s_addc_u32 s21, s21, 0
	s_add_u32 s22, s22, 0x2000
	s_addc_u32 s23, s23, 0
	global_load_dwordx4 v[136:139], v1, s[20:21]
	global_load_dwordx4 v[168:171], v49, s[22:23]
	s_add_u32 s20, s20, 0x2000
	s_addc_u32 s21, s21, 0
	s_add_u32 s22, s22, 0x2000
	s_addc_u32 s23, s23, 0
	global_load_dwordx4 v[140:143], v1, s[20:21]
	global_load_dwordx4 v[172:175], v49, s[22:23]
	s_add_u32 s20, s20, 0x2000
	s_addc_u32 s21, s21, 0
	s_add_u32 s22, s22, 0x2000
	s_addc_u32 s23, s23, 0
	global_load_dwordx4 v[144:147], v1, s[20:21]
	global_load_dwordx4 v[176:179], v49, s[22:23]
	s_add_u32 s20, s20, 0x2000
	s_addc_u32 s21, s21, 0
	s_add_u32 s22, s22, 0x2000
	s_addc_u32 s23, s23, 0
	global_load_dwordx4 v[148:151], v1, s[20:21]
	global_load_dwordx4 v[180:183], v49, s[22:23]
	s_add_u32 s20, s20, 0x2000
	s_addc_u32 s21, s21, 0
	s_add_u32 s22, s22, 0x2000
	s_addc_u32 s23, s23, 0
	global_load_dwordx4 v[152:155], v1, s[20:21]
	global_load_dwordx4 v[184:187], v49, s[22:23]
	s_add_u32 s20, s20, 0x2000
	s_addc_u32 s21, s21, 0
	s_add_u32 s22, s22, 0x2000
	s_addc_u32 s23, s23, 0
	global_load_dwordx4 v[156:159], v1, s[20:21]
	global_load_dwordx4 v[188:191], v49, s[22:23]
	s_add_u32 s20, s20, 0x2000
	s_addc_u32 s21, s21, 0
	s_add_u32 s22, s22, 0x2000
	s_addc_u32 s23, s23, 0
	s_waitcnt vmcnt(24)
	v_mov_b32_e32 v44, 1.0
	v_lshlrev_b32_e32 v12, 16, v64
	v_and_b32_e32 v13, 0xffff0000, v64
	v_lshlrev_b32_e32 v20, 16, v96
	v_and_b32_e32 v21, 0xffff0000, v96
	v_lshlrev_b32_e32 v14, 16, v65
	v_and_b32_e32 v15, 0xffff0000, v65
	v_lshlrev_b32_e32 v22, 16, v97
	v_and_b32_e32 v23, 0xffff0000, v97
	v_lshlrev_b32_e32 v16, 16, v66
	v_and_b32_e32 v17, 0xffff0000, v66
	v_lshlrev_b32_e32 v24, 16, v98
	v_and_b32_e32 v25, 0xffff0000, v98
	v_lshlrev_b32_e32 v18, 16, v67
	v_and_b32_e32 v19, 0xffff0000, v67
	v_lshlrev_b32_e32 v26, 16, v99
	v_and_b32_e32 v27, 0xffff0000, v99
	v_pk_fma_f32 v[20:21], v[44:45], v[20:21], v[12:13] op_sel_hi:[0,1,1] neg_lo:[1,0,0] neg_hi:[1,0,0]
	v_pk_fma_f32 v[22:23], v[44:45], v[22:23], v[14:15] op_sel_hi:[0,1,1] neg_lo:[1,0,0] neg_hi:[1,0,0]
	v_pk_fma_f32 v[24:25], v[44:45], v[24:25], v[16:17] op_sel_hi:[0,1,1] neg_lo:[1,0,0] neg_hi:[1,0,0]
	v_pk_fma_f32 v[26:27], v[44:45], v[26:27], v[18:19] op_sel_hi:[0,1,1] neg_lo:[1,0,0] neg_hi:[1,0,0]
	v_pk_add_f32 v[4:5], v[4:5], v[20:21]
	v_pk_add_f32 v[6:7], v[6:7], v[22:23]
	v_pk_add_f32 v[8:9], v[8:9], v[24:25]
	v_pk_add_f32 v[10:11], v[10:11], v[26:27]
	v_mov_b32_e32 v46, v3
	v_pk_fma_f32 v[28:29], v[46:47], v[4:5], v[12:13] op_sel_hi:[0,1,1] neg_lo:[0,0,1] neg_hi:[0,0,1]
	v_pk_fma_f32 v[30:31], v[46:47], v[6:7], v[14:15] op_sel_hi:[0,1,1] neg_lo:[0,0,1] neg_hi:[0,0,1]
	v_pk_fma_f32 v[32:33], v[46:47], v[8:9], v[16:17] op_sel_hi:[0,1,1] neg_lo:[0,0,1] neg_hi:[0,0,1]
	v_pk_fma_f32 v[34:35], v[46:47], v[10:11], v[18:19] op_sel_hi:[0,1,1] neg_lo:[0,0,1] neg_hi:[0,0,1]
	v_cvt_pk_bf16_f32 v36, v28, v29
	v_cvt_pk_bf16_f32 v37, v30, v31
	v_cvt_pk_bf16_f32 v38, v32, v33
	v_cvt_pk_bf16_f32 v39, v34, v35
	global_store_dwordx4 v1, v[36:39], s[24:25]
	s_add_u32 s24, s24, 0x2000
	s_addc_u32 s25, s25, 0
	v_lshlrev_b32_e32 v12, 16, v68
	v_and_b32_e32 v13, 0xffff0000, v68
	v_lshlrev_b32_e32 v20, 16, v100
	v_and_b32_e32 v21, 0xffff0000, v100
	v_lshlrev_b32_e32 v14, 16, v69
	v_and_b32_e32 v15, 0xffff0000, v69
	v_lshlrev_b32_e32 v22, 16, v101
	v_and_b32_e32 v23, 0xffff0000, v101
	v_lshlrev_b32_e32 v16, 16, v70
	v_and_b32_e32 v17, 0xffff0000, v70
	v_lshlrev_b32_e32 v24, 16, v102
	v_and_b32_e32 v25, 0xffff0000, v102
	v_lshlrev_b32_e32 v18, 16, v71
	v_and_b32_e32 v19, 0xffff0000, v71
	v_lshlrev_b32_e32 v26, 16, v103
	v_and_b32_e32 v27, 0xffff0000, v103
	v_pk_fma_f32 v[20:21], v[44:45], v[20:21], v[12:13] op_sel_hi:[0,1,1] neg_lo:[1,0,0] neg_hi:[1,0,0]
	v_pk_fma_f32 v[22:23], v[44:45], v[22:23], v[14:15] op_sel_hi:[0,1,1] neg_lo:[1,0,0] neg_hi:[1,0,0]
	v_pk_fma_f32 v[24:25], v[44:45], v[24:25], v[16:17] op_sel_hi:[0,1,1] neg_lo:[1,0,0] neg_hi:[1,0,0]
	v_pk_fma_f32 v[26:27], v[44:45], v[26:27], v[18:19] op_sel_hi:[0,1,1] neg_lo:[1,0,0] neg_hi:[1,0,0]
	v_pk_add_f32 v[4:5], v[4:5], v[20:21]
	v_pk_add_f32 v[6:7], v[6:7], v[22:23]
	v_pk_add_f32 v[8:9], v[8:9], v[24:25]
	v_pk_add_f32 v[10:11], v[10:11], v[26:27]
	v_mov_b32_e32 v46, v3
	v_pk_fma_f32 v[28:29], v[46:47], v[4:5], v[12:13] op_sel_hi:[0,1,1] neg_lo:[0,0,1] neg_hi:[0,0,1]
	v_pk_fma_f32 v[30:31], v[46:47], v[6:7], v[14:15] op_sel_hi:[0,1,1] neg_lo:[0,0,1] neg_hi:[0,0,1]
	v_pk_fma_f32 v[32:33], v[46:47], v[8:9], v[16:17] op_sel_hi:[0,1,1] neg_lo:[0,0,1] neg_hi:[0,0,1]
	v_pk_fma_f32 v[34:35], v[46:47], v[10:11], v[18:19] op_sel_hi:[0,1,1] neg_lo:[0,0,1] neg_hi:[0,0,1]
	v_cvt_pk_bf16_f32 v40, v28, v29
	v_cvt_pk_bf16_f32 v41, v30, v31
	v_cvt_pk_bf16_f32 v42, v32, v33
	v_cvt_pk_bf16_f32 v43, v34, v35
	global_store_dwordx4 v1, v[40:43], s[24:25]
	s_add_u32 s24, s24, 0x2000
	s_addc_u32 s25, s25, 0
	v_lshlrev_b32_e32 v12, 16, v72
	v_and_b32_e32 v13, 0xffff0000, v72
	v_lshlrev_b32_e32 v20, 16, v104
	v_and_b32_e32 v21, 0xffff0000, v104
	v_lshlrev_b32_e32 v14, 16, v73
	v_and_b32_e32 v15, 0xffff0000, v73
	v_lshlrev_b32_e32 v22, 16, v105
	v_and_b32_e32 v23, 0xffff0000, v105
	v_lshlrev_b32_e32 v16, 16, v74
	v_and_b32_e32 v17, 0xffff0000, v74
	v_lshlrev_b32_e32 v24, 16, v106
	v_and_b32_e32 v25, 0xffff0000, v106
	v_lshlrev_b32_e32 v18, 16, v75
	v_and_b32_e32 v19, 0xffff0000, v75
	v_lshlrev_b32_e32 v26, 16, v107
	v_and_b32_e32 v27, 0xffff0000, v107
	v_pk_fma_f32 v[20:21], v[44:45], v[20:21], v[12:13] op_sel_hi:[0,1,1] neg_lo:[1,0,0] neg_hi:[1,0,0]
	v_pk_fma_f32 v[22:23], v[44:45], v[22:23], v[14:15] op_sel_hi:[0,1,1] neg_lo:[1,0,0] neg_hi:[1,0,0]
	v_pk_fma_f32 v[24:25], v[44:45], v[24:25], v[16:17] op_sel_hi:[0,1,1] neg_lo:[1,0,0] neg_hi:[1,0,0]
	v_pk_fma_f32 v[26:27], v[44:45], v[26:27], v[18:19] op_sel_hi:[0,1,1] neg_lo:[1,0,0] neg_hi:[1,0,0]
	v_pk_add_f32 v[4:5], v[4:5], v[20:21]
	v_pk_add_f32 v[6:7], v[6:7], v[22:23]
	v_pk_add_f32 v[8:9], v[8:9], v[24:25]
	v_pk_add_f32 v[10:11], v[10:11], v[26:27]
	v_mov_b32_e32 v46, v3
	v_pk_fma_f32 v[28:29], v[46:47], v[4:5], v[12:13] op_sel_hi:[0,1,1] neg_lo:[0,0,1] neg_hi:[0,0,1]
	v_pk_fma_f32 v[30:31], v[46:47], v[6:7], v[14:15] op_sel_hi:[0,1,1] neg_lo:[0,0,1] neg_hi:[0,0,1]
	v_pk_fma_f32 v[32:33], v[46:47], v[8:9], v[16:17] op_sel_hi:[0,1,1] neg_lo:[0,0,1] neg_hi:[0,0,1]
	v_pk_fma_f32 v[34:35], v[46:47], v[10:11], v[18:19] op_sel_hi:[0,1,1] neg_lo:[0,0,1] neg_hi:[0,0,1]
	v_cvt_pk_bf16_f32 v36, v28, v29
	v_cvt_pk_bf16_f32 v37, v30, v31
	v_cvt_pk_bf16_f32 v38, v32, v33
	v_cvt_pk_bf16_f32 v39, v34, v35
	global_store_dwordx4 v1, v[36:39], s[24:25]
	s_add_u32 s24, s24, 0x2000
	s_addc_u32 s25, s25, 0
	v_lshlrev_b32_e32 v12, 16, v76
	v_and_b32_e32 v13, 0xffff0000, v76
	v_lshlrev_b32_e32 v20, 16, v108
	v_and_b32_e32 v21, 0xffff0000, v108
	v_lshlrev_b32_e32 v14, 16, v77
	v_and_b32_e32 v15, 0xffff0000, v77
	v_lshlrev_b32_e32 v22, 16, v109
	v_and_b32_e32 v23, 0xffff0000, v109
	v_lshlrev_b32_e32 v16, 16, v78
	v_and_b32_e32 v17, 0xffff0000, v78
	v_lshlrev_b32_e32 v24, 16, v110
	v_and_b32_e32 v25, 0xffff0000, v110
	v_lshlrev_b32_e32 v18, 16, v79
	v_and_b32_e32 v19, 0xffff0000, v79
	v_lshlrev_b32_e32 v26, 16, v111
	v_and_b32_e32 v27, 0xffff0000, v111
	v_pk_fma_f32 v[20:21], v[44:45], v[20:21], v[12:13] op_sel_hi:[0,1,1] neg_lo:[1,0,0] neg_hi:[1,0,0]
	v_pk_fma_f32 v[22:23], v[44:45], v[22:23], v[14:15] op_sel_hi:[0,1,1] neg_lo:[1,0,0] neg_hi:[1,0,0]
	v_pk_fma_f32 v[24:25], v[44:45], v[24:25], v[16:17] op_sel_hi:[0,1,1] neg_lo:[1,0,0] neg_hi:[1,0,0]
	v_pk_fma_f32 v[26:27], v[44:45], v[26:27], v[18:19] op_sel_hi:[0,1,1] neg_lo:[1,0,0] neg_hi:[1,0,0]
	v_pk_add_f32 v[4:5], v[4:5], v[20:21]
	v_pk_add_f32 v[6:7], v[6:7], v[22:23]
	v_pk_add_f32 v[8:9], v[8:9], v[24:25]
	v_pk_add_f32 v[10:11], v[10:11], v[26:27]
	v_mov_b32_e32 v46, v3
	v_pk_fma_f32 v[28:29], v[46:47], v[4:5], v[12:13] op_sel_hi:[0,1,1] neg_lo:[0,0,1] neg_hi:[0,0,1]
	v_pk_fma_f32 v[30:31], v[46:47], v[6:7], v[14:15] op_sel_hi:[0,1,1] neg_lo:[0,0,1] neg_hi:[0,0,1]
	v_pk_fma_f32 v[32:33], v[46:47], v[8:9], v[16:17] op_sel_hi:[0,1,1] neg_lo:[0,0,1] neg_hi:[0,0,1]
	v_pk_fma_f32 v[34:35], v[46:47], v[10:11], v[18:19] op_sel_hi:[0,1,1] neg_lo:[0,0,1] neg_hi:[0,0,1]
	v_cvt_pk_bf16_f32 v40, v28, v29
	v_cvt_pk_bf16_f32 v41, v30, v31
	v_cvt_pk_bf16_f32 v42, v32, v33
	v_cvt_pk_bf16_f32 v43, v34, v35
	global_store_dwordx4 v1, v[40:43], s[24:25]
	s_add_u32 s24, s24, 0x2000
	s_addc_u32 s25, s25, 0
	v_lshlrev_b32_e32 v12, 16, v80
	v_and_b32_e32 v13, 0xffff0000, v80
	v_lshlrev_b32_e32 v20, 16, v112
	v_and_b32_e32 v21, 0xffff0000, v112
	v_lshlrev_b32_e32 v14, 16, v81
	v_and_b32_e32 v15, 0xffff0000, v81
	v_lshlrev_b32_e32 v22, 16, v113
	v_and_b32_e32 v23, 0xffff0000, v113
	v_lshlrev_b32_e32 v16, 16, v82
	v_and_b32_e32 v17, 0xffff0000, v82
	v_lshlrev_b32_e32 v24, 16, v114
	v_and_b32_e32 v25, 0xffff0000, v114
	v_lshlrev_b32_e32 v18, 16, v83
	v_and_b32_e32 v19, 0xffff0000, v83
	v_lshlrev_b32_e32 v26, 16, v115
	v_and_b32_e32 v27, 0xffff0000, v115
	v_pk_fma_f32 v[20:21], v[44:45], v[20:21], v[12:13] op_sel_hi:[0,1,1] neg_lo:[1,0,0] neg_hi:[1,0,0]
	v_pk_fma_f32 v[22:23], v[44:45], v[22:23], v[14:15] op_sel_hi:[0,1,1] neg_lo:[1,0,0] neg_hi:[1,0,0]
	v_pk_fma_f32 v[24:25], v[44:45], v[24:25], v[16:17] op_sel_hi:[0,1,1] neg_lo:[1,0,0] neg_hi:[1,0,0]
	v_pk_fma_f32 v[26:27], v[44:45], v[26:27], v[18:19] op_sel_hi:[0,1,1] neg_lo:[1,0,0] neg_hi:[1,0,0]
	v_pk_add_f32 v[4:5], v[4:5], v[20:21]
	v_pk_add_f32 v[6:7], v[6:7], v[22:23]
	v_pk_add_f32 v[8:9], v[8:9], v[24:25]
	v_pk_add_f32 v[10:11], v[10:11], v[26:27]
	v_mov_b32_e32 v46, v3
	v_pk_fma_f32 v[28:29], v[46:47], v[4:5], v[12:13] op_sel_hi:[0,1,1] neg_lo:[0,0,1] neg_hi:[0,0,1]
	v_pk_fma_f32 v[30:31], v[46:47], v[6:7], v[14:15] op_sel_hi:[0,1,1] neg_lo:[0,0,1] neg_hi:[0,0,1]
	v_pk_fma_f32 v[32:33], v[46:47], v[8:9], v[16:17] op_sel_hi:[0,1,1] neg_lo:[0,0,1] neg_hi:[0,0,1]
	v_pk_fma_f32 v[34:35], v[46:47], v[10:11], v[18:19] op_sel_hi:[0,1,1] neg_lo:[0,0,1] neg_hi:[0,0,1]
	v_cvt_pk_bf16_f32 v36, v28, v29
	v_cvt_pk_bf16_f32 v37, v30, v31
	v_cvt_pk_bf16_f32 v38, v32, v33
	v_cvt_pk_bf16_f32 v39, v34, v35
	global_store_dwordx4 v1, v[36:39], s[24:25]
	s_add_u32 s24, s24, 0x2000
	s_addc_u32 s25, s25, 0
	v_lshlrev_b32_e32 v12, 16, v84
	v_and_b32_e32 v13, 0xffff0000, v84
	v_lshlrev_b32_e32 v20, 16, v116
	v_and_b32_e32 v21, 0xffff0000, v116
	v_lshlrev_b32_e32 v14, 16, v85
	v_and_b32_e32 v15, 0xffff0000, v85
	v_lshlrev_b32_e32 v22, 16, v117
	v_and_b32_e32 v23, 0xffff0000, v117
	v_lshlrev_b32_e32 v16, 16, v86
	v_and_b32_e32 v17, 0xffff0000, v86
	v_lshlrev_b32_e32 v24, 16, v118
	v_and_b32_e32 v25, 0xffff0000, v118
	v_lshlrev_b32_e32 v18, 16, v87
	v_and_b32_e32 v19, 0xffff0000, v87
	v_lshlrev_b32_e32 v26, 16, v119
	v_and_b32_e32 v27, 0xffff0000, v119
	v_pk_fma_f32 v[20:21], v[44:45], v[20:21], v[12:13] op_sel_hi:[0,1,1] neg_lo:[1,0,0] neg_hi:[1,0,0]
	v_pk_fma_f32 v[22:23], v[44:45], v[22:23], v[14:15] op_sel_hi:[0,1,1] neg_lo:[1,0,0] neg_hi:[1,0,0]
	v_pk_fma_f32 v[24:25], v[44:45], v[24:25], v[16:17] op_sel_hi:[0,1,1] neg_lo:[1,0,0] neg_hi:[1,0,0]
	v_pk_fma_f32 v[26:27], v[44:45], v[26:27], v[18:19] op_sel_hi:[0,1,1] neg_lo:[1,0,0] neg_hi:[1,0,0]
	v_pk_add_f32 v[4:5], v[4:5], v[20:21]
	v_pk_add_f32 v[6:7], v[6:7], v[22:23]
	v_pk_add_f32 v[8:9], v[8:9], v[24:25]
	v_pk_add_f32 v[10:11], v[10:11], v[26:27]
	v_mov_b32_e32 v46, v3
	v_pk_fma_f32 v[28:29], v[46:47], v[4:5], v[12:13] op_sel_hi:[0,1,1] neg_lo:[0,0,1] neg_hi:[0,0,1]
	v_pk_fma_f32 v[30:31], v[46:47], v[6:7], v[14:15] op_sel_hi:[0,1,1] neg_lo:[0,0,1] neg_hi:[0,0,1]
	v_pk_fma_f32 v[32:33], v[46:47], v[8:9], v[16:17] op_sel_hi:[0,1,1] neg_lo:[0,0,1] neg_hi:[0,0,1]
	v_pk_fma_f32 v[34:35], v[46:47], v[10:11], v[18:19] op_sel_hi:[0,1,1] neg_lo:[0,0,1] neg_hi:[0,0,1]
	v_cvt_pk_bf16_f32 v40, v28, v29
	v_cvt_pk_bf16_f32 v41, v30, v31
	v_cvt_pk_bf16_f32 v42, v32, v33
	v_cvt_pk_bf16_f32 v43, v34, v35
	global_store_dwordx4 v1, v[40:43], s[24:25]
	s_add_u32 s24, s24, 0x2000
	s_addc_u32 s25, s25, 0
	v_lshlrev_b32_e32 v12, 16, v88
	v_and_b32_e32 v13, 0xffff0000, v88
	v_lshlrev_b32_e32 v20, 16, v120
	v_and_b32_e32 v21, 0xffff0000, v120
	v_lshlrev_b32_e32 v14, 16, v89
	v_and_b32_e32 v15, 0xffff0000, v89
	v_lshlrev_b32_e32 v22, 16, v121
	v_and_b32_e32 v23, 0xffff0000, v121
	v_lshlrev_b32_e32 v16, 16, v90
	v_and_b32_e32 v17, 0xffff0000, v90
	v_lshlrev_b32_e32 v24, 16, v122
	v_and_b32_e32 v25, 0xffff0000, v122
	v_lshlrev_b32_e32 v18, 16, v91
	v_and_b32_e32 v19, 0xffff0000, v91
	v_lshlrev_b32_e32 v26, 16, v123
	v_and_b32_e32 v27, 0xffff0000, v123
	v_pk_fma_f32 v[20:21], v[44:45], v[20:21], v[12:13] op_sel_hi:[0,1,1] neg_lo:[1,0,0] neg_hi:[1,0,0]
	v_pk_fma_f32 v[22:23], v[44:45], v[22:23], v[14:15] op_sel_hi:[0,1,1] neg_lo:[1,0,0] neg_hi:[1,0,0]
	v_pk_fma_f32 v[24:25], v[44:45], v[24:25], v[16:17] op_sel_hi:[0,1,1] neg_lo:[1,0,0] neg_hi:[1,0,0]
	v_pk_fma_f32 v[26:27], v[44:45], v[26:27], v[18:19] op_sel_hi:[0,1,1] neg_lo:[1,0,0] neg_hi:[1,0,0]
	v_pk_add_f32 v[4:5], v[4:5], v[20:21]
	v_pk_add_f32 v[6:7], v[6:7], v[22:23]
	v_pk_add_f32 v[8:9], v[8:9], v[24:25]
	v_pk_add_f32 v[10:11], v[10:11], v[26:27]
	v_mov_b32_e32 v46, v3
	v_pk_fma_f32 v[28:29], v[46:47], v[4:5], v[12:13] op_sel_hi:[0,1,1] neg_lo:[0,0,1] neg_hi:[0,0,1]
	v_pk_fma_f32 v[30:31], v[46:47], v[6:7], v[14:15] op_sel_hi:[0,1,1] neg_lo:[0,0,1] neg_hi:[0,0,1]
	v_pk_fma_f32 v[32:33], v[46:47], v[8:9], v[16:17] op_sel_hi:[0,1,1] neg_lo:[0,0,1] neg_hi:[0,0,1]
	v_pk_fma_f32 v[34:35], v[46:47], v[10:11], v[18:19] op_sel_hi:[0,1,1] neg_lo:[0,0,1] neg_hi:[0,0,1]
	v_cvt_pk_bf16_f32 v36, v28, v29
	v_cvt_pk_bf16_f32 v37, v30, v31
	v_cvt_pk_bf16_f32 v38, v32, v33
	v_cvt_pk_bf16_f32 v39, v34, v35
	global_store_dwordx4 v1, v[36:39], s[24:25]
	s_add_u32 s24, s24, 0x2000
	s_addc_u32 s25, s25, 0
	v_lshlrev_b32_e32 v12, 16, v92
	v_and_b32_e32 v13, 0xffff0000, v92
	v_lshlrev_b32_e32 v20, 16, v124
	v_and_b32_e32 v21, 0xffff0000, v124
	v_lshlrev_b32_e32 v14, 16, v93
	v_and_b32_e32 v15, 0xffff0000, v93
	v_lshlrev_b32_e32 v22, 16, v125
	v_and_b32_e32 v23, 0xffff0000, v125
	v_lshlrev_b32_e32 v16, 16, v94
	v_and_b32_e32 v17, 0xffff0000, v94
	v_lshlrev_b32_e32 v24, 16, v126
	v_and_b32_e32 v25, 0xffff0000, v126
	v_lshlrev_b32_e32 v18, 16, v95
	v_and_b32_e32 v19, 0xffff0000, v95
	v_lshlrev_b32_e32 v26, 16, v127
	v_and_b32_e32 v27, 0xffff0000, v127
	v_pk_fma_f32 v[20:21], v[44:45], v[20:21], v[12:13] op_sel_hi:[0,1,1] neg_lo:[1,0,0] neg_hi:[1,0,0]
	v_pk_fma_f32 v[22:23], v[44:45], v[22:23], v[14:15] op_sel_hi:[0,1,1] neg_lo:[1,0,0] neg_hi:[1,0,0]
	v_pk_fma_f32 v[24:25], v[44:45], v[24:25], v[16:17] op_sel_hi:[0,1,1] neg_lo:[1,0,0] neg_hi:[1,0,0]
	v_pk_fma_f32 v[26:27], v[44:45], v[26:27], v[18:19] op_sel_hi:[0,1,1] neg_lo:[1,0,0] neg_hi:[1,0,0]
	v_pk_add_f32 v[4:5], v[4:5], v[20:21]
	v_pk_add_f32 v[6:7], v[6:7], v[22:23]
	v_pk_add_f32 v[8:9], v[8:9], v[24:25]
	v_pk_add_f32 v[10:11], v[10:11], v[26:27]
	v_mov_b32_e32 v46, v3
	v_pk_fma_f32 v[28:29], v[46:47], v[4:5], v[12:13] op_sel_hi:[0,1,1] neg_lo:[0,0,1] neg_hi:[0,0,1]
	v_pk_fma_f32 v[30:31], v[46:47], v[6:7], v[14:15] op_sel_hi:[0,1,1] neg_lo:[0,0,1] neg_hi:[0,0,1]
	v_pk_fma_f32 v[32:33], v[46:47], v[8:9], v[16:17] op_sel_hi:[0,1,1] neg_lo:[0,0,1] neg_hi:[0,0,1]
	v_pk_fma_f32 v[34:35], v[46:47], v[10:11], v[18:19] op_sel_hi:[0,1,1] neg_lo:[0,0,1] neg_hi:[0,0,1]
	v_cvt_pk_bf16_f32 v40, v28, v29
	v_cvt_pk_bf16_f32 v41, v30, v31
	v_cvt_pk_bf16_f32 v42, v32, v33
	v_cvt_pk_bf16_f32 v43, v34, v35
	global_store_dwordx4 v1, v[40:43], s[24:25]
	s_add_u32 s24, s24, 0x2000
	s_addc_u32 s25, s25, 0
	s_waitcnt vmcnt(8)
	v_mov_b32_e32 v44, 1.0
	v_lshlrev_b32_e32 v12, 16, v128
	v_and_b32_e32 v13, 0xffff0000, v128
	v_lshlrev_b32_e32 v20, 16, v160
	v_and_b32_e32 v21, 0xffff0000, v160
	v_lshlrev_b32_e32 v14, 16, v129
	v_and_b32_e32 v15, 0xffff0000, v129
	v_lshlrev_b32_e32 v22, 16, v161
	v_and_b32_e32 v23, 0xffff0000, v161
	v_lshlrev_b32_e32 v16, 16, v130
	v_and_b32_e32 v17, 0xffff0000, v130
	v_lshlrev_b32_e32 v24, 16, v162
	v_and_b32_e32 v25, 0xffff0000, v162
	v_lshlrev_b32_e32 v18, 16, v131
	v_and_b32_e32 v19, 0xffff0000, v131
	v_lshlrev_b32_e32 v26, 16, v163
	v_and_b32_e32 v27, 0xffff0000, v163
	v_pk_fma_f32 v[20:21], v[44:45], v[20:21], v[12:13] op_sel_hi:[0,1,1] neg_lo:[1,0,0] neg_hi:[1,0,0]
	v_pk_fma_f32 v[22:23], v[44:45], v[22:23], v[14:15] op_sel_hi:[0,1,1] neg_lo:[1,0,0] neg_hi:[1,0,0]
	v_pk_fma_f32 v[24:25], v[44:45], v[24:25], v[16:17] op_sel_hi:[0,1,1] neg_lo:[1,0,0] neg_hi:[1,0,0]
	v_pk_fma_f32 v[26:27], v[44:45], v[26:27], v[18:19] op_sel_hi:[0,1,1] neg_lo:[1,0,0] neg_hi:[1,0,0]
	v_pk_add_f32 v[4:5], v[4:5], v[20:21]
	v_pk_add_f32 v[6:7], v[6:7], v[22:23]
	v_pk_add_f32 v[8:9], v[8:9], v[24:25]
	v_pk_add_f32 v[10:11], v[10:11], v[26:27]
	v_mov_b32_e32 v46, v3
	v_pk_fma_f32 v[28:29], v[46:47], v[4:5], v[12:13] op_sel_hi:[0,1,1] neg_lo:[0,0,1] neg_hi:[0,0,1]
	v_pk_fma_f32 v[30:31], v[46:47], v[6:7], v[14:15] op_sel_hi:[0,1,1] neg_lo:[0,0,1] neg_hi:[0,0,1]
	v_pk_fma_f32 v[32:33], v[46:47], v[8:9], v[16:17] op_sel_hi:[0,1,1] neg_lo:[0,0,1] neg_hi:[0,0,1]
	v_pk_fma_f32 v[34:35], v[46:47], v[10:11], v[18:19] op_sel_hi:[0,1,1] neg_lo:[0,0,1] neg_hi:[0,0,1]
	v_cvt_pk_bf16_f32 v36, v28, v29
	v_cvt_pk_bf16_f32 v37, v30, v31
	v_cvt_pk_bf16_f32 v38, v32, v33
	v_cvt_pk_bf16_f32 v39, v34, v35
	global_store_dwordx4 v1, v[36:39], s[24:25]
	s_add_u32 s24, s24, 0x2000
	s_addc_u32 s25, s25, 0
	v_lshlrev_b32_e32 v12, 16, v132
	v_and_b32_e32 v13, 0xffff0000, v132
	v_lshlrev_b32_e32 v20, 16, v164
	v_and_b32_e32 v21, 0xffff0000, v164
	v_lshlrev_b32_e32 v14, 16, v133
	v_and_b32_e32 v15, 0xffff0000, v133
	v_lshlrev_b32_e32 v22, 16, v165
	v_and_b32_e32 v23, 0xffff0000, v165
	v_lshlrev_b32_e32 v16, 16, v134
	v_and_b32_e32 v17, 0xffff0000, v134
	v_lshlrev_b32_e32 v24, 16, v166
	v_and_b32_e32 v25, 0xffff0000, v166
	v_lshlrev_b32_e32 v18, 16, v135
	v_and_b32_e32 v19, 0xffff0000, v135
	v_lshlrev_b32_e32 v26, 16, v167
	v_and_b32_e32 v27, 0xffff0000, v167
	v_pk_fma_f32 v[20:21], v[44:45], v[20:21], v[12:13] op_sel_hi:[0,1,1] neg_lo:[1,0,0] neg_hi:[1,0,0]
	v_pk_fma_f32 v[22:23], v[44:45], v[22:23], v[14:15] op_sel_hi:[0,1,1] neg_lo:[1,0,0] neg_hi:[1,0,0]
	v_pk_fma_f32 v[24:25], v[44:45], v[24:25], v[16:17] op_sel_hi:[0,1,1] neg_lo:[1,0,0] neg_hi:[1,0,0]
	v_pk_fma_f32 v[26:27], v[44:45], v[26:27], v[18:19] op_sel_hi:[0,1,1] neg_lo:[1,0,0] neg_hi:[1,0,0]
	v_pk_add_f32 v[4:5], v[4:5], v[20:21]
	v_pk_add_f32 v[6:7], v[6:7], v[22:23]
	v_pk_add_f32 v[8:9], v[8:9], v[24:25]
	v_pk_add_f32 v[10:11], v[10:11], v[26:27]
	v_mov_b32_e32 v46, v3
	v_pk_fma_f32 v[28:29], v[46:47], v[4:5], v[12:13] op_sel_hi:[0,1,1] neg_lo:[0,0,1] neg_hi:[0,0,1]
	v_pk_fma_f32 v[30:31], v[46:47], v[6:7], v[14:15] op_sel_hi:[0,1,1] neg_lo:[0,0,1] neg_hi:[0,0,1]
	v_pk_fma_f32 v[32:33], v[46:47], v[8:9], v[16:17] op_sel_hi:[0,1,1] neg_lo:[0,0,1] neg_hi:[0,0,1]
	v_pk_fma_f32 v[34:35], v[46:47], v[10:11], v[18:19] op_sel_hi:[0,1,1] neg_lo:[0,0,1] neg_hi:[0,0,1]
	v_cvt_pk_bf16_f32 v40, v28, v29
	v_cvt_pk_bf16_f32 v41, v30, v31
	v_cvt_pk_bf16_f32 v42, v32, v33
	v_cvt_pk_bf16_f32 v43, v34, v35
	global_store_dwordx4 v1, v[40:43], s[24:25]
	s_add_u32 s24, s24, 0x2000
	s_addc_u32 s25, s25, 0
	v_lshlrev_b32_e32 v12, 16, v136
	v_and_b32_e32 v13, 0xffff0000, v136
	v_lshlrev_b32_e32 v20, 16, v168
	v_and_b32_e32 v21, 0xffff0000, v168
	v_lshlrev_b32_e32 v14, 16, v137
	v_and_b32_e32 v15, 0xffff0000, v137
	v_lshlrev_b32_e32 v22, 16, v169
	v_and_b32_e32 v23, 0xffff0000, v169
	v_lshlrev_b32_e32 v16, 16, v138
	v_and_b32_e32 v17, 0xffff0000, v138
	v_lshlrev_b32_e32 v24, 16, v170
	v_and_b32_e32 v25, 0xffff0000, v170
	v_lshlrev_b32_e32 v18, 16, v139
	v_and_b32_e32 v19, 0xffff0000, v139
	v_lshlrev_b32_e32 v26, 16, v171
	v_and_b32_e32 v27, 0xffff0000, v171
	v_pk_fma_f32 v[20:21], v[44:45], v[20:21], v[12:13] op_sel_hi:[0,1,1] neg_lo:[1,0,0] neg_hi:[1,0,0]
	v_pk_fma_f32 v[22:23], v[44:45], v[22:23], v[14:15] op_sel_hi:[0,1,1] neg_lo:[1,0,0] neg_hi:[1,0,0]
	v_pk_fma_f32 v[24:25], v[44:45], v[24:25], v[16:17] op_sel_hi:[0,1,1] neg_lo:[1,0,0] neg_hi:[1,0,0]
	v_pk_fma_f32 v[26:27], v[44:45], v[26:27], v[18:19] op_sel_hi:[0,1,1] neg_lo:[1,0,0] neg_hi:[1,0,0]
	v_pk_add_f32 v[4:5], v[4:5], v[20:21]
	v_pk_add_f32 v[6:7], v[6:7], v[22:23]
	v_pk_add_f32 v[8:9], v[8:9], v[24:25]
	v_pk_add_f32 v[10:11], v[10:11], v[26:27]
	v_mov_b32_e32 v46, v3
	v_pk_fma_f32 v[28:29], v[46:47], v[4:5], v[12:13] op_sel_hi:[0,1,1] neg_lo:[0,0,1] neg_hi:[0,0,1]
	v_pk_fma_f32 v[30:31], v[46:47], v[6:7], v[14:15] op_sel_hi:[0,1,1] neg_lo:[0,0,1] neg_hi:[0,0,1]
	v_pk_fma_f32 v[32:33], v[46:47], v[8:9], v[16:17] op_sel_hi:[0,1,1] neg_lo:[0,0,1] neg_hi:[0,0,1]
	v_pk_fma_f32 v[34:35], v[46:47], v[10:11], v[18:19] op_sel_hi:[0,1,1] neg_lo:[0,0,1] neg_hi:[0,0,1]
	v_cvt_pk_bf16_f32 v36, v28, v29
	v_cvt_pk_bf16_f32 v37, v30, v31
	v_cvt_pk_bf16_f32 v38, v32, v33
	v_cvt_pk_bf16_f32 v39, v34, v35
	global_store_dwordx4 v1, v[36:39], s[24:25]
	s_add_u32 s24, s24, 0x2000
	s_addc_u32 s25, s25, 0
	v_lshlrev_b32_e32 v12, 16, v140
	v_and_b32_e32 v13, 0xffff0000, v140
	v_lshlrev_b32_e32 v20, 16, v172
	v_and_b32_e32 v21, 0xffff0000, v172
	v_lshlrev_b32_e32 v14, 16, v141
	v_and_b32_e32 v15, 0xffff0000, v141
	v_lshlrev_b32_e32 v22, 16, v173
	v_and_b32_e32 v23, 0xffff0000, v173
	v_lshlrev_b32_e32 v16, 16, v142
	v_and_b32_e32 v17, 0xffff0000, v142
	v_lshlrev_b32_e32 v24, 16, v174
	v_and_b32_e32 v25, 0xffff0000, v174
	v_lshlrev_b32_e32 v18, 16, v143
	v_and_b32_e32 v19, 0xffff0000, v143
	v_lshlrev_b32_e32 v26, 16, v175
	v_and_b32_e32 v27, 0xffff0000, v175
	v_pk_fma_f32 v[20:21], v[44:45], v[20:21], v[12:13] op_sel_hi:[0,1,1] neg_lo:[1,0,0] neg_hi:[1,0,0]
	v_pk_fma_f32 v[22:23], v[44:45], v[22:23], v[14:15] op_sel_hi:[0,1,1] neg_lo:[1,0,0] neg_hi:[1,0,0]
	v_pk_fma_f32 v[24:25], v[44:45], v[24:25], v[16:17] op_sel_hi:[0,1,1] neg_lo:[1,0,0] neg_hi:[1,0,0]
	v_pk_fma_f32 v[26:27], v[44:45], v[26:27], v[18:19] op_sel_hi:[0,1,1] neg_lo:[1,0,0] neg_hi:[1,0,0]
	v_pk_add_f32 v[4:5], v[4:5], v[20:21]
	v_pk_add_f32 v[6:7], v[6:7], v[22:23]
	v_pk_add_f32 v[8:9], v[8:9], v[24:25]
	v_pk_add_f32 v[10:11], v[10:11], v[26:27]
	v_mov_b32_e32 v46, v3
	v_pk_fma_f32 v[28:29], v[46:47], v[4:5], v[12:13] op_sel_hi:[0,1,1] neg_lo:[0,0,1] neg_hi:[0,0,1]
	v_pk_fma_f32 v[30:31], v[46:47], v[6:7], v[14:15] op_sel_hi:[0,1,1] neg_lo:[0,0,1] neg_hi:[0,0,1]
	v_pk_fma_f32 v[32:33], v[46:47], v[8:9], v[16:17] op_sel_hi:[0,1,1] neg_lo:[0,0,1] neg_hi:[0,0,1]
	v_pk_fma_f32 v[34:35], v[46:47], v[10:11], v[18:19] op_sel_hi:[0,1,1] neg_lo:[0,0,1] neg_hi:[0,0,1]
	v_cvt_pk_bf16_f32 v40, v28, v29
	v_cvt_pk_bf16_f32 v41, v30, v31
	v_cvt_pk_bf16_f32 v42, v32, v33
	v_cvt_pk_bf16_f32 v43, v34, v35
	global_store_dwordx4 v1, v[40:43], s[24:25]
	s_add_u32 s24, s24, 0x2000
	s_addc_u32 s25, s25, 0
	v_lshlrev_b32_e32 v12, 16, v144
	v_and_b32_e32 v13, 0xffff0000, v144
	v_lshlrev_b32_e32 v20, 16, v176
	v_and_b32_e32 v21, 0xffff0000, v176
	v_lshlrev_b32_e32 v14, 16, v145
	v_and_b32_e32 v15, 0xffff0000, v145
	v_lshlrev_b32_e32 v22, 16, v177
	v_and_b32_e32 v23, 0xffff0000, v177
	v_lshlrev_b32_e32 v16, 16, v146
	v_and_b32_e32 v17, 0xffff0000, v146
	v_lshlrev_b32_e32 v24, 16, v178
	v_and_b32_e32 v25, 0xffff0000, v178
	v_lshlrev_b32_e32 v18, 16, v147
	v_and_b32_e32 v19, 0xffff0000, v147
	v_lshlrev_b32_e32 v26, 16, v179
	v_and_b32_e32 v27, 0xffff0000, v179
	v_pk_fma_f32 v[20:21], v[44:45], v[20:21], v[12:13] op_sel_hi:[0,1,1] neg_lo:[1,0,0] neg_hi:[1,0,0]
	v_pk_fma_f32 v[22:23], v[44:45], v[22:23], v[14:15] op_sel_hi:[0,1,1] neg_lo:[1,0,0] neg_hi:[1,0,0]
	v_pk_fma_f32 v[24:25], v[44:45], v[24:25], v[16:17] op_sel_hi:[0,1,1] neg_lo:[1,0,0] neg_hi:[1,0,0]
	v_pk_fma_f32 v[26:27], v[44:45], v[26:27], v[18:19] op_sel_hi:[0,1,1] neg_lo:[1,0,0] neg_hi:[1,0,0]
	v_pk_add_f32 v[4:5], v[4:5], v[20:21]
	v_pk_add_f32 v[6:7], v[6:7], v[22:23]
	v_pk_add_f32 v[8:9], v[8:9], v[24:25]
	v_pk_add_f32 v[10:11], v[10:11], v[26:27]
	v_mov_b32_e32 v46, v3
	v_pk_fma_f32 v[28:29], v[46:47], v[4:5], v[12:13] op_sel_hi:[0,1,1] neg_lo:[0,0,1] neg_hi:[0,0,1]
	v_pk_fma_f32 v[30:31], v[46:47], v[6:7], v[14:15] op_sel_hi:[0,1,1] neg_lo:[0,0,1] neg_hi:[0,0,1]
	v_pk_fma_f32 v[32:33], v[46:47], v[8:9], v[16:17] op_sel_hi:[0,1,1] neg_lo:[0,0,1] neg_hi:[0,0,1]
	v_pk_fma_f32 v[34:35], v[46:47], v[10:11], v[18:19] op_sel_hi:[0,1,1] neg_lo:[0,0,1] neg_hi:[0,0,1]
	v_cvt_pk_bf16_f32 v36, v28, v29
	v_cvt_pk_bf16_f32 v37, v30, v31
	v_cvt_pk_bf16_f32 v38, v32, v33
	v_cvt_pk_bf16_f32 v39, v34, v35
	global_store_dwordx4 v1, v[36:39], s[24:25]
	s_add_u32 s24, s24, 0x2000
	s_addc_u32 s25, s25, 0
	v_lshlrev_b32_e32 v12, 16, v148
	v_and_b32_e32 v13, 0xffff0000, v148
	v_lshlrev_b32_e32 v20, 16, v180
	v_and_b32_e32 v21, 0xffff0000, v180
	v_lshlrev_b32_e32 v14, 16, v149
	v_and_b32_e32 v15, 0xffff0000, v149
	v_lshlrev_b32_e32 v22, 16, v181
	v_and_b32_e32 v23, 0xffff0000, v181
	v_lshlrev_b32_e32 v16, 16, v150
	v_and_b32_e32 v17, 0xffff0000, v150
	v_lshlrev_b32_e32 v24, 16, v182
	v_and_b32_e32 v25, 0xffff0000, v182
	v_lshlrev_b32_e32 v18, 16, v151
	v_and_b32_e32 v19, 0xffff0000, v151
	v_lshlrev_b32_e32 v26, 16, v183
	v_and_b32_e32 v27, 0xffff0000, v183
	v_pk_fma_f32 v[20:21], v[44:45], v[20:21], v[12:13] op_sel_hi:[0,1,1] neg_lo:[1,0,0] neg_hi:[1,0,0]
	v_pk_fma_f32 v[22:23], v[44:45], v[22:23], v[14:15] op_sel_hi:[0,1,1] neg_lo:[1,0,0] neg_hi:[1,0,0]
	v_pk_fma_f32 v[24:25], v[44:45], v[24:25], v[16:17] op_sel_hi:[0,1,1] neg_lo:[1,0,0] neg_hi:[1,0,0]
	v_pk_fma_f32 v[26:27], v[44:45], v[26:27], v[18:19] op_sel_hi:[0,1,1] neg_lo:[1,0,0] neg_hi:[1,0,0]
	v_pk_add_f32 v[4:5], v[4:5], v[20:21]
	v_pk_add_f32 v[6:7], v[6:7], v[22:23]
	v_pk_add_f32 v[8:9], v[8:9], v[24:25]
	v_pk_add_f32 v[10:11], v[10:11], v[26:27]
	v_mov_b32_e32 v46, v3
	v_pk_fma_f32 v[28:29], v[46:47], v[4:5], v[12:13] op_sel_hi:[0,1,1] neg_lo:[0,0,1] neg_hi:[0,0,1]
	v_pk_fma_f32 v[30:31], v[46:47], v[6:7], v[14:15] op_sel_hi:[0,1,1] neg_lo:[0,0,1] neg_hi:[0,0,1]
	v_pk_fma_f32 v[32:33], v[46:47], v[8:9], v[16:17] op_sel_hi:[0,1,1] neg_lo:[0,0,1] neg_hi:[0,0,1]
	v_pk_fma_f32 v[34:35], v[46:47], v[10:11], v[18:19] op_sel_hi:[0,1,1] neg_lo:[0,0,1] neg_hi:[0,0,1]
	v_cvt_pk_bf16_f32 v40, v28, v29
	v_cvt_pk_bf16_f32 v41, v30, v31
	v_cvt_pk_bf16_f32 v42, v32, v33
	v_cvt_pk_bf16_f32 v43, v34, v35
	global_store_dwordx4 v1, v[40:43], s[24:25]
	s_add_u32 s24, s24, 0x2000
	s_addc_u32 s25, s25, 0
	v_lshlrev_b32_e32 v12, 16, v152
	v_and_b32_e32 v13, 0xffff0000, v152
	v_lshlrev_b32_e32 v20, 16, v184
	v_and_b32_e32 v21, 0xffff0000, v184
	v_lshlrev_b32_e32 v14, 16, v153
	v_and_b32_e32 v15, 0xffff0000, v153
	v_lshlrev_b32_e32 v22, 16, v185
	v_and_b32_e32 v23, 0xffff0000, v185
	v_lshlrev_b32_e32 v16, 16, v154
	v_and_b32_e32 v17, 0xffff0000, v154
	v_lshlrev_b32_e32 v24, 16, v186
	v_and_b32_e32 v25, 0xffff0000, v186
	v_lshlrev_b32_e32 v18, 16, v155
	v_and_b32_e32 v19, 0xffff0000, v155
	v_lshlrev_b32_e32 v26, 16, v187
	v_and_b32_e32 v27, 0xffff0000, v187
	v_pk_fma_f32 v[20:21], v[44:45], v[20:21], v[12:13] op_sel_hi:[0,1,1] neg_lo:[1,0,0] neg_hi:[1,0,0]
	v_pk_fma_f32 v[22:23], v[44:45], v[22:23], v[14:15] op_sel_hi:[0,1,1] neg_lo:[1,0,0] neg_hi:[1,0,0]
	v_pk_fma_f32 v[24:25], v[44:45], v[24:25], v[16:17] op_sel_hi:[0,1,1] neg_lo:[1,0,0] neg_hi:[1,0,0]
	v_pk_fma_f32 v[26:27], v[44:45], v[26:27], v[18:19] op_sel_hi:[0,1,1] neg_lo:[1,0,0] neg_hi:[1,0,0]
	v_pk_add_f32 v[4:5], v[4:5], v[20:21]
	v_pk_add_f32 v[6:7], v[6:7], v[22:23]
	v_pk_add_f32 v[8:9], v[8:9], v[24:25]
	v_pk_add_f32 v[10:11], v[10:11], v[26:27]
	v_mov_b32_e32 v46, v3
	v_pk_fma_f32 v[28:29], v[46:47], v[4:5], v[12:13] op_sel_hi:[0,1,1] neg_lo:[0,0,1] neg_hi:[0,0,1]
	v_pk_fma_f32 v[30:31], v[46:47], v[6:7], v[14:15] op_sel_hi:[0,1,1] neg_lo:[0,0,1] neg_hi:[0,0,1]
	v_pk_fma_f32 v[32:33], v[46:47], v[8:9], v[16:17] op_sel_hi:[0,1,1] neg_lo:[0,0,1] neg_hi:[0,0,1]
	v_pk_fma_f32 v[34:35], v[46:47], v[10:11], v[18:19] op_sel_hi:[0,1,1] neg_lo:[0,0,1] neg_hi:[0,0,1]
	v_cvt_pk_bf16_f32 v36, v28, v29
	v_cvt_pk_bf16_f32 v37, v30, v31
	v_cvt_pk_bf16_f32 v38, v32, v33
	v_cvt_pk_bf16_f32 v39, v34, v35
	global_store_dwordx4 v1, v[36:39], s[24:25]
	s_add_u32 s24, s24, 0x2000
	s_addc_u32 s25, s25, 0
	v_lshlrev_b32_e32 v12, 16, v156
	v_and_b32_e32 v13, 0xffff0000, v156
	v_lshlrev_b32_e32 v20, 16, v188
	v_and_b32_e32 v21, 0xffff0000, v188
	v_lshlrev_b32_e32 v14, 16, v157
	v_and_b32_e32 v15, 0xffff0000, v157
	v_lshlrev_b32_e32 v22, 16, v189
	v_and_b32_e32 v23, 0xffff0000, v189
	v_lshlrev_b32_e32 v16, 16, v158
	v_and_b32_e32 v17, 0xffff0000, v158
	v_lshlrev_b32_e32 v24, 16, v190
	v_and_b32_e32 v25, 0xffff0000, v190
	v_lshlrev_b32_e32 v18, 16, v159
	v_and_b32_e32 v19, 0xffff0000, v159
	v_lshlrev_b32_e32 v26, 16, v191
	v_and_b32_e32 v27, 0xffff0000, v191
	v_pk_fma_f32 v[20:21], v[44:45], v[20:21], v[12:13] op_sel_hi:[0,1,1] neg_lo:[1,0,0] neg_hi:[1,0,0]
	v_pk_fma_f32 v[22:23], v[44:45], v[22:23], v[14:15] op_sel_hi:[0,1,1] neg_lo:[1,0,0] neg_hi:[1,0,0]
	v_pk_fma_f32 v[24:25], v[44:45], v[24:25], v[16:17] op_sel_hi:[0,1,1] neg_lo:[1,0,0] neg_hi:[1,0,0]
	v_pk_fma_f32 v[26:27], v[44:45], v[26:27], v[18:19] op_sel_hi:[0,1,1] neg_lo:[1,0,0] neg_hi:[1,0,0]
	v_pk_add_f32 v[4:5], v[4:5], v[20:21]
	v_pk_add_f32 v[6:7], v[6:7], v[22:23]
	v_pk_add_f32 v[8:9], v[8:9], v[24:25]
	v_pk_add_f32 v[10:11], v[10:11], v[26:27]
	v_mov_b32_e32 v46, v3
	v_pk_fma_f32 v[28:29], v[46:47], v[4:5], v[12:13] op_sel_hi:[0,1,1] neg_lo:[0,0,1] neg_hi:[0,0,1]
	v_pk_fma_f32 v[30:31], v[46:47], v[6:7], v[14:15] op_sel_hi:[0,1,1] neg_lo:[0,0,1] neg_hi:[0,0,1]
	v_pk_fma_f32 v[32:33], v[46:47], v[8:9], v[16:17] op_sel_hi:[0,1,1] neg_lo:[0,0,1] neg_hi:[0,0,1]
	v_pk_fma_f32 v[34:35], v[46:47], v[10:11], v[18:19] op_sel_hi:[0,1,1] neg_lo:[0,0,1] neg_hi:[0,0,1]
	v_cvt_pk_bf16_f32 v40, v28, v29
	v_cvt_pk_bf16_f32 v41, v30, v31
	v_cvt_pk_bf16_f32 v42, v32, v33
	v_cvt_pk_bf16_f32 v43, v34, v35
	global_store_dwordx4 v1, v[40:43], s[24:25]
	s_add_u32 s24, s24, 0x2000
	s_addc_u32 s25, s25, 0
	s_branch .Lpool_next
.Lpool_next:
	s_add_i32 s7, s7, s10
	s_cmpk_gt_i32 s7, 0x5ff
	s_cbranch_scc0 .Lpool_item
	s_mov_b32 s6, -1

.LBB0_1335:
	s_mov_b64 s[0:1], s[78:79]
	s_load_dword s0, s[0:1], 0xa8
	s_waitcnt lgkmcnt(0)
	s_cmp_gt_i32 s0, 11
	s_cbranch_scc1 .LBB0_1763
	s_mov_b64 s[0:1], s[78:79]
	s_load_dword s0, s[0:1], 0xac
	s_waitcnt lgkmcnt(0)
	s_cmp_lt_i32 s0, 12
	s_cbranch_scc1 .LBB0_1763
	s_mov_b32 s95, -1
	s_mov_b64 s[0:1], s[78:79]
	s_load_dwordx2 s[2:3], s[0:1], 0xa0
	s_cmpk_lt_i32 s87, 0x1000
	s_mov_b32 s6, -1
	s_cselect_b64 s[4:5], -1, 0
	s_cmpk_gt_i32 s87, 0xfff
	s_cbranch_scc1 .LBB0_1343
	s_ashr_i32 s0, s87, 31
	s_lshr_b32 s0, s0, 29
	s_add_i32 s7, s87, s0
	s_and_b32 s0, s7, -8
	s_sub_i32 s8, s87, s0
	s_cmp_gt_i32 s8, -1
	s_cbranch_scc0 .LBB0_1340
	s_lshl_b32 s9, s8, 9
	s_cbranch_execz .LBB0_1341
	s_branch .LBB0_1342

.LBB0_1359:
	s_cmp_eq_u32 s95, s28
	s_cbranch_scc1 .Llean_p11
.Lorig_p11:
	s_mov_b32 s95, s28
	v_lshl_add_u32 v146, s28, 8, v177
	v_ashrrev_i32_e32 v147, 31, v146
	v_lshlrev_b64 v[144:145], 3, v[146:147]
	v_lshl_add_u64 v[150:151], s[12:13], 0, v[144:145]
	v_lshl_add_u64 v[170:171], s[14:15], 0, v[144:145]
	global_load_dwordx2 v[154:155], v[150:151], off
	global_load_dwordx2 v[172:173], v[170:171], off
	v_cvt_f32_i32_e32 v191, v123
	v_cvt_f32_i32_e32 v190, v122
	v_cvt_f32_i32_e32 v175, v125
	v_cvt_f32_i32_e32 v174, v124
	v_cvt_f32_i32_e32 v189, v121
	v_cvt_f32_i32_e32 v188, v120
	global_load_dwordx2 v[166:167], v[150:151], off offset:128
	global_load_dwordx2 v[162:163], v[150:151], off offset:256
	global_load_dwordx2 v[158:159], v[150:151], off offset:384
	global_load_dwordx2 v[164:165], v[170:171], off offset:128
	global_load_dwordx2 v[160:161], v[170:171], off offset:256
	global_load_dwordx2 v[156:157], v[170:171], off offset:384
	global_load_dwordx2 v[152:153], v[150:151], off offset:1024
	global_load_dwordx2 v[148:149], v[150:151], off offset:1152
	global_load_dwordx2 v[124:125], v[150:151], off offset:1280
	global_load_dwordx2 v[120:121], v[150:151], off offset:1408
	v_cvt_f32_i32_e32 v187, v127
	v_cvt_f32_i32_e32 v186, v126
	v_lshl_or_b32 v144, s0, 8, v179
	v_ashrrev_i32_e32 v145, 31, v144
	v_lshlrev_b64 v[168:169], 6, v[146:147]
	s_waitcnt vmcnt(0)
	v_ffbh_u32_e32 v122, v155
	v_ffbh_u32_e32 v123, v173
	v_min_u32_e32 v150, 32, v122
	v_min_u32_e32 v151, 32, v123
	v_lshlrev_b64 v[122:123], v150, v[154:155]
	v_lshlrev_b64 v[126:127], v151, v[172:173]
	v_min_u32_e32 v122, 1, v122
	v_min_u32_e32 v126, 1, v126
	v_or_b32_e32 v122, v123, v122
	v_or_b32_e32 v123, v127, v126
	v_cvt_f32_u32_e32 v122, v122
	v_cvt_f32_u32_e32 v123, v123
	v_sub_u32_e32 v126, 32, v150
	v_sub_u32_e32 v127, 32, v151
	v_ldexp_f32 v122, v122, v126
	v_ldexp_f32 v123, v123, v127
	v_fmamk_f32 v122, v122, 0x2f800000, v183
	v_fmamk_f32 v123, v123, 0x2f800000, v183
	v_rsq_f32_e32 v172, v122
	v_mul_f32_e32 v122, 0x4f800000, v123
	v_cmp_gt_f32_e32 vcc, s54, v123
	s_nop 1
	v_cndmask_b32_e32 v173, v123, v122, vcc
	global_load_dwordx2 v[154:155], v[170:171], off offset:1024
	global_load_dwordx2 v[150:151], v[170:171], off offset:1152
	global_load_dwordx2 v[126:127], v[170:171], off offset:1280
	global_load_dwordx2 v[122:123], v[170:171], off offset:1408
	v_sqrt_f32_e32 v185, v173
	v_mul_f32_e32 v170, 0x37820610, v172
	v_add_u32_e32 v171, -1, v185
	v_add_u32_e32 v172, 1, v185
	v_fma_f32 v192, -v171, v185, v173
	v_fma_f32 v193, -v172, v185, v173
	v_cmp_ge_f32_e64 s[0:1], 0, v192
	s_nop 1
	v_cndmask_b32_e64 v171, v185, v171, s[0:1]
	v_cmp_lt_f32_e64 s[0:1], 0, v193
	s_nop 1
	v_cndmask_b32_e64 v171, v171, v172, s[0:1]
	v_mul_f32_e32 v172, 0x37800000, v171
	v_cndmask_b32_e32 v171, v171, v172, vcc
	v_cmp_class_f32_e32 vcc, v173, v184
	s_nop 1
	v_cndmask_b32_e32 v171, v171, v173, vcc
	v_mul_f32_e32 v170, v170, v171
	v_mov_b32_e32 v232, v170
	v_rcp_f32_e32 v233, v170
	s_nop 0
	v_mul_f32_e32 v233, 0x4083851f, v233
	v_cvt_i32_f32_e32 v233, v233
	v_pk_mul_f32 v[174:175], v[170:171], v[174:175] op_sel_hi:[0,1]
	v_pk_mul_f32 v[172:173], v[170:171], v[186:187] op_sel_hi:[0,1]
	v_pk_mul_f32 v[188:189], v[170:171], v[188:189] op_sel_hi:[0,1]
	v_max_f32_e32 v185, 0, v175
	v_pk_mul_f32 v[186:187], v[170:171], v[190:191] op_sel_hi:[0,1]
	v_max_f32_e32 v171, 0, v174
	v_max_f32_e32 v174, 0, v188
	v_max_f32_e32 v188, 0, v189
	v_max_f32_e32 v172, 0, v172
	v_max_f32_e32 v173, 0, v173
	v_mul_f32_e32 v190, v185, v185
	v_max_f32_e32 v191, 0, v186
	v_mul_f32_e32 v175, v171, v171
	v_mul_f32_e32 v186, v188, v188
	v_mul_f32_e32 v189, v172, v172
	v_mul_f32_e32 v188, v173, v173
	v_mul_f32_e32 v173, 0x41700000, v190
	v_max_f32_e32 v192, 0, v187
	v_mul_f32_e32 v187, v174, v174
	v_mul_f32_e32 v172, 0x41700000, v175
	v_mul_f32_e32 v174, 0x41700000, v189
	v_min_f32_e32 v173, 0x437f0000, v173
	v_min_f32_e32 v172, 0x437f0000, v172
	v_min_f32_e32 v174, 0x437f0000, v174
	v_rndne_f32_e32 v173, v173
	v_rndne_f32_e32 v172, v172
	v_rndne_f32_e32 v174, v174
	v_cvt_i32_f32_e32 v173, v173
	v_mul_f32_e32 v185, v191, v191
	v_mul_f32_e32 v191, 0x41700000, v188
	v_mul_f32_e32 v193, 0x41700000, v186
	v_cvt_i32_f32_e32 v172, v172
	v_cvt_i32_f32_sdwa v174, v174 dst_sel:WORD_1 dst_unused:UNUSED_PAD src0_sel:DWORD
	v_mul_f32_e32 v171, v192, v192
	v_mul_f32_e32 v192, 0x41700000, v187
	v_mul_f32_e32 v194, 0x41700000, v185
	v_min_f32_e32 v191, 0x437f0000, v191
	v_min_f32_e32 v193, 0x437f0000, v193
	v_mul_f32_e32 v195, 0x41700000, v171
	v_min_f32_e32 v192, 0x437f0000, v192
	v_min_f32_e32 v194, 0x437f0000, v194
	v_rndne_f32_e32 v191, v191
	v_rndne_f32_e32 v193, v193
	v_min_f32_e32 v195, 0x437f0000, v195
	v_rndne_f32_e32 v192, v192
	v_rndne_f32_e32 v194, v194
	v_cvt_i32_f32_sdwa v191, v191 dst_sel:BYTE_3 dst_unused:UNUSED_PAD src0_sel:DWORD
	v_cvt_i32_f32_e32 v193, v193
	v_lshlrev_b32_e32 v173, 8, v173
	v_cvt_i32_f32_e32 v196, v192
	v_cvt_i32_f32_sdwa v194, v194 dst_sel:WORD_1 dst_unused:UNUSED_PAD src0_sel:DWORD
	v_or3_b32 v172, v173, v172, v174
	v_rndne_f32_e32 v173, v195
	v_cvt_i32_f32_sdwa v173, v173 dst_sel:BYTE_3 dst_unused:UNUSED_PAD src0_sel:DWORD
	v_bitop3_b32 v192, v172, s55, v191 bitop3:0x36
	v_lshlrev_b32_e32 v172, 8, v193
	v_or3_b32 v172, v172, v196, v194
	v_bitop3_b32 v193, v172, s55, v173 bitop3:0x36
	v_lshlrev_b64 v[172:173], 14, v[146:147]
	v_lshl_add_u64 v[172:173], s[10:11], 0, v[172:173]
	v_lshl_add_u64 v[172:173], v[172:173], 0, v[144:145]
	global_store_dwordx2 v[172:173], v[192:193], off
	v_max_f32_e32 v192, v185, v171
	v_max_f32_e32 v174, v175, v190
	v_max_f32_e32 v191, v189, v188
	v_max3_f32 v192, v187, v186, v192
	v_max3_f32 v174, v174, v191, v192
	v_cmp_lt_f32_e32 vcc, s56, v174
	s_and_saveexec_b64 s[0:1], vcc
	s_cbranch_execz .LBB0_1384
	v_cmp_lt_f32_e32 vcc, s56, v175
	s_and_saveexec_b64 s[28:29], vcc
	s_cbranch_execz .LBB0_1363
	v_lshl_add_u64 v[192:193], v[146:147], 2, s[6:7]
	global_atomic_add v174, v[192:193], v176, off sc0
	s_waitcnt vmcnt(0)
	v_cmp_gt_i32_e32 vcc, 8, v174
	s_and_b64 exec, exec, vcc
	s_cbranch_execz .LBB0_1363
	v_add_f32_e32 v193, 0xc1880000, v175
	v_lshl_add_u64 v[194:195], s[8:9], 0, v[168:169]
	v_ashrrev_i32_e32 v175, 31, v174
	v_mov_b32_e32 v192, v144
	v_lshl_add_u64 v[174:175], v[174:175], 3, v[194:195]
	global_store_dwordx2 v[174:175], v[192:193], off

.LBB0_1409:
	s_or_b64 exec, exec, s[0:1]
	v_ffbh_u32_e32 v112, v167
	v_min_u32_e32 v114, 32, v112
	v_lshlrev_b64 v[112:113], v114, v[166:167]
	v_min_u32_e32 v112, 1, v112
	v_or_b32_e32 v112, v113, v112
	v_cvt_f32_u32_e32 v112, v112
	v_ffbh_u32_e32 v113, v165
	v_min_u32_e32 v115, 32, v113
	v_sub_u32_e32 v113, 32, v114
	v_ldexp_f32 v114, v112, v113
	v_lshlrev_b64 v[112:113], v115, v[164:165]
	v_min_u32_e32 v112, 1, v112
	v_or_b32_e32 v112, v113, v112
	v_cvt_f32_u32_e32 v112, v112
	v_fmamk_f32 v113, v114, 0x2f800000, v183
	v_sub_u32_e32 v114, 32, v115
	v_rsq_f32_e32 v113, v113
	v_ldexp_f32 v112, v112, v114
	v_fmamk_f32 v112, v112, 0x2f800000, v183
	v_mul_f32_e32 v114, 0x4f800000, v112
	v_cmp_gt_f32_e32 vcc, s54, v112
	v_cvt_f32_i32_e32 v105, v105
	v_cvt_f32_i32_e32 v104, v104
	v_cndmask_b32_e32 v112, v112, v114, vcc
	v_sqrt_f32_e32 v114, v112
	v_cvt_f32_i32_e32 v109, v109
	v_cvt_f32_i32_e32 v108, v108
	v_mul_f32_e32 v113, 0x37820610, v113
	v_add_u32_e32 v115, -1, v114
	v_fma_f32 v116, -v115, v114, v112
	v_cmp_ge_f32_e64 s[0:1], 0, v116
	v_add_u32_e32 v116, 1, v114
	v_cvt_f32_i32_e32 v111, v111
	v_cndmask_b32_e64 v115, v114, v115, s[0:1]
	v_fma_f32 v114, -v116, v114, v112
	v_cmp_lt_f32_e64 s[0:1], 0, v114
	v_cvt_f32_i32_e32 v110, v110
	v_cvt_f32_i32_e32 v107, v107
	v_cndmask_b32_e64 v114, v115, v116, s[0:1]
	v_mul_f32_e32 v115, 0x37800000, v114
	v_cndmask_b32_e32 v114, v114, v115, vcc
	v_cmp_class_f32_e32 vcc, v112, v184
	v_cvt_f32_i32_e32 v106, v106
	s_nop 0
	v_cndmask_b32_e32 v112, v114, v112, vcc
	v_mul_f32_e32 v116, v113, v112
	v_mov_b32_e32 v234, v116
	v_rcp_f32_e32 v235, v116
	s_nop 0
	v_mul_f32_e32 v235, 0x4083851f, v235
	v_cvt_i32_f32_e32 v235, v235
	v_pk_mul_f32 v[104:105], v[116:117], v[104:105] op_sel_hi:[0,1]
	v_pk_mul_f32 v[108:109], v[116:117], v[108:109] op_sel_hi:[0,1]
	v_max_f32_e32 v104, 0, v104
	v_pk_mul_f32 v[164:165], v[116:117], v[110:111] op_sel_hi:[0,1]
	v_mul_f32_e32 v111, v104, v104
	v_max_f32_e32 v104, 0, v109
	v_mul_f32_e32 v119, v104, v104
	v_pk_mul_f32 v[166:167], v[116:117], v[106:107] op_sel_hi:[0,1]
	v_max_f32_e32 v106, 0, v108
	v_mul_f32_e32 v108, 0x41700000, v119
	v_max_f32_e32 v104, 0, v164
	v_min_f32_e32 v108, 0x437f0000, v108
	v_mul_f32_e32 v107, v106, v106
	v_mul_f32_e32 v118, v104, v104
	v_rndne_f32_e32 v108, v108
	v_mul_f32_e32 v106, 0x41700000, v107
	v_cvt_i32_f32_e32 v147, v108
	v_mul_f32_e32 v108, 0x41700000, v118
	v_min_f32_e32 v106, 0x437f0000, v106
	v_min_f32_e32 v108, 0x437f0000, v108
	v_rndne_f32_e32 v106, v106
	v_rndne_f32_e32 v108, v108
	v_cvt_i32_f32_e32 v106, v106
	v_cvt_i32_f32_sdwa v164, v108 dst_sel:WORD_1 dst_unused:UNUSED_PAD src0_sel:DWORD
	v_max_f32_e32 v105, 0, v105
	v_mul_f32_e32 v110, v105, v105
	v_max_f32_e32 v105, 0, v166
	v_max_f32_e32 v104, 0, v165
	v_mul_f32_e32 v109, v105, v105
	v_mul_f32_e32 v117, v104, v104
	v_lshlrev_b32_e32 v104, 8, v147
	v_max_f32_e32 v105, 0, v167
	v_or3_b32 v104, v104, v106, v164
	v_mul_f32_e32 v164, 0x41700000, v109
	v_mul_f32_e32 v108, v105, v105
	v_mul_f32_e32 v105, 0x41700000, v117
	v_mul_f32_e32 v147, 0x41700000, v110
	v_min_f32_e32 v164, 0x437f0000, v164
	v_min_f32_e32 v105, 0x437f0000, v105
	v_mul_f32_e32 v106, 0x41700000, v111
	v_min_f32_e32 v147, 0x437f0000, v147
	v_rndne_f32_e32 v164, v164
	v_rndne_f32_e32 v105, v105
	v_min_f32_e32 v106, 0x437f0000, v106
	v_rndne_f32_e32 v147, v147
	v_cvt_i32_f32_sdwa v165, v164 dst_sel:WORD_1 dst_unused:UNUSED_PAD src0_sel:DWORD
	v_mul_f32_e32 v164, 0x41700000, v108
	v_cvt_i32_f32_sdwa v105, v105 dst_sel:BYTE_3 dst_unused:UNUSED_PAD src0_sel:DWORD
	v_rndne_f32_e32 v106, v106
	v_cvt_i32_f32_e32 v147, v147
	v_min_f32_e32 v164, 0x437f0000, v164
	v_cvt_i32_f32_e32 v106, v106
	v_rndne_f32_e32 v164, v164
	v_cvt_i32_f32_sdwa v166, v164 dst_sel:BYTE_3 dst_unused:UNUSED_PAD src0_sel:DWORD
	v_or_b32_e32 v114, 16, v146
	v_bitop3_b32 v164, v104, s55, v105 bitop3:0x36
	v_lshlrev_b32_e32 v104, 8, v147
	v_ashrrev_i32_e32 v115, 31, v114
	v_or3_b32 v104, v104, v106, v165
	v_bitop3_b32 v165, v104, s55, v166 bitop3:0x36
	v_lshlrev_b64 v[104:105], 14, v[114:115]
	v_lshl_add_u64 v[104:105], s[10:11], 0, v[104:105]
	v_lshl_add_u64 v[104:105], v[104:105], 0, v[144:145]
	global_store_dwordx2 v[104:105], v[164:165], off
	v_max_f32_e32 v164, v109, v108
	v_max_f32_e32 v106, v107, v119
	v_max_f32_e32 v147, v118, v117
	v_max3_f32 v164, v111, v110, v164
	v_max3_f32 v106, v106, v147, v164
	v_lshlrev_b64 v[112:113], 6, v[114:115]
	v_cmp_lt_f32_e32 vcc, s56, v106
	s_and_saveexec_b64 s[0:1], vcc
	s_cbranch_execz .LBB0_1434
	v_cmp_lt_f32_e32 vcc, s56, v107
	s_and_saveexec_b64 s[28:29], vcc
	s_cbranch_execz .LBB0_1413
	v_lshl_add_u64 v[164:165], v[114:115], 2, s[6:7]
	global_atomic_add v106, v[164:165], v176, off sc0
	s_waitcnt vmcnt(0)
	v_cmp_gt_i32_e32 vcc, 8, v106
	s_and_b64 exec, exec, vcc
	s_cbranch_execz .LBB0_1413
	v_add_f32_e32 v165, 0xc1880000, v107
	v_lshl_add_u64 v[166:167], s[8:9], 0, v[112:113]
	v_ashrrev_i32_e32 v107, 31, v106
	v_mov_b32_e32 v164, v144
	v_lshl_add_u64 v[106:107], v[106:107], 3, v[166:167]
	global_store_dwordx2 v[106:107], v[164:165], off

.LBB0_1459:
	s_or_b64 exec, exec, s[0:1]
	v_ffbh_u32_e32 v96, v163
	v_min_u32_e32 v98, 32, v96
	v_lshlrev_b64 v[96:97], v98, v[162:163]
	v_min_u32_e32 v96, 1, v96
	v_or_b32_e32 v96, v97, v96
	v_cvt_f32_u32_e32 v96, v96
	v_ffbh_u32_e32 v97, v161
	v_min_u32_e32 v99, 32, v97
	v_sub_u32_e32 v97, 32, v98
	v_ldexp_f32 v98, v96, v97
	v_lshlrev_b64 v[96:97], v99, v[160:161]
	v_min_u32_e32 v96, 1, v96
	v_or_b32_e32 v96, v97, v96
	v_cvt_f32_u32_e32 v96, v96
	v_fmamk_f32 v97, v98, 0x2f800000, v183
	v_sub_u32_e32 v98, 32, v99
	v_rsq_f32_e32 v97, v97
	v_ldexp_f32 v96, v96, v98
	v_fmamk_f32 v96, v96, 0x2f800000, v183
	v_mul_f32_e32 v98, 0x4f800000, v96
	v_cmp_gt_f32_e32 vcc, s54, v96
	v_cvt_f32_i32_e32 v89, v89
	v_cvt_f32_i32_e32 v88, v88
	v_cndmask_b32_e32 v96, v96, v98, vcc
	v_sqrt_f32_e32 v98, v96
	v_cvt_f32_i32_e32 v93, v93
	v_cvt_f32_i32_e32 v92, v92
	v_mul_f32_e32 v97, 0x37820610, v97
	v_add_u32_e32 v99, -1, v98
	v_fma_f32 v100, -v99, v98, v96
	v_cmp_ge_f32_e64 s[0:1], 0, v100
	v_add_u32_e32 v100, 1, v98
	v_cvt_f32_i32_e32 v95, v95
	v_cndmask_b32_e64 v99, v98, v99, s[0:1]
	v_fma_f32 v98, -v100, v98, v96
	v_cmp_lt_f32_e64 s[0:1], 0, v98
	v_cvt_f32_i32_e32 v94, v94
	v_cvt_f32_i32_e32 v91, v91
	v_cndmask_b32_e64 v98, v99, v100, s[0:1]
	v_mul_f32_e32 v99, 0x37800000, v98
	v_cndmask_b32_e32 v98, v98, v99, vcc
	v_cmp_class_f32_e32 vcc, v96, v184
	v_cvt_f32_i32_e32 v90, v90
	s_nop 0
	v_cndmask_b32_e32 v96, v98, v96, vcc
	v_mul_f32_e32 v100, v97, v96
	v_mov_b32_e32 v236, v100
	v_rcp_f32_e32 v237, v100
	s_nop 0
	v_mul_f32_e32 v237, 0x4083851f, v237
	v_cvt_i32_f32_e32 v237, v237
	v_pk_mul_f32 v[88:89], v[100:101], v[88:89] op_sel_hi:[0,1]
	v_pk_mul_f32 v[92:93], v[100:101], v[92:93] op_sel_hi:[0,1]
	v_max_f32_e32 v88, 0, v88
	v_pk_mul_f32 v[104:105], v[100:101], v[94:95] op_sel_hi:[0,1]
	v_mul_f32_e32 v95, v88, v88
	v_max_f32_e32 v88, 0, v93
	v_mul_f32_e32 v103, v88, v88
	v_pk_mul_f32 v[106:107], v[100:101], v[90:91] op_sel_hi:[0,1]
	v_max_f32_e32 v90, 0, v92
	v_mul_f32_e32 v92, 0x41700000, v103
	v_max_f32_e32 v88, 0, v104
	v_min_f32_e32 v92, 0x437f0000, v92
	v_mul_f32_e32 v91, v90, v90
	v_mul_f32_e32 v102, v88, v88
	v_rndne_f32_e32 v92, v92
	v_mul_f32_e32 v90, 0x41700000, v91
	v_cvt_i32_f32_e32 v104, v92
	v_mul_f32_e32 v92, 0x41700000, v102
	v_min_f32_e32 v90, 0x437f0000, v90
	v_min_f32_e32 v92, 0x437f0000, v92
	v_max_f32_e32 v89, 0, v89
	v_rndne_f32_e32 v90, v90
	v_rndne_f32_e32 v92, v92
	v_mul_f32_e32 v94, v89, v89
	v_max_f32_e32 v88, 0, v105
	v_cvt_i32_f32_e32 v90, v90
	v_cvt_i32_f32_sdwa v105, v92 dst_sel:WORD_1 dst_unused:UNUSED_PAD src0_sel:DWORD
	v_mul_f32_e32 v101, v88, v88
	v_lshlrev_b32_e32 v88, 8, v104
	v_mul_f32_e32 v104, 0x41700000, v94
	v_max_f32_e32 v89, 0, v106
	v_min_f32_e32 v104, 0x437f0000, v104
	v_mul_f32_e32 v93, v89, v89
	v_rndne_f32_e32 v104, v104
	v_max_f32_e32 v89, 0, v107
	v_or3_b32 v88, v88, v90, v105
	v_cvt_i32_f32_e32 v105, v104
	v_mul_f32_e32 v104, 0x41700000, v93
	v_mul_f32_e32 v92, v89, v89
	v_mul_f32_e32 v89, 0x41700000, v101
	v_min_f32_e32 v104, 0x437f0000, v104
	v_min_f32_e32 v89, 0x437f0000, v89
	v_mul_f32_e32 v90, 0x41700000, v95
	v_rndne_f32_e32 v104, v104
	v_rndne_f32_e32 v89, v89
	v_min_f32_e32 v90, 0x437f0000, v90
	v_cvt_i32_f32_sdwa v106, v104 dst_sel:WORD_1 dst_unused:UNUSED_PAD src0_sel:DWORD
	v_mul_f32_e32 v104, 0x41700000, v92
	v_cvt_i32_f32_sdwa v89, v89 dst_sel:BYTE_3 dst_unused:UNUSED_PAD src0_sel:DWORD
	v_rndne_f32_e32 v90, v90
	v_min_f32_e32 v104, 0x437f0000, v104
	v_cvt_i32_f32_e32 v90, v90
	v_rndne_f32_e32 v104, v104
	v_cvt_i32_f32_sdwa v107, v104 dst_sel:BYTE_3 dst_unused:UNUSED_PAD src0_sel:DWORD
	v_or_b32_e32 v98, 32, v146
	v_bitop3_b32 v104, v88, s55, v89 bitop3:0x36
	v_lshlrev_b32_e32 v88, 8, v105
	v_ashrrev_i32_e32 v99, 31, v98
	v_or3_b32 v88, v88, v90, v106
	v_bitop3_b32 v105, v88, s55, v107 bitop3:0x36
	v_lshlrev_b64 v[88:89], 14, v[98:99]
	v_lshl_add_u64 v[88:89], s[10:11], 0, v[88:89]
	v_lshl_add_u64 v[88:89], v[88:89], 0, v[144:145]
	global_store_dwordx2 v[88:89], v[104:105], off
	v_max_f32_e32 v105, v93, v92
	v_max_f32_e32 v90, v91, v103
	v_max_f32_e32 v104, v102, v101
	v_max3_f32 v105, v95, v94, v105
	v_max3_f32 v90, v90, v104, v105
	v_lshlrev_b64 v[96:97], 6, v[98:99]
	v_cmp_lt_f32_e32 vcc, s56, v90
	s_and_saveexec_b64 s[0:1], vcc
	s_cbranch_execz .LBB0_1484
	v_cmp_lt_f32_e32 vcc, s56, v91
	s_and_saveexec_b64 s[28:29], vcc
	s_cbranch_execz .LBB0_1463
	v_lshl_add_u64 v[104:105], v[98:99], 2, s[6:7]
	global_atomic_add v90, v[104:105], v176, off sc0
	s_waitcnt vmcnt(0)
	v_cmp_gt_i32_e32 vcc, 8, v90
	s_and_b64 exec, exec, vcc
	s_cbranch_execz .LBB0_1463
	v_add_f32_e32 v105, 0xc1880000, v91
	v_lshl_add_u64 v[106:107], s[8:9], 0, v[96:97]
	v_ashrrev_i32_e32 v91, 31, v90
	v_mov_b32_e32 v104, v144
	v_lshl_add_u64 v[90:91], v[90:91], 3, v[106:107]
	global_store_dwordx2 v[90:91], v[104:105], off

.LBB0_1509:
	s_or_b64 exec, exec, s[0:1]
	v_ffbh_u32_e32 v80, v159
	v_min_u32_e32 v82, 32, v80
	v_lshlrev_b64 v[80:81], v82, v[158:159]
	v_min_u32_e32 v80, 1, v80
	v_or_b32_e32 v80, v81, v80
	v_cvt_f32_u32_e32 v80, v80
	v_ffbh_u32_e32 v81, v157
	v_min_u32_e32 v83, 32, v81
	v_sub_u32_e32 v81, 32, v82
	v_ldexp_f32 v82, v80, v81
	v_lshlrev_b64 v[80:81], v83, v[156:157]
	v_min_u32_e32 v80, 1, v80
	v_or_b32_e32 v80, v81, v80
	v_cvt_f32_u32_e32 v80, v80
	v_fmamk_f32 v81, v82, 0x2f800000, v183
	v_sub_u32_e32 v82, 32, v83
	v_rsq_f32_e32 v81, v81
	v_ldexp_f32 v80, v80, v82
	v_fmamk_f32 v80, v80, 0x2f800000, v183
	v_mul_f32_e32 v82, 0x4f800000, v80
	v_cmp_gt_f32_e32 vcc, s54, v80
	v_cvt_f32_i32_e32 v73, v73
	v_cvt_f32_i32_e32 v72, v72
	v_cndmask_b32_e32 v80, v80, v82, vcc
	v_sqrt_f32_e32 v82, v80
	v_cvt_f32_i32_e32 v77, v77
	v_cvt_f32_i32_e32 v76, v76
	v_mul_f32_e32 v81, 0x37820610, v81
	v_add_u32_e32 v83, -1, v82
	v_fma_f32 v84, -v83, v82, v80
	v_cmp_ge_f32_e64 s[0:1], 0, v84
	v_add_u32_e32 v84, 1, v82
	v_cvt_f32_i32_e32 v79, v79
	v_cndmask_b32_e64 v83, v82, v83, s[0:1]
	v_fma_f32 v82, -v84, v82, v80
	v_cmp_lt_f32_e64 s[0:1], 0, v82
	v_cvt_f32_i32_e32 v78, v78
	v_cvt_f32_i32_e32 v75, v75
	v_cndmask_b32_e64 v82, v83, v84, s[0:1]
	v_mul_f32_e32 v83, 0x37800000, v82
	v_cndmask_b32_e32 v82, v82, v83, vcc
	v_cmp_class_f32_e32 vcc, v80, v184
	v_cvt_f32_i32_e32 v74, v74
	s_nop 0
	v_cndmask_b32_e32 v80, v82, v80, vcc
	v_mul_f32_e32 v84, v81, v80
	v_mov_b32_e32 v238, v84
	v_rcp_f32_e32 v239, v84
	s_nop 0
	v_mul_f32_e32 v239, 0x4083851f, v239
	v_cvt_i32_f32_e32 v239, v239
	v_pk_mul_f32 v[72:73], v[84:85], v[72:73] op_sel_hi:[0,1]
	v_pk_mul_f32 v[76:77], v[84:85], v[76:77] op_sel_hi:[0,1]
	v_max_f32_e32 v72, 0, v72
	v_pk_mul_f32 v[88:89], v[84:85], v[78:79] op_sel_hi:[0,1]
	v_mul_f32_e32 v79, v72, v72
	v_max_f32_e32 v72, 0, v77
	v_mul_f32_e32 v87, v72, v72
	v_pk_mul_f32 v[90:91], v[84:85], v[74:75] op_sel_hi:[0,1]
	v_max_f32_e32 v74, 0, v76
	v_mul_f32_e32 v76, 0x41700000, v87
	v_max_f32_e32 v72, 0, v88
	v_min_f32_e32 v76, 0x437f0000, v76
	v_mul_f32_e32 v75, v74, v74
	v_mul_f32_e32 v86, v72, v72
	v_rndne_f32_e32 v76, v76
	v_mul_f32_e32 v74, 0x41700000, v75
	v_cvt_i32_f32_e32 v88, v76
	v_mul_f32_e32 v76, 0x41700000, v86
	v_min_f32_e32 v74, 0x437f0000, v74
	v_min_f32_e32 v76, 0x437f0000, v76
	v_max_f32_e32 v73, 0, v73
	v_rndne_f32_e32 v74, v74
	v_rndne_f32_e32 v76, v76
	v_mul_f32_e32 v78, v73, v73
	v_max_f32_e32 v72, 0, v89
	v_cvt_i32_f32_e32 v74, v74
	v_cvt_i32_f32_sdwa v89, v76 dst_sel:WORD_1 dst_unused:UNUSED_PAD src0_sel:DWORD
	v_mul_f32_e32 v85, v72, v72
	v_lshlrev_b32_e32 v72, 8, v88
	v_mul_f32_e32 v88, 0x41700000, v78
	v_max_f32_e32 v73, 0, v90
	v_min_f32_e32 v88, 0x437f0000, v88
	v_mul_f32_e32 v77, v73, v73
	v_rndne_f32_e32 v88, v88
	v_max_f32_e32 v73, 0, v91
	v_or3_b32 v72, v72, v74, v89
	v_cvt_i32_f32_e32 v89, v88
	v_mul_f32_e32 v88, 0x41700000, v77
	v_mul_f32_e32 v76, v73, v73
	v_mul_f32_e32 v73, 0x41700000, v85
	v_min_f32_e32 v88, 0x437f0000, v88
	v_min_f32_e32 v73, 0x437f0000, v73
	v_mul_f32_e32 v74, 0x41700000, v79
	v_rndne_f32_e32 v88, v88
	v_rndne_f32_e32 v73, v73
	v_min_f32_e32 v74, 0x437f0000, v74
	v_cvt_i32_f32_sdwa v90, v88 dst_sel:WORD_1 dst_unused:UNUSED_PAD src0_sel:DWORD
	v_mul_f32_e32 v88, 0x41700000, v76
	v_cvt_i32_f32_sdwa v73, v73 dst_sel:BYTE_3 dst_unused:UNUSED_PAD src0_sel:DWORD
	v_rndne_f32_e32 v74, v74
	v_min_f32_e32 v88, 0x437f0000, v88
	v_cvt_i32_f32_e32 v74, v74
	v_rndne_f32_e32 v88, v88
	v_cvt_i32_f32_sdwa v91, v88 dst_sel:BYTE_3 dst_unused:UNUSED_PAD src0_sel:DWORD
	v_or_b32_e32 v82, 48, v146
	v_bitop3_b32 v88, v72, s55, v73 bitop3:0x36
	v_lshlrev_b32_e32 v72, 8, v89
	v_ashrrev_i32_e32 v83, 31, v82
	v_or3_b32 v72, v72, v74, v90
	v_bitop3_b32 v89, v72, s55, v91 bitop3:0x36
	v_lshlrev_b64 v[72:73], 14, v[82:83]
	v_lshl_add_u64 v[72:73], s[10:11], 0, v[72:73]
	v_lshl_add_u64 v[72:73], v[72:73], 0, v[144:145]
	global_store_dwordx2 v[72:73], v[88:89], off
	v_max_f32_e32 v89, v77, v76
	v_max_f32_e32 v74, v75, v87
	v_max_f32_e32 v88, v86, v85
	v_max3_f32 v89, v79, v78, v89
	v_max3_f32 v74, v74, v88, v89
	v_lshlrev_b64 v[80:81], 6, v[82:83]
	v_cmp_lt_f32_e32 vcc, s56, v74
	s_and_saveexec_b64 s[0:1], vcc
	s_cbranch_execz .LBB0_1534
	v_cmp_lt_f32_e32 vcc, s56, v75
	s_and_saveexec_b64 s[28:29], vcc
	s_cbranch_execz .LBB0_1513
	v_lshl_add_u64 v[88:89], v[82:83], 2, s[6:7]
	global_atomic_add v74, v[88:89], v176, off sc0
	s_waitcnt vmcnt(0)
	v_cmp_gt_i32_e32 vcc, 8, v74
	s_and_b64 exec, exec, vcc
	s_cbranch_execz .LBB0_1513
	v_add_f32_e32 v89, 0xc1880000, v75
	v_lshl_add_u64 v[90:91], s[8:9], 0, v[80:81]
	v_ashrrev_i32_e32 v75, 31, v74
	v_mov_b32_e32 v88, v144
	v_lshl_add_u64 v[74:75], v[74:75], 3, v[90:91]
	global_store_dwordx2 v[74:75], v[88:89], off

.LBB0_1559:
	s_or_b64 exec, exec, s[0:1]
	v_ffbh_u32_e32 v64, v153
	v_min_u32_e32 v66, 32, v64
	v_lshlrev_b64 v[64:65], v66, v[152:153]
	v_min_u32_e32 v64, 1, v64
	v_or_b32_e32 v64, v65, v64
	v_cvt_f32_u32_e32 v64, v64
	s_waitcnt vmcnt(11)
	v_ffbh_u32_e32 v65, v155
	v_min_u32_e32 v67, 32, v65
	v_sub_u32_e32 v65, 32, v66
	v_ldexp_f32 v66, v64, v65
	v_lshlrev_b64 v[64:65], v67, v[154:155]
	v_min_u32_e32 v64, 1, v64
	v_or_b32_e32 v64, v65, v64
	v_cvt_f32_u32_e32 v64, v64
	v_fmamk_f32 v65, v66, 0x2f800000, v183
	v_sub_u32_e32 v66, 32, v67
	v_rsq_f32_e32 v65, v65
	v_ldexp_f32 v64, v64, v66
	v_fmamk_f32 v64, v64, 0x2f800000, v183
	v_mul_f32_e32 v66, 0x4f800000, v64
	v_cmp_gt_f32_e32 vcc, s54, v64
	v_cvt_f32_i32_e32 v57, v57
	v_cvt_f32_i32_e32 v56, v56
	v_cndmask_b32_e32 v64, v64, v66, vcc
	v_sqrt_f32_e32 v68, v64
	v_cvt_f32_i32_e32 v61, v61
	v_cvt_f32_i32_e32 v60, v60
	v_mul_f32_e32 v65, 0x37820610, v65
	v_add_u32_e32 v69, -1, v68
	v_fma_f32 v70, -v69, v68, v64
	v_cmp_ge_f32_e64 s[0:1], 0, v70
	v_add_u32_e32 v70, 1, v68
	v_cvt_f32_i32_e32 v63, v63
	v_cndmask_b32_e64 v69, v68, v69, s[0:1]
	v_fma_f32 v68, -v70, v68, v64
	v_cmp_lt_f32_e64 s[0:1], 0, v68
	v_cvt_f32_i32_e32 v62, v62
	v_cvt_f32_i32_e32 v59, v59
	v_cndmask_b32_e64 v68, v69, v70, s[0:1]
	v_mul_f32_e32 v69, 0x37800000, v68
	v_cndmask_b32_e32 v68, v68, v69, vcc
	v_cmp_class_f32_e32 vcc, v64, v184
	v_cvt_f32_i32_e32 v58, v58
	v_add_u32_e32 v66, 0x80, v146
	v_cndmask_b32_e32 v64, v68, v64, vcc
	v_mul_f32_e32 v68, v65, v64
	v_mov_b32_e32 v240, v68
	v_rcp_f32_e32 v241, v68
	s_nop 0
	v_mul_f32_e32 v241, 0x4083851f, v241
	v_cvt_i32_f32_e32 v241, v241
	v_pk_mul_f32 v[56:57], v[68:69], v[56:57] op_sel_hi:[0,1]
	v_pk_mul_f32 v[60:61], v[68:69], v[60:61] op_sel_hi:[0,1]
	v_max_f32_e32 v56, 0, v56
	v_pk_mul_f32 v[72:73], v[68:69], v[62:63] op_sel_hi:[0,1]
	v_mul_f32_e32 v63, v56, v56
	v_max_f32_e32 v56, 0, v61
	v_mul_f32_e32 v71, v56, v56
	v_pk_mul_f32 v[74:75], v[68:69], v[58:59] op_sel_hi:[0,1]
	v_max_f32_e32 v58, 0, v60
	v_mul_f32_e32 v60, 0x41700000, v71
	v_max_f32_e32 v56, 0, v72
	v_min_f32_e32 v60, 0x437f0000, v60
	v_mul_f32_e32 v59, v58, v58
	v_mul_f32_e32 v70, v56, v56
	v_rndne_f32_e32 v60, v60
	v_mul_f32_e32 v58, 0x41700000, v59
	v_cvt_i32_f32_e32 v72, v60
	v_mul_f32_e32 v60, 0x41700000, v70
	v_min_f32_e32 v58, 0x437f0000, v58
	v_min_f32_e32 v60, 0x437f0000, v60
	v_max_f32_e32 v57, 0, v57
	v_rndne_f32_e32 v58, v58
	v_rndne_f32_e32 v60, v60
	v_mul_f32_e32 v62, v57, v57
	v_max_f32_e32 v56, 0, v73
	v_cvt_i32_f32_e32 v58, v58
	v_cvt_i32_f32_sdwa v73, v60 dst_sel:WORD_1 dst_unused:UNUSED_PAD src0_sel:DWORD
	v_mul_f32_e32 v69, v56, v56
	v_lshlrev_b32_e32 v56, 8, v72
	v_mul_f32_e32 v72, 0x41700000, v62
	v_max_f32_e32 v57, 0, v74
	v_min_f32_e32 v72, 0x437f0000, v72
	v_mul_f32_e32 v61, v57, v57
	v_rndne_f32_e32 v72, v72
	v_max_f32_e32 v57, 0, v75
	v_or3_b32 v56, v56, v58, v73
	v_cvt_i32_f32_e32 v73, v72
	v_mul_f32_e32 v72, 0x41700000, v61
	v_mul_f32_e32 v60, v57, v57
	v_mul_f32_e32 v57, 0x41700000, v69
	v_min_f32_e32 v72, 0x437f0000, v72
	v_min_f32_e32 v57, 0x437f0000, v57
	v_mul_f32_e32 v58, 0x41700000, v63
	v_rndne_f32_e32 v72, v72
	v_rndne_f32_e32 v57, v57
	v_min_f32_e32 v58, 0x437f0000, v58
	v_cvt_i32_f32_sdwa v74, v72 dst_sel:WORD_1 dst_unused:UNUSED_PAD src0_sel:DWORD
	v_mul_f32_e32 v72, 0x41700000, v60
	v_cvt_i32_f32_sdwa v57, v57 dst_sel:BYTE_3 dst_unused:UNUSED_PAD src0_sel:DWORD
	v_rndne_f32_e32 v58, v58
	v_min_f32_e32 v72, 0x437f0000, v72
	v_cvt_i32_f32_e32 v58, v58
	v_rndne_f32_e32 v72, v72
	v_cvt_i32_f32_sdwa v75, v72 dst_sel:BYTE_3 dst_unused:UNUSED_PAD src0_sel:DWORD
	v_bitop3_b32 v72, v56, s55, v57 bitop3:0x36
	v_lshlrev_b32_e32 v56, 8, v73
	v_ashrrev_i32_e32 v67, 31, v66
	v_or3_b32 v56, v56, v58, v74
	v_bitop3_b32 v73, v56, s55, v75 bitop3:0x36
	v_lshlrev_b64 v[56:57], 14, v[66:67]
	v_lshl_add_u64 v[56:57], s[10:11], 0, v[56:57]
	v_lshl_add_u64 v[56:57], v[56:57], 0, v[144:145]
	global_store_dwordx2 v[56:57], v[72:73], off
	v_max_f32_e32 v73, v61, v60
	v_max_f32_e32 v58, v59, v71
	v_max_f32_e32 v72, v70, v69
	v_max3_f32 v73, v63, v62, v73
	v_max3_f32 v58, v58, v72, v73
	v_lshlrev_b64 v[64:65], 6, v[66:67]
	v_cmp_lt_f32_e32 vcc, s56, v58
	s_and_saveexec_b64 s[0:1], vcc
	s_cbranch_execz .LBB0_1584
	v_cmp_lt_f32_e32 vcc, s56, v59
	s_and_saveexec_b64 s[28:29], vcc
	s_cbranch_execz .LBB0_1563
	v_lshl_add_u64 v[72:73], v[66:67], 2, s[6:7]
	global_atomic_add v58, v[72:73], v176, off sc0
	s_waitcnt vmcnt(0)
	v_cmp_gt_i32_e32 vcc, 8, v58
	s_and_b64 exec, exec, vcc
	s_cbranch_execz .LBB0_1563
	v_add_f32_e32 v73, 0xc1880000, v59
	v_lshl_add_u64 v[74:75], s[8:9], 0, v[64:65]
	v_ashrrev_i32_e32 v59, 31, v58
	v_mov_b32_e32 v72, v144
	v_lshl_add_u64 v[58:59], v[58:59], 3, v[74:75]
	global_store_dwordx2 v[58:59], v[72:73], off

.LBB0_1609:
	s_or_b64 exec, exec, s[0:1]
	v_ffbh_u32_e32 v48, v149
	v_min_u32_e32 v50, 32, v48
	v_lshlrev_b64 v[48:49], v50, v[148:149]
	v_min_u32_e32 v48, 1, v48
	v_or_b32_e32 v48, v49, v48
	v_cvt_f32_u32_e32 v48, v48
	s_waitcnt vmcnt(12)
	v_ffbh_u32_e32 v49, v151
	v_min_u32_e32 v51, 32, v49
	v_sub_u32_e32 v49, 32, v50
	v_ldexp_f32 v50, v48, v49
	v_lshlrev_b64 v[48:49], v51, v[150:151]
	v_min_u32_e32 v48, 1, v48
	v_or_b32_e32 v48, v49, v48
	v_cvt_f32_u32_e32 v48, v48
	v_fmamk_f32 v49, v50, 0x2f800000, v183
	v_sub_u32_e32 v50, 32, v51
	v_rsq_f32_e32 v49, v49
	v_ldexp_f32 v48, v48, v50
	v_fmamk_f32 v48, v48, 0x2f800000, v183
	v_mul_f32_e32 v50, 0x4f800000, v48
	v_cmp_gt_f32_e32 vcc, s54, v48
	v_cvt_f32_i32_e32 v41, v41
	v_cvt_f32_i32_e32 v40, v40
	v_cndmask_b32_e32 v48, v48, v50, vcc
	v_sqrt_f32_e32 v50, v48
	v_cvt_f32_i32_e32 v45, v45
	v_cvt_f32_i32_e32 v44, v44
	v_mul_f32_e32 v49, 0x37820610, v49
	v_add_u32_e32 v51, -1, v50
	v_fma_f32 v52, -v51, v50, v48
	v_cmp_ge_f32_e64 s[0:1], 0, v52
	v_add_u32_e32 v52, 1, v50
	v_cvt_f32_i32_e32 v47, v47
	v_cndmask_b32_e64 v51, v50, v51, s[0:1]
	v_fma_f32 v50, -v52, v50, v48
	v_cmp_lt_f32_e64 s[0:1], 0, v50
	v_cvt_f32_i32_e32 v46, v46
	v_cvt_f32_i32_e32 v43, v43
	v_cndmask_b32_e64 v50, v51, v52, s[0:1]
	v_mul_f32_e32 v51, 0x37800000, v50
	v_cndmask_b32_e32 v50, v50, v51, vcc
	v_cmp_class_f32_e32 vcc, v48, v184
	v_cvt_f32_i32_e32 v42, v42
	s_nop 0
	v_cndmask_b32_e32 v48, v50, v48, vcc
	v_mul_f32_e32 v52, v49, v48
	v_mov_b32_e32 v242, v52
	v_rcp_f32_e32 v243, v52
	s_nop 0
	v_mul_f32_e32 v243, 0x4083851f, v243
	v_cvt_i32_f32_e32 v243, v243
	v_pk_mul_f32 v[40:41], v[52:53], v[40:41] op_sel_hi:[0,1]
	v_pk_mul_f32 v[44:45], v[52:53], v[44:45] op_sel_hi:[0,1]
	v_max_f32_e32 v40, 0, v40
	v_pk_mul_f32 v[56:57], v[52:53], v[46:47] op_sel_hi:[0,1]
	v_mul_f32_e32 v47, v40, v40
	v_max_f32_e32 v40, 0, v45
	v_mul_f32_e32 v55, v40, v40
	v_pk_mul_f32 v[58:59], v[52:53], v[42:43] op_sel_hi:[0,1]
	v_max_f32_e32 v42, 0, v44
	v_mul_f32_e32 v44, 0x41700000, v55
	v_max_f32_e32 v40, 0, v56
	v_min_f32_e32 v44, 0x437f0000, v44
	v_mul_f32_e32 v43, v42, v42
	v_mul_f32_e32 v54, v40, v40
	v_rndne_f32_e32 v44, v44
	v_mul_f32_e32 v42, 0x41700000, v43
	v_cvt_i32_f32_e32 v56, v44
	v_mul_f32_e32 v44, 0x41700000, v54
	v_min_f32_e32 v42, 0x437f0000, v42
	v_min_f32_e32 v44, 0x437f0000, v44
	v_max_f32_e32 v41, 0, v41
	v_rndne_f32_e32 v42, v42
	v_rndne_f32_e32 v44, v44
	v_mul_f32_e32 v46, v41, v41
	v_max_f32_e32 v40, 0, v57
	v_cvt_i32_f32_e32 v42, v42
	v_cvt_i32_f32_sdwa v57, v44 dst_sel:WORD_1 dst_unused:UNUSED_PAD src0_sel:DWORD
	v_mul_f32_e32 v53, v40, v40
	v_lshlrev_b32_e32 v40, 8, v56
	v_mul_f32_e32 v56, 0x41700000, v46
	v_max_f32_e32 v41, 0, v58
	v_min_f32_e32 v56, 0x437f0000, v56
	v_mul_f32_e32 v45, v41, v41
	v_rndne_f32_e32 v56, v56
	v_max_f32_e32 v41, 0, v59
	v_or3_b32 v40, v40, v42, v57
	v_cvt_i32_f32_e32 v57, v56
	v_mul_f32_e32 v56, 0x41700000, v45
	v_mul_f32_e32 v44, v41, v41
	v_mul_f32_e32 v41, 0x41700000, v53
	v_min_f32_e32 v56, 0x437f0000, v56
	v_min_f32_e32 v41, 0x437f0000, v41
	v_mul_f32_e32 v42, 0x41700000, v47
	v_rndne_f32_e32 v56, v56
	v_rndne_f32_e32 v41, v41
	v_min_f32_e32 v42, 0x437f0000, v42
	v_cvt_i32_f32_sdwa v58, v56 dst_sel:WORD_1 dst_unused:UNUSED_PAD src0_sel:DWORD
	v_mul_f32_e32 v56, 0x41700000, v44
	v_cvt_i32_f32_sdwa v41, v41 dst_sel:BYTE_3 dst_unused:UNUSED_PAD src0_sel:DWORD
	v_rndne_f32_e32 v42, v42
	v_min_f32_e32 v56, 0x437f0000, v56
	v_cvt_i32_f32_e32 v42, v42
	v_rndne_f32_e32 v56, v56
	v_cvt_i32_f32_sdwa v59, v56 dst_sel:BYTE_3 dst_unused:UNUSED_PAD src0_sel:DWORD
	v_add_u32_e32 v50, 0x90, v146
	v_bitop3_b32 v56, v40, s55, v41 bitop3:0x36
	v_lshlrev_b32_e32 v40, 8, v57
	v_ashrrev_i32_e32 v51, 31, v50
	v_or3_b32 v40, v40, v42, v58
	v_bitop3_b32 v57, v40, s55, v59 bitop3:0x36
	v_lshlrev_b64 v[40:41], 14, v[50:51]
	v_lshl_add_u64 v[40:41], s[10:11], 0, v[40:41]
	v_lshl_add_u64 v[40:41], v[40:41], 0, v[144:145]
	global_store_dwordx2 v[40:41], v[56:57], off
	v_max_f32_e32 v57, v45, v44
	v_max_f32_e32 v42, v43, v55
	v_max_f32_e32 v56, v54, v53
	v_max3_f32 v57, v47, v46, v57
	v_max3_f32 v42, v42, v56, v57
	v_lshlrev_b64 v[48:49], 6, v[50:51]
	v_cmp_lt_f32_e32 vcc, s56, v42
	s_and_saveexec_b64 s[0:1], vcc
	s_cbranch_execz .LBB0_1634
	v_cmp_lt_f32_e32 vcc, s56, v43
	s_and_saveexec_b64 s[28:29], vcc
	s_cbranch_execz .LBB0_1613
	v_lshl_add_u64 v[56:57], v[50:51], 2, s[6:7]
	global_atomic_add v42, v[56:57], v176, off sc0
	s_waitcnt vmcnt(0)
	v_cmp_gt_i32_e32 vcc, 8, v42
	s_and_b64 exec, exec, vcc
	s_cbranch_execz .LBB0_1613
	v_add_f32_e32 v57, 0xc1880000, v43
	v_lshl_add_u64 v[58:59], s[8:9], 0, v[48:49]
	v_ashrrev_i32_e32 v43, 31, v42
	v_mov_b32_e32 v56, v144
	v_lshl_add_u64 v[42:43], v[42:43], 3, v[58:59]
	global_store_dwordx2 v[42:43], v[56:57], off

.LBB0_1659:
	s_or_b64 exec, exec, s[0:1]
	v_ffbh_u32_e32 v32, v125
	v_min_u32_e32 v34, 32, v32
	v_lshlrev_b64 v[32:33], v34, v[124:125]
	v_min_u32_e32 v32, 1, v32
	v_or_b32_e32 v32, v33, v32
	v_cvt_f32_u32_e32 v32, v32
	s_waitcnt vmcnt(13)
	v_ffbh_u32_e32 v33, v127
	v_min_u32_e32 v35, 32, v33
	v_sub_u32_e32 v33, 32, v34
	v_ldexp_f32 v34, v32, v33
	v_lshlrev_b64 v[32:33], v35, v[126:127]
	v_min_u32_e32 v32, 1, v32
	v_or_b32_e32 v32, v33, v32
	v_cvt_f32_u32_e32 v32, v32
	v_fmamk_f32 v33, v34, 0x2f800000, v183
	v_sub_u32_e32 v34, 32, v35
	v_rsq_f32_e32 v33, v33
	v_ldexp_f32 v32, v32, v34
	v_fmamk_f32 v32, v32, 0x2f800000, v183
	v_mul_f32_e32 v34, 0x4f800000, v32
	v_cmp_gt_f32_e32 vcc, s54, v32
	v_cvt_f32_i32_e32 v25, v25
	v_cvt_f32_i32_e32 v24, v24
	v_cndmask_b32_e32 v32, v32, v34, vcc
	v_sqrt_f32_e32 v34, v32
	v_cvt_f32_i32_e32 v29, v29
	v_cvt_f32_i32_e32 v28, v28
	v_mul_f32_e32 v33, 0x37820610, v33
	v_add_u32_e32 v35, -1, v34
	v_fma_f32 v36, -v35, v34, v32
	v_cmp_ge_f32_e64 s[0:1], 0, v36
	v_add_u32_e32 v36, 1, v34
	v_cvt_f32_i32_e32 v31, v31
	v_cndmask_b32_e64 v35, v34, v35, s[0:1]
	v_fma_f32 v34, -v36, v34, v32
	v_cmp_lt_f32_e64 s[0:1], 0, v34
	v_cvt_f32_i32_e32 v30, v30
	v_cvt_f32_i32_e32 v27, v27
	v_cndmask_b32_e64 v34, v35, v36, s[0:1]
	v_mul_f32_e32 v35, 0x37800000, v34
	v_cndmask_b32_e32 v34, v34, v35, vcc
	v_cmp_class_f32_e32 vcc, v32, v184
	v_cvt_f32_i32_e32 v26, v26
	s_nop 0
	v_cndmask_b32_e32 v32, v34, v32, vcc
	v_mul_f32_e32 v36, v33, v32
	v_mov_b32_e32 v244, v36
	v_rcp_f32_e32 v245, v36
	s_nop 0
	v_mul_f32_e32 v245, 0x4083851f, v245
	v_cvt_i32_f32_e32 v245, v245
	v_pk_mul_f32 v[24:25], v[36:37], v[24:25] op_sel_hi:[0,1]
	v_pk_mul_f32 v[28:29], v[36:37], v[28:29] op_sel_hi:[0,1]
	v_max_f32_e32 v24, 0, v24
	v_pk_mul_f32 v[40:41], v[36:37], v[30:31] op_sel_hi:[0,1]
	v_mul_f32_e32 v31, v24, v24
	v_max_f32_e32 v24, 0, v29
	v_mul_f32_e32 v39, v24, v24
	v_pk_mul_f32 v[42:43], v[36:37], v[26:27] op_sel_hi:[0,1]
	v_max_f32_e32 v26, 0, v28
	v_mul_f32_e32 v28, 0x41700000, v39
	v_max_f32_e32 v24, 0, v40
	v_min_f32_e32 v28, 0x437f0000, v28
	v_mul_f32_e32 v27, v26, v26
	v_mul_f32_e32 v38, v24, v24
	v_rndne_f32_e32 v28, v28
	v_mul_f32_e32 v26, 0x41700000, v27
	v_cvt_i32_f32_e32 v40, v28
	v_mul_f32_e32 v28, 0x41700000, v38
	v_min_f32_e32 v26, 0x437f0000, v26
	v_min_f32_e32 v28, 0x437f0000, v28
	v_max_f32_e32 v25, 0, v25
	v_rndne_f32_e32 v26, v26
	v_rndne_f32_e32 v28, v28
	v_mul_f32_e32 v30, v25, v25
	v_max_f32_e32 v24, 0, v41
	v_cvt_i32_f32_e32 v26, v26
	v_cvt_i32_f32_sdwa v41, v28 dst_sel:WORD_1 dst_unused:UNUSED_PAD src0_sel:DWORD
	v_mul_f32_e32 v37, v24, v24
	v_lshlrev_b32_e32 v24, 8, v40
	v_mul_f32_e32 v40, 0x41700000, v30
	v_max_f32_e32 v25, 0, v42
	v_min_f32_e32 v40, 0x437f0000, v40
	v_mul_f32_e32 v29, v25, v25
	v_rndne_f32_e32 v40, v40
	v_max_f32_e32 v25, 0, v43
	v_or3_b32 v24, v24, v26, v41
	v_cvt_i32_f32_e32 v41, v40
	v_mul_f32_e32 v40, 0x41700000, v29
	v_mul_f32_e32 v28, v25, v25
	v_mul_f32_e32 v25, 0x41700000, v37
	v_min_f32_e32 v40, 0x437f0000, v40
	v_min_f32_e32 v25, 0x437f0000, v25
	v_mul_f32_e32 v26, 0x41700000, v31
	v_rndne_f32_e32 v40, v40
	v_rndne_f32_e32 v25, v25
	v_min_f32_e32 v26, 0x437f0000, v26
	v_cvt_i32_f32_sdwa v42, v40 dst_sel:WORD_1 dst_unused:UNUSED_PAD src0_sel:DWORD
	v_mul_f32_e32 v40, 0x41700000, v28
	v_cvt_i32_f32_sdwa v25, v25 dst_sel:BYTE_3 dst_unused:UNUSED_PAD src0_sel:DWORD
	v_rndne_f32_e32 v26, v26
	v_min_f32_e32 v40, 0x437f0000, v40
	v_cvt_i32_f32_e32 v26, v26
	v_rndne_f32_e32 v40, v40
	v_cvt_i32_f32_sdwa v43, v40 dst_sel:BYTE_3 dst_unused:UNUSED_PAD src0_sel:DWORD
	v_add_u32_e32 v34, 0xa0, v146
	v_bitop3_b32 v40, v24, s55, v25 bitop3:0x36
	v_lshlrev_b32_e32 v24, 8, v41
	v_ashrrev_i32_e32 v35, 31, v34
	v_or3_b32 v24, v24, v26, v42
	v_bitop3_b32 v41, v24, s55, v43 bitop3:0x36
	v_lshlrev_b64 v[24:25], 14, v[34:35]
	v_lshl_add_u64 v[24:25], s[10:11], 0, v[24:25]
	v_lshl_add_u64 v[24:25], v[24:25], 0, v[144:145]
	global_store_dwordx2 v[24:25], v[40:41], off
	v_max_f32_e32 v41, v29, v28
	v_max_f32_e32 v26, v27, v39
	v_max_f32_e32 v40, v38, v37
	v_max3_f32 v41, v31, v30, v41
	v_max3_f32 v26, v26, v40, v41
	v_lshlrev_b64 v[32:33], 6, v[34:35]
	v_cmp_lt_f32_e32 vcc, s56, v26
	s_and_saveexec_b64 s[0:1], vcc
	s_cbranch_execz .LBB0_1684
	v_cmp_lt_f32_e32 vcc, s56, v27
	s_and_saveexec_b64 s[28:29], vcc
	s_cbranch_execz .LBB0_1663
	v_lshl_add_u64 v[40:41], v[34:35], 2, s[6:7]
	global_atomic_add v26, v[40:41], v176, off sc0
	s_waitcnt vmcnt(0)
	v_cmp_gt_i32_e32 vcc, 8, v26
	s_and_b64 exec, exec, vcc
	s_cbranch_execz .LBB0_1663
	v_add_f32_e32 v41, 0xc1880000, v27
	v_lshl_add_u64 v[42:43], s[8:9], 0, v[32:33]
	v_ashrrev_i32_e32 v27, 31, v26
	v_mov_b32_e32 v40, v144
	v_lshl_add_u64 v[26:27], v[26:27], 3, v[42:43]
	global_store_dwordx2 v[26:27], v[40:41], off

.LBB0_1709:
	s_or_b64 exec, exec, s[0:1]
	v_ffbh_u32_e32 v16, v121
	v_min_u32_e32 v18, 32, v16
	v_lshlrev_b64 v[16:17], v18, v[120:121]
	v_min_u32_e32 v16, 1, v16
	v_or_b32_e32 v16, v17, v16
	v_cvt_f32_u32_e32 v16, v16
	s_waitcnt vmcnt(14)
	v_ffbh_u32_e32 v17, v123
	v_min_u32_e32 v19, 32, v17
	v_sub_u32_e32 v17, 32, v18
	v_ldexp_f32 v18, v16, v17
	v_lshlrev_b64 v[16:17], v19, v[122:123]
	v_min_u32_e32 v16, 1, v16
	v_or_b32_e32 v16, v17, v16
	v_cvt_f32_u32_e32 v16, v16
	v_fmamk_f32 v17, v18, 0x2f800000, v183
	v_sub_u32_e32 v18, 32, v19
	v_rsq_f32_e32 v17, v17
	v_ldexp_f32 v16, v16, v18
	v_fmamk_f32 v16, v16, 0x2f800000, v183
	v_mul_f32_e32 v18, 0x4f800000, v16
	v_cmp_gt_f32_e32 vcc, s54, v16
	v_cvt_f32_i32_e32 v9, v9
	v_cvt_f32_i32_e32 v8, v8
	v_cndmask_b32_e32 v16, v16, v18, vcc
	v_sqrt_f32_e32 v18, v16
	v_cvt_f32_i32_e32 v13, v13
	v_cvt_f32_i32_e32 v12, v12
	v_mul_f32_e32 v17, 0x37820610, v17
	v_add_u32_e32 v19, -1, v18
	v_fma_f32 v20, -v19, v18, v16
	v_cmp_ge_f32_e64 s[0:1], 0, v20
	v_add_u32_e32 v20, 1, v18
	v_cvt_f32_i32_e32 v15, v15
	v_cndmask_b32_e64 v19, v18, v19, s[0:1]
	v_fma_f32 v18, -v20, v18, v16
	v_cmp_lt_f32_e64 s[0:1], 0, v18
	v_cvt_f32_i32_e32 v14, v14
	v_cvt_f32_i32_e32 v11, v11
	v_cndmask_b32_e64 v18, v19, v20, s[0:1]
	v_mul_f32_e32 v19, 0x37800000, v18
	v_cndmask_b32_e32 v18, v18, v19, vcc
	v_cmp_class_f32_e32 vcc, v16, v184
	v_cvt_f32_i32_e32 v10, v10
	s_nop 0
	v_cndmask_b32_e32 v16, v18, v16, vcc
	v_mul_f32_e32 v20, v17, v16
	v_mov_b32_e32 v246, v20
	v_rcp_f32_e32 v247, v20
	s_nop 0
	v_mul_f32_e32 v247, 0x4083851f, v247
	v_cvt_i32_f32_e32 v247, v247
	v_pk_mul_f32 v[8:9], v[20:21], v[8:9] op_sel_hi:[0,1]
	v_pk_mul_f32 v[12:13], v[20:21], v[12:13] op_sel_hi:[0,1]
	v_max_f32_e32 v8, 0, v8
	v_pk_mul_f32 v[24:25], v[20:21], v[14:15] op_sel_hi:[0,1]
	v_mul_f32_e32 v15, v8, v8
	v_max_f32_e32 v8, 0, v13
	v_mul_f32_e32 v23, v8, v8
	v_pk_mul_f32 v[26:27], v[20:21], v[10:11] op_sel_hi:[0,1]
	v_max_f32_e32 v10, 0, v12
	v_mul_f32_e32 v12, 0x41700000, v23
	v_max_f32_e32 v8, 0, v24
	v_min_f32_e32 v12, 0x437f0000, v12
	v_mul_f32_e32 v11, v10, v10
	v_mul_f32_e32 v22, v8, v8
	v_rndne_f32_e32 v12, v12
	v_mul_f32_e32 v10, 0x41700000, v11
	v_cvt_i32_f32_e32 v24, v12
	v_mul_f32_e32 v12, 0x41700000, v22
	v_min_f32_e32 v10, 0x437f0000, v10
	v_min_f32_e32 v12, 0x437f0000, v12
	v_max_f32_e32 v9, 0, v9
	v_rndne_f32_e32 v10, v10
	v_rndne_f32_e32 v12, v12
	v_mul_f32_e32 v14, v9, v9
	v_max_f32_e32 v8, 0, v25
	v_cvt_i32_f32_e32 v10, v10
	v_cvt_i32_f32_sdwa v25, v12 dst_sel:WORD_1 dst_unused:UNUSED_PAD src0_sel:DWORD
	v_mul_f32_e32 v21, v8, v8
	v_lshlrev_b32_e32 v8, 8, v24
	v_mul_f32_e32 v24, 0x41700000, v14
	v_max_f32_e32 v9, 0, v26
	v_min_f32_e32 v24, 0x437f0000, v24
	v_mul_f32_e32 v13, v9, v9
	v_rndne_f32_e32 v24, v24
	v_max_f32_e32 v9, 0, v27
	v_or3_b32 v8, v8, v10, v25
	v_cvt_i32_f32_e32 v25, v24
	v_mul_f32_e32 v24, 0x41700000, v13
	v_mul_f32_e32 v12, v9, v9
	v_mul_f32_e32 v9, 0x41700000, v21
	v_min_f32_e32 v24, 0x437f0000, v24
	v_min_f32_e32 v9, 0x437f0000, v9
	v_mul_f32_e32 v10, 0x41700000, v15
	v_rndne_f32_e32 v24, v24
	v_rndne_f32_e32 v9, v9
	v_min_f32_e32 v10, 0x437f0000, v10
	v_cvt_i32_f32_sdwa v26, v24 dst_sel:WORD_1 dst_unused:UNUSED_PAD src0_sel:DWORD
	v_mul_f32_e32 v24, 0x41700000, v12
	v_cvt_i32_f32_sdwa v9, v9 dst_sel:BYTE_3 dst_unused:UNUSED_PAD src0_sel:DWORD
	v_rndne_f32_e32 v10, v10
	v_min_f32_e32 v24, 0x437f0000, v24
	v_cvt_i32_f32_e32 v10, v10
	v_rndne_f32_e32 v24, v24
	v_cvt_i32_f32_sdwa v27, v24 dst_sel:BYTE_3 dst_unused:UNUSED_PAD src0_sel:DWORD
	v_add_u32_e32 v18, 0xb0, v146
	v_bitop3_b32 v24, v8, s55, v9 bitop3:0x36
	v_lshlrev_b32_e32 v8, 8, v25
	v_ashrrev_i32_e32 v19, 31, v18
	v_or3_b32 v8, v8, v10, v26
	v_bitop3_b32 v25, v8, s55, v27 bitop3:0x36
	v_lshlrev_b64 v[8:9], 14, v[18:19]
	v_lshl_add_u64 v[8:9], s[10:11], 0, v[8:9]
	v_lshl_add_u64 v[8:9], v[8:9], 0, v[144:145]
	global_store_dwordx2 v[8:9], v[24:25], off
	v_max_f32_e32 v25, v13, v12
	v_max_f32_e32 v10, v11, v23
	v_max_f32_e32 v24, v22, v21
	v_max3_f32 v25, v15, v14, v25
	v_max3_f32 v10, v10, v24, v25
	v_lshlrev_b64 v[16:17], 6, v[18:19]
	v_cmp_lt_f32_e32 vcc, s56, v10
	s_and_saveexec_b64 s[0:1], vcc
	s_cbranch_execz .LBB0_1734
	v_cmp_lt_f32_e32 vcc, s56, v11
	s_and_saveexec_b64 s[28:29], vcc
	s_cbranch_execz .LBB0_1713
	v_lshl_add_u64 v[24:25], v[18:19], 2, s[6:7]
	global_atomic_add v10, v[24:25], v176, off sc0
	s_waitcnt vmcnt(0)
	v_cmp_gt_i32_e32 vcc, 8, v10
	s_and_b64 exec, exec, vcc
	s_cbranch_execz .LBB0_1713
	v_add_f32_e32 v145, 0xc1880000, v11
	v_lshl_add_u64 v[24:25], s[8:9], 0, v[16:17]
	v_ashrrev_i32_e32 v11, 31, v10
	v_lshl_add_u64 v[10:11], v[10:11], 3, v[24:25]
	global_store_dwordx2 v[10:11], v[144:145], off

.Ljoin_p11:
	s_andn2_b64 vcc, exec, s[4:5]
	s_cbranch_vccnz .LBB0_1347
	s_barrier
	s_branch .LBB0_1347
.Llean_p11:
	v_max3_i32 v228, v124, v125, v126
	v_max3_i32 v228, v228, v127, v120
	v_max3_i32 v228, v228, v121, v122
	v_max3_i32 v228, v228, v123, v116
	v_max3_i32 v228, v228, v117, v118
	v_max3_i32 v228, v228, v119, v112
	v_max3_i32 v228, v228, v113, v114
	v_max_i32_e32 v228, v228, v115
	v_cmp_ge_i32_e32 vcc, v228, v233
	v_max3_i32 v228, v108, v109, v110
	v_max3_i32 v228, v228, v111, v104
	v_max3_i32 v228, v228, v105, v106
	v_max3_i32 v228, v228, v107, v100
	v_max3_i32 v228, v228, v101, v102
	v_max3_i32 v228, v228, v103, v96
	v_max3_i32 v228, v228, v97, v98
	v_max_i32_e32 v228, v228, v99
	v_cmp_ge_i32_e64 s[96:97], v228, v235
	s_or_b64 vcc, vcc, s[96:97]
	v_max3_i32 v228, v92, v93, v94
	v_max3_i32 v228, v228, v95, v88
	v_max3_i32 v228, v228, v89, v90
	v_max3_i32 v228, v228, v91, v84
	v_max3_i32 v228, v228, v85, v86
	v_max3_i32 v228, v228, v87, v80
	v_max3_i32 v228, v228, v81, v82
	v_max_i32_e32 v228, v228, v83
	v_cmp_ge_i32_e64 s[96:97], v228, v237
	s_or_b64 vcc, vcc, s[96:97]
	v_max3_i32 v228, v76, v77, v78
	v_max3_i32 v228, v228, v79, v72
	v_max3_i32 v228, v228, v73, v74
	v_max3_i32 v228, v228, v75, v68
	v_max3_i32 v228, v228, v69, v70
	v_max3_i32 v228, v228, v71, v64
	v_max3_i32 v228, v228, v65, v66
	v_max_i32_e32 v228, v228, v67
	v_cmp_ge_i32_e64 s[96:97], v228, v239
	s_or_b64 vcc, vcc, s[96:97]
	v_max3_i32 v228, v60, v61, v62
	v_max3_i32 v228, v228, v63, v56
	v_max3_i32 v228, v228, v57, v58
	v_max3_i32 v228, v228, v59, v52
	v_max3_i32 v228, v228, v53, v54
	v_max3_i32 v228, v228, v55, v48
	v_max3_i32 v228, v228, v49, v50
	v_max_i32_e32 v228, v228, v51
	v_cmp_ge_i32_e64 s[96:97], v228, v241
	s_or_b64 vcc, vcc, s[96:97]
	v_max3_i32 v228, v44, v45, v46
	v_max3_i32 v228, v228, v47, v40
	v_max3_i32 v228, v228, v41, v42
	v_max3_i32 v228, v228, v43, v36
	v_max3_i32 v228, v228, v37, v38
	v_max3_i32 v228, v228, v39, v32
	v_max3_i32 v228, v228, v33, v34
	v_max_i32_e32 v228, v228, v35
	v_cmp_ge_i32_e64 s[96:97], v228, v243
	s_or_b64 vcc, vcc, s[96:97]
	v_max3_i32 v228, v28, v29, v30
	v_max3_i32 v228, v228, v31, v24
	v_max3_i32 v228, v228, v25, v26
	v_max3_i32 v228, v228, v27, v20
	v_max3_i32 v228, v228, v21, v22
	v_max3_i32 v228, v228, v23, v16
	v_max3_i32 v228, v228, v17, v18
	v_max_i32_e32 v228, v228, v19
	v_cmp_ge_i32_e64 s[96:97], v228, v245
	s_or_b64 vcc, vcc, s[96:97]
	v_max3_i32 v228, v12, v13, v14
	v_max3_i32 v228, v228, v15, v8
	v_max3_i32 v228, v228, v9, v10
	v_max3_i32 v228, v228, v11, v4
	v_max3_i32 v228, v228, v5, v6
	v_max3_i32 v228, v228, v7, v0
	v_max3_i32 v228, v228, v1, v2
	v_max_i32_e32 v228, v228, v3
	v_cmp_ge_i32_e64 s[96:97], v228, v247
	s_or_b64 vcc, vcc, s[96:97]
	s_cbranch_vccnz .Lorig_p11
	v_lshl_add_u32 v146, s28, 8, v177
	v_mov_b32_e32 v147, 0
	v_lshl_or_b32 v148, s0, 8, v179
	v_mov_b32_e32 v149, 0
	v_lshlrev_b64 v[146:147], 14, v[146:147]
	v_lshl_add_u64 v[146:147], s[10:11], 0, v[146:147]
	v_lshl_add_u64 v[150:151], v[146:147], 0, v[148:149]
	v_mov_b32_e32 v154, 0x41700000
	v_mov_b32_e32 v155, 0x41700000
	v_cvt_f32_i32_e32 v124, v124
	v_cvt_f32_i32_e32 v125, v125
	v_cvt_f32_i32_e32 v126, v126
	v_cvt_f32_i32_e32 v127, v127
	v_cvt_f32_i32_e32 v120, v120
	v_cvt_f32_i32_e32 v121, v121
	v_cvt_f32_i32_e32 v122, v122
	v_cvt_f32_i32_e32 v123, v123
	v_pk_mul_f32 v[124:125], v[232:233], v[124:125] op_sel_hi:[0,1]
	v_pk_mul_f32 v[126:127], v[232:233], v[126:127] op_sel_hi:[0,1]
	v_pk_mul_f32 v[120:121], v[232:233], v[120:121] op_sel_hi:[0,1]
	v_pk_mul_f32 v[122:123], v[232:233], v[122:123] op_sel_hi:[0,1]
	v_max_f32_e32 v124, 0, v124
	v_max_f32_e32 v125, 0, v125
	v_max_f32_e32 v126, 0, v126
	v_max_f32_e32 v127, 0, v127
	v_max_f32_e32 v120, 0, v120
	v_max_f32_e32 v121, 0, v121
	v_max_f32_e32 v122, 0, v122
	v_max_f32_e32 v123, 0, v123
	v_pk_mul_f32 v[124:125], v[124:125], v[124:125]
	v_pk_mul_f32 v[126:127], v[126:127], v[126:127]
	v_pk_mul_f32 v[120:121], v[120:121], v[120:121]
	v_pk_mul_f32 v[122:123], v[122:123], v[122:123]
	v_pk_mul_f32 v[124:125], v[154:155], v[124:125]
	v_pk_mul_f32 v[126:127], v[154:155], v[126:127]
	v_pk_mul_f32 v[120:121], v[154:155], v[120:121]
	v_pk_mul_f32 v[122:123], v[154:155], v[122:123]
	v_min_f32_e32 v124, 0x437f0000, v124
	v_min_f32_e32 v125, 0x437f0000, v125
	v_min_f32_e32 v126, 0x437f0000, v126
	v_min_f32_e32 v127, 0x437f0000, v127
	v_min_f32_e32 v120, 0x437f0000, v120
	v_min_f32_e32 v121, 0x437f0000, v121
	v_min_f32_e32 v122, 0x437f0000, v122
	v_min_f32_e32 v123, 0x437f0000, v123
	v_rndne_f32_e32 v124, v124
	v_rndne_f32_e32 v125, v125
	v_rndne_f32_e32 v126, v126
	v_rndne_f32_e32 v127, v127
	v_rndne_f32_e32 v120, v120
	v_rndne_f32_e32 v121, v121
	v_rndne_f32_e32 v122, v122
	v_rndne_f32_e32 v123, v123
	v_cvt_i32_f32_e32 v186, v124
	v_cvt_i32_f32_e32 v187, v120
	v_cvt_i32_f32_sdwa v186, v125 dst_sel:BYTE_1 dst_unused:UNUSED_PRESERVE src0_sel:DWORD
	v_cvt_i32_f32_sdwa v187, v121 dst_sel:BYTE_1 dst_unused:UNUSED_PRESERVE src0_sel:DWORD
	v_cvt_i32_f32_sdwa v186, v126 dst_sel:BYTE_2 dst_unused:UNUSED_PRESERVE src0_sel:DWORD
	v_cvt_i32_f32_sdwa v187, v122 dst_sel:BYTE_2 dst_unused:UNUSED_PRESERVE src0_sel:DWORD
	v_cvt_i32_f32_sdwa v186, v127 dst_sel:BYTE_3 dst_unused:UNUSED_PRESERVE src0_sel:DWORD
	v_cvt_i32_f32_sdwa v187, v123 dst_sel:BYTE_3 dst_unused:UNUSED_PRESERVE src0_sel:DWORD
	v_xor_b32_e32 v186, s55, v186
	v_xor_b32_e32 v187, s55, v187
	global_store_dwordx2 v[150:151], v[186:187], off
	v_cvt_f32_i32_e32 v116, v116
	v_cvt_f32_i32_e32 v117, v117
	v_cvt_f32_i32_e32 v118, v118
	v_cvt_f32_i32_e32 v119, v119
	v_cvt_f32_i32_e32 v112, v112
	v_cvt_f32_i32_e32 v113, v113
	v_cvt_f32_i32_e32 v114, v114
	v_cvt_f32_i32_e32 v115, v115
	v_pk_mul_f32 v[116:117], v[232:233], v[116:117] op_sel_hi:[0,1]
	v_pk_mul_f32 v[118:119], v[232:233], v[118:119] op_sel_hi:[0,1]
	v_pk_mul_f32 v[112:113], v[232:233], v[112:113] op_sel_hi:[0,1]
	v_pk_mul_f32 v[114:115], v[232:233], v[114:115] op_sel_hi:[0,1]
	v_max_f32_e32 v116, 0, v116
	v_max_f32_e32 v117, 0, v117
	v_max_f32_e32 v118, 0, v118
	v_max_f32_e32 v119, 0, v119
	v_max_f32_e32 v112, 0, v112
	v_max_f32_e32 v113, 0, v113
	v_max_f32_e32 v114, 0, v114
	v_max_f32_e32 v115, 0, v115
	v_pk_mul_f32 v[116:117], v[116:117], v[116:117]
	v_pk_mul_f32 v[118:119], v[118:119], v[118:119]
	v_pk_mul_f32 v[112:113], v[112:113], v[112:113]
	v_pk_mul_f32 v[114:115], v[114:115], v[114:115]
	v_pk_mul_f32 v[116:117], v[154:155], v[116:117]
	v_pk_mul_f32 v[118:119], v[154:155], v[118:119]
	v_pk_mul_f32 v[112:113], v[154:155], v[112:113]
	v_pk_mul_f32 v[114:115], v[154:155], v[114:115]
	v_min_f32_e32 v116, 0x437f0000, v116
	v_min_f32_e32 v117, 0x437f0000, v117
	v_min_f32_e32 v118, 0x437f0000, v118
	v_min_f32_e32 v119, 0x437f0000, v119
	v_min_f32_e32 v112, 0x437f0000, v112
	v_min_f32_e32 v113, 0x437f0000, v113
	v_min_f32_e32 v114, 0x437f0000, v114
	v_min_f32_e32 v115, 0x437f0000, v115
	v_rndne_f32_e32 v116, v116
	v_rndne_f32_e32 v117, v117
	v_rndne_f32_e32 v118, v118
	v_rndne_f32_e32 v119, v119
	v_rndne_f32_e32 v112, v112
	v_rndne_f32_e32 v113, v113
	v_rndne_f32_e32 v114, v114
	v_rndne_f32_e32 v115, v115
	v_cvt_i32_f32_e32 v188, v116
	v_cvt_i32_f32_e32 v189, v112
	v_cvt_i32_f32_sdwa v188, v117 dst_sel:BYTE_1 dst_unused:UNUSED_PRESERVE src0_sel:DWORD
	v_cvt_i32_f32_sdwa v189, v113 dst_sel:BYTE_1 dst_unused:UNUSED_PRESERVE src0_sel:DWORD
	v_cvt_i32_f32_sdwa v188, v118 dst_sel:BYTE_2 dst_unused:UNUSED_PRESERVE src0_sel:DWORD
	v_cvt_i32_f32_sdwa v189, v114 dst_sel:BYTE_2 dst_unused:UNUSED_PRESERVE src0_sel:DWORD
	v_cvt_i32_f32_sdwa v188, v119 dst_sel:BYTE_3 dst_unused:UNUSED_PRESERVE src0_sel:DWORD
	v_cvt_i32_f32_sdwa v189, v115 dst_sel:BYTE_3 dst_unused:UNUSED_PRESERVE src0_sel:DWORD
	v_xor_b32_e32 v188, s55, v188
	v_xor_b32_e32 v189, s55, v189
	global_store_dwordx2 v[150:151], v[188:189], off offset:128
	v_add_co_u32_e32 v152, vcc, 0x40000, v150
	s_nop 1
	v_addc_co_u32_e32 v153, vcc, 0, v151, vcc
	v_cvt_f32_i32_e32 v108, v108
	v_cvt_f32_i32_e32 v109, v109
	v_cvt_f32_i32_e32 v110, v110
	v_cvt_f32_i32_e32 v111, v111
	v_cvt_f32_i32_e32 v104, v104
	v_cvt_f32_i32_e32 v105, v105
	v_cvt_f32_i32_e32 v106, v106
	v_cvt_f32_i32_e32 v107, v107
	v_pk_mul_f32 v[108:109], v[234:235], v[108:109] op_sel_hi:[0,1]
	v_pk_mul_f32 v[110:111], v[234:235], v[110:111] op_sel_hi:[0,1]
	v_pk_mul_f32 v[104:105], v[234:235], v[104:105] op_sel_hi:[0,1]
	v_pk_mul_f32 v[106:107], v[234:235], v[106:107] op_sel_hi:[0,1]
	v_max_f32_e32 v108, 0, v108
	v_max_f32_e32 v109, 0, v109
	v_max_f32_e32 v110, 0, v110
	v_max_f32_e32 v111, 0, v111
	v_max_f32_e32 v104, 0, v104
	v_max_f32_e32 v105, 0, v105
	v_max_f32_e32 v106, 0, v106
	v_max_f32_e32 v107, 0, v107
	v_pk_mul_f32 v[108:109], v[108:109], v[108:109]
	v_pk_mul_f32 v[110:111], v[110:111], v[110:111]
	v_pk_mul_f32 v[104:105], v[104:105], v[104:105]
	v_pk_mul_f32 v[106:107], v[106:107], v[106:107]
	v_pk_mul_f32 v[108:109], v[154:155], v[108:109]
	v_pk_mul_f32 v[110:111], v[154:155], v[110:111]
	v_pk_mul_f32 v[104:105], v[154:155], v[104:105]
	v_pk_mul_f32 v[106:107], v[154:155], v[106:107]
	v_min_f32_e32 v108, 0x437f0000, v108
	v_min_f32_e32 v109, 0x437f0000, v109
	v_min_f32_e32 v110, 0x437f0000, v110
	v_min_f32_e32 v111, 0x437f0000, v111
	v_min_f32_e32 v104, 0x437f0000, v104
	v_min_f32_e32 v105, 0x437f0000, v105
	v_min_f32_e32 v106, 0x437f0000, v106
	v_min_f32_e32 v107, 0x437f0000, v107
	v_rndne_f32_e32 v108, v108
	v_rndne_f32_e32 v109, v109
	v_rndne_f32_e32 v110, v110
	v_rndne_f32_e32 v111, v111
	v_rndne_f32_e32 v104, v104
	v_rndne_f32_e32 v105, v105
	v_rndne_f32_e32 v106, v106
	v_rndne_f32_e32 v107, v107
	v_cvt_i32_f32_e32 v190, v108
	v_cvt_i32_f32_e32 v191, v104
	v_cvt_i32_f32_sdwa v190, v109 dst_sel:BYTE_1 dst_unused:UNUSED_PRESERVE src0_sel:DWORD
	v_cvt_i32_f32_sdwa v191, v105 dst_sel:BYTE_1 dst_unused:UNUSED_PRESERVE src0_sel:DWORD
	v_cvt_i32_f32_sdwa v190, v110 dst_sel:BYTE_2 dst_unused:UNUSED_PRESERVE src0_sel:DWORD
	v_cvt_i32_f32_sdwa v191, v106 dst_sel:BYTE_2 dst_unused:UNUSED_PRESERVE src0_sel:DWORD
	v_cvt_i32_f32_sdwa v190, v111 dst_sel:BYTE_3 dst_unused:UNUSED_PRESERVE src0_sel:DWORD
	v_cvt_i32_f32_sdwa v191, v107 dst_sel:BYTE_3 dst_unused:UNUSED_PRESERVE src0_sel:DWORD
	v_xor_b32_e32 v190, s55, v190
	v_xor_b32_e32 v191, s55, v191
	global_store_dwordx2 v[152:153], v[190:191], off
	v_cvt_f32_i32_e32 v100, v100
	v_cvt_f32_i32_e32 v101, v101
	v_cvt_f32_i32_e32 v102, v102
	v_cvt_f32_i32_e32 v103, v103
	v_cvt_f32_i32_e32 v96, v96
	v_cvt_f32_i32_e32 v97, v97
	v_cvt_f32_i32_e32 v98, v98
	v_cvt_f32_i32_e32 v99, v99
	v_pk_mul_f32 v[100:101], v[234:235], v[100:101] op_sel_hi:[0,1]
	v_pk_mul_f32 v[102:103], v[234:235], v[102:103] op_sel_hi:[0,1]
	v_pk_mul_f32 v[96:97], v[234:235], v[96:97] op_sel_hi:[0,1]
	v_pk_mul_f32 v[98:99], v[234:235], v[98:99] op_sel_hi:[0,1]
	v_max_f32_e32 v100, 0, v100
	v_max_f32_e32 v101, 0, v101
	v_max_f32_e32 v102, 0, v102
	v_max_f32_e32 v103, 0, v103
	v_max_f32_e32 v96, 0, v96
	v_max_f32_e32 v97, 0, v97
	v_max_f32_e32 v98, 0, v98
	v_max_f32_e32 v99, 0, v99
	v_pk_mul_f32 v[100:101], v[100:101], v[100:101]
	v_pk_mul_f32 v[102:103], v[102:103], v[102:103]
	v_pk_mul_f32 v[96:97], v[96:97], v[96:97]
	v_pk_mul_f32 v[98:99], v[98:99], v[98:99]
	v_pk_mul_f32 v[100:101], v[154:155], v[100:101]
	v_pk_mul_f32 v[102:103], v[154:155], v[102:103]
	v_pk_mul_f32 v[96:97], v[154:155], v[96:97]
	v_pk_mul_f32 v[98:99], v[154:155], v[98:99]
	v_min_f32_e32 v100, 0x437f0000, v100
	v_min_f32_e32 v101, 0x437f0000, v101
	v_min_f32_e32 v102, 0x437f0000, v102
	v_min_f32_e32 v103, 0x437f0000, v103
	v_min_f32_e32 v96, 0x437f0000, v96
	v_min_f32_e32 v97, 0x437f0000, v97
	v_min_f32_e32 v98, 0x437f0000, v98
	v_min_f32_e32 v99, 0x437f0000, v99
	v_rndne_f32_e32 v100, v100
	v_rndne_f32_e32 v101, v101
	v_rndne_f32_e32 v102, v102
	v_rndne_f32_e32 v103, v103
	v_rndne_f32_e32 v96, v96
	v_rndne_f32_e32 v97, v97
	v_rndne_f32_e32 v98, v98
	v_rndne_f32_e32 v99, v99
	v_cvt_i32_f32_e32 v192, v100
	v_cvt_i32_f32_e32 v193, v96
	v_cvt_i32_f32_sdwa v192, v101 dst_sel:BYTE_1 dst_unused:UNUSED_PRESERVE src0_sel:DWORD
	v_cvt_i32_f32_sdwa v193, v97 dst_sel:BYTE_1 dst_unused:UNUSED_PRESERVE src0_sel:DWORD
	v_cvt_i32_f32_sdwa v192, v102 dst_sel:BYTE_2 dst_unused:UNUSED_PRESERVE src0_sel:DWORD
	v_cvt_i32_f32_sdwa v193, v98 dst_sel:BYTE_2 dst_unused:UNUSED_PRESERVE src0_sel:DWORD
	v_cvt_i32_f32_sdwa v192, v103 dst_sel:BYTE_3 dst_unused:UNUSED_PRESERVE src0_sel:DWORD
	v_cvt_i32_f32_sdwa v193, v99 dst_sel:BYTE_3 dst_unused:UNUSED_PRESERVE src0_sel:DWORD
	v_xor_b32_e32 v192, s55, v192
	v_xor_b32_e32 v193, s55, v193
	global_store_dwordx2 v[152:153], v[192:193], off offset:128
	v_add_co_u32_e32 v152, vcc, 0x80000, v150
	s_nop 1
	v_addc_co_u32_e32 v153, vcc, 0, v151, vcc
	v_cvt_f32_i32_e32 v92, v92
	v_cvt_f32_i32_e32 v93, v93
	v_cvt_f32_i32_e32 v94, v94
	v_cvt_f32_i32_e32 v95, v95
	v_cvt_f32_i32_e32 v88, v88
	v_cvt_f32_i32_e32 v89, v89
	v_cvt_f32_i32_e32 v90, v90
	v_cvt_f32_i32_e32 v91, v91
	v_pk_mul_f32 v[92:93], v[236:237], v[92:93] op_sel_hi:[0,1]
	v_pk_mul_f32 v[94:95], v[236:237], v[94:95] op_sel_hi:[0,1]
	v_pk_mul_f32 v[88:89], v[236:237], v[88:89] op_sel_hi:[0,1]
	v_pk_mul_f32 v[90:91], v[236:237], v[90:91] op_sel_hi:[0,1]
	v_max_f32_e32 v92, 0, v92
	v_max_f32_e32 v93, 0, v93
	v_max_f32_e32 v94, 0, v94
	v_max_f32_e32 v95, 0, v95
	v_max_f32_e32 v88, 0, v88
	v_max_f32_e32 v89, 0, v89
	v_max_f32_e32 v90, 0, v90
	v_max_f32_e32 v91, 0, v91
	v_pk_mul_f32 v[92:93], v[92:93], v[92:93]
	v_pk_mul_f32 v[94:95], v[94:95], v[94:95]
	v_pk_mul_f32 v[88:89], v[88:89], v[88:89]
	v_pk_mul_f32 v[90:91], v[90:91], v[90:91]
	v_pk_mul_f32 v[92:93], v[154:155], v[92:93]
	v_pk_mul_f32 v[94:95], v[154:155], v[94:95]
	v_pk_mul_f32 v[88:89], v[154:155], v[88:89]
	v_pk_mul_f32 v[90:91], v[154:155], v[90:91]
	v_min_f32_e32 v92, 0x437f0000, v92
	v_min_f32_e32 v93, 0x437f0000, v93
	v_min_f32_e32 v94, 0x437f0000, v94
	v_min_f32_e32 v95, 0x437f0000, v95
	v_min_f32_e32 v88, 0x437f0000, v88
	v_min_f32_e32 v89, 0x437f0000, v89
	v_min_f32_e32 v90, 0x437f0000, v90
	v_min_f32_e32 v91, 0x437f0000, v91
	v_rndne_f32_e32 v92, v92
	v_rndne_f32_e32 v93, v93
	v_rndne_f32_e32 v94, v94
	v_rndne_f32_e32 v95, v95
	v_rndne_f32_e32 v88, v88
	v_rndne_f32_e32 v89, v89
	v_rndne_f32_e32 v90, v90
	v_rndne_f32_e32 v91, v91
	v_cvt_i32_f32_e32 v194, v92
	v_cvt_i32_f32_e32 v195, v88
	v_cvt_i32_f32_sdwa v194, v93 dst_sel:BYTE_1 dst_unused:UNUSED_PRESERVE src0_sel:DWORD
	v_cvt_i32_f32_sdwa v195, v89 dst_sel:BYTE_1 dst_unused:UNUSED_PRESERVE src0_sel:DWORD
	v_cvt_i32_f32_sdwa v194, v94 dst_sel:BYTE_2 dst_unused:UNUSED_PRESERVE src0_sel:DWORD
	v_cvt_i32_f32_sdwa v195, v90 dst_sel:BYTE_2 dst_unused:UNUSED_PRESERVE src0_sel:DWORD
	v_cvt_i32_f32_sdwa v194, v95 dst_sel:BYTE_3 dst_unused:UNUSED_PRESERVE src0_sel:DWORD
	v_cvt_i32_f32_sdwa v195, v91 dst_sel:BYTE_3 dst_unused:UNUSED_PRESERVE src0_sel:DWORD
	v_xor_b32_e32 v194, s55, v194
	v_xor_b32_e32 v195, s55, v195
	global_store_dwordx2 v[152:153], v[194:195], off
	v_cvt_f32_i32_e32 v84, v84
	v_cvt_f32_i32_e32 v85, v85
	v_cvt_f32_i32_e32 v86, v86
	v_cvt_f32_i32_e32 v87, v87
	v_cvt_f32_i32_e32 v80, v80
	v_cvt_f32_i32_e32 v81, v81
	v_cvt_f32_i32_e32 v82, v82
	v_cvt_f32_i32_e32 v83, v83
	v_pk_mul_f32 v[84:85], v[236:237], v[84:85] op_sel_hi:[0,1]
	v_pk_mul_f32 v[86:87], v[236:237], v[86:87] op_sel_hi:[0,1]
	v_pk_mul_f32 v[80:81], v[236:237], v[80:81] op_sel_hi:[0,1]
	v_pk_mul_f32 v[82:83], v[236:237], v[82:83] op_sel_hi:[0,1]
	v_max_f32_e32 v84, 0, v84
	v_max_f32_e32 v85, 0, v85
	v_max_f32_e32 v86, 0, v86
	v_max_f32_e32 v87, 0, v87
	v_max_f32_e32 v80, 0, v80
	v_max_f32_e32 v81, 0, v81
	v_max_f32_e32 v82, 0, v82
	v_max_f32_e32 v83, 0, v83
	v_pk_mul_f32 v[84:85], v[84:85], v[84:85]
	v_pk_mul_f32 v[86:87], v[86:87], v[86:87]
	v_pk_mul_f32 v[80:81], v[80:81], v[80:81]
	v_pk_mul_f32 v[82:83], v[82:83], v[82:83]
	v_pk_mul_f32 v[84:85], v[154:155], v[84:85]
	v_pk_mul_f32 v[86:87], v[154:155], v[86:87]
	v_pk_mul_f32 v[80:81], v[154:155], v[80:81]
	v_pk_mul_f32 v[82:83], v[154:155], v[82:83]
	v_min_f32_e32 v84, 0x437f0000, v84
	v_min_f32_e32 v85, 0x437f0000, v85
	v_min_f32_e32 v86, 0x437f0000, v86
	v_min_f32_e32 v87, 0x437f0000, v87
	v_min_f32_e32 v80, 0x437f0000, v80
	v_min_f32_e32 v81, 0x437f0000, v81
	v_min_f32_e32 v82, 0x437f0000, v82
	v_min_f32_e32 v83, 0x437f0000, v83
	v_rndne_f32_e32 v84, v84
	v_rndne_f32_e32 v85, v85
	v_rndne_f32_e32 v86, v86
	v_rndne_f32_e32 v87, v87
	v_rndne_f32_e32 v80, v80
	v_rndne_f32_e32 v81, v81
	v_rndne_f32_e32 v82, v82
	v_rndne_f32_e32 v83, v83
	v_cvt_i32_f32_e32 v196, v84
	v_cvt_i32_f32_e32 v197, v80
	v_cvt_i32_f32_sdwa v196, v85 dst_sel:BYTE_1 dst_unused:UNUSED_PRESERVE src0_sel:DWORD
	v_cvt_i32_f32_sdwa v197, v81 dst_sel:BYTE_1 dst_unused:UNUSED_PRESERVE src0_sel:DWORD
	v_cvt_i32_f32_sdwa v196, v86 dst_sel:BYTE_2 dst_unused:UNUSED_PRESERVE src0_sel:DWORD
	v_cvt_i32_f32_sdwa v197, v82 dst_sel:BYTE_2 dst_unused:UNUSED_PRESERVE src0_sel:DWORD
	v_cvt_i32_f32_sdwa v196, v87 dst_sel:BYTE_3 dst_unused:UNUSED_PRESERVE src0_sel:DWORD
	v_cvt_i32_f32_sdwa v197, v83 dst_sel:BYTE_3 dst_unused:UNUSED_PRESERVE src0_sel:DWORD
	v_xor_b32_e32 v196, s55, v196
	v_xor_b32_e32 v197, s55, v197
	global_store_dwordx2 v[152:153], v[196:197], off offset:128
	v_add_co_u32_e32 v152, vcc, 0xc0000, v150
	s_nop 1
	v_addc_co_u32_e32 v153, vcc, 0, v151, vcc
	v_cvt_f32_i32_e32 v76, v76
	v_cvt_f32_i32_e32 v77, v77
	v_cvt_f32_i32_e32 v78, v78
	v_cvt_f32_i32_e32 v79, v79
	v_cvt_f32_i32_e32 v72, v72
	v_cvt_f32_i32_e32 v73, v73
	v_cvt_f32_i32_e32 v74, v74
	v_cvt_f32_i32_e32 v75, v75
	v_pk_mul_f32 v[76:77], v[238:239], v[76:77] op_sel_hi:[0,1]
	v_pk_mul_f32 v[78:79], v[238:239], v[78:79] op_sel_hi:[0,1]
	v_pk_mul_f32 v[72:73], v[238:239], v[72:73] op_sel_hi:[0,1]
	v_pk_mul_f32 v[74:75], v[238:239], v[74:75] op_sel_hi:[0,1]
	v_max_f32_e32 v76, 0, v76
	v_max_f32_e32 v77, 0, v77
	v_max_f32_e32 v78, 0, v78
	v_max_f32_e32 v79, 0, v79
	v_max_f32_e32 v72, 0, v72
	v_max_f32_e32 v73, 0, v73
	v_max_f32_e32 v74, 0, v74
	v_max_f32_e32 v75, 0, v75
	v_pk_mul_f32 v[76:77], v[76:77], v[76:77]
	v_pk_mul_f32 v[78:79], v[78:79], v[78:79]
	v_pk_mul_f32 v[72:73], v[72:73], v[72:73]
	v_pk_mul_f32 v[74:75], v[74:75], v[74:75]
	v_pk_mul_f32 v[76:77], v[154:155], v[76:77]
	v_pk_mul_f32 v[78:79], v[154:155], v[78:79]
	v_pk_mul_f32 v[72:73], v[154:155], v[72:73]
	v_pk_mul_f32 v[74:75], v[154:155], v[74:75]
	v_min_f32_e32 v76, 0x437f0000, v76
	v_min_f32_e32 v77, 0x437f0000, v77
	v_min_f32_e32 v78, 0x437f0000, v78
	v_min_f32_e32 v79, 0x437f0000, v79
	v_min_f32_e32 v72, 0x437f0000, v72
	v_min_f32_e32 v73, 0x437f0000, v73
	v_min_f32_e32 v74, 0x437f0000, v74
	v_min_f32_e32 v75, 0x437f0000, v75
	v_rndne_f32_e32 v76, v76
	v_rndne_f32_e32 v77, v77
	v_rndne_f32_e32 v78, v78
	v_rndne_f32_e32 v79, v79
	v_rndne_f32_e32 v72, v72
	v_rndne_f32_e32 v73, v73
	v_rndne_f32_e32 v74, v74
	v_rndne_f32_e32 v75, v75
	v_cvt_i32_f32_e32 v198, v76
	v_cvt_i32_f32_e32 v199, v72
	v_cvt_i32_f32_sdwa v198, v77 dst_sel:BYTE_1 dst_unused:UNUSED_PRESERVE src0_sel:DWORD
	v_cvt_i32_f32_sdwa v199, v73 dst_sel:BYTE_1 dst_unused:UNUSED_PRESERVE src0_sel:DWORD
	v_cvt_i32_f32_sdwa v198, v78 dst_sel:BYTE_2 dst_unused:UNUSED_PRESERVE src0_sel:DWORD
	v_cvt_i32_f32_sdwa v199, v74 dst_sel:BYTE_2 dst_unused:UNUSED_PRESERVE src0_sel:DWORD
	v_cvt_i32_f32_sdwa v198, v79 dst_sel:BYTE_3 dst_unused:UNUSED_PRESERVE src0_sel:DWORD
	v_cvt_i32_f32_sdwa v199, v75 dst_sel:BYTE_3 dst_unused:UNUSED_PRESERVE src0_sel:DWORD
	v_xor_b32_e32 v198, s55, v198
	v_xor_b32_e32 v199, s55, v199
	global_store_dwordx2 v[152:153], v[198:199], off
	v_cvt_f32_i32_e32 v68, v68
	v_cvt_f32_i32_e32 v69, v69
	v_cvt_f32_i32_e32 v70, v70
	v_cvt_f32_i32_e32 v71, v71
	v_cvt_f32_i32_e32 v64, v64
	v_cvt_f32_i32_e32 v65, v65
	v_cvt_f32_i32_e32 v66, v66
	v_cvt_f32_i32_e32 v67, v67
	v_pk_mul_f32 v[68:69], v[238:239], v[68:69] op_sel_hi:[0,1]
	v_pk_mul_f32 v[70:71], v[238:239], v[70:71] op_sel_hi:[0,1]
	v_pk_mul_f32 v[64:65], v[238:239], v[64:65] op_sel_hi:[0,1]
	v_pk_mul_f32 v[66:67], v[238:239], v[66:67] op_sel_hi:[0,1]
	v_max_f32_e32 v68, 0, v68
	v_max_f32_e32 v69, 0, v69
	v_max_f32_e32 v70, 0, v70
	v_max_f32_e32 v71, 0, v71
	v_max_f32_e32 v64, 0, v64
	v_max_f32_e32 v65, 0, v65
	v_max_f32_e32 v66, 0, v66
	v_max_f32_e32 v67, 0, v67
	v_pk_mul_f32 v[68:69], v[68:69], v[68:69]
	v_pk_mul_f32 v[70:71], v[70:71], v[70:71]
	v_pk_mul_f32 v[64:65], v[64:65], v[64:65]
	v_pk_mul_f32 v[66:67], v[66:67], v[66:67]
	v_pk_mul_f32 v[68:69], v[154:155], v[68:69]
	v_pk_mul_f32 v[70:71], v[154:155], v[70:71]
	v_pk_mul_f32 v[64:65], v[154:155], v[64:65]
	v_pk_mul_f32 v[66:67], v[154:155], v[66:67]
	v_min_f32_e32 v68, 0x437f0000, v68
	v_min_f32_e32 v69, 0x437f0000, v69
	v_min_f32_e32 v70, 0x437f0000, v70
	v_min_f32_e32 v71, 0x437f0000, v71
	v_min_f32_e32 v64, 0x437f0000, v64
	v_min_f32_e32 v65, 0x437f0000, v65
	v_min_f32_e32 v66, 0x437f0000, v66
	v_min_f32_e32 v67, 0x437f0000, v67
	v_rndne_f32_e32 v68, v68
	v_rndne_f32_e32 v69, v69
	v_rndne_f32_e32 v70, v70
	v_rndne_f32_e32 v71, v71
	v_rndne_f32_e32 v64, v64
	v_rndne_f32_e32 v65, v65
	v_rndne_f32_e32 v66, v66
	v_rndne_f32_e32 v67, v67
	v_cvt_i32_f32_e32 v200, v68
	v_cvt_i32_f32_e32 v201, v64
	v_cvt_i32_f32_sdwa v200, v69 dst_sel:BYTE_1 dst_unused:UNUSED_PRESERVE src0_sel:DWORD
	v_cvt_i32_f32_sdwa v201, v65 dst_sel:BYTE_1 dst_unused:UNUSED_PRESERVE src0_sel:DWORD
	v_cvt_i32_f32_sdwa v200, v70 dst_sel:BYTE_2 dst_unused:UNUSED_PRESERVE src0_sel:DWORD
	v_cvt_i32_f32_sdwa v201, v66 dst_sel:BYTE_2 dst_unused:UNUSED_PRESERVE src0_sel:DWORD
	v_cvt_i32_f32_sdwa v200, v71 dst_sel:BYTE_3 dst_unused:UNUSED_PRESERVE src0_sel:DWORD
	v_cvt_i32_f32_sdwa v201, v67 dst_sel:BYTE_3 dst_unused:UNUSED_PRESERVE src0_sel:DWORD
	v_xor_b32_e32 v200, s55, v200
	v_xor_b32_e32 v201, s55, v201
	global_store_dwordx2 v[152:153], v[200:201], off offset:128
	v_add_co_u32_e32 v152, vcc, 0x200000, v150
	s_nop 1
	v_addc_co_u32_e32 v153, vcc, 0, v151, vcc
	v_cvt_f32_i32_e32 v60, v60
	v_cvt_f32_i32_e32 v61, v61
	v_cvt_f32_i32_e32 v62, v62
	v_cvt_f32_i32_e32 v63, v63
	v_cvt_f32_i32_e32 v56, v56
	v_cvt_f32_i32_e32 v57, v57
	v_cvt_f32_i32_e32 v58, v58
	v_cvt_f32_i32_e32 v59, v59
	v_pk_mul_f32 v[60:61], v[240:241], v[60:61] op_sel_hi:[0,1]
	v_pk_mul_f32 v[62:63], v[240:241], v[62:63] op_sel_hi:[0,1]
	v_pk_mul_f32 v[56:57], v[240:241], v[56:57] op_sel_hi:[0,1]
	v_pk_mul_f32 v[58:59], v[240:241], v[58:59] op_sel_hi:[0,1]
	v_max_f32_e32 v60, 0, v60
	v_max_f32_e32 v61, 0, v61
	v_max_f32_e32 v62, 0, v62
	v_max_f32_e32 v63, 0, v63
	v_max_f32_e32 v56, 0, v56
	v_max_f32_e32 v57, 0, v57
	v_max_f32_e32 v58, 0, v58
	v_max_f32_e32 v59, 0, v59
	v_pk_mul_f32 v[60:61], v[60:61], v[60:61]
	v_pk_mul_f32 v[62:63], v[62:63], v[62:63]
	v_pk_mul_f32 v[56:57], v[56:57], v[56:57]
	v_pk_mul_f32 v[58:59], v[58:59], v[58:59]
	v_pk_mul_f32 v[60:61], v[154:155], v[60:61]
	v_pk_mul_f32 v[62:63], v[154:155], v[62:63]
	v_pk_mul_f32 v[56:57], v[154:155], v[56:57]
	v_pk_mul_f32 v[58:59], v[154:155], v[58:59]
	v_min_f32_e32 v60, 0x437f0000, v60
	v_min_f32_e32 v61, 0x437f0000, v61
	v_min_f32_e32 v62, 0x437f0000, v62
	v_min_f32_e32 v63, 0x437f0000, v63
	v_min_f32_e32 v56, 0x437f0000, v56
	v_min_f32_e32 v57, 0x437f0000, v57
	v_min_f32_e32 v58, 0x437f0000, v58
	v_min_f32_e32 v59, 0x437f0000, v59
	v_rndne_f32_e32 v60, v60
	v_rndne_f32_e32 v61, v61
	v_rndne_f32_e32 v62, v62
	v_rndne_f32_e32 v63, v63
	v_rndne_f32_e32 v56, v56
	v_rndne_f32_e32 v57, v57
	v_rndne_f32_e32 v58, v58
	v_rndne_f32_e32 v59, v59
	v_cvt_i32_f32_e32 v186, v60
	v_cvt_i32_f32_e32 v187, v56
	v_cvt_i32_f32_sdwa v186, v61 dst_sel:BYTE_1 dst_unused:UNUSED_PRESERVE src0_sel:DWORD
	v_cvt_i32_f32_sdwa v187, v57 dst_sel:BYTE_1 dst_unused:UNUSED_PRESERVE src0_sel:DWORD
	v_cvt_i32_f32_sdwa v186, v62 dst_sel:BYTE_2 dst_unused:UNUSED_PRESERVE src0_sel:DWORD
	v_cvt_i32_f32_sdwa v187, v58 dst_sel:BYTE_2 dst_unused:UNUSED_PRESERVE src0_sel:DWORD
	v_cvt_i32_f32_sdwa v186, v63 dst_sel:BYTE_3 dst_unused:UNUSED_PRESERVE src0_sel:DWORD
	v_cvt_i32_f32_sdwa v187, v59 dst_sel:BYTE_3 dst_unused:UNUSED_PRESERVE src0_sel:DWORD
	v_xor_b32_e32 v186, s55, v186
	v_xor_b32_e32 v187, s55, v187
	global_store_dwordx2 v[152:153], v[186:187], off
	v_cvt_f32_i32_e32 v52, v52
	v_cvt_f32_i32_e32 v53, v53
	v_cvt_f32_i32_e32 v54, v54
	v_cvt_f32_i32_e32 v55, v55
	v_cvt_f32_i32_e32 v48, v48
	v_cvt_f32_i32_e32 v49, v49
	v_cvt_f32_i32_e32 v50, v50
	v_cvt_f32_i32_e32 v51, v51
	v_pk_mul_f32 v[52:53], v[240:241], v[52:53] op_sel_hi:[0,1]
	v_pk_mul_f32 v[54:55], v[240:241], v[54:55] op_sel_hi:[0,1]
	v_pk_mul_f32 v[48:49], v[240:241], v[48:49] op_sel_hi:[0,1]
	v_pk_mul_f32 v[50:51], v[240:241], v[50:51] op_sel_hi:[0,1]
	v_max_f32_e32 v52, 0, v52
	v_max_f32_e32 v53, 0, v53
	v_max_f32_e32 v54, 0, v54
	v_max_f32_e32 v55, 0, v55
	v_max_f32_e32 v48, 0, v48
	v_max_f32_e32 v49, 0, v49
	v_max_f32_e32 v50, 0, v50
	v_max_f32_e32 v51, 0, v51
	v_pk_mul_f32 v[52:53], v[52:53], v[52:53]
	v_pk_mul_f32 v[54:55], v[54:55], v[54:55]
	v_pk_mul_f32 v[48:49], v[48:49], v[48:49]
	v_pk_mul_f32 v[50:51], v[50:51], v[50:51]
	v_pk_mul_f32 v[52:53], v[154:155], v[52:53]
	v_pk_mul_f32 v[54:55], v[154:155], v[54:55]
	v_pk_mul_f32 v[48:49], v[154:155], v[48:49]
	v_pk_mul_f32 v[50:51], v[154:155], v[50:51]
	v_min_f32_e32 v52, 0x437f0000, v52
	v_min_f32_e32 v53, 0x437f0000, v53
	v_min_f32_e32 v54, 0x437f0000, v54
	v_min_f32_e32 v55, 0x437f0000, v55
	v_min_f32_e32 v48, 0x437f0000, v48
	v_min_f32_e32 v49, 0x437f0000, v49
	v_min_f32_e32 v50, 0x437f0000, v50
	v_min_f32_e32 v51, 0x437f0000, v51
	v_rndne_f32_e32 v52, v52
	v_rndne_f32_e32 v53, v53
	v_rndne_f32_e32 v54, v54
	v_rndne_f32_e32 v55, v55
	v_rndne_f32_e32 v48, v48
	v_rndne_f32_e32 v49, v49
	v_rndne_f32_e32 v50, v50
	v_rndne_f32_e32 v51, v51
	v_cvt_i32_f32_e32 v188, v52
	v_cvt_i32_f32_e32 v189, v48
	v_cvt_i32_f32_sdwa v188, v53 dst_sel:BYTE_1 dst_unused:UNUSED_PRESERVE src0_sel:DWORD
	v_cvt_i32_f32_sdwa v189, v49 dst_sel:BYTE_1 dst_unused:UNUSED_PRESERVE src0_sel:DWORD
	v_cvt_i32_f32_sdwa v188, v54 dst_sel:BYTE_2 dst_unused:UNUSED_PRESERVE src0_sel:DWORD
	v_cvt_i32_f32_sdwa v189, v50 dst_sel:BYTE_2 dst_unused:UNUSED_PRESERVE src0_sel:DWORD
	v_cvt_i32_f32_sdwa v188, v55 dst_sel:BYTE_3 dst_unused:UNUSED_PRESERVE src0_sel:DWORD
	v_cvt_i32_f32_sdwa v189, v51 dst_sel:BYTE_3 dst_unused:UNUSED_PRESERVE src0_sel:DWORD
	v_xor_b32_e32 v188, s55, v188
	v_xor_b32_e32 v189, s55, v189
	global_store_dwordx2 v[152:153], v[188:189], off offset:128
	v_add_co_u32_e32 v152, vcc, 0x240000, v150
	s_nop 1
	v_addc_co_u32_e32 v153, vcc, 0, v151, vcc
	v_cvt_f32_i32_e32 v44, v44
	v_cvt_f32_i32_e32 v45, v45
	v_cvt_f32_i32_e32 v46, v46
	v_cvt_f32_i32_e32 v47, v47
	v_cvt_f32_i32_e32 v40, v40
	v_cvt_f32_i32_e32 v41, v41
	v_cvt_f32_i32_e32 v42, v42
	v_cvt_f32_i32_e32 v43, v43
	v_pk_mul_f32 v[44:45], v[242:243], v[44:45] op_sel_hi:[0,1]
	v_pk_mul_f32 v[46:47], v[242:243], v[46:47] op_sel_hi:[0,1]
	v_pk_mul_f32 v[40:41], v[242:243], v[40:41] op_sel_hi:[0,1]
	v_pk_mul_f32 v[42:43], v[242:243], v[42:43] op_sel_hi:[0,1]
	v_max_f32_e32 v44, 0, v44
	v_max_f32_e32 v45, 0, v45
	v_max_f32_e32 v46, 0, v46
	v_max_f32_e32 v47, 0, v47
	v_max_f32_e32 v40, 0, v40
	v_max_f32_e32 v41, 0, v41
	v_max_f32_e32 v42, 0, v42
	v_max_f32_e32 v43, 0, v43
	v_pk_mul_f32 v[44:45], v[44:45], v[44:45]
	v_pk_mul_f32 v[46:47], v[46:47], v[46:47]
	v_pk_mul_f32 v[40:41], v[40:41], v[40:41]
	v_pk_mul_f32 v[42:43], v[42:43], v[42:43]
	v_pk_mul_f32 v[44:45], v[154:155], v[44:45]
	v_pk_mul_f32 v[46:47], v[154:155], v[46:47]
	v_pk_mul_f32 v[40:41], v[154:155], v[40:41]
	v_pk_mul_f32 v[42:43], v[154:155], v[42:43]
	v_min_f32_e32 v44, 0x437f0000, v44
	v_min_f32_e32 v45, 0x437f0000, v45
	v_min_f32_e32 v46, 0x437f0000, v46
	v_min_f32_e32 v47, 0x437f0000, v47
	v_min_f32_e32 v40, 0x437f0000, v40
	v_min_f32_e32 v41, 0x437f0000, v41
	v_min_f32_e32 v42, 0x437f0000, v42
	v_min_f32_e32 v43, 0x437f0000, v43
	v_rndne_f32_e32 v44, v44
	v_rndne_f32_e32 v45, v45
	v_rndne_f32_e32 v46, v46
	v_rndne_f32_e32 v47, v47
	v_rndne_f32_e32 v40, v40
	v_rndne_f32_e32 v41, v41
	v_rndne_f32_e32 v42, v42
	v_rndne_f32_e32 v43, v43
	v_cvt_i32_f32_e32 v190, v44
	v_cvt_i32_f32_e32 v191, v40
	v_cvt_i32_f32_sdwa v190, v45 dst_sel:BYTE_1 dst_unused:UNUSED_PRESERVE src0_sel:DWORD
	v_cvt_i32_f32_sdwa v191, v41 dst_sel:BYTE_1 dst_unused:UNUSED_PRESERVE src0_sel:DWORD
	v_cvt_i32_f32_sdwa v190, v46 dst_sel:BYTE_2 dst_unused:UNUSED_PRESERVE src0_sel:DWORD
	v_cvt_i32_f32_sdwa v191, v42 dst_sel:BYTE_2 dst_unused:UNUSED_PRESERVE src0_sel:DWORD
	v_cvt_i32_f32_sdwa v190, v47 dst_sel:BYTE_3 dst_unused:UNUSED_PRESERVE src0_sel:DWORD
	v_cvt_i32_f32_sdwa v191, v43 dst_sel:BYTE_3 dst_unused:UNUSED_PRESERVE src0_sel:DWORD
	v_xor_b32_e32 v190, s55, v190
	v_xor_b32_e32 v191, s55, v191
	global_store_dwordx2 v[152:153], v[190:191], off
	v_cvt_f32_i32_e32 v36, v36
	v_cvt_f32_i32_e32 v37, v37
	v_cvt_f32_i32_e32 v38, v38
	v_cvt_f32_i32_e32 v39, v39
	v_cvt_f32_i32_e32 v32, v32
	v_cvt_f32_i32_e32 v33, v33
	v_cvt_f32_i32_e32 v34, v34
	v_cvt_f32_i32_e32 v35, v35
	v_pk_mul_f32 v[36:37], v[242:243], v[36:37] op_sel_hi:[0,1]
	v_pk_mul_f32 v[38:39], v[242:243], v[38:39] op_sel_hi:[0,1]
	v_pk_mul_f32 v[32:33], v[242:243], v[32:33] op_sel_hi:[0,1]
	v_pk_mul_f32 v[34:35], v[242:243], v[34:35] op_sel_hi:[0,1]
	v_max_f32_e32 v36, 0, v36
	v_max_f32_e32 v37, 0, v37
	v_max_f32_e32 v38, 0, v38
	v_max_f32_e32 v39, 0, v39
	v_max_f32_e32 v32, 0, v32
	v_max_f32_e32 v33, 0, v33
	v_max_f32_e32 v34, 0, v34
	v_max_f32_e32 v35, 0, v35
	v_pk_mul_f32 v[36:37], v[36:37], v[36:37]
	v_pk_mul_f32 v[38:39], v[38:39], v[38:39]
	v_pk_mul_f32 v[32:33], v[32:33], v[32:33]
	v_pk_mul_f32 v[34:35], v[34:35], v[34:35]
	v_pk_mul_f32 v[36:37], v[154:155], v[36:37]
	v_pk_mul_f32 v[38:39], v[154:155], v[38:39]
	v_pk_mul_f32 v[32:33], v[154:155], v[32:33]
	v_pk_mul_f32 v[34:35], v[154:155], v[34:35]
	v_min_f32_e32 v36, 0x437f0000, v36
	v_min_f32_e32 v37, 0x437f0000, v37
	v_min_f32_e32 v38, 0x437f0000, v38
	v_min_f32_e32 v39, 0x437f0000, v39
	v_min_f32_e32 v32, 0x437f0000, v32
	v_min_f32_e32 v33, 0x437f0000, v33
	v_min_f32_e32 v34, 0x437f0000, v34
	v_min_f32_e32 v35, 0x437f0000, v35
	v_rndne_f32_e32 v36, v36
	v_rndne_f32_e32 v37, v37
	v_rndne_f32_e32 v38, v38
	v_rndne_f32_e32 v39, v39
	v_rndne_f32_e32 v32, v32
	v_rndne_f32_e32 v33, v33
	v_rndne_f32_e32 v34, v34
	v_rndne_f32_e32 v35, v35
	v_cvt_i32_f32_e32 v192, v36
	v_cvt_i32_f32_e32 v193, v32
	v_cvt_i32_f32_sdwa v192, v37 dst_sel:BYTE_1 dst_unused:UNUSED_PRESERVE src0_sel:DWORD
	v_cvt_i32_f32_sdwa v193, v33 dst_sel:BYTE_1 dst_unused:UNUSED_PRESERVE src0_sel:DWORD
	v_cvt_i32_f32_sdwa v192, v38 dst_sel:BYTE_2 dst_unused:UNUSED_PRESERVE src0_sel:DWORD
	v_cvt_i32_f32_sdwa v193, v34 dst_sel:BYTE_2 dst_unused:UNUSED_PRESERVE src0_sel:DWORD
	v_cvt_i32_f32_sdwa v192, v39 dst_sel:BYTE_3 dst_unused:UNUSED_PRESERVE src0_sel:DWORD
	v_cvt_i32_f32_sdwa v193, v35 dst_sel:BYTE_3 dst_unused:UNUSED_PRESERVE src0_sel:DWORD
	v_xor_b32_e32 v192, s55, v192
	v_xor_b32_e32 v193, s55, v193
	global_store_dwordx2 v[152:153], v[192:193], off offset:128
	v_add_co_u32_e32 v152, vcc, 0x280000, v150
	s_nop 1
	v_addc_co_u32_e32 v153, vcc, 0, v151, vcc
	v_cvt_f32_i32_e32 v28, v28
	v_cvt_f32_i32_e32 v29, v29
	v_cvt_f32_i32_e32 v30, v30
	v_cvt_f32_i32_e32 v31, v31
	v_cvt_f32_i32_e32 v24, v24
	v_cvt_f32_i32_e32 v25, v25
	v_cvt_f32_i32_e32 v26, v26
	v_cvt_f32_i32_e32 v27, v27
	v_pk_mul_f32 v[28:29], v[244:245], v[28:29] op_sel_hi:[0,1]
	v_pk_mul_f32 v[30:31], v[244:245], v[30:31] op_sel_hi:[0,1]
	v_pk_mul_f32 v[24:25], v[244:245], v[24:25] op_sel_hi:[0,1]
	v_pk_mul_f32 v[26:27], v[244:245], v[26:27] op_sel_hi:[0,1]
	v_max_f32_e32 v28, 0, v28
	v_max_f32_e32 v29, 0, v29
	v_max_f32_e32 v30, 0, v30
	v_max_f32_e32 v31, 0, v31
	v_max_f32_e32 v24, 0, v24
	v_max_f32_e32 v25, 0, v25
	v_max_f32_e32 v26, 0, v26
	v_max_f32_e32 v27, 0, v27
	v_pk_mul_f32 v[28:29], v[28:29], v[28:29]
	v_pk_mul_f32 v[30:31], v[30:31], v[30:31]
	v_pk_mul_f32 v[24:25], v[24:25], v[24:25]
	v_pk_mul_f32 v[26:27], v[26:27], v[26:27]
	v_pk_mul_f32 v[28:29], v[154:155], v[28:29]
	v_pk_mul_f32 v[30:31], v[154:155], v[30:31]
	v_pk_mul_f32 v[24:25], v[154:155], v[24:25]
	v_pk_mul_f32 v[26:27], v[154:155], v[26:27]
	v_min_f32_e32 v28, 0x437f0000, v28
	v_min_f32_e32 v29, 0x437f0000, v29
	v_min_f32_e32 v30, 0x437f0000, v30
	v_min_f32_e32 v31, 0x437f0000, v31
	v_min_f32_e32 v24, 0x437f0000, v24
	v_min_f32_e32 v25, 0x437f0000, v25
	v_min_f32_e32 v26, 0x437f0000, v26
	v_min_f32_e32 v27, 0x437f0000, v27
	v_rndne_f32_e32 v28, v28
	v_rndne_f32_e32 v29, v29
	v_rndne_f32_e32 v30, v30
	v_rndne_f32_e32 v31, v31
	v_rndne_f32_e32 v24, v24
	v_rndne_f32_e32 v25, v25
	v_rndne_f32_e32 v26, v26
	v_rndne_f32_e32 v27, v27
	v_cvt_i32_f32_e32 v194, v28
	v_cvt_i32_f32_e32 v195, v24
	v_cvt_i32_f32_sdwa v194, v29 dst_sel:BYTE_1 dst_unused:UNUSED_PRESERVE src0_sel:DWORD
	v_cvt_i32_f32_sdwa v195, v25 dst_sel:BYTE_1 dst_unused:UNUSED_PRESERVE src0_sel:DWORD
	v_cvt_i32_f32_sdwa v194, v30 dst_sel:BYTE_2 dst_unused:UNUSED_PRESERVE src0_sel:DWORD
	v_cvt_i32_f32_sdwa v195, v26 dst_sel:BYTE_2 dst_unused:UNUSED_PRESERVE src0_sel:DWORD
	v_cvt_i32_f32_sdwa v194, v31 dst_sel:BYTE_3 dst_unused:UNUSED_PRESERVE src0_sel:DWORD
	v_cvt_i32_f32_sdwa v195, v27 dst_sel:BYTE_3 dst_unused:UNUSED_PRESERVE src0_sel:DWORD
	v_xor_b32_e32 v194, s55, v194
	v_xor_b32_e32 v195, s55, v195
	global_store_dwordx2 v[152:153], v[194:195], off
	v_cvt_f32_i32_e32 v20, v20
	v_cvt_f32_i32_e32 v21, v21
	v_cvt_f32_i32_e32 v22, v22
	v_cvt_f32_i32_e32 v23, v23
	v_cvt_f32_i32_e32 v16, v16
	v_cvt_f32_i32_e32 v17, v17
	v_cvt_f32_i32_e32 v18, v18
	v_cvt_f32_i32_e32 v19, v19
	v_pk_mul_f32 v[20:21], v[244:245], v[20:21] op_sel_hi:[0,1]
	v_pk_mul_f32 v[22:23], v[244:245], v[22:23] op_sel_hi:[0,1]
	v_pk_mul_f32 v[16:17], v[244:245], v[16:17] op_sel_hi:[0,1]
	v_pk_mul_f32 v[18:19], v[244:245], v[18:19] op_sel_hi:[0,1]
	v_max_f32_e32 v20, 0, v20
	v_max_f32_e32 v21, 0, v21
	v_max_f32_e32 v22, 0, v22
	v_max_f32_e32 v23, 0, v23
	v_max_f32_e32 v16, 0, v16
	v_max_f32_e32 v17, 0, v17
	v_max_f32_e32 v18, 0, v18
	v_max_f32_e32 v19, 0, v19
	v_pk_mul_f32 v[20:21], v[20:21], v[20:21]
	v_pk_mul_f32 v[22:23], v[22:23], v[22:23]
	v_pk_mul_f32 v[16:17], v[16:17], v[16:17]
	v_pk_mul_f32 v[18:19], v[18:19], v[18:19]
	v_pk_mul_f32 v[20:21], v[154:155], v[20:21]
	v_pk_mul_f32 v[22:23], v[154:155], v[22:23]
	v_pk_mul_f32 v[16:17], v[154:155], v[16:17]
	v_pk_mul_f32 v[18:19], v[154:155], v[18:19]
	v_min_f32_e32 v20, 0x437f0000, v20
	v_min_f32_e32 v21, 0x437f0000, v21
	v_min_f32_e32 v22, 0x437f0000, v22
	v_min_f32_e32 v23, 0x437f0000, v23
	v_min_f32_e32 v16, 0x437f0000, v16
	v_min_f32_e32 v17, 0x437f0000, v17
	v_min_f32_e32 v18, 0x437f0000, v18
	v_min_f32_e32 v19, 0x437f0000, v19
	v_rndne_f32_e32 v20, v20
	v_rndne_f32_e32 v21, v21
	v_rndne_f32_e32 v22, v22
	v_rndne_f32_e32 v23, v23
	v_rndne_f32_e32 v16, v16
	v_rndne_f32_e32 v17, v17
	v_rndne_f32_e32 v18, v18
	v_rndne_f32_e32 v19, v19
	v_cvt_i32_f32_e32 v196, v20
	v_cvt_i32_f32_e32 v197, v16
	v_cvt_i32_f32_sdwa v196, v21 dst_sel:BYTE_1 dst_unused:UNUSED_PRESERVE src0_sel:DWORD
	v_cvt_i32_f32_sdwa v197, v17 dst_sel:BYTE_1 dst_unused:UNUSED_PRESERVE src0_sel:DWORD
	v_cvt_i32_f32_sdwa v196, v22 dst_sel:BYTE_2 dst_unused:UNUSED_PRESERVE src0_sel:DWORD
	v_cvt_i32_f32_sdwa v197, v18 dst_sel:BYTE_2 dst_unused:UNUSED_PRESERVE src0_sel:DWORD
	v_cvt_i32_f32_sdwa v196, v23 dst_sel:BYTE_3 dst_unused:UNUSED_PRESERVE src0_sel:DWORD
	v_cvt_i32_f32_sdwa v197, v19 dst_sel:BYTE_3 dst_unused:UNUSED_PRESERVE src0_sel:DWORD
	v_xor_b32_e32 v196, s55, v196
	v_xor_b32_e32 v197, s55, v197
	global_store_dwordx2 v[152:153], v[196:197], off offset:128
	v_add_co_u32_e32 v152, vcc, 0x2c0000, v150
	s_nop 1
	v_addc_co_u32_e32 v153, vcc, 0, v151, vcc
	v_cvt_f32_i32_e32 v12, v12
	v_cvt_f32_i32_e32 v13, v13
	v_cvt_f32_i32_e32 v14, v14
	v_cvt_f32_i32_e32 v15, v15
	v_cvt_f32_i32_e32 v8, v8
	v_cvt_f32_i32_e32 v9, v9
	v_cvt_f32_i32_e32 v10, v10
	v_cvt_f32_i32_e32 v11, v11
	v_pk_mul_f32 v[12:13], v[246:247], v[12:13] op_sel_hi:[0,1]
	v_pk_mul_f32 v[14:15], v[246:247], v[14:15] op_sel_hi:[0,1]
	v_pk_mul_f32 v[8:9], v[246:247], v[8:9] op_sel_hi:[0,1]
	v_pk_mul_f32 v[10:11], v[246:247], v[10:11] op_sel_hi:[0,1]
	v_max_f32_e32 v12, 0, v12
	v_max_f32_e32 v13, 0, v13
	v_max_f32_e32 v14, 0, v14
	v_max_f32_e32 v15, 0, v15
	v_max_f32_e32 v8, 0, v8
	v_max_f32_e32 v9, 0, v9
	v_max_f32_e32 v10, 0, v10
	v_max_f32_e32 v11, 0, v11
	v_pk_mul_f32 v[12:13], v[12:13], v[12:13]
	v_pk_mul_f32 v[14:15], v[14:15], v[14:15]
	v_pk_mul_f32 v[8:9], v[8:9], v[8:9]
	v_pk_mul_f32 v[10:11], v[10:11], v[10:11]
	v_pk_mul_f32 v[12:13], v[154:155], v[12:13]
	v_pk_mul_f32 v[14:15], v[154:155], v[14:15]
	v_pk_mul_f32 v[8:9], v[154:155], v[8:9]
	v_pk_mul_f32 v[10:11], v[154:155], v[10:11]
	v_min_f32_e32 v12, 0x437f0000, v12
	v_min_f32_e32 v13, 0x437f0000, v13
	v_min_f32_e32 v14, 0x437f0000, v14
	v_min_f32_e32 v15, 0x437f0000, v15
	v_min_f32_e32 v8, 0x437f0000, v8
	v_min_f32_e32 v9, 0x437f0000, v9
	v_min_f32_e32 v10, 0x437f0000, v10
	v_min_f32_e32 v11, 0x437f0000, v11
	v_rndne_f32_e32 v12, v12
	v_rndne_f32_e32 v13, v13
	v_rndne_f32_e32 v14, v14
	v_rndne_f32_e32 v15, v15
	v_rndne_f32_e32 v8, v8
	v_rndne_f32_e32 v9, v9
	v_rndne_f32_e32 v10, v10
	v_rndne_f32_e32 v11, v11
	v_cvt_i32_f32_e32 v198, v12
	v_cvt_i32_f32_e32 v199, v8
	v_cvt_i32_f32_sdwa v198, v13 dst_sel:BYTE_1 dst_unused:UNUSED_PRESERVE src0_sel:DWORD
	v_cvt_i32_f32_sdwa v199, v9 dst_sel:BYTE_1 dst_unused:UNUSED_PRESERVE src0_sel:DWORD
	v_cvt_i32_f32_sdwa v198, v14 dst_sel:BYTE_2 dst_unused:UNUSED_PRESERVE src0_sel:DWORD
	v_cvt_i32_f32_sdwa v199, v10 dst_sel:BYTE_2 dst_unused:UNUSED_PRESERVE src0_sel:DWORD
	v_cvt_i32_f32_sdwa v198, v15 dst_sel:BYTE_3 dst_unused:UNUSED_PRESERVE src0_sel:DWORD
	v_cvt_i32_f32_sdwa v199, v11 dst_sel:BYTE_3 dst_unused:UNUSED_PRESERVE src0_sel:DWORD
	v_xor_b32_e32 v198, s55, v198
	v_xor_b32_e32 v199, s55, v199
	global_store_dwordx2 v[152:153], v[198:199], off
	v_cvt_f32_i32_e32 v4, v4
	v_cvt_f32_i32_e32 v5, v5
	v_cvt_f32_i32_e32 v6, v6
	v_cvt_f32_i32_e32 v7, v7
	v_cvt_f32_i32_e32 v0, v0
	v_cvt_f32_i32_e32 v1, v1
	v_cvt_f32_i32_e32 v2, v2
	v_cvt_f32_i32_e32 v3, v3
	v_pk_mul_f32 v[4:5], v[246:247], v[4:5] op_sel_hi:[0,1]
	v_pk_mul_f32 v[6:7], v[246:247], v[6:7] op_sel_hi:[0,1]
	v_pk_mul_f32 v[0:1], v[246:247], v[0:1] op_sel_hi:[0,1]
	v_pk_mul_f32 v[2:3], v[246:247], v[2:3] op_sel_hi:[0,1]
	v_max_f32_e32 v4, 0, v4
	v_max_f32_e32 v5, 0, v5
	v_max_f32_e32 v6, 0, v6
	v_max_f32_e32 v7, 0, v7
	v_max_f32_e32 v0, 0, v0
	v_max_f32_e32 v1, 0, v1
	v_max_f32_e32 v2, 0, v2
	v_max_f32_e32 v3, 0, v3
	v_pk_mul_f32 v[4:5], v[4:5], v[4:5]
	v_pk_mul_f32 v[6:7], v[6:7], v[6:7]
	v_pk_mul_f32 v[0:1], v[0:1], v[0:1]
	v_pk_mul_f32 v[2:3], v[2:3], v[2:3]
	v_pk_mul_f32 v[4:5], v[154:155], v[4:5]
	v_pk_mul_f32 v[6:7], v[154:155], v[6:7]
	v_pk_mul_f32 v[0:1], v[154:155], v[0:1]
	v_pk_mul_f32 v[2:3], v[154:155], v[2:3]
	v_min_f32_e32 v4, 0x437f0000, v4
	v_min_f32_e32 v5, 0x437f0000, v5
	v_min_f32_e32 v6, 0x437f0000, v6
	v_min_f32_e32 v7, 0x437f0000, v7
	v_min_f32_e32 v0, 0x437f0000, v0
	v_min_f32_e32 v1, 0x437f0000, v1
	v_min_f32_e32 v2, 0x437f0000, v2
	v_min_f32_e32 v3, 0x437f0000, v3
	v_rndne_f32_e32 v4, v4
	v_rndne_f32_e32 v5, v5
	v_rndne_f32_e32 v6, v6
	v_rndne_f32_e32 v7, v7
	v_rndne_f32_e32 v0, v0
	v_rndne_f32_e32 v1, v1
	v_rndne_f32_e32 v2, v2
	v_rndne_f32_e32 v3, v3
	v_cvt_i32_f32_e32 v200, v4
	v_cvt_i32_f32_e32 v201, v0
	v_cvt_i32_f32_sdwa v200, v5 dst_sel:BYTE_1 dst_unused:UNUSED_PRESERVE src0_sel:DWORD
	v_cvt_i32_f32_sdwa v201, v1 dst_sel:BYTE_1 dst_unused:UNUSED_PRESERVE src0_sel:DWORD
	v_cvt_i32_f32_sdwa v200, v6 dst_sel:BYTE_2 dst_unused:UNUSED_PRESERVE src0_sel:DWORD
	v_cvt_i32_f32_sdwa v201, v2 dst_sel:BYTE_2 dst_unused:UNUSED_PRESERVE src0_sel:DWORD
	v_cvt_i32_f32_sdwa v200, v7 dst_sel:BYTE_3 dst_unused:UNUSED_PRESERVE src0_sel:DWORD
	v_cvt_i32_f32_sdwa v201, v3 dst_sel:BYTE_3 dst_unused:UNUSED_PRESERVE src0_sel:DWORD
	v_xor_b32_e32 v200, s55, v200
	v_xor_b32_e32 v201, s55, v201
	global_store_dwordx2 v[152:153], v[200:201], off offset:128
	s_andn2_b64 vcc, exec, s[2:3]
	s_mov_b64 s[0:1], -1
	s_cbranch_vccnz .LBB0_1348
	s_branch .Ljoin_p11
